# K-loop back-edge rotation: loop counter / pointer SALU block moved from after the last exit barrier into the last load part ahead of its entry barrier
# speedup vs baseline: 1.0079x; 1.0079x over previous
.LBB0_287:
	s_add_u32 s0, s22, 0xfffc0080
	s_addc_u32 s1, s23, -1
	s_add_i32 s72, 0, 0x10000
	s_cmp_eq_u32 s69, 12
	s_cselect_b32 s27, s18, s1
	s_cselect_b32 s26, s19, s0
	s_cselect_b32 s25, s45, s68
	s_cselect_b32 s24, s47, s59
	s_add_i32 m0, s53, 0xc000
	ds_read_b128 v[158:161], v165
	ds_read_b128 v[174:177], v165 offset:1024
	ds_read_b128 v[178:181], v165 offset:2048
	ds_read_b128 v[182:185], v165 offset:3072
	ds_read_b128 v[186:189], v165 offset:4096
	ds_read_b128 v[190:193], v165 offset:5120
	ds_read_b128 v[194:197], v165 offset:6144
	ds_read_b128 v[198:201], v165 offset:7168
	global_load_lds_dwordx4 v154, s[22:23]
	s_add_i32 m0, s53, 0xe000
	s_nop 0
	global_load_lds_dwordx4 v156, s[22:23]
	s_waitcnt vmcnt(10) lgkmcnt(8)
	s_setprio 1
	s_barrier
	s_waitcnt lgkmcnt(0)
	v_mfma_f32_16x16x32_bf16 v[144:147], v[68:71], v[158:161], v[144:147]
	v_mfma_f32_16x16x32_bf16 v[140:143], v[76:79], v[158:161], v[140:143]
	v_mfma_f32_16x16x32_bf16 v[128:131], v[68:71], v[178:181], v[128:131]
	v_mfma_f32_16x16x32_bf16 v[124:127], v[76:79], v[178:181], v[124:127]
	v_mfma_f32_16x16x32_bf16 v[112:115], v[68:71], v[186:189], v[112:115]
	v_mfma_f32_16x16x32_bf16 v[108:111], v[76:79], v[186:189], v[108:111]
	v_mfma_f32_16x16x32_bf16 v[96:99], v[68:71], v[194:197], v[96:99]
	v_mfma_f32_16x16x32_bf16 v[92:95], v[76:79], v[194:197], v[92:95]
	v_mfma_f32_16x16x32_bf16 v[144:147], v[72:75], v[174:177], v[144:147]
	v_mfma_f32_16x16x32_bf16 v[140:143], v[80:83], v[174:177], v[140:143]
	v_mfma_f32_16x16x32_bf16 v[128:131], v[72:75], v[182:185], v[128:131]
	v_mfma_f32_16x16x32_bf16 v[124:127], v[80:83], v[182:185], v[124:127]
	v_mfma_f32_16x16x32_bf16 v[112:115], v[72:75], v[190:193], v[112:115]
	v_mfma_f32_16x16x32_bf16 v[108:111], v[80:83], v[190:193], v[108:111]
	v_mfma_f32_16x16x32_bf16 v[96:99], v[72:75], v[198:201], v[96:99]
	v_mfma_f32_16x16x32_bf16 v[92:95], v[80:83], v[198:201], v[92:95]
	s_barrier
	s_setprio 0
	s_add_i32 s73, 0, 0x14000
	s_add_i32 s0, s72, s52
	v_add_u32_e32 v166, s73, v163
	v_lshl_add_u64 v[218:219], s[24:25], 0, v[26:27]
	s_mov_b32 m0, s0
	ds_read_b128 v[202:205], v166
	ds_read_b128 v[206:209], v166 offset:1024
	ds_read_b128 v[210:213], v166 offset:2048
	ds_read_b128 v[214:217], v166 offset:3072
	global_load_lds_dwordx4 v[218:219], off
	v_lshl_add_u64 v[220:221], s[24:25], 0, v[148:149]
	s_add_i32 m0, s0, 0x2000
	s_nop 0
	global_load_lds_dwordx4 v[220:221], off
	s_waitcnt vmcnt(10)
	s_setprio 1
	s_barrier
	s_waitcnt lgkmcnt(0)
	v_mfma_f32_16x16x32_bf16 v[136:139], v[202:205], v[158:161], v[136:139]
	v_mfma_f32_16x16x32_bf16 v[132:135], v[210:213], v[158:161], v[132:135]
	v_mfma_f32_16x16x32_bf16 v[120:123], v[202:205], v[178:181], v[120:123]
	v_mfma_f32_16x16x32_bf16 v[116:119], v[210:213], v[178:181], v[116:119]
	v_mfma_f32_16x16x32_bf16 v[104:107], v[202:205], v[186:189], v[104:107]
	v_mfma_f32_16x16x32_bf16 v[100:103], v[210:213], v[186:189], v[100:103]
	v_mfma_f32_16x16x32_bf16 v[88:91], v[202:205], v[194:197], v[88:91]
	v_mfma_f32_16x16x32_bf16 v[84:87], v[210:213], v[194:197], v[84:87]
	v_mfma_f32_16x16x32_bf16 v[136:139], v[206:209], v[174:177], v[136:139]
	v_mfma_f32_16x16x32_bf16 v[132:135], v[214:217], v[174:177], v[132:135]
	v_mfma_f32_16x16x32_bf16 v[120:123], v[206:209], v[182:185], v[120:123]
	v_mfma_f32_16x16x32_bf16 v[116:119], v[214:217], v[182:185], v[116:119]
	v_mfma_f32_16x16x32_bf16 v[104:107], v[206:209], v[190:193], v[104:107]
	v_mfma_f32_16x16x32_bf16 v[100:103], v[214:217], v[190:193], v[100:103]
	v_mfma_f32_16x16x32_bf16 v[88:91], v[206:209], v[198:201], v[88:91]
	v_mfma_f32_16x16x32_bf16 v[84:87], v[214:217], v[198:201], v[84:87]
	s_barrier
	s_setprio 0
	s_mov_b32 m0, s53
	v_lshl_add_u64 v[222:223], s[26:27], 0, v[152:153]
	ds_read_b128 v[158:161], v165 offset:16384
	ds_read_b128 v[174:177], v165 offset:17408
	ds_read_b128 v[178:181], v165 offset:18432
	ds_read_b128 v[182:185], v165 offset:19456
	ds_read_b128 v[186:189], v165 offset:20480
	ds_read_b128 v[190:193], v165 offset:21504
	ds_read_b128 v[194:197], v165 offset:22528
	ds_read_b128 v[198:201], v165 offset:23552
	global_load_lds_dwordx4 v[222:223], off
	v_lshl_add_u64 v[224:225], s[26:27], 0, v[150:151]
	s_mov_b32 m0, s54
	s_nop 0
	global_load_lds_dwordx4 v[224:225], off
	s_waitcnt vmcnt(10)
	s_setprio 1
	s_barrier
	s_waitcnt lgkmcnt(0)
	v_mfma_f32_16x16x32_bf16 v[64:67], v[68:71], v[158:161], v[64:67]
	v_mfma_f32_16x16x32_bf16 v[60:63], v[76:79], v[158:161], v[60:63]
	v_mfma_f32_16x16x32_bf16 v[48:51], v[68:71], v[178:181], v[48:51]
	v_mfma_f32_16x16x32_bf16 v[44:47], v[76:79], v[178:181], v[44:47]
	v_mfma_f32_16x16x32_bf16 v[32:35], v[68:71], v[186:189], v[32:35]
	v_mfma_f32_16x16x32_bf16 v[28:31], v[76:79], v[186:189], v[28:31]
	v_mfma_f32_16x16x32_bf16 v[14:17], v[68:71], v[194:197], v[14:17]
	v_mfma_f32_16x16x32_bf16 v[10:13], v[76:79], v[194:197], v[10:13]
	v_mfma_f32_16x16x32_bf16 v[64:67], v[72:75], v[174:177], v[64:67]
	v_mfma_f32_16x16x32_bf16 v[60:63], v[80:83], v[174:177], v[60:63]
	v_mfma_f32_16x16x32_bf16 v[48:51], v[72:75], v[182:185], v[48:51]
	v_mfma_f32_16x16x32_bf16 v[44:47], v[80:83], v[182:185], v[44:47]
	v_mfma_f32_16x16x32_bf16 v[32:35], v[72:75], v[190:193], v[32:35]
	v_mfma_f32_16x16x32_bf16 v[28:31], v[80:83], v[190:193], v[28:31]
	v_mfma_f32_16x16x32_bf16 v[14:17], v[72:75], v[198:201], v[14:17]
	v_mfma_f32_16x16x32_bf16 v[10:13], v[80:83], v[198:201], v[10:13]
	s_barrier
	s_setprio 0
	s_add_u32 s0, s24, 0x40000
	s_addc_u32 s1, s25, 0
	s_add_i32 s72, s73, s52
	s_mov_b32 m0, s72
	s_nop 0
	global_load_lds_dwordx4 v26, s[0:1]
	s_add_i32 m0, s72, 0x2000
	s_nop 0
	global_load_lds_dwordx4 v148, s[0:1]
	v_add_u32_e32 v80, 0x18000, v163
	ds_read_b128 v[68:71], v80
	ds_read_b128 v[72:75], v80 offset:1024
	ds_read_b128 v[76:79], v80 offset:2048
	ds_read_b128 v[80:83], v80 offset:3072
	s_waitcnt vmcnt(10)
	s_setprio 1
	s_barrier
	v_mfma_f32_16x16x32_bf16 v[56:59], v[202:205], v[158:161], v[56:59]
	v_mfma_f32_16x16x32_bf16 v[52:55], v[210:213], v[158:161], v[52:55]
	v_mfma_f32_16x16x32_bf16 v[40:43], v[202:205], v[178:181], v[40:43]
	v_mfma_f32_16x16x32_bf16 v[36:39], v[210:213], v[178:181], v[36:39]
	v_mfma_f32_16x16x32_bf16 v[22:25], v[202:205], v[186:189], v[22:25]
	v_mfma_f32_16x16x32_bf16 v[18:21], v[210:213], v[186:189], v[18:21]
	v_mfma_f32_16x16x32_bf16 v[6:9], v[202:205], v[194:197], v[6:9]
	v_mfma_f32_16x16x32_bf16 v[2:5], v[210:213], v[194:197], v[2:5]
	v_mfma_f32_16x16x32_bf16 v[56:59], v[206:209], v[174:177], v[56:59]
	v_mfma_f32_16x16x32_bf16 v[52:55], v[214:217], v[174:177], v[52:55]
	v_mfma_f32_16x16x32_bf16 v[40:43], v[206:209], v[182:185], v[40:43]
	v_mfma_f32_16x16x32_bf16 v[36:39], v[214:217], v[182:185], v[36:39]
	v_mfma_f32_16x16x32_bf16 v[22:25], v[206:209], v[190:193], v[22:25]
	v_mfma_f32_16x16x32_bf16 v[18:21], v[214:217], v[190:193], v[18:21]
	v_mfma_f32_16x16x32_bf16 v[6:9], v[206:209], v[198:201], v[6:9]
	v_mfma_f32_16x16x32_bf16 v[2:5], v[214:217], v[198:201], v[2:5]
	s_barrier
	s_setprio 0
	s_add_i32 s72, 0, 0x18000
	s_add_u32 s0, s26, 0x40000
	s_addc_u32 s1, s27, 0
	s_mov_b32 m0, s55
	ds_read_b128 v[158:161], v165 offset:32768
	ds_read_b128 v[174:177], v165 offset:33792
	ds_read_b128 v[178:181], v165 offset:34816
	ds_read_b128 v[182:185], v165 offset:35840
	ds_read_b128 v[186:189], v165 offset:36864
	ds_read_b128 v[190:193], v165 offset:37888
	ds_read_b128 v[194:197], v165 offset:38912
	ds_read_b128 v[198:201], v165 offset:39936
	global_load_lds_dwordx4 v152, s[0:1]
	s_mov_b32 m0, s56
	s_nop 0
	global_load_lds_dwordx4 v150, s[0:1]
	s_waitcnt vmcnt(10) lgkmcnt(8)
	s_setprio 1
	s_barrier
	s_waitcnt lgkmcnt(0)
	v_mfma_f32_16x16x32_bf16 v[144:147], v[68:71], v[158:161], v[144:147]
	v_mfma_f32_16x16x32_bf16 v[140:143], v[76:79], v[158:161], v[140:143]
	v_mfma_f32_16x16x32_bf16 v[128:131], v[68:71], v[178:181], v[128:131]
	v_mfma_f32_16x16x32_bf16 v[124:127], v[76:79], v[178:181], v[124:127]
	v_mfma_f32_16x16x32_bf16 v[112:115], v[68:71], v[186:189], v[112:115]
	v_mfma_f32_16x16x32_bf16 v[108:111], v[76:79], v[186:189], v[108:111]
	v_mfma_f32_16x16x32_bf16 v[96:99], v[68:71], v[194:197], v[96:99]
	v_mfma_f32_16x16x32_bf16 v[92:95], v[76:79], v[194:197], v[92:95]
	v_mfma_f32_16x16x32_bf16 v[144:147], v[72:75], v[174:177], v[144:147]
	v_mfma_f32_16x16x32_bf16 v[140:143], v[80:83], v[174:177], v[140:143]
	v_mfma_f32_16x16x32_bf16 v[128:131], v[72:75], v[182:185], v[128:131]
	v_mfma_f32_16x16x32_bf16 v[124:127], v[80:83], v[182:185], v[124:127]
	v_mfma_f32_16x16x32_bf16 v[112:115], v[72:75], v[190:193], v[112:115]
	v_mfma_f32_16x16x32_bf16 v[108:111], v[80:83], v[190:193], v[108:111]
	v_mfma_f32_16x16x32_bf16 v[96:99], v[72:75], v[198:201], v[96:99]
	v_mfma_f32_16x16x32_bf16 v[92:95], v[80:83], v[198:201], v[92:95]
	s_barrier
	s_setprio 0
	s_add_i32 s26, 0, 0x1c000
	s_add_i32 s0, s72, s52
	v_add_u32_e32 v166, s26, v163
	v_lshl_add_u64 v[218:219], v[218:219], 0, s[12:13]
	s_mov_b32 m0, s0
	ds_read_b128 v[202:205], v166
	ds_read_b128 v[206:209], v166 offset:1024
	ds_read_b128 v[210:213], v166 offset:2048
	ds_read_b128 v[214:217], v166 offset:3072
	global_load_lds_dwordx4 v[218:219], off
	v_lshl_add_u64 v[218:219], v[220:221], 0, s[12:13]
	s_add_i32 m0, s0, 0x2000
	s_nop 0
	global_load_lds_dwordx4 v[218:219], off
	s_waitcnt vmcnt(10)
	s_setprio 1
	s_barrier
	s_waitcnt lgkmcnt(0)
	v_mfma_f32_16x16x32_bf16 v[136:139], v[202:205], v[158:161], v[136:139]
	v_mfma_f32_16x16x32_bf16 v[132:135], v[210:213], v[158:161], v[132:135]
	v_mfma_f32_16x16x32_bf16 v[120:123], v[202:205], v[178:181], v[120:123]
	v_mfma_f32_16x16x32_bf16 v[116:119], v[210:213], v[178:181], v[116:119]
	v_mfma_f32_16x16x32_bf16 v[104:107], v[202:205], v[186:189], v[104:107]
	v_mfma_f32_16x16x32_bf16 v[100:103], v[210:213], v[186:189], v[100:103]
	v_mfma_f32_16x16x32_bf16 v[88:91], v[202:205], v[194:197], v[88:91]
	v_mfma_f32_16x16x32_bf16 v[84:87], v[210:213], v[194:197], v[84:87]
	v_mfma_f32_16x16x32_bf16 v[136:139], v[206:209], v[174:177], v[136:139]
	v_mfma_f32_16x16x32_bf16 v[132:135], v[214:217], v[174:177], v[132:135]
	v_mfma_f32_16x16x32_bf16 v[120:123], v[206:209], v[182:185], v[120:123]
	v_mfma_f32_16x16x32_bf16 v[116:119], v[214:217], v[182:185], v[116:119]
	v_mfma_f32_16x16x32_bf16 v[104:107], v[206:209], v[190:193], v[104:107]
	v_mfma_f32_16x16x32_bf16 v[100:103], v[214:217], v[190:193], v[100:103]
	v_mfma_f32_16x16x32_bf16 v[88:91], v[206:209], v[198:201], v[88:91]
	v_mfma_f32_16x16x32_bf16 v[84:87], v[214:217], v[198:201], v[84:87]
	s_barrier
	s_setprio 0
	s_mov_b32 m0, s30
	v_lshl_add_u64 v[218:219], v[222:223], 0, s[12:13]
	ds_read_b128 v[158:161], v165 offset:49152
	ds_read_b128 v[174:177], v165 offset:50176
	ds_read_b128 v[178:181], v165 offset:51200
	ds_read_b128 v[182:185], v165 offset:52224
	ds_read_b128 v[186:189], v165 offset:53248
	ds_read_b128 v[190:193], v165 offset:54272
	ds_read_b128 v[194:197], v165 offset:55296
	ds_read_b128 v[198:201], v165 offset:56320
	global_load_lds_dwordx4 v[218:219], off
	v_lshl_add_u64 v[218:219], v[224:225], 0, s[12:13]
	s_mov_b32 m0, s31
	s_nop 0
	global_load_lds_dwordx4 v[218:219], off
	s_waitcnt vmcnt(10)
	s_setprio 1
	s_barrier
	s_waitcnt lgkmcnt(0)
	v_mfma_f32_16x16x32_bf16 v[64:67], v[68:71], v[158:161], v[64:67]
	v_mfma_f32_16x16x32_bf16 v[60:63], v[76:79], v[158:161], v[60:63]
	v_mfma_f32_16x16x32_bf16 v[48:51], v[68:71], v[178:181], v[48:51]
	v_mfma_f32_16x16x32_bf16 v[44:47], v[76:79], v[178:181], v[44:47]
	v_mfma_f32_16x16x32_bf16 v[32:35], v[68:71], v[186:189], v[32:35]
	v_mfma_f32_16x16x32_bf16 v[28:31], v[76:79], v[186:189], v[28:31]
	v_mfma_f32_16x16x32_bf16 v[14:17], v[68:71], v[194:197], v[14:17]
	v_mfma_f32_16x16x32_bf16 v[10:13], v[76:79], v[194:197], v[10:13]
	v_mfma_f32_16x16x32_bf16 v[64:67], v[72:75], v[174:177], v[64:67]
	v_mfma_f32_16x16x32_bf16 v[60:63], v[80:83], v[174:177], v[60:63]
	v_mfma_f32_16x16x32_bf16 v[48:51], v[72:75], v[182:185], v[48:51]
	v_mfma_f32_16x16x32_bf16 v[44:47], v[80:83], v[182:185], v[44:47]
	v_mfma_f32_16x16x32_bf16 v[32:35], v[72:75], v[190:193], v[32:35]
	v_mfma_f32_16x16x32_bf16 v[28:31], v[80:83], v[190:193], v[28:31]
	v_mfma_f32_16x16x32_bf16 v[14:17], v[72:75], v[198:201], v[14:17]
	v_mfma_f32_16x16x32_bf16 v[10:13], v[80:83], v[198:201], v[10:13]
	s_barrier
	s_setprio 0
	s_add_u32 s0, s24, 0x40080
	s_addc_u32 s1, s25, 0
	s_add_i32 s24, s26, s52
	s_mov_b32 m0, s24
	s_nop 0
	global_load_lds_dwordx4 v26, s[0:1]
	s_add_i32 m0, s24, 0x2000
	s_nop 0
	global_load_lds_dwordx4 v148, s[0:1]
	v_add_u32_e32 v80, 0x10000, v163
	ds_read_b128 v[68:71], v80
	ds_read_b128 v[72:75], v80 offset:1024
	ds_read_b128 v[76:79], v80 offset:2048
	ds_read_b128 v[80:83], v80 offset:3072
	s_add_i32 s69, s69, 2
	s_add_u32 s22, s22, 0x100
	s_addc_u32 s23, s23, 0
	s_add_u32 s59, s59, 0x100
	s_addc_u32 s68, s68, 0
	s_cmp_gt_u32 s69, 13
	s_waitcnt vmcnt(10)
	s_setprio 1
	s_barrier
	v_mfma_f32_16x16x32_bf16 v[56:59], v[202:205], v[158:161], v[56:59]
	v_mfma_f32_16x16x32_bf16 v[52:55], v[210:213], v[158:161], v[52:55]
	v_mfma_f32_16x16x32_bf16 v[40:43], v[202:205], v[178:181], v[40:43]
	v_mfma_f32_16x16x32_bf16 v[36:39], v[210:213], v[178:181], v[36:39]
	v_mfma_f32_16x16x32_bf16 v[22:25], v[202:205], v[186:189], v[22:25]
	v_mfma_f32_16x16x32_bf16 v[18:21], v[210:213], v[186:189], v[18:21]
	v_mfma_f32_16x16x32_bf16 v[6:9], v[202:205], v[194:197], v[6:9]
	v_mfma_f32_16x16x32_bf16 v[2:5], v[210:213], v[194:197], v[2:5]
	v_mfma_f32_16x16x32_bf16 v[56:59], v[206:209], v[174:177], v[56:59]
	v_mfma_f32_16x16x32_bf16 v[52:55], v[214:217], v[174:177], v[52:55]
	v_mfma_f32_16x16x32_bf16 v[40:43], v[206:209], v[182:185], v[40:43]
	v_mfma_f32_16x16x32_bf16 v[36:39], v[214:217], v[182:185], v[36:39]
	v_mfma_f32_16x16x32_bf16 v[22:25], v[206:209], v[190:193], v[22:25]
	v_mfma_f32_16x16x32_bf16 v[18:21], v[214:217], v[190:193], v[18:21]
	v_mfma_f32_16x16x32_bf16 v[6:9], v[206:209], v[198:201], v[6:9]
	v_mfma_f32_16x16x32_bf16 v[2:5], v[214:217], v[198:201], v[2:5]
	s_barrier
	s_setprio 0
	s_cbranch_scc0 .LBB0_287
	s_waitcnt lgkmcnt(0)
	s_cmpk_gt_i32 s58, 0xff
	s_mov_b64 s[18:19], 0xb000
	s_cbranch_scc1 .LBB0_283
	s_ashr_i32 s0, s58, 5
	s_mul_hi_i32 s19, s0, 0x1600
	s_mul_i32 s18, s0, 0x1600
	s_branch .LBB0_283

.LBB0_361:
	s_add_u32 s28, s26, 0x100
	s_addc_u32 s29, s27, 0
	s_add_i32 s0, 0, 0x10000
	s_cmp_eq_u32 s46, 40
	s_cselect_b32 s35, s45, s29
	s_cselect_b32 s34, s44, s28
	s_cselect_b32 s31, s23, s19
	s_cselect_b32 s30, s22, s18
	s_add_i32 m0, s20, 0xc000
	ds_read_b128 v[172:175], v224
	ds_read_b128 v[176:179], v224 offset:1024
	ds_read_b128 v[180:183], v224 offset:2048
	ds_read_b128 v[184:187], v224 offset:3072
	ds_read_b128 v[188:191], v224 offset:4096
	ds_read_b128 v[192:195], v224 offset:5120
	ds_read_b128 v[196:199], v224 offset:6144
	ds_read_b128 v[200:203], v224 offset:7168
	global_load_lds_dwordx4 v152, s[26:27]
	v_lshl_add_u64 v[164:165], s[26:27], 0, v[154:155]
	s_add_i32 m0, s20, 0xe000
	s_nop 0
	global_load_lds_dwordx4 v[164:165], off
	s_waitcnt vmcnt(10) lgkmcnt(8)
	s_setprio 1
	s_barrier
	s_waitcnt lgkmcnt(0)
	v_mfma_f32_16x16x32_bf16 v[128:131], v[132:135], v[172:175], v[128:131]
	v_mfma_f32_16x16x32_bf16 v[124:127], v[156:159], v[172:175], v[124:127]
	v_mfma_f32_16x16x32_bf16 v[120:123], v[132:135], v[180:183], v[120:123]
	v_mfma_f32_16x16x32_bf16 v[116:119], v[156:159], v[180:183], v[116:119]
	v_mfma_f32_16x16x32_bf16 v[112:115], v[132:135], v[188:191], v[112:115]
	v_mfma_f32_16x16x32_bf16 v[108:111], v[156:159], v[188:191], v[108:111]
	v_mfma_f32_16x16x32_bf16 v[104:107], v[132:135], v[196:199], v[104:107]
	v_mfma_f32_16x16x32_bf16 v[100:103], v[156:159], v[196:199], v[100:103]
	v_mfma_f32_16x16x32_bf16 v[128:131], v[136:139], v[176:179], v[128:131]
	v_mfma_f32_16x16x32_bf16 v[124:127], v[160:163], v[176:179], v[124:127]
	v_mfma_f32_16x16x32_bf16 v[120:123], v[136:139], v[184:187], v[120:123]
	v_mfma_f32_16x16x32_bf16 v[116:119], v[160:163], v[184:187], v[116:119]
	v_mfma_f32_16x16x32_bf16 v[112:115], v[136:139], v[192:195], v[112:115]
	v_mfma_f32_16x16x32_bf16 v[108:111], v[160:163], v[192:195], v[108:111]
	v_mfma_f32_16x16x32_bf16 v[104:107], v[136:139], v[200:203], v[104:107]
	v_mfma_f32_16x16x32_bf16 v[100:103], v[160:163], v[200:203], v[100:103]
	s_barrier
	s_setprio 0
	s_add_i32 s26, 0, 0x14000
	v_add_u32_e32 v164, s26, v222
	s_add_i32 s0, s0, s17
	ds_read_b128 v[204:207], v164
	ds_read_b128 v[208:211], v164 offset:1024
	ds_read_b128 v[212:215], v164 offset:2048
	ds_read_b128 v[216:219], v164 offset:3072
	v_lshl_add_u64 v[164:165], s[30:31], 0, v[26:27]
	s_mov_b32 m0, s0
	v_lshl_add_u64 v[166:167], s[30:31], 0, v[140:141]
	global_load_lds_dwordx4 v[164:165], off
	s_add_i32 m0, s0, 0x2000
	s_nop 0
	global_load_lds_dwordx4 v[166:167], off
	s_waitcnt vmcnt(10)
	s_setprio 1
	s_barrier
	s_waitcnt lgkmcnt(0)
	v_mfma_f32_16x16x32_bf16 v[64:67], v[204:207], v[172:175], v[64:67]
	v_mfma_f32_16x16x32_bf16 v[60:63], v[212:215], v[172:175], v[60:63]
	v_mfma_f32_16x16x32_bf16 v[56:59], v[204:207], v[180:183], v[56:59]
	v_mfma_f32_16x16x32_bf16 v[52:55], v[212:215], v[180:183], v[52:55]
	v_mfma_f32_16x16x32_bf16 v[48:51], v[204:207], v[188:191], v[48:51]
	v_mfma_f32_16x16x32_bf16 v[44:47], v[212:215], v[188:191], v[44:47]
	v_mfma_f32_16x16x32_bf16 v[40:43], v[204:207], v[196:199], v[40:43]
	v_mfma_f32_16x16x32_bf16 v[36:39], v[212:215], v[196:199], v[36:39]
	v_mfma_f32_16x16x32_bf16 v[64:67], v[208:211], v[176:179], v[64:67]
	v_mfma_f32_16x16x32_bf16 v[60:63], v[216:219], v[176:179], v[60:63]
	v_mfma_f32_16x16x32_bf16 v[56:59], v[208:211], v[184:187], v[56:59]
	v_mfma_f32_16x16x32_bf16 v[52:55], v[216:219], v[184:187], v[52:55]
	v_mfma_f32_16x16x32_bf16 v[48:51], v[208:211], v[192:195], v[48:51]
	v_mfma_f32_16x16x32_bf16 v[44:47], v[216:219], v[192:195], v[44:47]
	v_mfma_f32_16x16x32_bf16 v[40:43], v[208:211], v[200:203], v[40:43]
	v_mfma_f32_16x16x32_bf16 v[36:39], v[216:219], v[200:203], v[36:39]
	s_barrier
	s_setprio 0
	s_mov_b32 m0, s20
	v_lshl_add_u64 v[168:169], s[34:35], 0, v[144:145]
	ds_read_b128 v[172:175], v224 offset:16384
	ds_read_b128 v[176:179], v224 offset:17408
	ds_read_b128 v[180:183], v224 offset:18432
	ds_read_b128 v[184:187], v224 offset:19456
	ds_read_b128 v[188:191], v224 offset:20480
	ds_read_b128 v[192:195], v224 offset:21504
	ds_read_b128 v[196:199], v224 offset:22528
	ds_read_b128 v[200:203], v224 offset:23552
	global_load_lds_dwordx4 v[168:169], off
	v_lshl_add_u64 v[220:221], s[34:35], 0, v[142:143]
	s_mov_b32 m0, s21
	s_nop 0
	global_load_lds_dwordx4 v[220:221], off
	s_waitcnt vmcnt(10)
	s_setprio 1
	s_barrier
	s_waitcnt lgkmcnt(0)
	v_mfma_f32_16x16x32_bf16 v[96:99], v[132:135], v[172:175], v[96:99]
	v_mfma_f32_16x16x32_bf16 v[92:95], v[156:159], v[172:175], v[92:95]
	v_mfma_f32_16x16x32_bf16 v[88:91], v[132:135], v[180:183], v[88:91]
	v_mfma_f32_16x16x32_bf16 v[84:87], v[156:159], v[180:183], v[84:87]
	v_mfma_f32_16x16x32_bf16 v[80:83], v[132:135], v[188:191], v[80:83]
	v_mfma_f32_16x16x32_bf16 v[76:79], v[156:159], v[188:191], v[76:79]
	v_mfma_f32_16x16x32_bf16 v[72:75], v[132:135], v[196:199], v[72:75]
	v_mfma_f32_16x16x32_bf16 v[68:71], v[156:159], v[196:199], v[68:71]
	v_mfma_f32_16x16x32_bf16 v[96:99], v[136:139], v[176:179], v[96:99]
	v_mfma_f32_16x16x32_bf16 v[92:95], v[160:163], v[176:179], v[92:95]
	v_mfma_f32_16x16x32_bf16 v[88:91], v[136:139], v[184:187], v[88:91]
	v_mfma_f32_16x16x32_bf16 v[84:87], v[160:163], v[184:187], v[84:87]
	v_mfma_f32_16x16x32_bf16 v[80:83], v[136:139], v[192:195], v[80:83]
	v_mfma_f32_16x16x32_bf16 v[76:79], v[160:163], v[192:195], v[76:79]
	v_mfma_f32_16x16x32_bf16 v[72:75], v[136:139], v[200:203], v[72:75]
	v_mfma_f32_16x16x32_bf16 v[68:71], v[160:163], v[200:203], v[68:71]
	s_barrier
	s_setprio 0
	s_add_u32 s0, s30, 0xb0000
	s_addc_u32 s1, s31, 0
	s_add_i32 s26, s26, s17
	s_mov_b32 m0, s26
	s_nop 0
	global_load_lds_dwordx4 v26, s[0:1]
	s_add_i32 m0, s26, 0x2000
	s_nop 0
	global_load_lds_dwordx4 v140, s[0:1]
	v_add_u32_e32 v160, 0x18000, v222
	ds_read_b128 v[132:135], v160
	ds_read_b128 v[136:139], v160 offset:1024
	ds_read_b128 v[156:159], v160 offset:2048
	ds_read_b128 v[160:163], v160 offset:3072
	s_waitcnt vmcnt(10)
	s_setprio 1
	s_barrier
	v_mfma_f32_16x16x32_bf16 v[32:35], v[204:207], v[172:175], v[32:35]
	v_mfma_f32_16x16x32_bf16 v[28:31], v[212:215], v[172:175], v[28:31]
	v_mfma_f32_16x16x32_bf16 v[22:25], v[204:207], v[180:183], v[22:25]
	v_mfma_f32_16x16x32_bf16 v[18:21], v[212:215], v[180:183], v[18:21]
	v_mfma_f32_16x16x32_bf16 v[14:17], v[204:207], v[188:191], v[14:17]
	v_mfma_f32_16x16x32_bf16 v[10:13], v[212:215], v[188:191], v[10:13]
	v_mfma_f32_16x16x32_bf16 v[6:9], v[204:207], v[196:199], v[6:9]
	v_mfma_f32_16x16x32_bf16 v[2:5], v[212:215], v[196:199], v[2:5]
	v_mfma_f32_16x16x32_bf16 v[32:35], v[208:211], v[176:179], v[32:35]
	v_mfma_f32_16x16x32_bf16 v[28:31], v[216:219], v[176:179], v[28:31]
	v_mfma_f32_16x16x32_bf16 v[22:25], v[208:211], v[184:187], v[22:25]
	v_mfma_f32_16x16x32_bf16 v[18:21], v[216:219], v[184:187], v[18:21]
	v_mfma_f32_16x16x32_bf16 v[14:17], v[208:211], v[192:195], v[14:17]
	v_mfma_f32_16x16x32_bf16 v[10:13], v[216:219], v[192:195], v[10:13]
	v_mfma_f32_16x16x32_bf16 v[6:9], v[208:211], v[200:203], v[6:9]
	v_mfma_f32_16x16x32_bf16 v[2:5], v[216:219], v[200:203], v[2:5]
	s_barrier
	s_setprio 0
	s_add_i32 s26, 0, 0x18000
	s_add_u32 s0, s34, 0xb0000
	s_addc_u32 s1, s35, 0
	s_mov_b32 m0, s36
	ds_read_b128 v[172:175], v224 offset:32768
	ds_read_b128 v[176:179], v224 offset:33792
	ds_read_b128 v[180:183], v224 offset:34816
	ds_read_b128 v[184:187], v224 offset:35840
	ds_read_b128 v[188:191], v224 offset:36864
	ds_read_b128 v[192:195], v224 offset:37888
	ds_read_b128 v[196:199], v224 offset:38912
	ds_read_b128 v[200:203], v224 offset:39936
	global_load_lds_dwordx4 v144, s[0:1]
	s_mov_b32 m0, s37
	s_nop 0
	global_load_lds_dwordx4 v142, s[0:1]
	s_waitcnt vmcnt(10) lgkmcnt(8)
	s_setprio 1
	s_barrier
	s_waitcnt lgkmcnt(0)
	v_mfma_f32_16x16x32_bf16 v[128:131], v[132:135], v[172:175], v[128:131]
	v_mfma_f32_16x16x32_bf16 v[124:127], v[156:159], v[172:175], v[124:127]
	v_mfma_f32_16x16x32_bf16 v[120:123], v[132:135], v[180:183], v[120:123]
	v_mfma_f32_16x16x32_bf16 v[116:119], v[156:159], v[180:183], v[116:119]
	v_mfma_f32_16x16x32_bf16 v[112:115], v[132:135], v[188:191], v[112:115]
	v_mfma_f32_16x16x32_bf16 v[108:111], v[156:159], v[188:191], v[108:111]
	v_mfma_f32_16x16x32_bf16 v[104:107], v[132:135], v[196:199], v[104:107]
	v_mfma_f32_16x16x32_bf16 v[100:103], v[156:159], v[196:199], v[100:103]
	v_mfma_f32_16x16x32_bf16 v[128:131], v[136:139], v[176:179], v[128:131]
	v_mfma_f32_16x16x32_bf16 v[124:127], v[160:163], v[176:179], v[124:127]
	v_mfma_f32_16x16x32_bf16 v[120:123], v[136:139], v[184:187], v[120:123]
	v_mfma_f32_16x16x32_bf16 v[116:119], v[160:163], v[184:187], v[116:119]
	v_mfma_f32_16x16x32_bf16 v[112:115], v[136:139], v[192:195], v[112:115]
	v_mfma_f32_16x16x32_bf16 v[108:111], v[160:163], v[192:195], v[108:111]
	v_mfma_f32_16x16x32_bf16 v[104:107], v[136:139], v[200:203], v[104:107]
	v_mfma_f32_16x16x32_bf16 v[100:103], v[160:163], v[200:203], v[100:103]
	s_barrier
	s_setprio 0
	s_add_i32 s27, 0, 0x1c000
	s_add_i32 s0, s26, s17
	v_add_u32_e32 v216, s27, v222
	v_lshl_add_u64 v[164:165], v[164:165], 0, s[12:13]
	s_mov_b32 m0, s0
	ds_read_b128 v[204:207], v216
	ds_read_b128 v[208:211], v216 offset:1024
	ds_read_b128 v[212:215], v216 offset:2048
	ds_read_b128 v[216:219], v216 offset:3072
	global_load_lds_dwordx4 v[164:165], off
	v_lshl_add_u64 v[164:165], v[166:167], 0, s[12:13]
	s_add_i32 m0, s0, 0x2000
	s_nop 0
	global_load_lds_dwordx4 v[164:165], off
	s_waitcnt vmcnt(10)
	s_setprio 1
	s_barrier
	s_waitcnt lgkmcnt(0)
	v_mfma_f32_16x16x32_bf16 v[64:67], v[204:207], v[172:175], v[64:67]
	v_mfma_f32_16x16x32_bf16 v[60:63], v[212:215], v[172:175], v[60:63]
	v_mfma_f32_16x16x32_bf16 v[56:59], v[204:207], v[180:183], v[56:59]
	v_mfma_f32_16x16x32_bf16 v[52:55], v[212:215], v[180:183], v[52:55]
	v_mfma_f32_16x16x32_bf16 v[48:51], v[204:207], v[188:191], v[48:51]
	v_mfma_f32_16x16x32_bf16 v[44:47], v[212:215], v[188:191], v[44:47]
	v_mfma_f32_16x16x32_bf16 v[40:43], v[204:207], v[196:199], v[40:43]
	v_mfma_f32_16x16x32_bf16 v[36:39], v[212:215], v[196:199], v[36:39]
	v_mfma_f32_16x16x32_bf16 v[64:67], v[208:211], v[176:179], v[64:67]
	v_mfma_f32_16x16x32_bf16 v[60:63], v[216:219], v[176:179], v[60:63]
	v_mfma_f32_16x16x32_bf16 v[56:59], v[208:211], v[184:187], v[56:59]
	v_mfma_f32_16x16x32_bf16 v[52:55], v[216:219], v[184:187], v[52:55]
	v_mfma_f32_16x16x32_bf16 v[48:51], v[208:211], v[192:195], v[48:51]
	v_mfma_f32_16x16x32_bf16 v[44:47], v[216:219], v[192:195], v[44:47]
	v_mfma_f32_16x16x32_bf16 v[40:43], v[208:211], v[200:203], v[40:43]
	v_mfma_f32_16x16x32_bf16 v[36:39], v[216:219], v[200:203], v[36:39]
	s_barrier
	s_setprio 0
	s_mov_b32 m0, s59
	v_lshl_add_u64 v[164:165], v[168:169], 0, s[12:13]
	ds_read_b128 v[172:175], v224 offset:49152
	ds_read_b128 v[176:179], v224 offset:50176
	ds_read_b128 v[180:183], v224 offset:51200
	ds_read_b128 v[184:187], v224 offset:52224
	ds_read_b128 v[188:191], v224 offset:53248
	ds_read_b128 v[192:195], v224 offset:54272
	ds_read_b128 v[196:199], v224 offset:55296
	ds_read_b128 v[200:203], v224 offset:56320
	global_load_lds_dwordx4 v[164:165], off
	v_lshl_add_u64 v[164:165], v[220:221], 0, s[12:13]
	s_mov_b32 m0, s68
	s_nop 0
	global_load_lds_dwordx4 v[164:165], off
	s_waitcnt vmcnt(10)
	s_setprio 1
	s_barrier
	s_waitcnt lgkmcnt(0)
	v_mfma_f32_16x16x32_bf16 v[96:99], v[132:135], v[172:175], v[96:99]
	v_mfma_f32_16x16x32_bf16 v[92:95], v[156:159], v[172:175], v[92:95]
	v_mfma_f32_16x16x32_bf16 v[88:91], v[132:135], v[180:183], v[88:91]
	v_mfma_f32_16x16x32_bf16 v[84:87], v[156:159], v[180:183], v[84:87]
	v_mfma_f32_16x16x32_bf16 v[80:83], v[132:135], v[188:191], v[80:83]
	v_mfma_f32_16x16x32_bf16 v[76:79], v[156:159], v[188:191], v[76:79]
	v_mfma_f32_16x16x32_bf16 v[72:75], v[132:135], v[196:199], v[72:75]
	v_mfma_f32_16x16x32_bf16 v[68:71], v[156:159], v[196:199], v[68:71]
	v_mfma_f32_16x16x32_bf16 v[96:99], v[136:139], v[176:179], v[96:99]
	v_mfma_f32_16x16x32_bf16 v[92:95], v[160:163], v[176:179], v[92:95]
	v_mfma_f32_16x16x32_bf16 v[88:91], v[136:139], v[184:187], v[88:91]
	v_mfma_f32_16x16x32_bf16 v[84:87], v[160:163], v[184:187], v[84:87]
	v_mfma_f32_16x16x32_bf16 v[80:83], v[136:139], v[192:195], v[80:83]
	v_mfma_f32_16x16x32_bf16 v[76:79], v[160:163], v[192:195], v[76:79]
	v_mfma_f32_16x16x32_bf16 v[72:75], v[136:139], v[200:203], v[72:75]
	v_mfma_f32_16x16x32_bf16 v[68:71], v[160:163], v[200:203], v[68:71]
	s_barrier
	s_setprio 0
	s_add_u32 s0, s30, 0xb0080
	s_addc_u32 s1, s31, 0
	s_add_i32 s26, s27, s17
	s_mov_b32 m0, s26
	s_nop 0
	global_load_lds_dwordx4 v26, s[0:1]
	s_add_i32 m0, s26, 0x2000
	s_nop 0
	global_load_lds_dwordx4 v140, s[0:1]
	v_add_u32_e32 v160, 0x10000, v222
	ds_read_b128 v[132:135], v160
	ds_read_b128 v[136:139], v160 offset:1024
	ds_read_b128 v[156:159], v160 offset:2048
	ds_read_b128 v[160:163], v160 offset:3072
	s_add_i32 s46, s46, 2
	s_add_u32 s18, s18, 0x100
	s_addc_u32 s19, s19, 0
	s_cmp_gt_u32 s46, 41
	s_mov_b64 s[26:27], s[28:29]
	s_waitcnt vmcnt(10)
	s_setprio 1
	s_barrier
	v_mfma_f32_16x16x32_bf16 v[32:35], v[204:207], v[172:175], v[32:35]
	v_mfma_f32_16x16x32_bf16 v[28:31], v[212:215], v[172:175], v[28:31]
	v_mfma_f32_16x16x32_bf16 v[22:25], v[204:207], v[180:183], v[22:25]
	v_mfma_f32_16x16x32_bf16 v[18:21], v[212:215], v[180:183], v[18:21]
	v_mfma_f32_16x16x32_bf16 v[14:17], v[204:207], v[188:191], v[14:17]
	v_mfma_f32_16x16x32_bf16 v[10:13], v[212:215], v[188:191], v[10:13]
	v_mfma_f32_16x16x32_bf16 v[6:9], v[204:207], v[196:199], v[6:9]
	v_mfma_f32_16x16x32_bf16 v[2:5], v[212:215], v[196:199], v[2:5]
	v_mfma_f32_16x16x32_bf16 v[32:35], v[208:211], v[176:179], v[32:35]
	v_mfma_f32_16x16x32_bf16 v[28:31], v[216:219], v[176:179], v[28:31]
	v_mfma_f32_16x16x32_bf16 v[22:25], v[208:211], v[184:187], v[22:25]
	v_mfma_f32_16x16x32_bf16 v[18:21], v[216:219], v[184:187], v[18:21]
	v_mfma_f32_16x16x32_bf16 v[14:17], v[208:211], v[192:195], v[14:17]
	v_mfma_f32_16x16x32_bf16 v[10:13], v[216:219], v[192:195], v[10:13]
	v_mfma_f32_16x16x32_bf16 v[6:9], v[208:211], v[200:203], v[6:9]
	v_mfma_f32_16x16x32_bf16 v[2:5], v[216:219], v[200:203], v[2:5]
	s_barrier
	s_setprio 0
	s_cbranch_scc0 .LBB0_361
	s_waitcnt lgkmcnt(0)
	s_min_i32 s0, s24, 0x100
	s_ashr_i32 s0, s0, 5
	s_ashr_i32 s1, s0, 31
	s_add_i32 s18, s24, 0xffffff00
	s_cmpk_lt_i32 s24, 0x100
	s_cselect_b32 s18, s24, s18
	s_cselect_b32 s27, 0, s58
	s_cselect_b32 s26, 0, s57
	s_ashr_i32 s19, s18, 31
	s_lshl_b64 s[18:19], s[18:19], 19
	s_add_u32 s26, s50, s26
	v_lshl_or_b32 v178, s25, 8, v223
	s_addc_u32 s27, s51, s27
	s_ashr_i32 s25, s24, 31
	v_lshl_add_u64 v[132:133], s[18:19], 0, v[146:147]
	s_lshl_b64 s[18:19], s[24:25], 19
	v_lshl_add_u64 v[184:185], v[148:149], 0, s[18:19]
	s_lshl_b64 s[24:25], s[24:25], 10
	s_mul_i32 s18, s0, 0x9000
	v_ashrrev_i32_e32 v179, 31, v178
	s_mul_hi_i32 s19, s0, 0x9000
	s_add_u32 s18, s48, s18
	s_addc_u32 s19, s49, s19
	v_lshlrev_b64 v[186:187], 2, v[178:179]
	v_lshl_add_u64 v[156:157], s[18:19], 0, v[186:187]
	v_lshl_add_u64 v[180:181], v[132:133], 0, v[178:179]
	v_lshl_add_u64 v[182:183], v[132:133], 1, s[26:27]
	global_load_dwordx4 v[132:135], v[156:157], off offset:16
	global_load_dwordx4 v[136:139], v[156:157], off
	s_lshl_b64 s[0:1], s[0:1], 12
	s_add_u32 s28, s52, s0
	s_addc_u32 s29, s53, s1
	v_lshl_add_u64 v[196:197], v[180:181], 1, s[26:27]
	v_lshl_add_u64 v[180:181], s[28:29], 0, v[186:187]
	v_add_co_u32_e32 v210, vcc, s65, v196
	v_lshlrev_b64 v[188:189], 1, v[178:179]
	s_nop 0
	v_addc_co_u32_e32 v211, vcc, 0, v197, vcc
	s_mov_b32 s1, 0x20000
	v_lshl_add_u64 v[178:179], v[184:185], 0, v[188:189]
	v_add_co_u32_e32 v184, vcc, s1, v196
	s_mov_b32 s18, 0x30000
	s_nop 0
	v_addc_co_u32_e32 v185, vcc, 0, v197, vcc
	v_lshl_add_u64 v[182:183], v[182:183], 0, v[188:189]
	v_add_co_u32_e32 v188, vcc, s18, v196
	s_mov_b32 s0, 0x8000
	s_nop 0
	v_addc_co_u32_e32 v189, vcc, 0, v197, vcc
	s_mov_b32 s19, 0x80000
	s_mov_b32 s26, 0x90000
	s_waitcnt vmcnt(0)
	v_pk_mul_f32 v[172:173], v[134:135], 0.5 op_sel_hi:[1,0]
	v_pk_mul_f32 v[176:177], v[138:139], 0.5 op_sel_hi:[1,0]
	v_pk_mul_f32 v[174:175], v[136:137], 0.5 op_sel_hi:[1,0]
	v_pk_mul_f32 v[164:165], v[132:133], 0.5 op_sel_hi:[1,0]
	global_load_dwordx4 v[132:135], v[156:157], off offset:528
	global_load_dwordx4 v[136:139], v[156:157], off offset:512
	s_waitcnt vmcnt(0)
	v_pk_mul_f32 v[158:159], v[134:135], 0.5 op_sel_hi:[1,0]
	v_pk_mul_f32 v[162:163], v[138:139], 0.5 op_sel_hi:[1,0]
	v_pk_mul_f32 v[160:161], v[136:137], 0.5 op_sel_hi:[1,0]
	v_pk_mul_f32 v[156:157], v[132:133], 0.5 op_sel_hi:[1,0]
	global_load_dwordx4 v[132:135], v[180:181], off offset:16
	global_load_dwordx4 v[136:139], v[180:181], off
	global_load_dwordx4 v[190:193], v[196:197], off offset:2048
	global_load_dwordx4 v[198:201], v[210:211], off offset:2048
	global_load_dwordx4 v[202:205], v[184:185], off offset:2048
	global_load_dwordx4 v[206:209], v[188:189], off offset:2048
	s_waitcnt vmcnt(0)
	v_lshlrev_b32_e32 v186, 16, v190
	v_and_b32_e32 v187, 0xffff0000, v190
	v_lshlrev_b32_e32 v190, 16, v191
	v_and_b32_e32 v191, 0xffff0000, v191
	v_lshlrev_b32_e32 v194, 16, v192
	v_and_b32_e32 v195, 0xffff0000, v192
	v_lshlrev_b32_e32 v192, 16, v193
	v_and_b32_e32 v193, 0xffff0000, v193
	v_pk_fma_f32 v[130:131], v[130:131], v[176:177], v[190:191]
	v_pk_fma_f32 v[128:129], v[128:129], v[174:175], v[186:187]
	v_pk_fma_f32 v[126:127], v[126:127], v[172:173], v[192:193]
	v_pk_fma_f32 v[124:125], v[124:125], v[164:165], v[194:195]
	v_cvt_pk_bf16_f32 v190, v128, v129
	v_cvt_pk_bf16_f32 v191, v130, v131
	v_cvt_pk_bf16_f32 v192, v124, v125
	v_cvt_pk_bf16_f32 v193, v126, v127
	v_lshlrev_b32_e32 v130, 16, v190
	v_and_b32_e32 v131, 0xffff0000, v190
	v_lshlrev_b32_e32 v128, 16, v191
	v_and_b32_e32 v129, 0xffff0000, v191
	v_lshlrev_b32_e32 v126, 16, v192
	v_and_b32_e32 v127, 0xffff0000, v192
	v_lshlrev_b32_e32 v124, 16, v193
	v_and_b32_e32 v125, 0xffff0000, v193
	v_lshlrev_b32_e32 v212, 16, v198
	v_and_b32_e32 v213, 0xffff0000, v198
	v_lshlrev_b32_e32 v198, 16, v199
	v_and_b32_e32 v199, 0xffff0000, v199
	global_store_dwordx4 v[182:183], v[190:193], off offset:2048
	v_pk_mul_f32 v[186:187], v[138:139], v[128:129]
	v_pk_mul_f32 v[194:195], v[134:135], v[124:125]
	v_pk_mul_f32 v[190:191], v[136:137], v[130:131]
	v_pk_mul_f32 v[192:193], v[132:133], v[126:127]
	v_lshlrev_b32_e32 v214, 16, v200
	v_and_b32_e32 v215, 0xffff0000, v200
	v_lshlrev_b32_e32 v200, 16, v201
	v_and_b32_e32 v201, 0xffff0000, v201
	v_cvt_pk_bf16_f32 v190, v190, v191
	v_cvt_pk_bf16_f32 v191, v186, v187
	v_cvt_pk_bf16_f32 v192, v192, v193
	v_cvt_pk_bf16_f32 v193, v194, v195
	v_pk_fma_f32 v[122:123], v[122:123], v[176:177], v[198:199]
	v_pk_fma_f32 v[120:121], v[120:121], v[174:175], v[212:213]
	global_store_dwordx4 v[178:179], v[190:193], off
	v_pk_fma_f32 v[118:119], v[118:119], v[172:173], v[200:201]
	v_pk_fma_f32 v[116:117], v[116:117], v[164:165], v[214:215]
	v_cvt_pk_bf16_f32 v190, v120, v121
	v_cvt_pk_bf16_f32 v191, v122, v123
	v_add_co_u32_e32 v186, vcc, s65, v182
	v_cvt_pk_bf16_f32 v192, v116, v117
	v_cvt_pk_bf16_f32 v193, v118, v119
	v_addc_co_u32_e32 v187, vcc, 0, v183, vcc
	v_lshlrev_b32_e32 v122, 16, v190
	v_and_b32_e32 v123, 0xffff0000, v190
	v_lshlrev_b32_e32 v120, 16, v191
	v_and_b32_e32 v121, 0xffff0000, v191
	global_store_dwordx4 v[186:187], v[190:193], off offset:2048
	v_lshlrev_b32_e32 v118, 16, v192
	v_and_b32_e32 v119, 0xffff0000, v192
	v_lshlrev_b32_e32 v116, 16, v193
	v_and_b32_e32 v117, 0xffff0000, v193
	v_pk_mul_f32 v[190:191], v[138:139], v[120:121]
	v_pk_mul_f32 v[192:193], v[136:137], v[122:123]
	v_pk_mul_f32 v[198:199], v[134:135], v[116:117]
	v_pk_mul_f32 v[194:195], v[132:133], v[118:119]
	v_cvt_pk_bf16_f32 v192, v192, v193
	v_cvt_pk_bf16_f32 v193, v190, v191
	v_add_co_u32_e32 v190, vcc, s0, v178
	v_cvt_pk_bf16_f32 v194, v194, v195
	v_cvt_pk_bf16_f32 v195, v198, v199
	v_addc_co_u32_e32 v191, vcc, 0, v179, vcc
	global_store_dwordx4 v[190:191], v[192:195], off
	v_lshlrev_b32_e32 v198, 16, v202
	v_and_b32_e32 v199, 0xffff0000, v202
	v_add_co_u32_e32 v192, vcc, s19, v196
	v_lshlrev_b32_e32 v200, 16, v203
	s_nop 0
	v_addc_co_u32_e32 v193, vcc, 0, v197, vcc
	v_add_co_u32_e32 v194, vcc, s26, v196
	v_and_b32_e32 v201, 0xffff0000, v203
	global_load_dwordx4 v[212:215], v[192:193], off offset:2048
	v_addc_co_u32_e32 v195, vcc, 0, v197, vcc
	v_lshlrev_b32_e32 v202, 16, v204
	v_and_b32_e32 v203, 0xffff0000, v204
	v_lshlrev_b32_e32 v204, 16, v205
	v_and_b32_e32 v205, 0xffff0000, v205
	v_pk_fma_f32 v[114:115], v[114:115], v[176:177], v[200:201]
	v_pk_fma_f32 v[112:113], v[112:113], v[174:175], v[198:199]
	v_pk_fma_f32 v[110:111], v[110:111], v[172:173], v[204:205]
	v_pk_fma_f32 v[108:109], v[108:109], v[164:165], v[202:203]
	v_cvt_pk_bf16_f32 v200, v112, v113
	v_cvt_pk_bf16_f32 v201, v114, v115
	v_add_co_u32_e32 v198, vcc, s1, v182
	v_cvt_pk_bf16_f32 v202, v108, v109
	v_cvt_pk_bf16_f32 v203, v110, v111
	v_addc_co_u32_e32 v199, vcc, 0, v183, vcc
	v_lshlrev_b32_e32 v114, 16, v200
	v_and_b32_e32 v115, 0xffff0000, v200
	v_lshlrev_b32_e32 v112, 16, v201
	v_and_b32_e32 v113, 0xffff0000, v201
	global_load_dwordx4 v[216:219], v[194:195], off offset:2048
	v_lshlrev_b32_e32 v110, 16, v202
	global_store_dwordx4 v[198:199], v[200:203], off offset:2048
	v_and_b32_e32 v111, 0xffff0000, v202
	v_lshlrev_b32_e32 v108, 16, v203
	v_and_b32_e32 v109, 0xffff0000, v203
	v_pk_mul_f32 v[200:201], v[138:139], v[112:113]
	v_pk_mul_f32 v[202:203], v[136:137], v[114:115]
	v_lshlrev_b32_e32 v220, 16, v206
	v_and_b32_e32 v221, 0xffff0000, v206
	v_lshlrev_b32_e32 v206, 16, v207
	v_and_b32_e32 v207, 0xffff0000, v207
	v_pk_mul_f32 v[238:239], v[134:135], v[108:109]
	v_pk_mul_f32 v[204:205], v[132:133], v[110:111]
	v_cvt_pk_bf16_f32 v202, v202, v203
	v_cvt_pk_bf16_f32 v203, v200, v201
	v_add_co_u32_e32 v200, vcc, s65, v178
	v_lshlrev_b32_e32 v234, 16, v208
	v_and_b32_e32 v235, 0xffff0000, v208
	v_lshlrev_b32_e32 v208, 16, v209
	v_and_b32_e32 v209, 0xffff0000, v209
	v_cvt_pk_bf16_f32 v204, v204, v205
	v_cvt_pk_bf16_f32 v205, v238, v239
	v_addc_co_u32_e32 v201, vcc, 0, v179, vcc
	v_pk_fma_f32 v[106:107], v[106:107], v[176:177], v[206:207]
	v_pk_fma_f32 v[104:105], v[104:105], v[174:175], v[220:221]
	global_store_dwordx4 v[200:201], v[202:205], off
	v_pk_fma_f32 v[102:103], v[102:103], v[172:173], v[208:209]
	v_pk_fma_f32 v[100:101], v[100:101], v[164:165], v[234:235]
	v_cvt_pk_bf16_f32 v204, v104, v105
	v_cvt_pk_bf16_f32 v205, v106, v107
	v_add_co_u32_e32 v202, vcc, s18, v182
	v_cvt_pk_bf16_f32 v206, v100, v101
	v_cvt_pk_bf16_f32 v207, v102, v103
	v_addc_co_u32_e32 v203, vcc, 0, v183, vcc
	v_lshlrev_b32_e32 v106, 16, v204
	v_and_b32_e32 v107, 0xffff0000, v204
	v_lshlrev_b32_e32 v104, 16, v205
	v_and_b32_e32 v105, 0xffff0000, v205
	global_store_dwordx4 v[202:203], v[204:207], off offset:2048
	v_lshlrev_b32_e32 v102, 16, v206
	v_and_b32_e32 v103, 0xffff0000, v206
	v_lshlrev_b32_e32 v100, 16, v207
	v_and_b32_e32 v101, 0xffff0000, v207
	v_pk_mul_f32 v[204:205], v[138:139], v[104:105]
	v_pk_mul_f32 v[206:207], v[136:137], v[106:107]
	s_mov_b32 s0, 0x18000
	v_pk_mul_f32 v[220:221], v[134:135], v[100:101]
	v_pk_mul_f32 v[208:209], v[132:133], v[102:103]
	v_cvt_pk_bf16_f32 v206, v206, v207
	v_cvt_pk_bf16_f32 v207, v204, v205
	v_add_co_u32_e32 v204, vcc, s0, v178
	v_cvt_pk_bf16_f32 v208, v208, v209
	v_cvt_pk_bf16_f32 v209, v220, v221
	v_addc_co_u32_e32 v205, vcc, 0, v179, vcc
	global_store_dwordx4 v[204:205], v[206:209], off
	s_mov_b32 s0, 0xb0000
	s_waitcnt vmcnt(0)
	v_lshlrev_b32_e32 v220, 16, v212
	v_add_co_u32_e32 v206, vcc, s76, v196
	v_and_b32_e32 v221, 0xffff0000, v212
	s_nop 0
	v_addc_co_u32_e32 v207, vcc, 0, v197, vcc
	global_load_dwordx4 v[238:241], v[206:207], off offset:2048
	v_add_co_u32_e32 v208, vcc, s0, v196
	v_lshlrev_b32_e32 v212, 16, v213
	s_nop 0
	v_addc_co_u32_e32 v209, vcc, 0, v197, vcc
	global_load_dwordx4 v[242:245], v[208:209], off offset:2048
	v_and_b32_e32 v213, 0xffff0000, v213
	v_lshlrev_b32_e32 v234, 16, v214
	v_and_b32_e32 v235, 0xffff0000, v214
	v_lshlrev_b32_e32 v214, 16, v215
	v_and_b32_e32 v215, 0xffff0000, v215
	v_pk_fma_f32 v[98:99], v[98:99], v[176:177], v[212:213]
	v_pk_fma_f32 v[96:97], v[96:97], v[174:175], v[220:221]
	v_pk_fma_f32 v[94:95], v[94:95], v[172:173], v[214:215]
	v_pk_fma_f32 v[92:93], v[92:93], v[164:165], v[234:235]
	v_cvt_pk_bf16_f32 v214, v96, v97
	v_cvt_pk_bf16_f32 v215, v98, v99
	v_add_co_u32_e32 v212, vcc, s19, v182
	v_lshlrev_b32_e32 v246, 16, v216
	v_and_b32_e32 v247, 0xffff0000, v216
	v_lshlrev_b32_e32 v248, 16, v217
	v_and_b32_e32 v249, 0xffff0000, v217
	v_cvt_pk_bf16_f32 v216, v92, v93
	v_cvt_pk_bf16_f32 v217, v94, v95
	v_addc_co_u32_e32 v213, vcc, 0, v183, vcc
	v_lshlrev_b32_e32 v98, 16, v214
	v_and_b32_e32 v99, 0xffff0000, v214
	v_lshlrev_b32_e32 v96, 16, v215
	v_and_b32_e32 v97, 0xffff0000, v215
	global_store_dwordx4 v[212:213], v[214:217], off offset:2048
	v_lshlrev_b32_e32 v94, 16, v216
	v_and_b32_e32 v95, 0xffff0000, v216
	v_lshlrev_b32_e32 v92, 16, v217
	v_and_b32_e32 v93, 0xffff0000, v217
	v_pk_mul_f32 v[214:215], v[138:139], v[96:97]
	v_pk_mul_f32 v[216:217], v[136:137], v[98:99]
	s_mov_b32 s1, 0x40000
	v_lshlrev_b32_e32 v250, 16, v218
	v_and_b32_e32 v251, 0xffff0000, v218
	v_lshlrev_b32_e32 v252, 16, v219
	v_and_b32_e32 v253, 0xffff0000, v219
	v_pk_mul_f32 v[220:221], v[134:135], v[92:93]
	v_pk_mul_f32 v[218:219], v[132:133], v[94:95]
	v_cvt_pk_bf16_f32 v216, v216, v217
	v_cvt_pk_bf16_f32 v217, v214, v215
	v_add_co_u32_e32 v214, vcc, s1, v178
	v_cvt_pk_bf16_f32 v218, v218, v219
	v_cvt_pk_bf16_f32 v219, v220, v221
	v_addc_co_u32_e32 v215, vcc, 0, v179, vcc
	v_pk_fma_f32 v[90:91], v[90:91], v[176:177], v[248:249]
	global_store_dwordx4 v[214:215], v[216:219], off
	v_pk_fma_f32 v[88:89], v[88:89], v[174:175], v[246:247]
	v_pk_fma_f32 v[86:87], v[86:87], v[172:173], v[252:253]
	v_pk_fma_f32 v[84:85], v[84:85], v[164:165], v[250:251]
	v_cvt_pk_bf16_f32 v219, v90, v91
	v_add_co_u32_e32 v216, vcc, s26, v182
	v_cvt_pk_bf16_f32 v218, v88, v89
	v_cvt_pk_bf16_f32 v220, v84, v85
	v_cvt_pk_bf16_f32 v221, v86, v87
	v_addc_co_u32_e32 v217, vcc, 0, v183, vcc
	v_lshlrev_b32_e32 v88, 16, v219
	v_and_b32_e32 v89, 0xffff0000, v219
	global_store_dwordx4 v[216:217], v[218:221], off offset:2048
	v_lshlrev_b32_e32 v90, 16, v218
	v_and_b32_e32 v91, 0xffff0000, v218
	v_lshlrev_b32_e32 v86, 16, v220
	v_and_b32_e32 v87, 0xffff0000, v220
	v_lshlrev_b32_e32 v84, 16, v221
	v_and_b32_e32 v85, 0xffff0000, v221
	v_pk_mul_f32 v[218:219], v[138:139], v[88:89]
	s_mov_b32 s1, 0x48000
	v_pk_mul_f32 v[220:221], v[136:137], v[90:91]
	v_pk_mul_f32 v[234:235], v[134:135], v[84:85]
	v_pk_mul_f32 v[248:249], v[132:133], v[86:87]
	v_cvt_pk_bf16_f32 v247, v218, v219
	v_add_co_u32_e32 v218, vcc, s1, v178
	v_cvt_pk_bf16_f32 v246, v220, v221
	v_cvt_pk_bf16_f32 v248, v248, v249
	v_cvt_pk_bf16_f32 v249, v234, v235
	v_addc_co_u32_e32 v219, vcc, 0, v179, vcc
	global_store_dwordx4 v[218:219], v[246:249], off
	global_load_dwordx4 v[246:249], v[196:197], off offset:2304
	s_nop 0
	global_load_dwordx4 v[250:253], v[210:211], off offset:2304
	s_waitcnt vmcnt(0)
	v_lshlrev_b32_e32 v210, 16, v239
	v_and_b32_e32 v211, 0xffff0000, v239
	v_lshlrev_b32_e32 v196, 16, v238
	v_and_b32_e32 v197, 0xffff0000, v238
	v_pk_fma_f32 v[82:83], v[82:83], v[176:177], v[210:211]
	v_lshlrev_b32_e32 v220, 16, v240
	v_and_b32_e32 v221, 0xffff0000, v240
	v_lshlrev_b32_e32 v234, 16, v241
	v_and_b32_e32 v235, 0xffff0000, v241
	v_pk_fma_f32 v[80:81], v[80:81], v[174:175], v[196:197]
	v_cvt_pk_bf16_f32 v239, v82, v83
	v_pk_fma_f32 v[78:79], v[78:79], v[172:173], v[234:235]
	v_pk_fma_f32 v[76:77], v[76:77], v[164:165], v[220:221]
	v_cvt_pk_bf16_f32 v238, v80, v81
	v_add_co_u32_e32 v196, vcc, s76, v182
	v_lshlrev_b32_e32 v80, 16, v239
	v_and_b32_e32 v81, 0xffff0000, v239
	v_cvt_pk_bf16_f32 v240, v76, v77
	v_cvt_pk_bf16_f32 v241, v78, v79
	v_addc_co_u32_e32 v197, vcc, 0, v183, vcc
	v_pk_mul_f32 v[210:211], v[138:139], v[80:81]
	v_lshlrev_b32_e32 v166, 16, v242
	v_and_b32_e32 v167, 0xffff0000, v242
	v_lshlrev_b32_e32 v242, 16, v243
	v_and_b32_e32 v243, 0xffff0000, v243
	v_lshlrev_b32_e32 v168, 16, v244
	v_and_b32_e32 v169, 0xffff0000, v244
	v_lshlrev_b32_e32 v244, 16, v245
	v_and_b32_e32 v245, 0xffff0000, v245
	global_store_dwordx4 v[196:197], v[238:241], off offset:2048
	v_lshlrev_b32_e32 v82, 16, v238
	v_and_b32_e32 v83, 0xffff0000, v238
	v_cvt_pk_bf16_f32 v239, v210, v211
	v_add_co_u32_e32 v210, vcc, s77, v178
	v_lshlrev_b32_e32 v78, 16, v240
	v_and_b32_e32 v79, 0xffff0000, v240
	v_lshlrev_b32_e32 v76, 16, v241
	v_and_b32_e32 v77, 0xffff0000, v241
	v_pk_mul_f32 v[220:221], v[136:137], v[82:83]
	v_addc_co_u32_e32 v211, vcc, 0, v179, vcc
	v_pk_fma_f32 v[74:75], v[74:75], v[176:177], v[242:243]
	v_pk_fma_f32 v[72:73], v[72:73], v[174:175], v[166:167]
	v_pk_fma_f32 v[166:167], v[70:71], v[172:173], v[244:245]
	v_pk_fma_f32 v[70:71], v[68:69], v[164:165], v[168:169]
	v_pk_mul_f32 v[234:235], v[134:135], v[76:77]
	v_pk_mul_f32 v[240:241], v[132:133], v[78:79]
	v_cvt_pk_bf16_f32 v238, v220, v221
	v_cvt_pk_bf16_f32 v68, v72, v73
	v_cvt_pk_bf16_f32 v69, v74, v75
	v_cvt_pk_bf16_f32 v70, v70, v71
	v_cvt_pk_bf16_f32 v71, v166, v167
	v_add_co_u32_e32 v220, vcc, s0, v182
	v_cvt_pk_bf16_f32 v240, v240, v241
	v_cvt_pk_bf16_f32 v241, v234, v235
	v_addc_co_u32_e32 v221, vcc, 0, v183, vcc
	v_lshlrev_b32_e32 v176, 16, v68
	v_and_b32_e32 v177, 0xffff0000, v68
	v_lshlrev_b32_e32 v174, 16, v69
	v_and_b32_e32 v175, 0xffff0000, v69
	v_lshlrev_b32_e32 v172, 16, v70
	v_and_b32_e32 v173, 0xffff0000, v70
	v_lshlrev_b32_e32 v164, 16, v71
	v_and_b32_e32 v165, 0xffff0000, v71
	s_mov_b32 s0, 0x58000
	global_store_dwordx4 v[210:211], v[238:241], off
	global_store_dwordx4 v[220:221], v[68:71], off offset:2048
	v_pk_mul_f32 v[72:73], v[134:135], v[164:165]
	v_pk_mul_f32 v[74:75], v[132:133], v[172:173]
	v_pk_mul_f32 v[70:71], v[138:139], v[174:175]
	v_pk_mul_f32 v[68:69], v[136:137], v[176:177]
	v_add_co_u32_e32 v132, vcc, s0, v178
	v_cvt_pk_bf16_f32 v68, v68, v69
	v_cvt_pk_bf16_f32 v69, v70, v71
	v_cvt_pk_bf16_f32 v70, v74, v75
	v_cvt_pk_bf16_f32 v71, v72, v73
	v_addc_co_u32_e32 v133, vcc, 0, v179, vcc
	global_store_dwordx4 v[132:133], v[68:71], off
	global_load_dwordx4 v[134:137], v[184:185], off offset:2304
	global_load_dwordx4 v[238:241], v[188:189], off offset:2304
	s_nop 0
	global_load_dwordx4 v[68:71], v[180:181], off offset:528
	global_load_dwordx4 v[72:75], v[180:181], off offset:512
	v_lshlrev_b32_e32 v138, 16, v246
	v_and_b32_e32 v139, 0xffff0000, v246
	v_lshlrev_b32_e32 v166, 16, v247
	v_and_b32_e32 v167, 0xffff0000, v247
	v_lshlrev_b32_e32 v168, 16, v248
	v_and_b32_e32 v169, 0xffff0000, v248
	v_lshlrev_b32_e32 v180, 16, v249
	v_and_b32_e32 v181, 0xffff0000, v249
	v_pk_fma_f32 v[66:67], v[66:67], v[162:163], v[166:167]
	v_pk_fma_f32 v[64:65], v[64:65], v[160:161], v[138:139]
	v_pk_fma_f32 v[62:63], v[62:63], v[158:159], v[180:181]
	v_pk_fma_f32 v[60:61], v[60:61], v[156:157], v[168:169]
	v_cvt_pk_bf16_f32 v242, v64, v65
	v_cvt_pk_bf16_f32 v243, v66, v67
	v_cvt_pk_bf16_f32 v244, v60, v61
	v_cvt_pk_bf16_f32 v245, v62, v63
	v_lshlrev_b32_e32 v66, 16, v242
	v_and_b32_e32 v67, 0xffff0000, v242
	v_lshlrev_b32_e32 v64, 16, v243
	v_and_b32_e32 v65, 0xffff0000, v243
	v_lshlrev_b32_e32 v62, 16, v244
	v_and_b32_e32 v63, 0xffff0000, v244
	v_lshlrev_b32_e32 v60, 16, v245
	v_and_b32_e32 v61, 0xffff0000, v245
	v_lshlrev_b32_e32 v184, 16, v250
	v_and_b32_e32 v185, 0xffff0000, v250
	v_lshlrev_b32_e32 v188, 16, v251
	v_and_b32_e32 v189, 0xffff0000, v251
	v_lshlrev_b32_e32 v234, 16, v252
	v_and_b32_e32 v235, 0xffff0000, v252
	v_lshlrev_b32_e32 v246, 16, v253
	v_and_b32_e32 v247, 0xffff0000, v253
	global_store_dwordx4 v[182:183], v[242:245], off offset:2304
	v_pk_fma_f32 v[58:59], v[58:59], v[162:163], v[188:189]
	v_pk_fma_f32 v[56:57], v[56:57], v[160:161], v[184:185]
	v_pk_fma_f32 v[54:55], v[54:55], v[158:159], v[246:247]
	v_pk_fma_f32 v[52:53], v[52:53], v[156:157], v[234:235]
	s_waitcnt vmcnt(0)
	v_lshlrev_b32_e32 v188, 16, v240
	v_pk_mul_f32 v[168:169], v[70:71], v[60:61]
	v_pk_mul_f32 v[138:139], v[74:75], v[64:65]
	v_pk_mul_f32 v[166:167], v[72:73], v[66:67]
	v_pk_mul_f32 v[182:183], v[68:69], v[62:63]
	v_cvt_pk_bf16_f32 v180, v166, v167
	v_cvt_pk_bf16_f32 v181, v138, v139
	v_cvt_pk_bf16_f32 v182, v182, v183
	v_cvt_pk_bf16_f32 v183, v168, v169
	global_store_dwordx4 v[178:179], v[180:183], off offset:256
	v_cvt_pk_bf16_f32 v178, v56, v57
	v_cvt_pk_bf16_f32 v179, v58, v59
	v_cvt_pk_bf16_f32 v180, v52, v53
	v_cvt_pk_bf16_f32 v181, v54, v55
	v_lshlrev_b32_e32 v58, 16, v178
	v_and_b32_e32 v59, 0xffff0000, v178
	v_lshlrev_b32_e32 v56, 16, v179
	v_and_b32_e32 v57, 0xffff0000, v179
	v_lshlrev_b32_e32 v54, 16, v180
	v_and_b32_e32 v55, 0xffff0000, v180
	v_lshlrev_b32_e32 v52, 16, v181
	v_and_b32_e32 v53, 0xffff0000, v181
	global_store_dwordx4 v[186:187], v[178:181], off offset:2304
	v_pk_mul_f32 v[138:139], v[74:75], v[56:57]
	v_pk_mul_f32 v[166:167], v[72:73], v[58:59]
	v_pk_mul_f32 v[168:169], v[70:71], v[52:53]
	v_pk_mul_f32 v[180:181], v[68:69], v[54:55]
	v_cvt_pk_bf16_f32 v178, v166, v167
	v_cvt_pk_bf16_f32 v179, v138, v139
	v_cvt_pk_bf16_f32 v180, v180, v181
	v_cvt_pk_bf16_f32 v181, v168, v169
	v_lshlrev_b32_e32 v138, 16, v134
	v_and_b32_e32 v139, 0xffff0000, v134
	v_lshlrev_b32_e32 v134, 16, v135
	v_and_b32_e32 v135, 0xffff0000, v135
	v_lshlrev_b32_e32 v166, 16, v136
	v_and_b32_e32 v167, 0xffff0000, v136
	v_lshlrev_b32_e32 v136, 16, v137
	v_and_b32_e32 v137, 0xffff0000, v137
	global_store_dwordx4 v[190:191], v[178:181], off offset:256
	v_pk_fma_f32 v[50:51], v[50:51], v[162:163], v[134:135]
	v_pk_fma_f32 v[48:49], v[48:49], v[160:161], v[138:139]
	v_pk_fma_f32 v[46:47], v[46:47], v[158:159], v[136:137]
	v_pk_fma_f32 v[44:45], v[44:45], v[156:157], v[166:167]
	global_load_dwordx4 v[178:181], v[192:193], off offset:2304
	global_load_dwordx4 v[182:185], v[194:195], off offset:2304
	v_cvt_pk_bf16_f32 v134, v48, v49
	v_cvt_pk_bf16_f32 v135, v50, v51
	v_cvt_pk_bf16_f32 v136, v44, v45
	v_cvt_pk_bf16_f32 v137, v46, v47
	v_lshlrev_b32_e32 v50, 16, v134
	v_and_b32_e32 v51, 0xffff0000, v134
	v_lshlrev_b32_e32 v48, 16, v135
	v_and_b32_e32 v49, 0xffff0000, v135
	v_lshlrev_b32_e32 v46, 16, v136
	v_and_b32_e32 v47, 0xffff0000, v136
	v_lshlrev_b32_e32 v44, 16, v137
	v_and_b32_e32 v45, 0xffff0000, v137
	v_lshlrev_b32_e32 v168, 16, v238
	v_and_b32_e32 v169, 0xffff0000, v238
	v_lshlrev_b32_e32 v186, 16, v239
	v_and_b32_e32 v187, 0xffff0000, v239
	v_and_b32_e32 v189, 0xffff0000, v240
	v_lshlrev_b32_e32 v190, 16, v241
	v_and_b32_e32 v191, 0xffff0000, v241
	global_store_dwordx4 v[198:199], v[134:137], off offset:2304
	v_pk_mul_f32 v[138:139], v[70:71], v[44:45]
	v_pk_mul_f32 v[166:167], v[68:69], v[46:47]
	v_pk_mul_f32 v[136:137], v[74:75], v[48:49]
	v_pk_mul_f32 v[134:135], v[72:73], v[50:51]
	v_pk_fma_f32 v[42:43], v[42:43], v[162:163], v[186:187]
	v_cvt_pk_bf16_f32 v134, v134, v135
	v_cvt_pk_bf16_f32 v135, v136, v137
	v_cvt_pk_bf16_f32 v136, v166, v167
	v_cvt_pk_bf16_f32 v137, v138, v139
	v_pk_fma_f32 v[40:41], v[40:41], v[160:161], v[168:169]
	v_pk_fma_f32 v[38:39], v[38:39], v[158:159], v[190:191]
	v_pk_fma_f32 v[36:37], v[36:37], v[156:157], v[188:189]
	global_store_dwordx4 v[200:201], v[134:137], off offset:256
	v_mul_f32_e32 v67, v67, v67
	v_mul_f32_e32 v65, v65, v65
	v_cvt_pk_bf16_f32 v134, v40, v41
	v_cvt_pk_bf16_f32 v135, v42, v43
	v_cvt_pk_bf16_f32 v136, v36, v37
	v_cvt_pk_bf16_f32 v137, v38, v39
	v_lshlrev_b32_e32 v42, 16, v134
	v_and_b32_e32 v43, 0xffff0000, v134
	v_lshlrev_b32_e32 v40, 16, v135
	v_and_b32_e32 v41, 0xffff0000, v135
	v_lshlrev_b32_e32 v38, 16, v136
	v_and_b32_e32 v39, 0xffff0000, v136
	v_lshlrev_b32_e32 v36, 16, v137
	v_and_b32_e32 v37, 0xffff0000, v137
	global_store_dwordx4 v[202:203], v[134:137], off offset:2304
	v_pk_mul_f32 v[138:139], v[70:71], v[36:37]
	v_pk_mul_f32 v[166:167], v[68:69], v[38:39]
	v_pk_mul_f32 v[136:137], v[74:75], v[40:41]
	v_pk_mul_f32 v[134:135], v[72:73], v[42:43]
	v_fmac_f32_e32 v67, v66, v66
	v_cvt_pk_bf16_f32 v134, v134, v135
	v_cvt_pk_bf16_f32 v135, v136, v137
	v_cvt_pk_bf16_f32 v136, v166, v167
	v_cvt_pk_bf16_f32 v137, v138, v139
	global_store_dwordx4 v[204:205], v[134:137], off offset:256
	global_load_dwordx4 v[134:137], v[206:207], off offset:2304
	s_nop 0
	global_load_dwordx4 v[186:189], v[208:209], off offset:2304
	v_fmac_f32_e32 v65, v64, v64
	v_mul_f32_e32 v63, v63, v63
	v_mul_f32_e32 v61, v61, v61
	v_add_f32_e32 v64, v67, v65
	v_fmac_f32_e32 v63, v62, v62
	v_fmac_f32_e32 v61, v60, v60
	v_add_f32_e32 v60, v63, v61
	s_waitcnt vmcnt(0)
	v_lshlrev_b32_e32 v138, 16, v178
	v_and_b32_e32 v139, 0xffff0000, v178
	v_lshlrev_b32_e32 v166, 16, v179
	v_and_b32_e32 v167, 0xffff0000, v179
	v_lshlrev_b32_e32 v168, 16, v180
	v_and_b32_e32 v169, 0xffff0000, v180
	v_lshlrev_b32_e32 v178, 16, v181
	v_and_b32_e32 v179, 0xffff0000, v181
	v_pk_fma_f32 v[34:35], v[34:35], v[162:163], v[166:167]
	v_pk_fma_f32 v[32:33], v[32:33], v[160:161], v[138:139]
	v_pk_fma_f32 v[30:31], v[30:31], v[158:159], v[178:179]
	v_pk_fma_f32 v[28:29], v[28:29], v[156:157], v[168:169]
	v_cvt_pk_bf16_f32 v178, v32, v33
	v_cvt_pk_bf16_f32 v179, v34, v35
	v_cvt_pk_bf16_f32 v180, v28, v29
	v_cvt_pk_bf16_f32 v181, v30, v31
	v_lshlrev_b32_e32 v34, 16, v178
	v_and_b32_e32 v35, 0xffff0000, v178
	v_lshlrev_b32_e32 v32, 16, v179
	v_and_b32_e32 v33, 0xffff0000, v179
	v_lshlrev_b32_e32 v30, 16, v180
	v_and_b32_e32 v31, 0xffff0000, v180
	v_lshlrev_b32_e32 v28, 16, v181
	v_and_b32_e32 v29, 0xffff0000, v181
	v_lshlrev_b32_e32 v190, 16, v182
	v_and_b32_e32 v191, 0xffff0000, v182
	v_lshlrev_b32_e32 v182, 16, v183
	v_and_b32_e32 v183, 0xffff0000, v183
	global_store_dwordx4 v[212:213], v[178:181], off offset:2304
	v_pk_mul_f32 v[138:139], v[74:75], v[32:33]
	v_pk_mul_f32 v[166:167], v[72:73], v[34:35]
	v_pk_mul_f32 v[168:169], v[70:71], v[28:29]
	v_pk_mul_f32 v[180:181], v[68:69], v[30:31]
	v_cvt_pk_bf16_f32 v178, v166, v167
	v_cvt_pk_bf16_f32 v179, v138, v139
	v_cvt_pk_bf16_f32 v180, v180, v181
	v_cvt_pk_bf16_f32 v181, v168, v169
	v_pk_fma_f32 v[24:25], v[24:25], v[162:163], v[182:183]
	v_pk_fma_f32 v[22:23], v[22:23], v[160:161], v[190:191]
	v_lshlrev_b32_e32 v192, 16, v184
	v_and_b32_e32 v193, 0xffff0000, v184
	v_lshlrev_b32_e32 v184, 16, v185
	v_and_b32_e32 v185, 0xffff0000, v185
	global_store_dwordx4 v[214:215], v[178:181], off offset:256
	v_pk_fma_f32 v[20:21], v[20:21], v[158:159], v[184:185]
	v_pk_fma_f32 v[18:19], v[18:19], v[156:157], v[192:193]
	v_cvt_pk_bf16_f32 v178, v22, v23
	v_cvt_pk_bf16_f32 v179, v24, v25
	v_lshlrev_b32_e32 v24, 16, v178
	v_and_b32_e32 v25, 0xffff0000, v178
	v_lshlrev_b32_e32 v22, 16, v179
	v_and_b32_e32 v23, 0xffff0000, v179
	v_cvt_pk_bf16_f32 v180, v18, v19
	v_cvt_pk_bf16_f32 v181, v20, v21
	v_pk_mul_f32 v[138:139], v[74:75], v[22:23]
	v_pk_mul_f32 v[166:167], v[72:73], v[24:25]
	global_store_dwordx4 v[216:217], v[178:181], off offset:2304
	v_lshlrev_b32_e32 v20, 16, v180
	v_and_b32_e32 v21, 0xffff0000, v180
	v_cvt_pk_bf16_f32 v178, v166, v167
	v_cvt_pk_bf16_f32 v179, v138, v139
	v_lshlrev_b32_e32 v138, 16, v134
	v_and_b32_e32 v139, 0xffff0000, v134
	v_lshlrev_b32_e32 v134, 16, v135
	v_and_b32_e32 v135, 0xffff0000, v135
	v_lshlrev_b32_e32 v166, 16, v136
	v_and_b32_e32 v167, 0xffff0000, v136
	v_lshlrev_b32_e32 v136, 16, v137
	v_and_b32_e32 v137, 0xffff0000, v137
	v_lshlrev_b32_e32 v18, 16, v181
	v_and_b32_e32 v19, 0xffff0000, v181
	v_pk_fma_f32 v[16:17], v[16:17], v[162:163], v[134:135]
	v_pk_fma_f32 v[14:15], v[14:15], v[160:161], v[138:139]
	v_pk_fma_f32 v[12:13], v[12:13], v[158:159], v[136:137]
	v_pk_fma_f32 v[10:11], v[10:11], v[156:157], v[166:167]
	v_pk_mul_f32 v[168:169], v[70:71], v[18:19]
	v_pk_mul_f32 v[180:181], v[68:69], v[20:21]
	v_cvt_pk_bf16_f32 v134, v14, v15
	v_cvt_pk_bf16_f32 v135, v16, v17
	v_cvt_pk_bf16_f32 v136, v10, v11
	v_cvt_pk_bf16_f32 v137, v12, v13
	v_cvt_pk_bf16_f32 v180, v180, v181
	v_cvt_pk_bf16_f32 v181, v168, v169
	v_lshlrev_b32_e32 v16, 16, v134
	v_and_b32_e32 v17, 0xffff0000, v134
	v_lshlrev_b32_e32 v14, 16, v135
	v_and_b32_e32 v15, 0xffff0000, v135
	v_lshlrev_b32_e32 v12, 16, v136
	v_and_b32_e32 v13, 0xffff0000, v136
	v_lshlrev_b32_e32 v10, 16, v137
	v_and_b32_e32 v11, 0xffff0000, v137
	global_store_dwordx4 v[218:219], v[178:181], off offset:256
	v_lshlrev_b32_e32 v168, 16, v186
	v_and_b32_e32 v169, 0xffff0000, v186
	v_lshlrev_b32_e32 v178, 16, v187
	v_and_b32_e32 v179, 0xffff0000, v187
	v_lshlrev_b32_e32 v180, 16, v188
	v_and_b32_e32 v181, 0xffff0000, v188
	v_lshlrev_b32_e32 v182, 16, v189
	v_and_b32_e32 v183, 0xffff0000, v189
	global_store_dwordx4 v[196:197], v[134:137], off offset:2304
	v_pk_mul_f32 v[138:139], v[70:71], v[10:11]
	v_pk_mul_f32 v[166:167], v[68:69], v[12:13]
	v_pk_mul_f32 v[136:137], v[74:75], v[14:15]
	v_pk_mul_f32 v[134:135], v[72:73], v[16:17]
	v_pk_fma_f32 v[8:9], v[8:9], v[162:163], v[178:179]
	v_cvt_pk_bf16_f32 v134, v134, v135
	v_cvt_pk_bf16_f32 v135, v136, v137
	v_cvt_pk_bf16_f32 v136, v166, v167
	v_cvt_pk_bf16_f32 v137, v138, v139
	v_pk_fma_f32 v[6:7], v[6:7], v[160:161], v[168:169]
	v_pk_fma_f32 v[4:5], v[4:5], v[158:159], v[182:183]
	v_pk_fma_f32 v[2:3], v[2:3], v[156:157], v[180:181]
	global_store_dwordx4 v[210:211], v[134:137], off offset:256
	s_nop 1
	v_cvt_pk_bf16_f32 v134, v6, v7
	v_cvt_pk_bf16_f32 v135, v8, v9
	v_cvt_pk_bf16_f32 v136, v2, v3
	v_cvt_pk_bf16_f32 v137, v4, v5
	v_lshlrev_b32_e32 v8, 16, v134
	v_and_b32_e32 v9, 0xffff0000, v134
	v_lshlrev_b32_e32 v6, 16, v135
	v_and_b32_e32 v7, 0xffff0000, v135
	v_lshlrev_b32_e32 v4, 16, v136
	v_and_b32_e32 v5, 0xffff0000, v136
	v_lshlrev_b32_e32 v2, 16, v137
	v_and_b32_e32 v3, 0xffff0000, v137
	global_store_dwordx4 v[220:221], v[134:137], off offset:2304
	v_pk_mul_f32 v[74:75], v[74:75], v[6:7]
	v_pk_mul_f32 v[72:73], v[72:73], v[8:9]
	v_pk_mul_f32 v[134:135], v[70:71], v[2:3]
	v_pk_mul_f32 v[70:71], v[68:69], v[4:5]
	v_cvt_pk_bf16_f32 v68, v72, v73
	v_cvt_pk_bf16_f32 v69, v74, v75
	v_cvt_pk_bf16_f32 v70, v70, v71
	v_cvt_pk_bf16_f32 v71, v134, v135
	global_store_dwordx4 v[132:133], v[68:71], off offset:256
	v_xor_b32_e32 v72, 32, v227
	v_mul_f32_e32 v73, v129, v129
	v_and_b32_e32 v71, 64, v227
	v_xor_b32_e32 v70, 16, v227
	v_add_u32_e32 v71, 64, v71
	v_cmp_lt_i32_e32 vcc, v70, v71
	v_fmac_f32_e32 v73, v128, v128
	v_mul_f32_e32 v74, v125, v125
	v_cndmask_b32_e32 v70, v227, v70, vcc
	v_cmp_lt_i32_e32 vcc, v72, v71
	v_fmac_f32_e32 v74, v124, v124
	v_lshlrev_b32_e32 v70, 2, v70
	v_cndmask_b32_e32 v71, v227, v72, vcc
	v_mul_f32_e32 v72, v131, v131
	v_fmac_f32_e32 v72, v130, v130
	v_add_f32_e32 v72, v72, v73
	v_mul_f32_e32 v73, v127, v127
	v_fmac_f32_e32 v73, v126, v126
	v_add_f32_e32 v73, v73, v74
	v_add_f32_e32 v72, v72, v73
	v_add_f32_e32 v64, v72, v64
	v_add_f32_e32 v60, v60, v64
	ds_bpermute_b32 v61, v70, v60
	v_lshlrev_b32_e32 v71, 2, v71
	v_lshl_add_u64 v[68:69], v[150:151], 0, s[24:25]
	s_waitcnt lgkmcnt(0)
	v_add_f32_e32 v60, v60, v61
	ds_bpermute_b32 v61, v71, v60
	s_and_saveexec_b64 s[18:19], s[40:41]
	s_cbranch_execz .LBB0_364
	s_waitcnt lgkmcnt(0)
	v_add_f32_e32 v60, v60, v61
	global_atomic_add_f32 v[68:69], v60, off

.LBB0_395:
	s_add_u32 s26, s24, 0x100
	s_addc_u32 s27, s25, 0
	s_add_i32 s0, 0, 0x10000
	s_cmp_eq_u32 s52, 40
	s_cselect_b32 s31, s43, s27
	s_cselect_b32 s30, s42, s26
	s_cselect_b32 s29, s45, s19
	s_cselect_b32 s28, s44, s18
	s_add_i32 m0, s69, 0xc000
	ds_read_b128 v[172:175], v235
	ds_read_b128 v[176:179], v235 offset:1024
	ds_read_b128 v[180:183], v235 offset:2048
	ds_read_b128 v[184:187], v235 offset:3072
	ds_read_b128 v[188:191], v235 offset:4096
	ds_read_b128 v[192:195], v235 offset:5120
	ds_read_b128 v[196:199], v235 offset:6144
	ds_read_b128 v[200:203], v235 offset:7168
	global_load_lds_dwordx4 v152, s[24:25]
	v_lshl_add_u64 v[164:165], s[24:25], 0, v[154:155]
	s_add_i32 m0, s69, 0xe000
	s_nop 0
	global_load_lds_dwordx4 v[164:165], off
	s_waitcnt vmcnt(10) lgkmcnt(8)
	s_setprio 1
	s_barrier
	s_waitcnt lgkmcnt(0)
	v_mfma_f32_16x16x32_bf16 v[136:139], v[100:103], v[172:175], v[136:139]
	v_mfma_f32_16x16x32_bf16 v[132:135], v[156:159], v[172:175], v[132:135]
	v_mfma_f32_16x16x32_bf16 v[128:131], v[100:103], v[180:183], v[128:131]
	v_mfma_f32_16x16x32_bf16 v[124:127], v[156:159], v[180:183], v[124:127]
	v_mfma_f32_16x16x32_bf16 v[120:123], v[100:103], v[188:191], v[120:123]
	v_mfma_f32_16x16x32_bf16 v[116:119], v[156:159], v[188:191], v[116:119]
	v_mfma_f32_16x16x32_bf16 v[112:115], v[100:103], v[196:199], v[112:115]
	v_mfma_f32_16x16x32_bf16 v[108:111], v[156:159], v[196:199], v[108:111]
	v_mfma_f32_16x16x32_bf16 v[136:139], v[104:107], v[176:179], v[136:139]
	v_mfma_f32_16x16x32_bf16 v[132:135], v[160:163], v[176:179], v[132:135]
	v_mfma_f32_16x16x32_bf16 v[128:131], v[104:107], v[184:187], v[128:131]
	v_mfma_f32_16x16x32_bf16 v[124:127], v[160:163], v[184:187], v[124:127]
	v_mfma_f32_16x16x32_bf16 v[120:123], v[104:107], v[192:195], v[120:123]
	v_mfma_f32_16x16x32_bf16 v[116:119], v[160:163], v[192:195], v[116:119]
	v_mfma_f32_16x16x32_bf16 v[112:115], v[104:107], v[200:203], v[112:115]
	v_mfma_f32_16x16x32_bf16 v[108:111], v[160:163], v[200:203], v[108:111]
	s_barrier
	s_setprio 0
	s_add_i32 s24, 0, 0x14000
	v_add_u32_e32 v164, s24, v233
	s_add_i32 s0, s0, s68
	ds_read_b128 v[204:207], v164
	ds_read_b128 v[208:211], v164 offset:1024
	ds_read_b128 v[212:215], v164 offset:2048
	ds_read_b128 v[216:219], v164 offset:3072
	v_lshl_add_u64 v[164:165], s[28:29], 0, v[26:27]
	s_mov_b32 m0, s0
	v_lshl_add_u64 v[220:221], s[28:29], 0, v[140:141]
	global_load_lds_dwordx4 v[164:165], off
	s_add_i32 m0, s0, 0x2000
	s_nop 0
	global_load_lds_dwordx4 v[220:221], off
	s_waitcnt vmcnt(10)
	s_setprio 1
	s_barrier
	s_waitcnt lgkmcnt(0)
	v_mfma_f32_16x16x32_bf16 v[64:67], v[204:207], v[172:175], v[64:67]
	v_mfma_f32_16x16x32_bf16 v[60:63], v[212:215], v[172:175], v[60:63]
	v_mfma_f32_16x16x32_bf16 v[56:59], v[204:207], v[180:183], v[56:59]
	v_mfma_f32_16x16x32_bf16 v[52:55], v[212:215], v[180:183], v[52:55]
	v_mfma_f32_16x16x32_bf16 v[48:51], v[204:207], v[188:191], v[48:51]
	v_mfma_f32_16x16x32_bf16 v[44:47], v[212:215], v[188:191], v[44:47]
	v_mfma_f32_16x16x32_bf16 v[40:43], v[204:207], v[196:199], v[40:43]
	v_mfma_f32_16x16x32_bf16 v[36:39], v[212:215], v[196:199], v[36:39]
	v_mfma_f32_16x16x32_bf16 v[64:67], v[208:211], v[176:179], v[64:67]
	v_mfma_f32_16x16x32_bf16 v[60:63], v[216:219], v[176:179], v[60:63]
	v_mfma_f32_16x16x32_bf16 v[56:59], v[208:211], v[184:187], v[56:59]
	v_mfma_f32_16x16x32_bf16 v[52:55], v[216:219], v[184:187], v[52:55]
	v_mfma_f32_16x16x32_bf16 v[48:51], v[208:211], v[192:195], v[48:51]
	v_mfma_f32_16x16x32_bf16 v[44:47], v[216:219], v[192:195], v[44:47]
	v_mfma_f32_16x16x32_bf16 v[40:43], v[208:211], v[200:203], v[40:43]
	v_mfma_f32_16x16x32_bf16 v[36:39], v[216:219], v[200:203], v[36:39]
	s_barrier
	s_setprio 0
	s_mov_b32 m0, s69
	v_lshl_add_u64 v[222:223], s[30:31], 0, v[144:145]
	ds_read_b128 v[172:175], v235 offset:16384
	ds_read_b128 v[176:179], v235 offset:17408
	ds_read_b128 v[180:183], v235 offset:18432
	ds_read_b128 v[184:187], v235 offset:19456
	ds_read_b128 v[188:191], v235 offset:20480
	ds_read_b128 v[192:195], v235 offset:21504
	ds_read_b128 v[196:199], v235 offset:22528
	ds_read_b128 v[200:203], v235 offset:23552
	global_load_lds_dwordx4 v[222:223], off
	v_lshl_add_u64 v[224:225], s[30:31], 0, v[142:143]
	s_mov_b32 m0, s72
	s_nop 0
	global_load_lds_dwordx4 v[224:225], off
	s_waitcnt vmcnt(10)
	s_setprio 1
	s_barrier
	s_waitcnt lgkmcnt(0)
	v_mfma_f32_16x16x32_bf16 v[96:99], v[100:103], v[172:175], v[96:99]
	v_mfma_f32_16x16x32_bf16 v[92:95], v[156:159], v[172:175], v[92:95]
	v_mfma_f32_16x16x32_bf16 v[88:91], v[100:103], v[180:183], v[88:91]
	v_mfma_f32_16x16x32_bf16 v[84:87], v[156:159], v[180:183], v[84:87]
	v_mfma_f32_16x16x32_bf16 v[80:83], v[100:103], v[188:191], v[80:83]
	v_mfma_f32_16x16x32_bf16 v[76:79], v[156:159], v[188:191], v[76:79]
	v_mfma_f32_16x16x32_bf16 v[72:75], v[100:103], v[196:199], v[72:75]
	v_mfma_f32_16x16x32_bf16 v[68:71], v[156:159], v[196:199], v[68:71]
	v_mfma_f32_16x16x32_bf16 v[96:99], v[104:107], v[176:179], v[96:99]
	v_mfma_f32_16x16x32_bf16 v[92:95], v[160:163], v[176:179], v[92:95]
	v_mfma_f32_16x16x32_bf16 v[88:91], v[104:107], v[184:187], v[88:91]
	v_mfma_f32_16x16x32_bf16 v[84:87], v[160:163], v[184:187], v[84:87]
	v_mfma_f32_16x16x32_bf16 v[80:83], v[104:107], v[192:195], v[80:83]
	v_mfma_f32_16x16x32_bf16 v[76:79], v[160:163], v[192:195], v[76:79]
	v_mfma_f32_16x16x32_bf16 v[72:75], v[104:107], v[200:203], v[72:75]
	v_mfma_f32_16x16x32_bf16 v[68:71], v[160:163], v[200:203], v[68:71]
	s_barrier
	s_setprio 0
	s_add_u32 s0, s28, 0xb0000
	s_addc_u32 s1, s29, 0
	s_add_i32 s24, s24, s68
	s_mov_b32 m0, s24
	s_nop 0
	global_load_lds_dwordx4 v26, s[0:1]
	s_add_i32 m0, s24, 0x2000
	s_nop 0
	global_load_lds_dwordx4 v140, s[0:1]
	v_add_u32_e32 v160, 0x18000, v233
	ds_read_b128 v[100:103], v160
	ds_read_b128 v[104:107], v160 offset:1024
	ds_read_b128 v[156:159], v160 offset:2048
	ds_read_b128 v[160:163], v160 offset:3072
	s_waitcnt vmcnt(10)
	s_setprio 1
	s_barrier
	v_mfma_f32_16x16x32_bf16 v[32:35], v[204:207], v[172:175], v[32:35]
	v_mfma_f32_16x16x32_bf16 v[28:31], v[212:215], v[172:175], v[28:31]
	v_mfma_f32_16x16x32_bf16 v[22:25], v[204:207], v[180:183], v[22:25]
	v_mfma_f32_16x16x32_bf16 v[18:21], v[212:215], v[180:183], v[18:21]
	v_mfma_f32_16x16x32_bf16 v[14:17], v[204:207], v[188:191], v[14:17]
	v_mfma_f32_16x16x32_bf16 v[10:13], v[212:215], v[188:191], v[10:13]
	v_mfma_f32_16x16x32_bf16 v[6:9], v[204:207], v[196:199], v[6:9]
	v_mfma_f32_16x16x32_bf16 v[2:5], v[212:215], v[196:199], v[2:5]
	v_mfma_f32_16x16x32_bf16 v[32:35], v[208:211], v[176:179], v[32:35]
	v_mfma_f32_16x16x32_bf16 v[28:31], v[216:219], v[176:179], v[28:31]
	v_mfma_f32_16x16x32_bf16 v[22:25], v[208:211], v[184:187], v[22:25]
	v_mfma_f32_16x16x32_bf16 v[18:21], v[216:219], v[184:187], v[18:21]
	v_mfma_f32_16x16x32_bf16 v[14:17], v[208:211], v[192:195], v[14:17]
	v_mfma_f32_16x16x32_bf16 v[10:13], v[216:219], v[192:195], v[10:13]
	v_mfma_f32_16x16x32_bf16 v[6:9], v[208:211], v[200:203], v[6:9]
	v_mfma_f32_16x16x32_bf16 v[2:5], v[216:219], v[200:203], v[2:5]
	s_barrier
	s_setprio 0
	s_add_i32 s24, 0, 0x18000
	s_add_u32 s0, s30, 0xb0000
	s_addc_u32 s1, s31, 0
	s_mov_b32 m0, s73
	ds_read_b128 v[172:175], v235 offset:32768
	ds_read_b128 v[176:179], v235 offset:33792
	ds_read_b128 v[180:183], v235 offset:34816
	ds_read_b128 v[184:187], v235 offset:35840
	ds_read_b128 v[188:191], v235 offset:36864
	ds_read_b128 v[192:195], v235 offset:37888
	ds_read_b128 v[196:199], v235 offset:38912
	ds_read_b128 v[200:203], v235 offset:39936
	global_load_lds_dwordx4 v144, s[0:1]
	s_mov_b32 m0, s81
	s_nop 0
	global_load_lds_dwordx4 v142, s[0:1]
	s_waitcnt vmcnt(10) lgkmcnt(8)
	s_setprio 1
	s_barrier
	s_waitcnt lgkmcnt(0)
	v_mfma_f32_16x16x32_bf16 v[136:139], v[100:103], v[172:175], v[136:139]
	v_mfma_f32_16x16x32_bf16 v[132:135], v[156:159], v[172:175], v[132:135]
	v_mfma_f32_16x16x32_bf16 v[128:131], v[100:103], v[180:183], v[128:131]
	v_mfma_f32_16x16x32_bf16 v[124:127], v[156:159], v[180:183], v[124:127]
	v_mfma_f32_16x16x32_bf16 v[120:123], v[100:103], v[188:191], v[120:123]
	v_mfma_f32_16x16x32_bf16 v[116:119], v[156:159], v[188:191], v[116:119]
	v_mfma_f32_16x16x32_bf16 v[112:115], v[100:103], v[196:199], v[112:115]
	v_mfma_f32_16x16x32_bf16 v[108:111], v[156:159], v[196:199], v[108:111]
	v_mfma_f32_16x16x32_bf16 v[136:139], v[104:107], v[176:179], v[136:139]
	v_mfma_f32_16x16x32_bf16 v[132:135], v[160:163], v[176:179], v[132:135]
	v_mfma_f32_16x16x32_bf16 v[128:131], v[104:107], v[184:187], v[128:131]
	v_mfma_f32_16x16x32_bf16 v[124:127], v[160:163], v[184:187], v[124:127]
	v_mfma_f32_16x16x32_bf16 v[120:123], v[104:107], v[192:195], v[120:123]
	v_mfma_f32_16x16x32_bf16 v[116:119], v[160:163], v[192:195], v[116:119]
	v_mfma_f32_16x16x32_bf16 v[112:115], v[104:107], v[200:203], v[112:115]
	v_mfma_f32_16x16x32_bf16 v[108:111], v[160:163], v[200:203], v[108:111]
	s_barrier
	s_setprio 0
	s_add_i32 s25, 0, 0x1c000
	s_add_i32 s0, s24, s68
	v_add_u32_e32 v166, s25, v233
	v_lshl_add_u64 v[164:165], v[164:165], 0, s[12:13]
	s_mov_b32 m0, s0
	ds_read_b128 v[204:207], v166
	ds_read_b128 v[208:211], v166 offset:1024
	ds_read_b128 v[212:215], v166 offset:2048
	ds_read_b128 v[216:219], v166 offset:3072
	global_load_lds_dwordx4 v[164:165], off
	v_lshl_add_u64 v[164:165], v[220:221], 0, s[12:13]
	s_add_i32 m0, s0, 0x2000
	s_nop 0
	global_load_lds_dwordx4 v[164:165], off
	s_waitcnt vmcnt(10)
	s_setprio 1
	s_barrier
	s_waitcnt lgkmcnt(0)
	v_mfma_f32_16x16x32_bf16 v[64:67], v[204:207], v[172:175], v[64:67]
	v_mfma_f32_16x16x32_bf16 v[60:63], v[212:215], v[172:175], v[60:63]
	v_mfma_f32_16x16x32_bf16 v[56:59], v[204:207], v[180:183], v[56:59]
	v_mfma_f32_16x16x32_bf16 v[52:55], v[212:215], v[180:183], v[52:55]
	v_mfma_f32_16x16x32_bf16 v[48:51], v[204:207], v[188:191], v[48:51]
	v_mfma_f32_16x16x32_bf16 v[44:47], v[212:215], v[188:191], v[44:47]
	v_mfma_f32_16x16x32_bf16 v[40:43], v[204:207], v[196:199], v[40:43]
	v_mfma_f32_16x16x32_bf16 v[36:39], v[212:215], v[196:199], v[36:39]
	v_mfma_f32_16x16x32_bf16 v[64:67], v[208:211], v[176:179], v[64:67]
	v_mfma_f32_16x16x32_bf16 v[60:63], v[216:219], v[176:179], v[60:63]
	v_mfma_f32_16x16x32_bf16 v[56:59], v[208:211], v[184:187], v[56:59]
	v_mfma_f32_16x16x32_bf16 v[52:55], v[216:219], v[184:187], v[52:55]
	v_mfma_f32_16x16x32_bf16 v[48:51], v[208:211], v[192:195], v[48:51]
	v_mfma_f32_16x16x32_bf16 v[44:47], v[216:219], v[192:195], v[44:47]
	v_mfma_f32_16x16x32_bf16 v[40:43], v[208:211], v[200:203], v[40:43]
	v_mfma_f32_16x16x32_bf16 v[36:39], v[216:219], v[200:203], v[36:39]
	s_barrier
	s_setprio 0
	s_mov_b32 m0, s21
	v_lshl_add_u64 v[164:165], v[222:223], 0, s[12:13]
	ds_read_b128 v[172:175], v235 offset:49152
	ds_read_b128 v[176:179], v235 offset:50176
	ds_read_b128 v[180:183], v235 offset:51200
	ds_read_b128 v[184:187], v235 offset:52224
	ds_read_b128 v[188:191], v235 offset:53248
	ds_read_b128 v[192:195], v235 offset:54272
	ds_read_b128 v[196:199], v235 offset:55296
	ds_read_b128 v[200:203], v235 offset:56320
	global_load_lds_dwordx4 v[164:165], off
	v_lshl_add_u64 v[164:165], v[224:225], 0, s[12:13]
	s_mov_b32 m0, s48
	s_nop 0
	global_load_lds_dwordx4 v[164:165], off
	s_waitcnt vmcnt(10)
	s_setprio 1
	s_barrier
	s_waitcnt lgkmcnt(0)
	v_mfma_f32_16x16x32_bf16 v[96:99], v[100:103], v[172:175], v[96:99]
	v_mfma_f32_16x16x32_bf16 v[92:95], v[156:159], v[172:175], v[92:95]
	v_mfma_f32_16x16x32_bf16 v[88:91], v[100:103], v[180:183], v[88:91]
	v_mfma_f32_16x16x32_bf16 v[84:87], v[156:159], v[180:183], v[84:87]
	v_mfma_f32_16x16x32_bf16 v[80:83], v[100:103], v[188:191], v[80:83]
	v_mfma_f32_16x16x32_bf16 v[76:79], v[156:159], v[188:191], v[76:79]
	v_mfma_f32_16x16x32_bf16 v[72:75], v[100:103], v[196:199], v[72:75]
	v_mfma_f32_16x16x32_bf16 v[68:71], v[156:159], v[196:199], v[68:71]
	v_mfma_f32_16x16x32_bf16 v[96:99], v[104:107], v[176:179], v[96:99]
	v_mfma_f32_16x16x32_bf16 v[92:95], v[160:163], v[176:179], v[92:95]
	v_mfma_f32_16x16x32_bf16 v[88:91], v[104:107], v[184:187], v[88:91]
	v_mfma_f32_16x16x32_bf16 v[84:87], v[160:163], v[184:187], v[84:87]
	v_mfma_f32_16x16x32_bf16 v[80:83], v[104:107], v[192:195], v[80:83]
	v_mfma_f32_16x16x32_bf16 v[76:79], v[160:163], v[192:195], v[76:79]
	v_mfma_f32_16x16x32_bf16 v[72:75], v[104:107], v[200:203], v[72:75]
	v_mfma_f32_16x16x32_bf16 v[68:71], v[160:163], v[200:203], v[68:71]
	s_barrier
	s_setprio 0
	s_add_u32 s0, s28, 0xb0080
	s_addc_u32 s1, s29, 0
	s_add_i32 s24, s25, s68
	s_mov_b32 m0, s24
	s_nop 0
	global_load_lds_dwordx4 v26, s[0:1]
	s_add_i32 m0, s24, 0x2000
	s_nop 0
	global_load_lds_dwordx4 v140, s[0:1]
	v_add_u32_e32 v160, 0x10000, v233
	ds_read_b128 v[100:103], v160
	ds_read_b128 v[104:107], v160 offset:1024
	ds_read_b128 v[156:159], v160 offset:2048
	ds_read_b128 v[160:163], v160 offset:3072
	s_add_i32 s52, s52, 2
	s_add_u32 s18, s18, 0x100
	s_addc_u32 s19, s19, 0
	s_cmp_gt_u32 s52, 41
	s_mov_b64 s[24:25], s[26:27]
	s_waitcnt vmcnt(10)
	s_setprio 1
	s_barrier
	v_mfma_f32_16x16x32_bf16 v[32:35], v[204:207], v[172:175], v[32:35]
	v_mfma_f32_16x16x32_bf16 v[28:31], v[212:215], v[172:175], v[28:31]
	v_mfma_f32_16x16x32_bf16 v[22:25], v[204:207], v[180:183], v[22:25]
	v_mfma_f32_16x16x32_bf16 v[18:21], v[212:215], v[180:183], v[18:21]
	v_mfma_f32_16x16x32_bf16 v[14:17], v[204:207], v[188:191], v[14:17]
	v_mfma_f32_16x16x32_bf16 v[10:13], v[212:215], v[188:191], v[10:13]
	v_mfma_f32_16x16x32_bf16 v[6:9], v[204:207], v[196:199], v[6:9]
	v_mfma_f32_16x16x32_bf16 v[2:5], v[212:215], v[196:199], v[2:5]
	v_mfma_f32_16x16x32_bf16 v[32:35], v[208:211], v[176:179], v[32:35]
	v_mfma_f32_16x16x32_bf16 v[28:31], v[216:219], v[176:179], v[28:31]
	v_mfma_f32_16x16x32_bf16 v[22:25], v[208:211], v[184:187], v[22:25]
	v_mfma_f32_16x16x32_bf16 v[18:21], v[216:219], v[184:187], v[18:21]
	v_mfma_f32_16x16x32_bf16 v[14:17], v[208:211], v[192:195], v[14:17]
	v_mfma_f32_16x16x32_bf16 v[10:13], v[216:219], v[192:195], v[10:13]
	v_mfma_f32_16x16x32_bf16 v[6:9], v[208:211], v[200:203], v[6:9]
	v_mfma_f32_16x16x32_bf16 v[2:5], v[216:219], v[200:203], v[2:5]
	s_barrier
	s_setprio 0
	s_cbranch_scc0 .LBB0_395
	s_waitcnt lgkmcnt(0)
	s_min_i32 s0, s22, 0x100
	s_ashr_i32 s0, s0, 5
	s_ashr_i32 s1, s0, 31
	s_add_i32 s18, s22, 0xffffff00
	s_cmpk_lt_i32 s22, 0x100
	s_cselect_b32 s18, s22, s18
	s_cselect_b32 s25, 0, s35
	s_cselect_b32 s24, 0, s34
	s_cselect_b32 s26, 0, s57
	s_cselect_b32 s27, 0, s58
	s_ashr_i32 s19, s18, 31
	s_add_u32 s24, s46, s24
	s_addc_u32 s25, s47, s25
	s_lshl_b64 s[18:19], s[18:19], 20
	v_lshl_add_u64 v[100:101], s[18:19], 0, v[146:147]
	s_add_u32 s18, s50, s26
	v_lshl_or_b32 v172, s23, 8, v234
	s_addc_u32 s19, s51, s27
	s_ashr_i32 s23, s22, 31
	v_lshl_add_u64 v[180:181], s[18:19], 0, v[100:101]
	s_lshl_b64 s[18:19], s[22:23], 19
	v_lshl_add_u64 v[184:185], v[148:149], 0, s[18:19]
	s_lshl_b64 s[52:53], s[22:23], 10
	s_mul_i32 s18, s0, 0x9000
	v_ashrrev_i32_e32 v173, 31, v172
	s_mul_hi_i32 s19, s0, 0x9000
	s_add_u32 s18, s36, s18
	s_addc_u32 s19, s37, s19
	v_lshlrev_b64 v[186:187], 2, v[172:173]
	v_lshl_add_u64 v[156:157], s[18:19], 0, v[186:187]
	v_lshl_add_u64 v[164:165], s[24:25], 0, v[100:101]
	global_load_dwordx4 v[100:103], v[156:157], off offset:16
	global_load_dwordx4 v[104:107], v[156:157], off
	s_lshl_b64 s[0:1], s[0:1], 12
	s_add_u32 s0, s59, s0
	s_addc_u32 s1, s20, s1
	v_lshl_add_u64 v[164:165], v[164:165], 0, v[186:187]
	s_mov_b32 s18, 0x20000
	s_waitcnt vmcnt(0)
	v_pk_mul_f32 v[178:179], v[102:103], 0.5 op_sel_hi:[1,0]
	v_pk_mul_f32 v[174:175], v[106:107], 0.5 op_sel_hi:[1,0]
	v_pk_mul_f32 v[176:177], v[104:105], 0.5 op_sel_hi:[1,0]
	v_pk_mul_f32 v[210:211], v[100:101], 0.5 op_sel_hi:[1,0]
	global_load_dwordx4 v[100:103], v[156:157], off offset:528
	global_load_dwordx4 v[104:107], v[156:157], off offset:512
	s_waitcnt vmcnt(0)
	v_pk_mul_f32 v[162:163], v[100:101], 0.5 op_sel_hi:[1,0]
	v_lshlrev_b64 v[100:101], 1, v[172:173]
	v_lshl_add_u64 v[182:183], v[180:181], 0, v[100:101]
	v_lshl_add_u64 v[180:181], v[184:185], 0, v[100:101]
	v_lshl_add_u64 v[184:185], s[0:1], 0, v[186:187]
	v_pk_mul_f32 v[156:157], v[106:107], 0.5 op_sel_hi:[1,0]
	v_pk_mul_f32 v[158:159], v[104:105], 0.5 op_sel_hi:[1,0]
	v_pk_mul_f32 v[160:161], v[102:103], 0.5 op_sel_hi:[1,0]
	global_load_dwordx4 v[100:103], v[184:185], off offset:16
	global_load_dwordx4 v[104:107], v[184:185], off
	global_load_dwordx4 v[188:191], v[164:165], off offset:16
	global_load_dwordx4 v[192:195], v[164:165], off
	v_add_co_u32_e32 v186, vcc, s65, v164
	s_mov_b64 s[0:1], 0x10000
	s_nop 0
	v_addc_co_u32_e32 v187, vcc, 0, v165, vcc
	v_lshl_add_u64 v[172:173], v[164:165], 0, s[0:1]
	global_load_dwordx4 v[196:199], v[186:187], off
	global_load_dwordx4 v[200:203], v[172:173], off offset:16
	s_mov_b32 s0, 0x8000
	s_waitcnt vmcnt(0)
	v_pk_fma_f32 v[134:135], v[134:135], v[178:179], v[190:191]
	v_pk_fma_f32 v[138:139], v[138:139], v[174:175], v[194:195]
	v_pk_fma_f32 v[136:137], v[136:137], v[176:177], v[192:193]
	v_pk_fma_f32 v[132:133], v[132:133], v[210:211], v[188:189]
	v_cvt_pk_bf16_f32 v188, v136, v137
	v_cvt_pk_bf16_f32 v189, v138, v139
	v_cvt_pk_bf16_f32 v190, v132, v133
	v_cvt_pk_bf16_f32 v191, v134, v135
	v_lshlrev_b32_e32 v138, 16, v188
	v_and_b32_e32 v139, 0xffff0000, v188
	v_lshlrev_b32_e32 v136, 16, v189
	v_and_b32_e32 v137, 0xffff0000, v189
	global_store_dwordx4 v[182:183], v[188:191], off offset:2048
	v_lshlrev_b32_e32 v134, 16, v190
	v_and_b32_e32 v135, 0xffff0000, v190
	v_lshlrev_b32_e32 v132, 16, v191
	v_and_b32_e32 v133, 0xffff0000, v191
	v_pk_mul_f32 v[172:173], v[106:107], v[136:137]
	v_pk_mul_f32 v[188:189], v[104:105], v[138:139]
	v_pk_mul_f32 v[192:193], v[102:103], v[132:133]
	v_pk_mul_f32 v[190:191], v[100:101], v[134:135]
	v_cvt_pk_bf16_f32 v188, v188, v189
	v_cvt_pk_bf16_f32 v189, v172, v173
	v_pk_fma_f32 v[130:131], v[130:131], v[174:175], v[198:199]
	v_pk_fma_f32 v[128:129], v[128:129], v[176:177], v[196:197]
	v_pk_fma_f32 v[172:173], v[126:127], v[178:179], v[202:203]
	v_pk_fma_f32 v[126:127], v[124:125], v[210:211], v[200:201]
	v_add_co_u32_e32 v202, vcc, s65, v182
	v_cvt_pk_bf16_f32 v190, v190, v191
	v_cvt_pk_bf16_f32 v191, v192, v193
	v_cvt_pk_bf16_f32 v124, v128, v129
	v_cvt_pk_bf16_f32 v125, v130, v131
	v_cvt_pk_bf16_f32 v126, v126, v127
	v_cvt_pk_bf16_f32 v127, v172, v173
	v_addc_co_u32_e32 v203, vcc, 0, v183, vcc
	global_store_dwordx4 v[180:181], v[188:191], off
	global_store_dwordx4 v[202:203], v[124:127], off offset:2048
	v_lshlrev_b32_e32 v128, 16, v124
	v_and_b32_e32 v129, 0xffff0000, v124
	v_lshlrev_b32_e32 v124, 16, v125
	v_and_b32_e32 v125, 0xffff0000, v125
	v_lshlrev_b32_e32 v130, 16, v126
	v_and_b32_e32 v131, 0xffff0000, v126
	v_lshlrev_b32_e32 v126, 16, v127
	v_and_b32_e32 v127, 0xffff0000, v127
	v_pk_mul_f32 v[172:173], v[106:107], v[124:125]
	v_pk_mul_f32 v[188:189], v[104:105], v[128:129]
	v_pk_mul_f32 v[192:193], v[102:103], v[126:127]
	v_pk_mul_f32 v[190:191], v[100:101], v[130:131]
	v_add_co_u32_e32 v220, vcc, s0, v180
	v_cvt_pk_bf16_f32 v188, v188, v189
	v_cvt_pk_bf16_f32 v189, v172, v173
	v_cvt_pk_bf16_f32 v190, v190, v191
	v_cvt_pk_bf16_f32 v191, v192, v193
	v_addc_co_u32_e32 v221, vcc, 0, v181, vcc
	global_store_dwordx4 v[220:221], v[188:191], off
	s_mov_b64 s[0:1], 0x20000
	v_lshl_add_u64 v[172:173], v[164:165], 0, s[0:1]
	v_add_co_u32_e32 v188, vcc, s18, v164
	s_mov_b64 s[0:1], 0x30000
	s_nop 0
	v_addc_co_u32_e32 v189, vcc, 0, v165, vcc
	global_load_dwordx4 v[192:195], v[188:189], off
	global_load_dwordx4 v[196:199], v[172:173], off offset:16
	v_lshl_add_u64 v[172:173], v[164:165], 0, s[0:1]
	s_mov_b32 s0, 0x30000
	v_add_co_u32_e32 v190, vcc, s0, v164
	s_waitcnt vmcnt(0)
	v_pk_fma_f32 v[120:121], v[120:121], v[176:177], v[192:193]
	v_addc_co_u32_e32 v191, vcc, 0, v165, vcc
	global_load_dwordx4 v[204:207], v[190:191], off
	global_load_dwordx4 v[212:215], v[172:173], off offset:16
	v_pk_fma_f32 v[122:123], v[122:123], v[174:175], v[194:195]
	v_pk_fma_f32 v[118:119], v[118:119], v[178:179], v[198:199]
	v_pk_fma_f32 v[116:117], v[116:117], v[210:211], v[196:197]
	v_cvt_pk_bf16_f32 v194, v120, v121
	v_add_co_u32_e32 v192, vcc, s18, v182
	v_cvt_pk_bf16_f32 v195, v122, v123
	v_cvt_pk_bf16_f32 v196, v116, v117
	v_cvt_pk_bf16_f32 v197, v118, v119
	v_addc_co_u32_e32 v193, vcc, 0, v183, vcc
	v_lshlrev_b32_e32 v122, 16, v194
	v_and_b32_e32 v123, 0xffff0000, v194
	global_store_dwordx4 v[192:193], v[194:197], off offset:2048
	v_lshlrev_b32_e32 v120, 16, v195
	v_and_b32_e32 v121, 0xffff0000, v195
	v_pk_mul_f32 v[194:195], v[104:105], v[122:123]
	v_lshlrev_b32_e32 v118, 16, v196
	v_and_b32_e32 v119, 0xffff0000, v196
	v_cvt_pk_bf16_f32 v196, v194, v195
	v_add_co_u32_e32 v194, vcc, s65, v180
	v_lshlrev_b32_e32 v116, 16, v197
	v_and_b32_e32 v117, 0xffff0000, v197
	v_pk_mul_f32 v[172:173], v[106:107], v[120:121]
	v_addc_co_u32_e32 v195, vcc, 0, v181, vcc
	v_pk_mul_f32 v[200:201], v[102:103], v[116:117]
	v_pk_mul_f32 v[198:199], v[100:101], v[118:119]
	v_cvt_pk_bf16_f32 v197, v172, v173
	v_cvt_pk_bf16_f32 v198, v198, v199
	v_cvt_pk_bf16_f32 v199, v200, v201
	global_store_dwordx4 v[194:195], v[196:199], off
	s_mov_b32 s18, 0x80000
	s_waitcnt vmcnt(0)
	v_pk_fma_f32 v[114:115], v[114:115], v[174:175], v[206:207]
	v_pk_fma_f32 v[112:113], v[112:113], v[176:177], v[204:205]
	v_pk_fma_f32 v[172:173], v[110:111], v[178:179], v[214:215]
	v_pk_fma_f32 v[110:111], v[108:109], v[210:211], v[212:213]
	v_add_co_u32_e32 v212, vcc, s0, v182
	v_cvt_pk_bf16_f32 v108, v112, v113
	v_cvt_pk_bf16_f32 v109, v114, v115
	v_cvt_pk_bf16_f32 v110, v110, v111
	v_cvt_pk_bf16_f32 v111, v172, v173
	v_addc_co_u32_e32 v213, vcc, 0, v183, vcc
	global_store_dwordx4 v[212:213], v[108:111], off offset:2048
	v_lshlrev_b32_e32 v112, 16, v108
	v_and_b32_e32 v113, 0xffff0000, v108
	v_lshlrev_b32_e32 v172, 16, v109
	v_and_b32_e32 v173, 0xffff0000, v109
	v_lshlrev_b32_e32 v114, 16, v110
	v_and_b32_e32 v115, 0xffff0000, v110
	v_lshlrev_b32_e32 v108, 16, v111
	v_and_b32_e32 v109, 0xffff0000, v111
	s_mov_b32 s0, 0x18000
	v_pk_mul_f32 v[110:111], v[106:107], v[172:173]
	v_pk_mul_f32 v[196:197], v[104:105], v[112:113]
	v_pk_mul_f32 v[200:201], v[102:103], v[108:109]
	v_pk_mul_f32 v[198:199], v[100:101], v[114:115]
	v_add_co_u32_e32 v222, vcc, s0, v180
	v_cvt_pk_bf16_f32 v196, v196, v197
	v_cvt_pk_bf16_f32 v197, v110, v111
	v_cvt_pk_bf16_f32 v198, v198, v199
	v_cvt_pk_bf16_f32 v199, v200, v201
	v_addc_co_u32_e32 v223, vcc, 0, v181, vcc
	global_store_dwordx4 v[222:223], v[196:199], off
	s_mov_b64 s[0:1], 0x80000
	v_lshl_add_u64 v[110:111], v[164:165], 0, s[0:1]
	v_add_co_u32_e32 v196, vcc, s18, v164
	s_mov_b64 s[0:1], 0x90000
	s_nop 0
	v_addc_co_u32_e32 v197, vcc, 0, v165, vcc
	global_load_dwordx4 v[204:207], v[196:197], off
	global_load_dwordx4 v[214:217], v[110:111], off offset:16
	v_lshl_add_u64 v[110:111], v[164:165], 0, s[0:1]
	s_mov_b32 s0, 0x90000
	v_add_co_u32_e32 v198, vcc, s0, v164
	s_mov_b32 s1, 0x40000
	s_nop 0
	v_addc_co_u32_e32 v199, vcc, 0, v165, vcc
	global_load_dwordx4 v[238:241], v[198:199], off
	global_load_dwordx4 v[242:245], v[110:111], off offset:16
	v_add_co_u32_e32 v200, vcc, s18, v182
	s_waitcnt vmcnt(0)
	v_pk_fma_f32 v[96:97], v[96:97], v[176:177], v[204:205]
	v_pk_fma_f32 v[98:99], v[98:99], v[174:175], v[206:207]
	v_pk_fma_f32 v[94:95], v[94:95], v[178:179], v[216:217]
	v_pk_fma_f32 v[92:93], v[92:93], v[210:211], v[214:215]
	v_cvt_pk_bf16_f32 v204, v96, v97
	v_cvt_pk_bf16_f32 v205, v98, v99
	v_cvt_pk_bf16_f32 v206, v92, v93
	v_cvt_pk_bf16_f32 v207, v94, v95
	v_addc_co_u32_e32 v201, vcc, 0, v183, vcc
	v_lshlrev_b32_e32 v98, 16, v204
	v_and_b32_e32 v99, 0xffff0000, v204
	global_store_dwordx4 v[200:201], v[204:207], off offset:2048
	v_lshlrev_b32_e32 v96, 16, v205
	v_and_b32_e32 v97, 0xffff0000, v205
	v_pk_mul_f32 v[204:205], v[104:105], v[98:99]
	v_lshlrev_b32_e32 v94, 16, v206
	v_and_b32_e32 v95, 0xffff0000, v206
	v_cvt_pk_bf16_f32 v206, v204, v205
	v_add_co_u32_e32 v204, vcc, s1, v180
	v_lshlrev_b32_e32 v92, 16, v207
	v_and_b32_e32 v93, 0xffff0000, v207
	v_pk_mul_f32 v[110:111], v[106:107], v[96:97]
	v_addc_co_u32_e32 v205, vcc, 0, v181, vcc
	v_pk_mul_f32 v[214:215], v[102:103], v[92:93]
	v_pk_mul_f32 v[208:209], v[100:101], v[94:95]
	v_cvt_pk_bf16_f32 v207, v110, v111
	v_pk_fma_f32 v[90:91], v[90:91], v[174:175], v[240:241]
	v_pk_fma_f32 v[88:89], v[88:89], v[176:177], v[238:239]
	v_pk_fma_f32 v[110:111], v[86:87], v[178:179], v[244:245]
	v_pk_fma_f32 v[86:87], v[84:85], v[210:211], v[242:243]
	v_add_co_u32_e32 v218, vcc, s0, v182
	v_cvt_pk_bf16_f32 v208, v208, v209
	v_cvt_pk_bf16_f32 v209, v214, v215
	v_cvt_pk_bf16_f32 v84, v88, v89
	v_cvt_pk_bf16_f32 v85, v90, v91
	v_cvt_pk_bf16_f32 v86, v86, v87
	v_cvt_pk_bf16_f32 v87, v110, v111
	v_addc_co_u32_e32 v219, vcc, 0, v183, vcc
	global_store_dwordx4 v[204:205], v[206:209], off
	global_store_dwordx4 v[218:219], v[84:87], off offset:2048
	v_lshlrev_b32_e32 v88, 16, v84
	v_and_b32_e32 v89, 0xffff0000, v84
	v_lshlrev_b32_e32 v110, 16, v85
	v_and_b32_e32 v111, 0xffff0000, v85
	v_lshlrev_b32_e32 v90, 16, v86
	v_and_b32_e32 v91, 0xffff0000, v86
	v_lshlrev_b32_e32 v84, 16, v87
	v_and_b32_e32 v85, 0xffff0000, v87
	s_mov_b32 s0, 0x48000
	v_pk_mul_f32 v[86:87], v[106:107], v[110:111]
	v_pk_mul_f32 v[206:207], v[104:105], v[88:89]
	v_pk_mul_f32 v[214:215], v[102:103], v[84:85]
	v_pk_mul_f32 v[208:209], v[100:101], v[90:91]
	v_add_co_u32_e32 v224, vcc, s0, v180
	v_cvt_pk_bf16_f32 v206, v206, v207
	v_cvt_pk_bf16_f32 v207, v86, v87
	v_cvt_pk_bf16_f32 v208, v208, v209
	v_cvt_pk_bf16_f32 v209, v214, v215
	v_addc_co_u32_e32 v225, vcc, 0, v181, vcc
	global_store_dwordx4 v[224:225], v[206:209], off
	s_mov_b64 s[0:1], 0xa0000
	v_lshl_add_u64 v[86:87], v[164:165], 0, s[0:1]
	v_add_co_u32_e32 v206, vcc, s76, v164
	s_mov_b64 s[0:1], 0xb0000
	s_nop 0
	v_addc_co_u32_e32 v207, vcc, 0, v165, vcc
	global_load_dwordx4 v[214:217], v[206:207], off
	global_load_dwordx4 v[238:241], v[86:87], off offset:16
	v_lshl_add_u64 v[86:87], v[164:165], 0, s[0:1]
	s_mov_b32 s0, 0xb0000
	v_add_co_u32_e32 v208, vcc, s0, v164
	s_waitcnt vmcnt(0)
	v_pk_fma_f32 v[80:81], v[80:81], v[176:177], v[214:215]
	v_addc_co_u32_e32 v209, vcc, 0, v165, vcc
	global_load_dwordx4 v[242:245], v[208:209], off
	global_load_dwordx4 v[246:249], v[86:87], off offset:16
	v_pk_fma_f32 v[82:83], v[82:83], v[174:175], v[216:217]
	v_pk_fma_f32 v[76:77], v[76:77], v[210:211], v[238:239]
	v_cvt_pk_bf16_f32 v238, v80, v81
	v_pk_fma_f32 v[78:79], v[78:79], v[178:179], v[240:241]
	v_cvt_pk_bf16_f32 v239, v82, v83
	v_add_co_u32_e32 v214, vcc, s76, v182
	v_lshlrev_b32_e32 v82, 16, v238
	v_and_b32_e32 v83, 0xffff0000, v238
	v_cvt_pk_bf16_f32 v240, v76, v77
	v_cvt_pk_bf16_f32 v241, v78, v79
	v_addc_co_u32_e32 v215, vcc, 0, v183, vcc
	v_lshlrev_b32_e32 v80, 16, v239
	v_and_b32_e32 v81, 0xffff0000, v239
	v_pk_mul_f32 v[216:217], v[104:105], v[82:83]
	global_store_dwordx4 v[214:215], v[238:241], off offset:2048
	v_pk_mul_f32 v[86:87], v[106:107], v[80:81]
	v_lshlrev_b32_e32 v78, 16, v240
	v_cvt_pk_bf16_f32 v238, v216, v217
	v_add_co_u32_e32 v216, vcc, s77, v180
	v_and_b32_e32 v79, 0xffff0000, v240
	v_lshlrev_b32_e32 v76, 16, v241
	v_and_b32_e32 v77, 0xffff0000, v241
	v_cvt_pk_bf16_f32 v239, v86, v87
	v_addc_co_u32_e32 v217, vcc, 0, v181, vcc
	v_pk_mul_f32 v[250:251], v[102:103], v[76:77]
	v_pk_mul_f32 v[240:241], v[100:101], v[78:79]
	s_waitcnt vmcnt(0)
	v_pk_fma_f32 v[74:75], v[74:75], v[174:175], v[244:245]
	v_pk_fma_f32 v[72:73], v[72:73], v[176:177], v[242:243]
	v_pk_fma_f32 v[86:87], v[70:71], v[178:179], v[248:249]
	v_pk_fma_f32 v[70:71], v[68:69], v[210:211], v[246:247]
	v_cvt_pk_bf16_f32 v68, v72, v73
	v_cvt_pk_bf16_f32 v69, v74, v75
	v_cvt_pk_bf16_f32 v70, v70, v71
	v_cvt_pk_bf16_f32 v71, v86, v87
	v_add_co_u32_e32 v210, vcc, s0, v182
	v_cvt_pk_bf16_f32 v240, v240, v241
	v_cvt_pk_bf16_f32 v241, v250, v251
	v_addc_co_u32_e32 v211, vcc, 0, v183, vcc
	v_lshlrev_b32_e32 v86, 16, v68
	v_and_b32_e32 v87, 0xffff0000, v68
	v_lshlrev_b32_e32 v178, 16, v69
	v_and_b32_e32 v179, 0xffff0000, v69
	v_lshlrev_b32_e32 v176, 16, v70
	v_and_b32_e32 v177, 0xffff0000, v70
	v_lshlrev_b32_e32 v174, 16, v71
	v_and_b32_e32 v175, 0xffff0000, v71
	s_mov_b32 s0, 0x58000
	global_store_dwordx4 v[216:217], v[238:241], off
	global_store_dwordx4 v[210:211], v[68:71], off offset:2048
	v_pk_mul_f32 v[72:73], v[102:103], v[174:175]
	v_pk_mul_f32 v[74:75], v[100:101], v[176:177]
	v_pk_mul_f32 v[70:71], v[106:107], v[178:179]
	v_pk_mul_f32 v[68:69], v[104:105], v[86:87]
	v_add_co_u32_e32 v100, vcc, s0, v180
	v_cvt_pk_bf16_f32 v68, v68, v69
	v_cvt_pk_bf16_f32 v69, v70, v71
	v_cvt_pk_bf16_f32 v70, v74, v75
	v_cvt_pk_bf16_f32 v71, v72, v73
	v_addc_co_u32_e32 v101, vcc, 0, v181, vcc
	global_store_dwordx4 v[100:101], v[68:71], off
	global_load_dwordx4 v[68:71], v[184:185], off offset:528
	s_nop 0
	global_load_dwordx4 v[72:75], v[184:185], off offset:512
	global_load_dwordx4 v[102:105], v[164:165], off offset:528
	global_load_dwordx4 v[238:241], v[164:165], off offset:512
	s_mov_b64 s[0:1], 0x10200
	v_lshl_add_u64 v[106:107], v[164:165], 0, s[0:1]
	global_load_dwordx4 v[184:187], v[186:187], off offset:512
	s_nop 0
	global_load_dwordx4 v[242:245], v[106:107], off offset:16
	s_mov_b64 s[0:1], 0x20200
	s_waitcnt vmcnt(0)
	v_pk_fma_f32 v[62:63], v[62:63], v[160:161], v[104:105]
	v_pk_fma_f32 v[66:67], v[66:67], v[156:157], v[240:241]
	v_pk_fma_f32 v[64:65], v[64:65], v[158:159], v[238:239]
	v_pk_fma_f32 v[60:61], v[60:61], v[162:163], v[102:103]
	v_cvt_pk_bf16_f32 v102, v64, v65
	v_cvt_pk_bf16_f32 v103, v66, v67
	v_cvt_pk_bf16_f32 v104, v60, v61
	v_cvt_pk_bf16_f32 v105, v62, v63
	v_lshlrev_b32_e32 v66, 16, v102
	v_and_b32_e32 v67, 0xffff0000, v102
	v_lshlrev_b32_e32 v64, 16, v103
	v_and_b32_e32 v65, 0xffff0000, v103
	v_lshlrev_b32_e32 v62, 16, v104
	v_and_b32_e32 v63, 0xffff0000, v104
	v_lshlrev_b32_e32 v60, 16, v105
	v_and_b32_e32 v61, 0xffff0000, v105
	global_store_dwordx4 v[182:183], v[102:105], off offset:2304
	v_pk_mul_f32 v[106:107], v[70:71], v[60:61]
	v_pk_mul_f32 v[182:183], v[68:69], v[62:63]
	v_pk_mul_f32 v[104:105], v[74:75], v[64:65]
	v_pk_mul_f32 v[102:103], v[72:73], v[66:67]
	v_pk_fma_f32 v[58:59], v[58:59], v[156:157], v[186:187]
	v_cvt_pk_bf16_f32 v102, v102, v103
	v_cvt_pk_bf16_f32 v103, v104, v105
	v_cvt_pk_bf16_f32 v104, v182, v183
	v_cvt_pk_bf16_f32 v105, v106, v107
	v_pk_fma_f32 v[56:57], v[56:57], v[158:159], v[184:185]
	v_pk_fma_f32 v[54:55], v[54:55], v[160:161], v[244:245]
	v_pk_fma_f32 v[52:53], v[52:53], v[162:163], v[242:243]
	global_store_dwordx4 v[180:181], v[102:105], off offset:256
	v_mul_f32_e32 v67, v67, v67
	v_mul_f32_e32 v65, v65, v65
	v_cvt_pk_bf16_f32 v102, v56, v57
	v_cvt_pk_bf16_f32 v103, v58, v59
	v_cvt_pk_bf16_f32 v104, v52, v53
	v_cvt_pk_bf16_f32 v105, v54, v55
	v_lshlrev_b32_e32 v58, 16, v102
	v_and_b32_e32 v59, 0xffff0000, v102
	v_lshlrev_b32_e32 v56, 16, v103
	v_and_b32_e32 v57, 0xffff0000, v103
	v_lshlrev_b32_e32 v54, 16, v104
	v_and_b32_e32 v55, 0xffff0000, v104
	v_lshlrev_b32_e32 v52, 16, v105
	v_and_b32_e32 v53, 0xffff0000, v105
	global_store_dwordx4 v[202:203], v[102:105], off offset:2304
	v_pk_mul_f32 v[106:107], v[70:71], v[52:53]
	v_pk_mul_f32 v[180:181], v[68:69], v[54:55]
	v_pk_mul_f32 v[104:105], v[74:75], v[56:57]
	v_pk_mul_f32 v[102:103], v[72:73], v[58:59]
	v_fmac_f32_e32 v67, v66, v66
	v_cvt_pk_bf16_f32 v102, v102, v103
	v_cvt_pk_bf16_f32 v103, v104, v105
	v_cvt_pk_bf16_f32 v104, v180, v181
	v_cvt_pk_bf16_f32 v105, v106, v107
	global_store_dwordx4 v[220:221], v[102:105], off offset:256
	v_lshl_add_u64 v[106:107], v[164:165], 0, s[0:1]
	global_load_dwordx4 v[102:105], v[188:189], off offset:512
	global_load_dwordx4 v[180:183], v[106:107], off offset:16
	s_mov_b64 s[0:1], 0x30200
	v_lshl_add_u64 v[106:107], v[164:165], 0, s[0:1]
	global_load_dwordx4 v[184:187], v[190:191], off offset:512
	s_nop 0
	global_load_dwordx4 v[188:191], v[106:107], off offset:16
	s_mov_b64 s[0:1], 0x80200
	v_fmac_f32_e32 v65, v64, v64
	v_mul_f32_e32 v63, v63, v63
	v_mul_f32_e32 v61, v61, v61
	v_add_f32_e32 v64, v67, v65
	v_fmac_f32_e32 v63, v62, v62
	v_fmac_f32_e32 v61, v60, v60
	v_add_f32_e32 v60, v63, v61
	s_waitcnt vmcnt(0)
	v_pk_fma_f32 v[50:51], v[50:51], v[156:157], v[104:105]
	v_pk_fma_f32 v[48:49], v[48:49], v[158:159], v[102:103]
	v_pk_fma_f32 v[46:47], v[46:47], v[160:161], v[182:183]
	v_pk_fma_f32 v[44:45], v[44:45], v[162:163], v[180:181]
	v_cvt_pk_bf16_f32 v102, v48, v49
	v_cvt_pk_bf16_f32 v103, v50, v51
	v_cvt_pk_bf16_f32 v104, v44, v45
	v_cvt_pk_bf16_f32 v105, v46, v47
	v_lshlrev_b32_e32 v50, 16, v102
	v_and_b32_e32 v51, 0xffff0000, v102
	v_lshlrev_b32_e32 v48, 16, v103
	v_and_b32_e32 v49, 0xffff0000, v103
	v_lshlrev_b32_e32 v46, 16, v104
	v_and_b32_e32 v47, 0xffff0000, v104
	v_lshlrev_b32_e32 v44, 16, v105
	v_and_b32_e32 v45, 0xffff0000, v105
	global_store_dwordx4 v[192:193], v[102:105], off offset:2304
	v_pk_mul_f32 v[106:107], v[70:71], v[44:45]
	v_pk_mul_f32 v[180:181], v[68:69], v[46:47]
	v_pk_mul_f32 v[104:105], v[74:75], v[48:49]
	v_pk_mul_f32 v[102:103], v[72:73], v[50:51]
	v_pk_fma_f32 v[42:43], v[42:43], v[156:157], v[186:187]
	v_cvt_pk_bf16_f32 v102, v102, v103
	v_cvt_pk_bf16_f32 v103, v104, v105
	v_cvt_pk_bf16_f32 v104, v180, v181
	v_cvt_pk_bf16_f32 v105, v106, v107
	v_pk_fma_f32 v[40:41], v[40:41], v[158:159], v[184:185]
	v_pk_fma_f32 v[38:39], v[38:39], v[160:161], v[190:191]
	v_pk_fma_f32 v[36:37], v[36:37], v[162:163], v[188:189]
	global_store_dwordx4 v[194:195], v[102:105], off offset:256
	s_nop 1
	v_cvt_pk_bf16_f32 v102, v40, v41
	v_cvt_pk_bf16_f32 v103, v42, v43
	v_cvt_pk_bf16_f32 v104, v36, v37
	v_cvt_pk_bf16_f32 v105, v38, v39
	v_lshlrev_b32_e32 v42, 16, v102
	v_and_b32_e32 v43, 0xffff0000, v102
	v_lshlrev_b32_e32 v40, 16, v103
	v_and_b32_e32 v41, 0xffff0000, v103
	v_lshlrev_b32_e32 v38, 16, v104
	v_and_b32_e32 v39, 0xffff0000, v104
	v_lshlrev_b32_e32 v36, 16, v105
	v_and_b32_e32 v37, 0xffff0000, v105
	global_store_dwordx4 v[212:213], v[102:105], off offset:2304
	v_pk_mul_f32 v[106:107], v[70:71], v[36:37]
	v_pk_mul_f32 v[180:181], v[68:69], v[38:39]
	v_pk_mul_f32 v[104:105], v[74:75], v[40:41]
	v_pk_mul_f32 v[102:103], v[72:73], v[42:43]
	s_nop 0
	v_cvt_pk_bf16_f32 v102, v102, v103
	v_cvt_pk_bf16_f32 v103, v104, v105
	v_cvt_pk_bf16_f32 v104, v180, v181
	v_cvt_pk_bf16_f32 v105, v106, v107
	global_store_dwordx4 v[222:223], v[102:105], off offset:256
	v_lshl_add_u64 v[106:107], v[164:165], 0, s[0:1]
	global_load_dwordx4 v[102:105], v[196:197], off offset:512
	global_load_dwordx4 v[180:183], v[106:107], off offset:16
	s_mov_b64 s[0:1], 0x90200
	v_lshl_add_u64 v[106:107], v[164:165], 0, s[0:1]
	global_load_dwordx4 v[184:187], v[198:199], off offset:512
	global_load_dwordx4 v[188:191], v[106:107], off offset:16
	s_mov_b64 s[0:1], 0xa0200
	s_waitcnt vmcnt(0)
	v_pk_fma_f32 v[34:35], v[34:35], v[156:157], v[104:105]
	v_pk_fma_f32 v[32:33], v[32:33], v[158:159], v[102:103]
	v_pk_fma_f32 v[30:31], v[30:31], v[160:161], v[182:183]
	v_pk_fma_f32 v[28:29], v[28:29], v[162:163], v[180:181]
	v_cvt_pk_bf16_f32 v102, v32, v33
	v_cvt_pk_bf16_f32 v103, v34, v35
	v_cvt_pk_bf16_f32 v104, v28, v29
	v_cvt_pk_bf16_f32 v105, v30, v31
	v_lshlrev_b32_e32 v34, 16, v102
	v_and_b32_e32 v35, 0xffff0000, v102
	v_lshlrev_b32_e32 v32, 16, v103
	v_and_b32_e32 v33, 0xffff0000, v103
	v_lshlrev_b32_e32 v30, 16, v104
	v_and_b32_e32 v31, 0xffff0000, v104
	v_lshlrev_b32_e32 v28, 16, v105
	v_and_b32_e32 v29, 0xffff0000, v105
	global_store_dwordx4 v[200:201], v[102:105], off offset:2304
	v_pk_mul_f32 v[106:107], v[70:71], v[28:29]
	v_pk_mul_f32 v[180:181], v[68:69], v[30:31]
	v_pk_mul_f32 v[104:105], v[74:75], v[32:33]
	v_pk_mul_f32 v[102:103], v[72:73], v[34:35]
	v_pk_fma_f32 v[24:25], v[24:25], v[156:157], v[186:187]
	v_cvt_pk_bf16_f32 v102, v102, v103
	v_cvt_pk_bf16_f32 v103, v104, v105
	v_cvt_pk_bf16_f32 v104, v180, v181
	v_cvt_pk_bf16_f32 v105, v106, v107
	v_pk_fma_f32 v[22:23], v[22:23], v[158:159], v[184:185]
	v_pk_fma_f32 v[20:21], v[20:21], v[160:161], v[190:191]
	v_pk_fma_f32 v[18:19], v[18:19], v[162:163], v[188:189]
	global_store_dwordx4 v[204:205], v[102:105], off offset:256
	s_nop 1
	v_cvt_pk_bf16_f32 v102, v22, v23
	v_cvt_pk_bf16_f32 v103, v24, v25
	v_cvt_pk_bf16_f32 v104, v18, v19
	v_cvt_pk_bf16_f32 v105, v20, v21
	v_lshlrev_b32_e32 v24, 16, v102
	v_and_b32_e32 v25, 0xffff0000, v102
	v_lshlrev_b32_e32 v22, 16, v103
	v_and_b32_e32 v23, 0xffff0000, v103
	v_lshlrev_b32_e32 v20, 16, v104
	v_and_b32_e32 v21, 0xffff0000, v104
	v_lshlrev_b32_e32 v18, 16, v105
	v_and_b32_e32 v19, 0xffff0000, v105
	global_store_dwordx4 v[218:219], v[102:105], off offset:2304
	v_pk_mul_f32 v[106:107], v[70:71], v[18:19]
	v_pk_mul_f32 v[180:181], v[68:69], v[20:21]
	v_pk_mul_f32 v[104:105], v[74:75], v[22:23]
	v_pk_mul_f32 v[102:103], v[72:73], v[24:25]
	s_nop 0
	v_cvt_pk_bf16_f32 v102, v102, v103
	v_cvt_pk_bf16_f32 v103, v104, v105
	v_cvt_pk_bf16_f32 v104, v180, v181
	v_cvt_pk_bf16_f32 v105, v106, v107
	global_store_dwordx4 v[224:225], v[102:105], off offset:256
	v_lshl_add_u64 v[106:107], v[164:165], 0, s[0:1]
	global_load_dwordx4 v[102:105], v[206:207], off offset:512
	global_load_dwordx4 v[180:183], v[106:107], off offset:16
	s_mov_b64 s[0:1], 0xb0200
	v_lshl_add_u64 v[106:107], v[164:165], 0, s[0:1]
	global_load_dwordx4 v[184:187], v[208:209], off offset:512
	global_load_dwordx4 v[188:191], v[106:107], off offset:16
	s_waitcnt vmcnt(0)
	v_pk_fma_f32 v[16:17], v[16:17], v[156:157], v[104:105]
	v_pk_fma_f32 v[14:15], v[14:15], v[158:159], v[102:103]
	v_pk_fma_f32 v[102:103], v[12:13], v[160:161], v[182:183]
	v_pk_fma_f32 v[12:13], v[10:11], v[162:163], v[180:181]
	v_cvt_pk_bf16_f32 v10, v14, v15
	v_cvt_pk_bf16_f32 v11, v16, v17
	v_cvt_pk_bf16_f32 v12, v12, v13
	v_cvt_pk_bf16_f32 v13, v102, v103
	v_lshlrev_b32_e32 v102, 16, v10
	v_and_b32_e32 v103, 0xffff0000, v10
	v_lshlrev_b32_e32 v16, 16, v11
	v_and_b32_e32 v17, 0xffff0000, v11
	global_store_dwordx4 v[214:215], v[10:13], off offset:2304
	v_lshlrev_b32_e32 v14, 16, v12
	v_and_b32_e32 v15, 0xffff0000, v12
	v_lshlrev_b32_e32 v12, 16, v13
	v_and_b32_e32 v13, 0xffff0000, v13
	v_pk_mul_f32 v[10:11], v[74:75], v[16:17]
	v_pk_mul_f32 v[104:105], v[72:73], v[102:103]
	v_pk_mul_f32 v[164:165], v[70:71], v[12:13]
	v_pk_mul_f32 v[106:107], v[68:69], v[14:15]
	v_cvt_pk_bf16_f32 v104, v104, v105
	v_cvt_pk_bf16_f32 v105, v10, v11
	v_pk_fma_f32 v[8:9], v[8:9], v[156:157], v[186:187]
	v_pk_fma_f32 v[6:7], v[6:7], v[158:159], v[184:185]
	v_pk_fma_f32 v[10:11], v[4:5], v[160:161], v[190:191]
	v_pk_fma_f32 v[4:5], v[2:3], v[162:163], v[188:189]
	v_cvt_pk_bf16_f32 v106, v106, v107
	v_cvt_pk_bf16_f32 v107, v164, v165
	v_cvt_pk_bf16_f32 v2, v6, v7
	v_cvt_pk_bf16_f32 v3, v8, v9
	v_cvt_pk_bf16_f32 v4, v4, v5
	v_cvt_pk_bf16_f32 v5, v10, v11
	global_store_dwordx4 v[216:217], v[104:107], off offset:256
	global_store_dwordx4 v[210:211], v[2:5], off offset:2304
	v_lshlrev_b32_e32 v10, 16, v2
	v_and_b32_e32 v11, 0xffff0000, v2
	v_lshlrev_b32_e32 v8, 16, v3
	v_and_b32_e32 v9, 0xffff0000, v3
	v_lshlrev_b32_e32 v6, 16, v4
	v_and_b32_e32 v7, 0xffff0000, v4
	v_lshlrev_b32_e32 v4, 16, v5
	v_and_b32_e32 v5, 0xffff0000, v5
	v_pk_mul_f32 v[2:3], v[74:75], v[8:9]
	v_pk_mul_f32 v[72:73], v[72:73], v[10:11]
	v_pk_mul_f32 v[74:75], v[70:71], v[4:5]
	v_pk_mul_f32 v[70:71], v[68:69], v[6:7]
	v_cvt_pk_bf16_f32 v68, v72, v73
	v_cvt_pk_bf16_f32 v69, v2, v3
	v_cvt_pk_bf16_f32 v70, v70, v71
	v_cvt_pk_bf16_f32 v71, v74, v75
	global_store_dwordx4 v[100:101], v[68:71], off offset:256
	v_mul_f32_e32 v72, v133, v133
	v_fmac_f32_e32 v72, v132, v132
	v_and_b32_e32 v69, 64, v227
	v_xor_b32_e32 v68, 16, v227
	v_add_u32_e32 v69, 64, v69
	v_cmp_lt_i32_e32 vcc, v68, v69
	v_xor_b32_e32 v70, 32, v227
	v_mul_f32_e32 v71, v137, v137
	v_cndmask_b32_e32 v68, v227, v68, vcc
	v_cmp_lt_i32_e32 vcc, v70, v69
	v_fmac_f32_e32 v71, v136, v136
	v_lshlrev_b32_e32 v68, 2, v68
	v_cndmask_b32_e32 v69, v227, v70, vcc
	v_mul_f32_e32 v70, v139, v139
	v_fmac_f32_e32 v70, v138, v138
	v_add_f32_e32 v70, v70, v71
	v_mul_f32_e32 v71, v135, v135
	v_fmac_f32_e32 v71, v134, v134
	v_add_f32_e32 v71, v71, v72
	v_add_f32_e32 v70, v70, v71
	v_add_f32_e32 v64, v70, v64
	v_add_f32_e32 v60, v64, v60
	ds_bpermute_b32 v61, v68, v60
	v_lshlrev_b32_e32 v69, 2, v69
	v_lshl_add_u64 v[2:3], v[150:151], 0, s[52:53]
	s_waitcnt lgkmcnt(0)
	v_add_f32_e32 v60, v60, v61
	ds_bpermute_b32 v61, v69, v60
	s_and_saveexec_b64 s[18:19], s[38:39]
	s_cbranch_execz .LBB0_398
	s_waitcnt lgkmcnt(0)
	v_add_f32_e32 v60, v60, v61
	global_atomic_add_f32 v[2:3], v60, off

.LBB0_479:
	s_add_u32 s0, s22, 0xfffc0080
	s_addc_u32 s1, s23, -1
	s_add_i32 s69, 0, 0x10000
	s_cmp_eq_u32 s68, 12
	s_cselect_b32 s27, s35, s1
	s_cselect_b32 s26, s40, s0
	s_cselect_b32 s25, s41, s59
	s_cselect_b32 s24, s49, s51
	s_add_i32 m0, s37, 0xc000
	ds_read_b128 v[158:161], v165
	ds_read_b128 v[172:175], v165 offset:1024
	ds_read_b128 v[176:179], v165 offset:2048
	ds_read_b128 v[180:183], v165 offset:3072
	ds_read_b128 v[184:187], v165 offset:4096
	ds_read_b128 v[188:191], v165 offset:5120
	ds_read_b128 v[192:195], v165 offset:6144
	ds_read_b128 v[196:199], v165 offset:7168
	global_load_lds_dwordx4 v146, s[22:23]
	v_lshl_add_u64 v[166:167], s[22:23], 0, v[148:149]
	s_add_i32 m0, s37, 0xe000
	s_nop 0
	global_load_lds_dwordx4 v[166:167], off
	s_waitcnt vmcnt(10) lgkmcnt(8)
	s_setprio 1
	s_barrier
	s_waitcnt lgkmcnt(0)
	v_mfma_f32_16x16x32_bf16 v[136:139], v[100:103], v[158:161], v[136:139]
	v_mfma_f32_16x16x32_bf16 v[132:135], v[150:153], v[158:161], v[132:135]
	v_mfma_f32_16x16x32_bf16 v[128:131], v[100:103], v[176:179], v[128:131]
	v_mfma_f32_16x16x32_bf16 v[124:127], v[150:153], v[176:179], v[124:127]
	v_mfma_f32_16x16x32_bf16 v[120:123], v[100:103], v[184:187], v[120:123]
	v_mfma_f32_16x16x32_bf16 v[116:119], v[150:153], v[184:187], v[116:119]
	v_mfma_f32_16x16x32_bf16 v[112:115], v[100:103], v[192:195], v[112:115]
	v_mfma_f32_16x16x32_bf16 v[108:111], v[150:153], v[192:195], v[108:111]
	v_mfma_f32_16x16x32_bf16 v[136:139], v[104:107], v[172:175], v[136:139]
	v_mfma_f32_16x16x32_bf16 v[132:135], v[154:157], v[172:175], v[132:135]
	v_mfma_f32_16x16x32_bf16 v[128:131], v[104:107], v[180:183], v[128:131]
	v_mfma_f32_16x16x32_bf16 v[124:127], v[154:157], v[180:183], v[124:127]
	v_mfma_f32_16x16x32_bf16 v[120:123], v[104:107], v[188:191], v[120:123]
	v_mfma_f32_16x16x32_bf16 v[116:119], v[154:157], v[188:191], v[116:119]
	v_mfma_f32_16x16x32_bf16 v[112:115], v[104:107], v[196:199], v[112:115]
	v_mfma_f32_16x16x32_bf16 v[108:111], v[154:157], v[196:199], v[108:111]
	s_barrier
	s_setprio 0
	s_add_i32 s72, 0, 0x14000
	v_add_u32_e32 v166, s72, v163
	s_add_i32 s0, s69, s36
	ds_read_b128 v[200:203], v166
	ds_read_b128 v[204:207], v166 offset:1024
	ds_read_b128 v[208:211], v166 offset:2048
	ds_read_b128 v[212:215], v166 offset:3072
	v_lshl_add_u64 v[166:167], s[24:25], 0, v[26:27]
	s_mov_b32 m0, s0
	v_lshl_add_u64 v[168:169], s[24:25], 0, v[140:141]
	global_load_lds_dwordx4 v[166:167], off
	s_add_i32 m0, s0, 0x2000
	s_nop 0
	global_load_lds_dwordx4 v[168:169], off
	s_waitcnt vmcnt(10)
	s_setprio 1
	s_barrier
	s_waitcnt lgkmcnt(0)
	v_mfma_f32_16x16x32_bf16 v[64:67], v[200:203], v[158:161], v[64:67]
	v_mfma_f32_16x16x32_bf16 v[60:63], v[208:211], v[158:161], v[60:63]
	v_mfma_f32_16x16x32_bf16 v[56:59], v[200:203], v[176:179], v[56:59]
	v_mfma_f32_16x16x32_bf16 v[52:55], v[208:211], v[176:179], v[52:55]
	v_mfma_f32_16x16x32_bf16 v[48:51], v[200:203], v[184:187], v[48:51]
	v_mfma_f32_16x16x32_bf16 v[44:47], v[208:211], v[184:187], v[44:47]
	v_mfma_f32_16x16x32_bf16 v[40:43], v[200:203], v[192:195], v[40:43]
	v_mfma_f32_16x16x32_bf16 v[36:39], v[208:211], v[192:195], v[36:39]
	v_mfma_f32_16x16x32_bf16 v[64:67], v[204:207], v[172:175], v[64:67]
	v_mfma_f32_16x16x32_bf16 v[60:63], v[212:215], v[172:175], v[60:63]
	v_mfma_f32_16x16x32_bf16 v[56:59], v[204:207], v[180:183], v[56:59]
	v_mfma_f32_16x16x32_bf16 v[52:55], v[212:215], v[180:183], v[52:55]
	v_mfma_f32_16x16x32_bf16 v[48:51], v[204:207], v[188:191], v[48:51]
	v_mfma_f32_16x16x32_bf16 v[44:47], v[212:215], v[188:191], v[44:47]
	v_mfma_f32_16x16x32_bf16 v[40:43], v[204:207], v[196:199], v[40:43]
	v_mfma_f32_16x16x32_bf16 v[36:39], v[212:215], v[196:199], v[36:39]
	s_barrier
	s_setprio 0
	s_mov_b32 m0, s37
	v_lshl_add_u64 v[216:217], s[26:27], 0, v[144:145]
	ds_read_b128 v[158:161], v165 offset:16384
	ds_read_b128 v[172:175], v165 offset:17408
	ds_read_b128 v[176:179], v165 offset:18432
	ds_read_b128 v[180:183], v165 offset:19456
	ds_read_b128 v[184:187], v165 offset:20480
	ds_read_b128 v[188:191], v165 offset:21504
	ds_read_b128 v[192:195], v165 offset:22528
	ds_read_b128 v[196:199], v165 offset:23552
	global_load_lds_dwordx4 v[216:217], off
	v_lshl_add_u64 v[218:219], s[26:27], 0, v[142:143]
	s_mov_b32 m0, s56
	s_nop 0
	global_load_lds_dwordx4 v[218:219], off
	s_waitcnt vmcnt(10)
	s_setprio 1
	s_barrier
	s_waitcnt lgkmcnt(0)
	v_mfma_f32_16x16x32_bf16 v[96:99], v[100:103], v[158:161], v[96:99]
	v_mfma_f32_16x16x32_bf16 v[92:95], v[150:153], v[158:161], v[92:95]
	v_mfma_f32_16x16x32_bf16 v[88:91], v[100:103], v[176:179], v[88:91]
	v_mfma_f32_16x16x32_bf16 v[84:87], v[150:153], v[176:179], v[84:87]
	v_mfma_f32_16x16x32_bf16 v[80:83], v[100:103], v[184:187], v[80:83]
	v_mfma_f32_16x16x32_bf16 v[76:79], v[150:153], v[184:187], v[76:79]
	v_mfma_f32_16x16x32_bf16 v[72:75], v[100:103], v[192:195], v[72:75]
	v_mfma_f32_16x16x32_bf16 v[68:71], v[150:153], v[192:195], v[68:71]
	v_mfma_f32_16x16x32_bf16 v[96:99], v[104:107], v[172:175], v[96:99]
	v_mfma_f32_16x16x32_bf16 v[92:95], v[154:157], v[172:175], v[92:95]
	v_mfma_f32_16x16x32_bf16 v[88:91], v[104:107], v[180:183], v[88:91]
	v_mfma_f32_16x16x32_bf16 v[84:87], v[154:157], v[180:183], v[84:87]
	v_mfma_f32_16x16x32_bf16 v[80:83], v[104:107], v[188:191], v[80:83]
	v_mfma_f32_16x16x32_bf16 v[76:79], v[154:157], v[188:191], v[76:79]
	v_mfma_f32_16x16x32_bf16 v[72:75], v[104:107], v[196:199], v[72:75]
	v_mfma_f32_16x16x32_bf16 v[68:71], v[154:157], v[196:199], v[68:71]
	s_barrier
	s_setprio 0
	s_add_u32 s0, s24, 0x40000
	s_addc_u32 s1, s25, 0
	s_add_i32 s69, s72, s36
	s_mov_b32 m0, s69
	s_nop 0
	global_load_lds_dwordx4 v26, s[0:1]
	s_add_i32 m0, s69, 0x2000
	s_nop 0
	global_load_lds_dwordx4 v140, s[0:1]
	v_add_u32_e32 v154, 0x18000, v163
	ds_read_b128 v[100:103], v154
	ds_read_b128 v[104:107], v154 offset:1024
	ds_read_b128 v[150:153], v154 offset:2048
	ds_read_b128 v[154:157], v154 offset:3072
	s_waitcnt vmcnt(10)
	s_setprio 1
	s_barrier
	v_mfma_f32_16x16x32_bf16 v[32:35], v[200:203], v[158:161], v[32:35]
	v_mfma_f32_16x16x32_bf16 v[28:31], v[208:211], v[158:161], v[28:31]
	v_mfma_f32_16x16x32_bf16 v[22:25], v[200:203], v[176:179], v[22:25]
	v_mfma_f32_16x16x32_bf16 v[18:21], v[208:211], v[176:179], v[18:21]
	v_mfma_f32_16x16x32_bf16 v[14:17], v[200:203], v[184:187], v[14:17]
	v_mfma_f32_16x16x32_bf16 v[10:13], v[208:211], v[184:187], v[10:13]
	v_mfma_f32_16x16x32_bf16 v[6:9], v[200:203], v[192:195], v[6:9]
	v_mfma_f32_16x16x32_bf16 v[2:5], v[208:211], v[192:195], v[2:5]
	v_mfma_f32_16x16x32_bf16 v[32:35], v[204:207], v[172:175], v[32:35]
	v_mfma_f32_16x16x32_bf16 v[28:31], v[212:215], v[172:175], v[28:31]
	v_mfma_f32_16x16x32_bf16 v[22:25], v[204:207], v[180:183], v[22:25]
	v_mfma_f32_16x16x32_bf16 v[18:21], v[212:215], v[180:183], v[18:21]
	v_mfma_f32_16x16x32_bf16 v[14:17], v[204:207], v[188:191], v[14:17]
	v_mfma_f32_16x16x32_bf16 v[10:13], v[212:215], v[188:191], v[10:13]
	v_mfma_f32_16x16x32_bf16 v[6:9], v[204:207], v[196:199], v[6:9]
	v_mfma_f32_16x16x32_bf16 v[2:5], v[212:215], v[196:199], v[2:5]
	s_barrier
	s_setprio 0
	s_add_i32 s69, 0, 0x18000
	s_add_u32 s0, s26, 0x40000
	s_addc_u32 s1, s27, 0
	s_mov_b32 m0, s57
	ds_read_b128 v[158:161], v165 offset:32768
	ds_read_b128 v[172:175], v165 offset:33792
	ds_read_b128 v[176:179], v165 offset:34816
	ds_read_b128 v[180:183], v165 offset:35840
	ds_read_b128 v[184:187], v165 offset:36864
	ds_read_b128 v[188:191], v165 offset:37888
	ds_read_b128 v[192:195], v165 offset:38912
	ds_read_b128 v[196:199], v165 offset:39936
	global_load_lds_dwordx4 v144, s[0:1]
	s_mov_b32 m0, s58
	s_nop 0
	global_load_lds_dwordx4 v142, s[0:1]
	s_waitcnt vmcnt(10) lgkmcnt(8)
	s_setprio 1
	s_barrier
	s_waitcnt lgkmcnt(0)
	v_mfma_f32_16x16x32_bf16 v[136:139], v[100:103], v[158:161], v[136:139]
	v_mfma_f32_16x16x32_bf16 v[132:135], v[150:153], v[158:161], v[132:135]
	v_mfma_f32_16x16x32_bf16 v[128:131], v[100:103], v[176:179], v[128:131]
	v_mfma_f32_16x16x32_bf16 v[124:127], v[150:153], v[176:179], v[124:127]
	v_mfma_f32_16x16x32_bf16 v[120:123], v[100:103], v[184:187], v[120:123]
	v_mfma_f32_16x16x32_bf16 v[116:119], v[150:153], v[184:187], v[116:119]
	v_mfma_f32_16x16x32_bf16 v[112:115], v[100:103], v[192:195], v[112:115]
	v_mfma_f32_16x16x32_bf16 v[108:111], v[150:153], v[192:195], v[108:111]
	v_mfma_f32_16x16x32_bf16 v[136:139], v[104:107], v[172:175], v[136:139]
	v_mfma_f32_16x16x32_bf16 v[132:135], v[154:157], v[172:175], v[132:135]
	v_mfma_f32_16x16x32_bf16 v[128:131], v[104:107], v[180:183], v[128:131]
	v_mfma_f32_16x16x32_bf16 v[124:127], v[154:157], v[180:183], v[124:127]
	v_mfma_f32_16x16x32_bf16 v[120:123], v[104:107], v[188:191], v[120:123]
	v_mfma_f32_16x16x32_bf16 v[116:119], v[154:157], v[188:191], v[116:119]
	v_mfma_f32_16x16x32_bf16 v[112:115], v[104:107], v[196:199], v[112:115]
	v_mfma_f32_16x16x32_bf16 v[108:111], v[154:157], v[196:199], v[108:111]
	s_barrier
	s_setprio 0
	s_add_i32 s26, 0, 0x1c000
	s_add_i32 s0, s69, s36
	v_add_u32_e32 v212, s26, v163
	v_lshl_add_u64 v[166:167], v[166:167], 0, s[12:13]
	s_mov_b32 m0, s0
	ds_read_b128 v[200:203], v212
	ds_read_b128 v[204:207], v212 offset:1024
	ds_read_b128 v[208:211], v212 offset:2048
	ds_read_b128 v[212:215], v212 offset:3072
	global_load_lds_dwordx4 v[166:167], off
	v_lshl_add_u64 v[166:167], v[168:169], 0, s[12:13]
	s_add_i32 m0, s0, 0x2000
	s_nop 0
	global_load_lds_dwordx4 v[166:167], off
	s_waitcnt vmcnt(10)
	s_setprio 1
	s_barrier
	s_waitcnt lgkmcnt(0)
	v_mfma_f32_16x16x32_bf16 v[64:67], v[200:203], v[158:161], v[64:67]
	v_mfma_f32_16x16x32_bf16 v[60:63], v[208:211], v[158:161], v[60:63]
	v_mfma_f32_16x16x32_bf16 v[56:59], v[200:203], v[176:179], v[56:59]
	v_mfma_f32_16x16x32_bf16 v[52:55], v[208:211], v[176:179], v[52:55]
	v_mfma_f32_16x16x32_bf16 v[48:51], v[200:203], v[184:187], v[48:51]
	v_mfma_f32_16x16x32_bf16 v[44:47], v[208:211], v[184:187], v[44:47]
	v_mfma_f32_16x16x32_bf16 v[40:43], v[200:203], v[192:195], v[40:43]
	v_mfma_f32_16x16x32_bf16 v[36:39], v[208:211], v[192:195], v[36:39]
	v_mfma_f32_16x16x32_bf16 v[64:67], v[204:207], v[172:175], v[64:67]
	v_mfma_f32_16x16x32_bf16 v[60:63], v[212:215], v[172:175], v[60:63]
	v_mfma_f32_16x16x32_bf16 v[56:59], v[204:207], v[180:183], v[56:59]
	v_mfma_f32_16x16x32_bf16 v[52:55], v[212:215], v[180:183], v[52:55]
	v_mfma_f32_16x16x32_bf16 v[48:51], v[204:207], v[188:191], v[48:51]
	v_mfma_f32_16x16x32_bf16 v[44:47], v[212:215], v[188:191], v[44:47]
	v_mfma_f32_16x16x32_bf16 v[40:43], v[204:207], v[196:199], v[40:43]
	v_mfma_f32_16x16x32_bf16 v[36:39], v[212:215], v[196:199], v[36:39]
	s_barrier
	s_setprio 0
	s_mov_b32 m0, s28
	v_lshl_add_u64 v[166:167], v[216:217], 0, s[12:13]
	ds_read_b128 v[158:161], v165 offset:49152
	ds_read_b128 v[172:175], v165 offset:50176
	ds_read_b128 v[176:179], v165 offset:51200
	ds_read_b128 v[180:183], v165 offset:52224
	ds_read_b128 v[184:187], v165 offset:53248
	ds_read_b128 v[188:191], v165 offset:54272
	ds_read_b128 v[192:195], v165 offset:55296
	ds_read_b128 v[196:199], v165 offset:56320
	global_load_lds_dwordx4 v[166:167], off
	v_lshl_add_u64 v[166:167], v[218:219], 0, s[12:13]
	s_mov_b32 m0, s29
	s_nop 0
	global_load_lds_dwordx4 v[166:167], off
	s_waitcnt vmcnt(10)
	s_setprio 1
	s_barrier
	s_waitcnt lgkmcnt(0)
	v_mfma_f32_16x16x32_bf16 v[96:99], v[100:103], v[158:161], v[96:99]
	v_mfma_f32_16x16x32_bf16 v[92:95], v[150:153], v[158:161], v[92:95]
	v_mfma_f32_16x16x32_bf16 v[88:91], v[100:103], v[176:179], v[88:91]
	v_mfma_f32_16x16x32_bf16 v[84:87], v[150:153], v[176:179], v[84:87]
	v_mfma_f32_16x16x32_bf16 v[80:83], v[100:103], v[184:187], v[80:83]
	v_mfma_f32_16x16x32_bf16 v[76:79], v[150:153], v[184:187], v[76:79]
	v_mfma_f32_16x16x32_bf16 v[72:75], v[100:103], v[192:195], v[72:75]
	v_mfma_f32_16x16x32_bf16 v[68:71], v[150:153], v[192:195], v[68:71]
	v_mfma_f32_16x16x32_bf16 v[96:99], v[104:107], v[172:175], v[96:99]
	v_mfma_f32_16x16x32_bf16 v[92:95], v[154:157], v[172:175], v[92:95]
	v_mfma_f32_16x16x32_bf16 v[88:91], v[104:107], v[180:183], v[88:91]
	v_mfma_f32_16x16x32_bf16 v[84:87], v[154:157], v[180:183], v[84:87]
	v_mfma_f32_16x16x32_bf16 v[80:83], v[104:107], v[188:191], v[80:83]
	v_mfma_f32_16x16x32_bf16 v[76:79], v[154:157], v[188:191], v[76:79]
	v_mfma_f32_16x16x32_bf16 v[72:75], v[104:107], v[196:199], v[72:75]
	v_mfma_f32_16x16x32_bf16 v[68:71], v[154:157], v[196:199], v[68:71]
	s_barrier
	s_setprio 0
	s_add_u32 s0, s24, 0x40080
	s_addc_u32 s1, s25, 0
	s_add_i32 s24, s26, s36
	s_mov_b32 m0, s24
	s_nop 0
	global_load_lds_dwordx4 v26, s[0:1]
	s_add_i32 m0, s24, 0x2000
	s_nop 0
	global_load_lds_dwordx4 v140, s[0:1]
	v_add_u32_e32 v154, 0x10000, v163
	ds_read_b128 v[100:103], v154
	ds_read_b128 v[104:107], v154 offset:1024
	ds_read_b128 v[150:153], v154 offset:2048
	ds_read_b128 v[154:157], v154 offset:3072
	s_add_i32 s68, s68, 2
	s_add_u32 s22, s22, 0x100
	s_addc_u32 s23, s23, 0
	s_add_u32 s51, s51, 0x100
	s_addc_u32 s59, s59, 0
	s_cmp_gt_u32 s68, 13
	s_waitcnt vmcnt(10)
	s_setprio 1
	s_barrier
	v_mfma_f32_16x16x32_bf16 v[32:35], v[200:203], v[158:161], v[32:35]
	v_mfma_f32_16x16x32_bf16 v[28:31], v[208:211], v[158:161], v[28:31]
	v_mfma_f32_16x16x32_bf16 v[22:25], v[200:203], v[176:179], v[22:25]
	v_mfma_f32_16x16x32_bf16 v[18:21], v[208:211], v[176:179], v[18:21]
	v_mfma_f32_16x16x32_bf16 v[14:17], v[200:203], v[184:187], v[14:17]
	v_mfma_f32_16x16x32_bf16 v[10:13], v[208:211], v[184:187], v[10:13]
	v_mfma_f32_16x16x32_bf16 v[6:9], v[200:203], v[192:195], v[6:9]
	v_mfma_f32_16x16x32_bf16 v[2:5], v[208:211], v[192:195], v[2:5]
	v_mfma_f32_16x16x32_bf16 v[32:35], v[204:207], v[172:175], v[32:35]
	v_mfma_f32_16x16x32_bf16 v[28:31], v[212:215], v[172:175], v[28:31]
	v_mfma_f32_16x16x32_bf16 v[22:25], v[204:207], v[180:183], v[22:25]
	v_mfma_f32_16x16x32_bf16 v[18:21], v[212:215], v[180:183], v[18:21]
	v_mfma_f32_16x16x32_bf16 v[14:17], v[204:207], v[188:191], v[14:17]
	v_mfma_f32_16x16x32_bf16 v[10:13], v[212:215], v[188:191], v[10:13]
	v_mfma_f32_16x16x32_bf16 v[6:9], v[204:207], v[196:199], v[6:9]
	v_mfma_f32_16x16x32_bf16 v[2:5], v[212:215], v[196:199], v[2:5]
	s_barrier
	s_setprio 0
	s_cbranch_scc0 .LBB0_479
	s_waitcnt lgkmcnt(0)
	s_cmpk_gt_i32 s34, 0xff
	s_mov_b64 s[22:23], 0xb000
	s_cbranch_scc1 .LBB0_482
	s_ashr_i32 s0, s34, 5
	s_mul_hi_i32 s23, s0, 0x1600
	s_mul_i32 s22, s0, 0x1600

.LBB0_887:
	s_add_u32 s24, s22, 0x100
	s_addc_u32 s25, s23, 0
	s_add_i32 s0, 0, 0x10000
	s_cmp_eq_u32 s51, 4
	s_cselect_b32 s29, s47, s25
	s_cselect_b32 s28, s46, s24
	s_cselect_b32 s27, s18, s50
	s_cselect_b32 s26, s19, s45
	s_add_i32 m0, s58, 0xc000
	ds_read_b128 v[150:153], v193
	ds_read_b128 v[154:157], v193 offset:1024
	ds_read_b128 v[158:161], v193 offset:2048
	ds_read_b128 v[162:165], v193 offset:3072
	ds_read_b128 v[184:187], v193 offset:4096
	ds_read_b128 v[194:197], v193 offset:5120
	ds_read_b128 v[198:201], v193 offset:6144
	ds_read_b128 v[202:205], v193 offset:7168
	global_load_lds_dwordx4 v180, s[22:23]
	s_add_i32 m0, s58, 0xe000
	s_nop 0
	global_load_lds_dwordx4 v182, s[22:23]
	s_waitcnt vmcnt(10) lgkmcnt(8)
	s_setprio 1
	s_barrier
	s_waitcnt lgkmcnt(0)
	v_mfma_f32_16x16x32_bf16 v[130:133], v[134:137], v[150:153], v[130:133]
	v_mfma_f32_16x16x32_bf16 v[126:129], v[142:145], v[150:153], v[126:129]
	v_mfma_f32_16x16x32_bf16 v[122:125], v[134:137], v[158:161], v[122:125]
	v_mfma_f32_16x16x32_bf16 v[118:121], v[142:145], v[158:161], v[118:121]
	v_mfma_f32_16x16x32_bf16 v[114:117], v[134:137], v[184:187], v[114:117]
	v_mfma_f32_16x16x32_bf16 v[110:113], v[142:145], v[184:187], v[110:113]
	v_mfma_f32_16x16x32_bf16 v[106:109], v[134:137], v[198:201], v[106:109]
	v_mfma_f32_16x16x32_bf16 v[102:105], v[142:145], v[198:201], v[102:105]
	v_mfma_f32_16x16x32_bf16 v[130:133], v[138:141], v[154:157], v[130:133]
	v_mfma_f32_16x16x32_bf16 v[126:129], v[146:149], v[154:157], v[126:129]
	v_mfma_f32_16x16x32_bf16 v[122:125], v[138:141], v[162:165], v[122:125]
	v_mfma_f32_16x16x32_bf16 v[118:121], v[146:149], v[162:165], v[118:121]
	v_mfma_f32_16x16x32_bf16 v[114:117], v[138:141], v[194:197], v[114:117]
	v_mfma_f32_16x16x32_bf16 v[110:113], v[146:149], v[194:197], v[110:113]
	v_mfma_f32_16x16x32_bf16 v[106:109], v[138:141], v[202:205], v[106:109]
	v_mfma_f32_16x16x32_bf16 v[102:105], v[146:149], v[202:205], v[102:105]
	s_barrier
	s_setprio 0
	s_add_i32 s22, 0, 0x14000
	s_add_i32 s0, s0, s55
	v_add_u32_e32 v26, s22, v191
	v_lshl_add_u64 v[166:167], s[26:27], 0, v[176:177]
	s_mov_b32 m0, s0
	ds_read_b128 v[206:209], v26
	ds_read_b128 v[210:213], v26 offset:1024
	ds_read_b128 v[214:217], v26 offset:2048
	ds_read_b128 v[218:221], v26 offset:3072
	global_load_lds_dwordx4 v[166:167], off
	v_lshl_add_u64 v[168:169], s[26:27], 0, v[172:173]
	s_add_i32 m0, s0, 0x2000
	s_nop 0
	global_load_lds_dwordx4 v[168:169], off
	s_waitcnt vmcnt(10)
	s_setprio 1
	s_barrier
	s_waitcnt lgkmcnt(0)
	v_mfma_f32_16x16x32_bf16 v[98:101], v[206:209], v[150:153], v[98:101]
	v_mfma_f32_16x16x32_bf16 v[94:97], v[214:217], v[150:153], v[94:97]
	v_mfma_f32_16x16x32_bf16 v[90:93], v[206:209], v[158:161], v[90:93]
	v_mfma_f32_16x16x32_bf16 v[86:89], v[214:217], v[158:161], v[86:89]
	v_mfma_f32_16x16x32_bf16 v[82:85], v[206:209], v[184:187], v[82:85]
	v_mfma_f32_16x16x32_bf16 v[78:81], v[214:217], v[184:187], v[78:81]
	v_mfma_f32_16x16x32_bf16 v[74:77], v[206:209], v[198:201], v[74:77]
	v_mfma_f32_16x16x32_bf16 v[70:73], v[214:217], v[198:201], v[70:73]
	v_mfma_f32_16x16x32_bf16 v[98:101], v[210:213], v[154:157], v[98:101]
	v_mfma_f32_16x16x32_bf16 v[94:97], v[218:221], v[154:157], v[94:97]
	v_mfma_f32_16x16x32_bf16 v[90:93], v[210:213], v[162:165], v[90:93]
	v_mfma_f32_16x16x32_bf16 v[86:89], v[218:221], v[162:165], v[86:89]
	v_mfma_f32_16x16x32_bf16 v[82:85], v[210:213], v[194:197], v[82:85]
	v_mfma_f32_16x16x32_bf16 v[78:81], v[218:221], v[194:197], v[78:81]
	v_mfma_f32_16x16x32_bf16 v[74:77], v[210:213], v[202:205], v[74:77]
	v_mfma_f32_16x16x32_bf16 v[70:73], v[218:221], v[202:205], v[70:73]
	s_barrier
	s_setprio 0
	s_mov_b32 m0, s58
	v_lshl_add_u64 v[188:189], s[28:29], 0, v[178:179]
	ds_read_b128 v[150:153], v193 offset:16384
	ds_read_b128 v[154:157], v193 offset:17408
	ds_read_b128 v[158:161], v193 offset:18432
	ds_read_b128 v[162:165], v193 offset:19456
	ds_read_b128 v[184:187], v193 offset:20480
	ds_read_b128 v[194:197], v193 offset:21504
	ds_read_b128 v[198:201], v193 offset:22528
	ds_read_b128 v[202:205], v193 offset:23552
	global_load_lds_dwordx4 v[188:189], off
	v_lshl_add_u64 v[222:223], s[28:29], 0, v[174:175]
	s_mov_b32 m0, s59
	s_nop 0
	global_load_lds_dwordx4 v[222:223], off
	s_waitcnt vmcnt(10)
	s_setprio 1
	s_barrier
	s_waitcnt lgkmcnt(0)
	v_mfma_f32_16x16x32_bf16 v[66:69], v[134:137], v[150:153], v[66:69]
	v_mfma_f32_16x16x32_bf16 v[62:65], v[142:145], v[150:153], v[62:65]
	v_mfma_f32_16x16x32_bf16 v[58:61], v[134:137], v[158:161], v[58:61]
	v_mfma_f32_16x16x32_bf16 v[54:57], v[142:145], v[158:161], v[54:57]
	v_mfma_f32_16x16x32_bf16 v[50:53], v[134:137], v[184:187], v[50:53]
	v_mfma_f32_16x16x32_bf16 v[46:49], v[142:145], v[184:187], v[46:49]
	v_mfma_f32_16x16x32_bf16 v[42:45], v[134:137], v[198:201], v[42:45]
	v_mfma_f32_16x16x32_bf16 v[38:41], v[142:145], v[198:201], v[38:41]
	v_mfma_f32_16x16x32_bf16 v[66:69], v[138:141], v[154:157], v[66:69]
	v_mfma_f32_16x16x32_bf16 v[62:65], v[146:149], v[154:157], v[62:65]
	v_mfma_f32_16x16x32_bf16 v[58:61], v[138:141], v[162:165], v[58:61]
	v_mfma_f32_16x16x32_bf16 v[54:57], v[146:149], v[162:165], v[54:57]
	v_mfma_f32_16x16x32_bf16 v[50:53], v[138:141], v[194:197], v[50:53]
	v_mfma_f32_16x16x32_bf16 v[46:49], v[146:149], v[194:197], v[46:49]
	v_mfma_f32_16x16x32_bf16 v[42:45], v[138:141], v[202:205], v[42:45]
	v_mfma_f32_16x16x32_bf16 v[38:41], v[146:149], v[202:205], v[38:41]
	s_barrier
	s_setprio 0
	s_add_u32 s0, s26, 0x20000
	s_addc_u32 s1, s27, 0
	s_add_i32 s22, s22, s55
	s_mov_b32 m0, s22
	s_nop 0
	global_load_lds_dwordx4 v176, s[0:1]
	s_add_i32 m0, s22, 0x2000
	s_nop 0
	global_load_lds_dwordx4 v172, s[0:1]
	v_add_u32_e32 v26, 0x18000, v191
	ds_read_b128 v[134:137], v26
	ds_read_b128 v[138:141], v26 offset:1024
	ds_read_b128 v[142:145], v26 offset:2048
	ds_read_b128 v[146:149], v26 offset:3072
	s_waitcnt vmcnt(10)
	s_setprio 1
	s_barrier
	v_mfma_f32_16x16x32_bf16 v[34:37], v[206:209], v[150:153], v[34:37]
	v_mfma_f32_16x16x32_bf16 v[28:31], v[214:217], v[150:153], v[30:33]
	v_mfma_f32_16x16x32_bf16 v[22:25], v[206:209], v[158:161], v[22:25]
	v_mfma_f32_16x16x32_bf16 v[18:21], v[214:217], v[158:161], v[18:21]
	v_mfma_f32_16x16x32_bf16 v[14:17], v[206:209], v[184:187], v[14:17]
	v_mfma_f32_16x16x32_bf16 v[10:13], v[214:217], v[184:187], v[10:13]
	v_mfma_f32_16x16x32_bf16 v[6:9], v[206:209], v[198:201], v[6:9]
	v_mfma_f32_16x16x32_bf16 v[2:5], v[214:217], v[198:201], v[2:5]
	v_mfma_f32_16x16x32_bf16 v[34:37], v[210:213], v[154:157], v[34:37]
	v_mfma_f32_16x16x32_bf16 v[28:31], v[218:221], v[154:157], v[28:31]
	v_mfma_f32_16x16x32_bf16 v[22:25], v[210:213], v[162:165], v[22:25]
	v_mfma_f32_16x16x32_bf16 v[18:21], v[218:221], v[162:165], v[18:21]
	v_mfma_f32_16x16x32_bf16 v[14:17], v[210:213], v[194:197], v[14:17]
	v_mfma_f32_16x16x32_bf16 v[10:13], v[218:221], v[194:197], v[10:13]
	v_mfma_f32_16x16x32_bf16 v[6:9], v[210:213], v[202:205], v[6:9]
	v_mfma_f32_16x16x32_bf16 v[2:5], v[218:221], v[202:205], v[2:5]
	s_barrier
	s_setprio 0
	s_add_i32 s22, 0, 0x18000
	s_add_u32 s0, s28, 0x140000
	s_addc_u32 s1, s29, 0
	s_mov_b32 m0, s68
	ds_read_b128 v[150:153], v193 offset:32768
	ds_read_b128 v[154:157], v193 offset:33792
	ds_read_b128 v[158:161], v193 offset:34816
	ds_read_b128 v[162:165], v193 offset:35840
	ds_read_b128 v[184:187], v193 offset:36864
	ds_read_b128 v[194:197], v193 offset:37888
	ds_read_b128 v[198:201], v193 offset:38912
	ds_read_b128 v[202:205], v193 offset:39936
	global_load_lds_dwordx4 v178, s[0:1]
	s_mov_b32 m0, s69
	s_nop 0
	global_load_lds_dwordx4 v174, s[0:1]
	s_waitcnt vmcnt(10) lgkmcnt(8)
	s_setprio 1
	s_barrier
	s_waitcnt lgkmcnt(0)
	v_mfma_f32_16x16x32_bf16 v[130:133], v[134:137], v[150:153], v[130:133]
	v_mfma_f32_16x16x32_bf16 v[126:129], v[142:145], v[150:153], v[126:129]
	v_mfma_f32_16x16x32_bf16 v[122:125], v[134:137], v[158:161], v[122:125]
	v_mfma_f32_16x16x32_bf16 v[118:121], v[142:145], v[158:161], v[118:121]
	v_mfma_f32_16x16x32_bf16 v[114:117], v[134:137], v[184:187], v[114:117]
	v_mfma_f32_16x16x32_bf16 v[110:113], v[142:145], v[184:187], v[110:113]
	v_mfma_f32_16x16x32_bf16 v[106:109], v[134:137], v[198:201], v[106:109]
	v_mfma_f32_16x16x32_bf16 v[102:105], v[142:145], v[198:201], v[102:105]
	v_mfma_f32_16x16x32_bf16 v[130:133], v[138:141], v[154:157], v[130:133]
	v_mfma_f32_16x16x32_bf16 v[126:129], v[146:149], v[154:157], v[126:129]
	v_mfma_f32_16x16x32_bf16 v[122:125], v[138:141], v[162:165], v[122:125]
	v_mfma_f32_16x16x32_bf16 v[118:121], v[146:149], v[162:165], v[118:121]
	v_mfma_f32_16x16x32_bf16 v[114:117], v[138:141], v[194:197], v[114:117]
	v_mfma_f32_16x16x32_bf16 v[110:113], v[146:149], v[194:197], v[110:113]
	v_mfma_f32_16x16x32_bf16 v[106:109], v[138:141], v[202:205], v[106:109]
	v_mfma_f32_16x16x32_bf16 v[102:105], v[146:149], v[202:205], v[102:105]
	s_barrier
	s_setprio 0
	s_add_i32 s23, 0, 0x1c000
	s_add_i32 s0, s22, s55
	v_add_u32_e32 v26, s23, v191
	v_lshl_add_u64 v[32:33], v[166:167], 0, s[12:13]
	s_mov_b32 m0, s0
	ds_read_b128 v[206:209], v26
	ds_read_b128 v[210:213], v26 offset:1024
	ds_read_b128 v[214:217], v26 offset:2048
	ds_read_b128 v[218:221], v26 offset:3072
	global_load_lds_dwordx4 v[32:33], off
	v_lshl_add_u64 v[32:33], v[168:169], 0, s[12:13]
	s_add_i32 m0, s0, 0x2000
	s_nop 0
	global_load_lds_dwordx4 v[32:33], off
	s_waitcnt vmcnt(10)
	s_setprio 1
	s_barrier
	s_waitcnt lgkmcnt(0)
	v_mfma_f32_16x16x32_bf16 v[98:101], v[206:209], v[150:153], v[98:101]
	v_mfma_f32_16x16x32_bf16 v[94:97], v[214:217], v[150:153], v[94:97]
	v_mfma_f32_16x16x32_bf16 v[90:93], v[206:209], v[158:161], v[90:93]
	v_mfma_f32_16x16x32_bf16 v[86:89], v[214:217], v[158:161], v[86:89]
	v_mfma_f32_16x16x32_bf16 v[82:85], v[206:209], v[184:187], v[82:85]
	v_mfma_f32_16x16x32_bf16 v[78:81], v[214:217], v[184:187], v[78:81]
	v_mfma_f32_16x16x32_bf16 v[74:77], v[206:209], v[198:201], v[74:77]
	v_mfma_f32_16x16x32_bf16 v[70:73], v[214:217], v[198:201], v[70:73]
	v_mfma_f32_16x16x32_bf16 v[98:101], v[210:213], v[154:157], v[98:101]
	v_mfma_f32_16x16x32_bf16 v[94:97], v[218:221], v[154:157], v[94:97]
	v_mfma_f32_16x16x32_bf16 v[90:93], v[210:213], v[162:165], v[90:93]
	v_mfma_f32_16x16x32_bf16 v[86:89], v[218:221], v[162:165], v[86:89]
	v_mfma_f32_16x16x32_bf16 v[82:85], v[210:213], v[194:197], v[82:85]
	v_mfma_f32_16x16x32_bf16 v[78:81], v[218:221], v[194:197], v[78:81]
	v_mfma_f32_16x16x32_bf16 v[74:77], v[210:213], v[202:205], v[74:77]
	v_mfma_f32_16x16x32_bf16 v[70:73], v[218:221], v[202:205], v[70:73]
	s_barrier
	s_setprio 0
	s_mov_b32 m0, s30
	v_lshl_add_u64 v[32:33], v[188:189], 0, s[12:13]
	ds_read_b128 v[150:153], v193 offset:49152
	ds_read_b128 v[154:157], v193 offset:50176
	ds_read_b128 v[158:161], v193 offset:51200
	ds_read_b128 v[162:165], v193 offset:52224
	ds_read_b128 v[184:187], v193 offset:53248
	ds_read_b128 v[194:197], v193 offset:54272
	ds_read_b128 v[198:201], v193 offset:55296
	ds_read_b128 v[202:205], v193 offset:56320
	global_load_lds_dwordx4 v[32:33], off
	v_lshl_add_u64 v[32:33], v[222:223], 0, s[12:13]
	s_mov_b32 m0, s34
	s_nop 0
	global_load_lds_dwordx4 v[32:33], off
	s_waitcnt vmcnt(10)
	s_setprio 1
	s_barrier
	s_waitcnt lgkmcnt(0)
	v_mfma_f32_16x16x32_bf16 v[66:69], v[134:137], v[150:153], v[66:69]
	v_mfma_f32_16x16x32_bf16 v[62:65], v[142:145], v[150:153], v[62:65]
	v_mfma_f32_16x16x32_bf16 v[58:61], v[134:137], v[158:161], v[58:61]
	v_mfma_f32_16x16x32_bf16 v[54:57], v[142:145], v[158:161], v[54:57]
	v_mfma_f32_16x16x32_bf16 v[50:53], v[134:137], v[184:187], v[50:53]
	v_mfma_f32_16x16x32_bf16 v[46:49], v[142:145], v[184:187], v[46:49]
	v_mfma_f32_16x16x32_bf16 v[42:45], v[134:137], v[198:201], v[42:45]
	v_mfma_f32_16x16x32_bf16 v[38:41], v[142:145], v[198:201], v[38:41]
	v_mfma_f32_16x16x32_bf16 v[66:69], v[138:141], v[154:157], v[66:69]
	v_mfma_f32_16x16x32_bf16 v[62:65], v[146:149], v[154:157], v[62:65]
	v_mfma_f32_16x16x32_bf16 v[58:61], v[138:141], v[162:165], v[58:61]
	v_mfma_f32_16x16x32_bf16 v[54:57], v[146:149], v[162:165], v[54:57]
	v_mfma_f32_16x16x32_bf16 v[50:53], v[138:141], v[194:197], v[50:53]
	v_mfma_f32_16x16x32_bf16 v[46:49], v[146:149], v[194:197], v[46:49]
	v_mfma_f32_16x16x32_bf16 v[42:45], v[138:141], v[202:205], v[42:45]
	v_mfma_f32_16x16x32_bf16 v[38:41], v[146:149], v[202:205], v[38:41]
	s_barrier
	s_setprio 0
	s_add_u32 s0, s26, 0x20080
	s_addc_u32 s1, s27, 0
	s_add_i32 s22, s23, s55
	s_mov_b32 m0, s22
	s_nop 0
	global_load_lds_dwordx4 v176, s[0:1]
	s_add_i32 m0, s22, 0x2000
	s_nop 0
	global_load_lds_dwordx4 v172, s[0:1]
	v_add_u32_e32 v26, 0x10000, v191
	ds_read_b128 v[134:137], v26
	ds_read_b128 v[138:141], v26 offset:1024
	ds_read_b128 v[142:145], v26 offset:2048
	ds_read_b128 v[146:149], v26 offset:3072
	s_add_i32 s51, s51, 2
	s_add_u32 s45, s45, 0x100
	s_addc_u32 s50, s50, 0
	s_cmp_gt_u32 s51, 5
	s_mov_b64 s[22:23], s[24:25]
	s_waitcnt vmcnt(10)
	s_setprio 1
	s_barrier
	v_mfma_f32_16x16x32_bf16 v[32:35], v[206:209], v[150:153], v[34:37]
	v_mfma_f32_16x16x32_bf16 v[28:31], v[214:217], v[150:153], v[28:31]
	v_mfma_f32_16x16x32_bf16 v[22:25], v[206:209], v[158:161], v[22:25]
	v_mfma_f32_16x16x32_bf16 v[18:21], v[214:217], v[158:161], v[18:21]
	v_mfma_f32_16x16x32_bf16 v[14:17], v[206:209], v[184:187], v[14:17]
	v_mfma_f32_16x16x32_bf16 v[10:13], v[214:217], v[184:187], v[10:13]
	v_mfma_f32_16x16x32_bf16 v[6:9], v[206:209], v[198:201], v[6:9]
	v_mfma_f32_16x16x32_bf16 v[2:5], v[214:217], v[198:201], v[2:5]
	v_mfma_f32_16x16x32_bf16 v[34:37], v[210:213], v[154:157], v[32:35]
	v_mfma_f32_16x16x32_bf16 v[30:33], v[218:221], v[154:157], v[28:31]
	v_mfma_f32_16x16x32_bf16 v[22:25], v[210:213], v[162:165], v[22:25]
	v_mfma_f32_16x16x32_bf16 v[18:21], v[218:221], v[162:165], v[18:21]
	v_mfma_f32_16x16x32_bf16 v[14:17], v[210:213], v[194:197], v[14:17]
	v_mfma_f32_16x16x32_bf16 v[10:13], v[218:221], v[194:197], v[10:13]
	v_mfma_f32_16x16x32_bf16 v[6:9], v[210:213], v[202:205], v[6:9]
	v_mfma_f32_16x16x32_bf16 v[2:5], v[218:221], v[202:205], v[2:5]
	s_barrier
	s_setprio 0
	s_cbranch_scc0 .LBB0_887
	s_waitcnt lgkmcnt(0)
	v_lshl_or_b32 v186, s17, 8, v192
	v_ashrrev_i32_e32 v187, 31, v186
	v_lshl_add_u32 v26, s16, 8, v190
	s_cmp_lg_u32 s81, 0
	v_lshl_add_u64 v[28:29], v[186:187], 1, s[40:41]
	s_cselect_b64 s[50:51], -1, 0
	s_cmp_eq_u32 s81, 0
	v_mad_i64_i32 v[184:185], s[0:1], v26, s78, v[28:29]
	v_or_b32_e32 v198, 16, v26
	v_or_b32_e32 v197, 32, v26
	v_or_b32_e32 v196, 48, v26
	v_add_u32_e32 v195, 0x80, v26
	v_add_u32_e32 v194, 0x90, v26
	s_cbranch_scc1 .LBB0_894
	v_add_co_u32_e32 v134, vcc, 0x2000, v184
	v_mad_i64_i32 v[166:167], s[0:1], v26, s78, 0
	s_nop 0
	v_addc_co_u32_e32 v135, vcc, 0, v185, vcc
	global_load_dwordx4 v[162:165], v[134:135], off
	global_load_dwordx4 v[158:161], v[134:135], off offset:256
	v_mad_i64_i32 v[134:135], s[0:1], v198, s78, v[28:29]
	v_add_co_u32_e32 v134, vcc, 0x2000, v134
	v_lshlrev_b64 v[186:187], 1, v[186:187]
	s_nop 0
	v_addc_co_u32_e32 v135, vcc, 0, v135, vcc
	global_load_dwordx4 v[154:157], v[134:135], off
	global_load_dwordx4 v[150:153], v[134:135], off offset:256
	v_mad_i64_i32 v[134:135], s[0:1], v197, s78, v[28:29]
	v_add_co_u32_e32 v134, vcc, 0x2000, v134
	s_movk_i32 s16, 0x2000
	s_nop 0
	v_addc_co_u32_e32 v135, vcc, 0, v135, vcc
	global_load_dwordx4 v[146:149], v[134:135], off
	global_load_dwordx4 v[142:145], v[134:135], off offset:256
	v_mad_i64_i32 v[134:135], s[0:1], v196, s78, v[28:29]
	v_add_co_u32_e32 v134, vcc, 0x2000, v134
	s_nop 1
	v_addc_co_u32_e32 v135, vcc, 0, v135, vcc
	global_load_dwordx4 v[138:141], v[134:135], off
	s_nop 0
	global_load_dwordx4 v[134:137], v[134:135], off offset:256
	s_waitcnt vmcnt(0)
	v_lshlrev_b32_e32 v168, 16, v162
	v_and_b32_e32 v162, 0xffff0000, v162
	v_mul_f32_e32 v162, 0xbfb8aa3b, v162
	v_exp_f32_e32 v162, v162
	v_mul_f32_e32 v168, 0xbfb8aa3b, v168
	v_exp_f32_e32 v168, v168
	v_add_f32_e32 v162, 1.0, v162
	v_rcp_f32_e32 v169, v162
	v_lshlrev_b32_e32 v162, 16, v163
	v_and_b32_e32 v163, 0xffff0000, v163
	v_mul_f32_e32 v162, 0xbfb8aa3b, v162
	v_mul_f32_e32 v163, 0xbfb8aa3b, v163
	v_exp_f32_e32 v162, v162
	v_exp_f32_e32 v163, v163
	v_add_f32_e32 v168, 1.0, v168
	v_rcp_f32_e32 v168, v168
	v_add_f32_e32 v162, 1.0, v162
	v_add_f32_e32 v163, 1.0, v163
	v_rcp_f32_e32 v162, v162
	v_rcp_f32_e32 v163, v163
	v_pk_mul_f32 v[168:169], v[130:131], v[168:169]
	v_pk_mul_f32 v[188:189], v[132:133], v[162:163]
	v_lshlrev_b32_e32 v162, 16, v164
	v_and_b32_e32 v163, 0xffff0000, v164
	v_mul_f32_e32 v162, 0xbfb8aa3b, v162
	v_mul_f32_e32 v163, 0xbfb8aa3b, v163
	v_exp_f32_e32 v162, v162
	v_exp_f32_e32 v163, v163
	v_add_f32_e32 v162, 1.0, v162
	v_add_f32_e32 v163, 1.0, v163
	v_rcp_f32_e32 v162, v162
	v_rcp_f32_e32 v163, v163
	s_nop 0
	v_pk_mul_f32 v[200:201], v[126:127], v[162:163]
	v_lshlrev_b32_e32 v162, 16, v165
	v_and_b32_e32 v163, 0xffff0000, v165
	v_mul_f32_e32 v162, 0xbfb8aa3b, v162
	v_mul_f32_e32 v163, 0xbfb8aa3b, v163
	v_exp_f32_e32 v162, v162
	v_exp_f32_e32 v163, v163
	v_cvt_pk_bf16_f32 v164, v200, v201
	v_add_f32_e32 v162, 1.0, v162
	v_add_f32_e32 v163, 1.0, v163
	v_rcp_f32_e32 v162, v162
	v_rcp_f32_e32 v163, v163
	s_nop 0
	v_pk_mul_f32 v[202:203], v[128:129], v[162:163]
	v_cvt_pk_bf16_f32 v163, v188, v189
	v_lshl_add_u64 v[188:189], s[42:43], 0, v[166:167]
	v_cvt_pk_bf16_f32 v162, v168, v169
	v_cvt_pk_bf16_f32 v165, v202, v203
	v_lshl_add_u64 v[188:189], v[188:189], 0, v[186:187]
	global_store_dwordx4 v[188:189], v[162:165], off
	s_nop 1
	v_lshlrev_b32_e32 v162, 16, v158
	v_and_b32_e32 v158, 0xffff0000, v158
	v_mul_f32_e32 v158, 0xbfb8aa3b, v158
	v_exp_f32_e32 v158, v158
	v_mul_f32_e32 v162, 0xbfb8aa3b, v162
	v_exp_f32_e32 v162, v162
	v_add_f32_e32 v158, 1.0, v158
	v_rcp_f32_e32 v163, v158
	v_lshlrev_b32_e32 v158, 16, v159
	v_and_b32_e32 v159, 0xffff0000, v159
	v_mul_f32_e32 v158, 0xbfb8aa3b, v158
	v_mul_f32_e32 v159, 0xbfb8aa3b, v159
	v_exp_f32_e32 v158, v158
	v_exp_f32_e32 v159, v159
	v_add_f32_e32 v162, 1.0, v162
	v_rcp_f32_e32 v162, v162
	v_add_f32_e32 v158, 1.0, v158
	v_add_f32_e32 v159, 1.0, v159
	v_rcp_f32_e32 v158, v158
	v_rcp_f32_e32 v159, v159
	v_pk_mul_f32 v[162:163], v[98:99], v[162:163]
	v_pk_mul_f32 v[164:165], v[100:101], v[158:159]
	v_lshlrev_b32_e32 v158, 16, v160
	v_and_b32_e32 v159, 0xffff0000, v160
	v_mul_f32_e32 v158, 0xbfb8aa3b, v158
	v_mul_f32_e32 v159, 0xbfb8aa3b, v159
	v_exp_f32_e32 v158, v158
	v_exp_f32_e32 v159, v159
	v_add_f32_e32 v158, 1.0, v158
	v_add_f32_e32 v159, 1.0, v159
	v_rcp_f32_e32 v158, v158
	v_rcp_f32_e32 v159, v159
	s_nop 0
	v_pk_mul_f32 v[166:167], v[94:95], v[158:159]
	v_lshlrev_b32_e32 v158, 16, v161
	v_and_b32_e32 v159, 0xffff0000, v161
	v_mul_f32_e32 v158, 0xbfb8aa3b, v158
	v_mul_f32_e32 v159, 0xbfb8aa3b, v159
	v_exp_f32_e32 v158, v158
	v_exp_f32_e32 v159, v159
	v_cvt_pk_bf16_f32 v160, v166, v167
	v_add_f32_e32 v158, 1.0, v158
	v_add_f32_e32 v159, 1.0, v159
	v_rcp_f32_e32 v158, v158
	v_rcp_f32_e32 v159, v159
	s_nop 0
	v_pk_mul_f32 v[168:169], v[96:97], v[158:159]
	v_cvt_pk_bf16_f32 v158, v162, v163
	v_cvt_pk_bf16_f32 v159, v164, v165
	v_cvt_pk_bf16_f32 v161, v168, v169
	global_store_dwordx4 v[188:189], v[158:161], off offset:256
	s_nop 1
	v_lshlrev_b32_e32 v158, 16, v154
	v_and_b32_e32 v154, 0xffff0000, v154
	v_mul_f32_e32 v154, 0xbfb8aa3b, v154
	v_exp_f32_e32 v154, v154
	v_mul_f32_e32 v158, 0xbfb8aa3b, v158
	v_exp_f32_e32 v158, v158
	v_add_f32_e32 v154, 1.0, v154
	v_rcp_f32_e32 v159, v154
	v_lshlrev_b32_e32 v154, 16, v155
	v_and_b32_e32 v155, 0xffff0000, v155
	v_mul_f32_e32 v154, 0xbfb8aa3b, v154
	v_mul_f32_e32 v155, 0xbfb8aa3b, v155
	v_exp_f32_e32 v154, v154
	v_exp_f32_e32 v155, v155
	v_add_f32_e32 v158, 1.0, v158
	v_rcp_f32_e32 v158, v158
	v_add_f32_e32 v154, 1.0, v154
	v_add_f32_e32 v155, 1.0, v155
	v_rcp_f32_e32 v154, v154
	v_rcp_f32_e32 v155, v155
	v_pk_mul_f32 v[158:159], v[122:123], v[158:159]
	v_pk_mul_f32 v[160:161], v[124:125], v[154:155]
	v_lshlrev_b32_e32 v154, 16, v156
	v_and_b32_e32 v155, 0xffff0000, v156
	v_mul_f32_e32 v154, 0xbfb8aa3b, v154
	v_mul_f32_e32 v155, 0xbfb8aa3b, v155
	v_exp_f32_e32 v154, v154
	v_exp_f32_e32 v155, v155
	v_add_f32_e32 v154, 1.0, v154
	v_add_f32_e32 v155, 1.0, v155
	v_rcp_f32_e32 v154, v154
	v_rcp_f32_e32 v155, v155
	s_nop 0
	v_pk_mul_f32 v[162:163], v[118:119], v[154:155]
	v_lshlrev_b32_e32 v154, 16, v157
	v_and_b32_e32 v155, 0xffff0000, v157
	v_mul_f32_e32 v154, 0xbfb8aa3b, v154
	v_mul_f32_e32 v155, 0xbfb8aa3b, v155
	v_exp_f32_e32 v154, v154
	v_exp_f32_e32 v155, v155
	v_cvt_pk_bf16_f32 v156, v162, v163
	v_mov_b64_e32 v[162:163], s[42:43]
	v_add_f32_e32 v154, 1.0, v154
	v_add_f32_e32 v155, 1.0, v155
	v_rcp_f32_e32 v154, v154
	v_rcp_f32_e32 v155, v155
	s_nop 0
	v_pk_mul_f32 v[164:165], v[120:121], v[154:155]
	v_cvt_pk_bf16_f32 v154, v158, v159
	v_mad_i64_i32 v[158:159], s[0:1], v198, s78, v[162:163]
	v_cvt_pk_bf16_f32 v155, v160, v161
	v_cvt_pk_bf16_f32 v157, v164, v165
	v_lshl_add_u64 v[158:159], v[158:159], 0, v[186:187]
	global_store_dwordx4 v[158:159], v[154:157], off
	s_nop 1
	v_lshlrev_b32_e32 v154, 16, v150
	v_and_b32_e32 v150, 0xffff0000, v150
	v_mul_f32_e32 v150, 0xbfb8aa3b, v150
	v_exp_f32_e32 v150, v150
	v_mul_f32_e32 v154, 0xbfb8aa3b, v154
	v_exp_f32_e32 v154, v154
	v_add_f32_e32 v150, 1.0, v150
	v_rcp_f32_e32 v155, v150
	v_lshlrev_b32_e32 v150, 16, v151
	v_and_b32_e32 v151, 0xffff0000, v151
	v_mul_f32_e32 v150, 0xbfb8aa3b, v150
	v_mul_f32_e32 v151, 0xbfb8aa3b, v151
	v_exp_f32_e32 v150, v150
	v_exp_f32_e32 v151, v151
	v_add_f32_e32 v154, 1.0, v154
	v_rcp_f32_e32 v154, v154
	v_add_f32_e32 v150, 1.0, v150
	v_add_f32_e32 v151, 1.0, v151
	v_rcp_f32_e32 v150, v150
	v_rcp_f32_e32 v151, v151
	v_pk_mul_f32 v[154:155], v[90:91], v[154:155]
	v_pk_mul_f32 v[156:157], v[92:93], v[150:151]
	v_lshlrev_b32_e32 v150, 16, v152
	v_and_b32_e32 v151, 0xffff0000, v152
	v_mul_f32_e32 v150, 0xbfb8aa3b, v150
	v_mul_f32_e32 v151, 0xbfb8aa3b, v151
	v_exp_f32_e32 v150, v150
	v_exp_f32_e32 v151, v151
	v_add_f32_e32 v150, 1.0, v150
	v_add_f32_e32 v151, 1.0, v151
	v_rcp_f32_e32 v150, v150
	v_rcp_f32_e32 v151, v151
	s_nop 0
	v_pk_mul_f32 v[160:161], v[86:87], v[150:151]
	v_lshlrev_b32_e32 v150, 16, v153
	v_and_b32_e32 v151, 0xffff0000, v153
	v_mul_f32_e32 v150, 0xbfb8aa3b, v150
	v_mul_f32_e32 v151, 0xbfb8aa3b, v151
	v_exp_f32_e32 v150, v150
	v_exp_f32_e32 v151, v151
	v_cvt_pk_bf16_f32 v152, v160, v161
	v_add_f32_e32 v150, 1.0, v150
	v_add_f32_e32 v151, 1.0, v151
	v_rcp_f32_e32 v150, v150
	v_rcp_f32_e32 v151, v151
	s_nop 0
	v_pk_mul_f32 v[164:165], v[88:89], v[150:151]
	v_cvt_pk_bf16_f32 v150, v154, v155
	v_cvt_pk_bf16_f32 v151, v156, v157
	v_cvt_pk_bf16_f32 v153, v164, v165
	global_store_dwordx4 v[158:159], v[150:153], off offset:256
	v_add_u32_e32 v165, 0xa0, v26
	v_add_u32_e32 v164, 0xb0, v26
	v_lshlrev_b32_e32 v150, 16, v146
	v_and_b32_e32 v146, 0xffff0000, v146
	v_mul_f32_e32 v146, 0xbfb8aa3b, v146
	v_exp_f32_e32 v146, v146
	v_mul_f32_e32 v150, 0xbfb8aa3b, v150
	v_exp_f32_e32 v150, v150
	v_add_f32_e32 v146, 1.0, v146
	v_rcp_f32_e32 v151, v146
	v_lshlrev_b32_e32 v146, 16, v147
	v_and_b32_e32 v147, 0xffff0000, v147
	v_mul_f32_e32 v146, 0xbfb8aa3b, v146
	v_mul_f32_e32 v147, 0xbfb8aa3b, v147
	v_exp_f32_e32 v146, v146
	v_exp_f32_e32 v147, v147
	v_add_f32_e32 v150, 1.0, v150
	v_rcp_f32_e32 v150, v150
	v_add_f32_e32 v146, 1.0, v146
	v_add_f32_e32 v147, 1.0, v147
	v_rcp_f32_e32 v146, v146
	v_rcp_f32_e32 v147, v147
	v_pk_mul_f32 v[150:151], v[114:115], v[150:151]
	v_pk_mul_f32 v[152:153], v[116:117], v[146:147]
	v_lshlrev_b32_e32 v146, 16, v148
	v_and_b32_e32 v147, 0xffff0000, v148
	v_mul_f32_e32 v146, 0xbfb8aa3b, v146
	v_mul_f32_e32 v147, 0xbfb8aa3b, v147
	v_exp_f32_e32 v146, v146
	v_exp_f32_e32 v147, v147
	v_add_f32_e32 v146, 1.0, v146
	v_add_f32_e32 v147, 1.0, v147
	v_rcp_f32_e32 v146, v146
	v_rcp_f32_e32 v147, v147
	s_nop 0
	v_pk_mul_f32 v[154:155], v[110:111], v[146:147]
	v_lshlrev_b32_e32 v146, 16, v149
	v_and_b32_e32 v147, 0xffff0000, v149
	v_mul_f32_e32 v146, 0xbfb8aa3b, v146
	v_mul_f32_e32 v147, 0xbfb8aa3b, v147
	v_exp_f32_e32 v146, v146
	v_exp_f32_e32 v147, v147
	v_cvt_pk_bf16_f32 v148, v154, v155
	v_add_f32_e32 v146, 1.0, v146
	v_add_f32_e32 v147, 1.0, v147
	v_rcp_f32_e32 v146, v146
	v_rcp_f32_e32 v147, v147
	s_nop 0
	v_pk_mul_f32 v[156:157], v[112:113], v[146:147]
	v_cvt_pk_bf16_f32 v146, v150, v151
	v_mad_i64_i32 v[150:151], s[0:1], v197, s78, v[162:163]
	v_cvt_pk_bf16_f32 v147, v152, v153
	v_cvt_pk_bf16_f32 v149, v156, v157
	v_lshl_add_u64 v[150:151], v[150:151], 0, v[186:187]
	global_store_dwordx4 v[150:151], v[146:149], off
	s_nop 1
	v_lshlrev_b32_e32 v146, 16, v142
	v_and_b32_e32 v142, 0xffff0000, v142
	v_mul_f32_e32 v142, 0xbfb8aa3b, v142
	v_exp_f32_e32 v142, v142
	v_mul_f32_e32 v146, 0xbfb8aa3b, v146
	v_exp_f32_e32 v146, v146
	v_add_f32_e32 v142, 1.0, v142
	v_rcp_f32_e32 v147, v142
	v_lshlrev_b32_e32 v142, 16, v143
	v_and_b32_e32 v143, 0xffff0000, v143
	v_mul_f32_e32 v142, 0xbfb8aa3b, v142
	v_mul_f32_e32 v143, 0xbfb8aa3b, v143
	v_exp_f32_e32 v142, v142
	v_exp_f32_e32 v143, v143
	v_add_f32_e32 v146, 1.0, v146
	v_rcp_f32_e32 v146, v146
	v_add_f32_e32 v142, 1.0, v142
	v_add_f32_e32 v143, 1.0, v143
	v_rcp_f32_e32 v142, v142
	v_rcp_f32_e32 v143, v143
	v_pk_mul_f32 v[146:147], v[82:83], v[146:147]
	v_pk_mul_f32 v[148:149], v[84:85], v[142:143]
	v_lshlrev_b32_e32 v142, 16, v144
	v_and_b32_e32 v143, 0xffff0000, v144
	v_mul_f32_e32 v142, 0xbfb8aa3b, v142
	v_mul_f32_e32 v143, 0xbfb8aa3b, v143
	v_exp_f32_e32 v142, v142
	v_exp_f32_e32 v143, v143
	v_add_f32_e32 v142, 1.0, v142
	v_add_f32_e32 v143, 1.0, v143
	v_rcp_f32_e32 v142, v142
	v_rcp_f32_e32 v143, v143
	s_nop 0
	v_pk_mul_f32 v[152:153], v[78:79], v[142:143]
	v_lshlrev_b32_e32 v142, 16, v145
	v_and_b32_e32 v143, 0xffff0000, v145
	v_mul_f32_e32 v142, 0xbfb8aa3b, v142
	v_mul_f32_e32 v143, 0xbfb8aa3b, v143
	v_exp_f32_e32 v142, v142
	v_exp_f32_e32 v143, v143
	v_cvt_pk_bf16_f32 v144, v152, v153
	v_add_f32_e32 v142, 1.0, v142
	v_add_f32_e32 v143, 1.0, v143
	v_rcp_f32_e32 v142, v142
	v_rcp_f32_e32 v143, v143
	s_nop 0
	v_pk_mul_f32 v[154:155], v[80:81], v[142:143]
	v_cvt_pk_bf16_f32 v142, v146, v147
	v_cvt_pk_bf16_f32 v143, v148, v149
	v_cvt_pk_bf16_f32 v145, v154, v155
	global_store_dwordx4 v[150:151], v[142:145], off offset:256
	s_nop 1
	v_lshlrev_b32_e32 v142, 16, v138
	v_and_b32_e32 v138, 0xffff0000, v138
	v_mul_f32_e32 v138, 0xbfb8aa3b, v138
	v_exp_f32_e32 v138, v138
	v_mul_f32_e32 v142, 0xbfb8aa3b, v142
	v_exp_f32_e32 v142, v142
	v_add_f32_e32 v138, 1.0, v138
	v_rcp_f32_e32 v143, v138
	v_lshlrev_b32_e32 v138, 16, v139
	v_and_b32_e32 v139, 0xffff0000, v139
	v_mul_f32_e32 v138, 0xbfb8aa3b, v138
	v_mul_f32_e32 v139, 0xbfb8aa3b, v139
	v_exp_f32_e32 v138, v138
	v_exp_f32_e32 v139, v139
	v_add_f32_e32 v142, 1.0, v142
	v_rcp_f32_e32 v142, v142
	v_add_f32_e32 v138, 1.0, v138
	v_add_f32_e32 v139, 1.0, v139
	v_rcp_f32_e32 v138, v138
	v_rcp_f32_e32 v139, v139
	v_pk_mul_f32 v[142:143], v[106:107], v[142:143]
	v_pk_mul_f32 v[144:145], v[108:109], v[138:139]
	v_lshlrev_b32_e32 v138, 16, v140
	v_and_b32_e32 v139, 0xffff0000, v140
	v_mul_f32_e32 v138, 0xbfb8aa3b, v138
	v_mul_f32_e32 v139, 0xbfb8aa3b, v139
	v_exp_f32_e32 v138, v138
	v_exp_f32_e32 v139, v139
	v_add_f32_e32 v138, 1.0, v138
	v_add_f32_e32 v139, 1.0, v139
	v_rcp_f32_e32 v138, v138
	v_rcp_f32_e32 v139, v139
	s_nop 0
	v_pk_mul_f32 v[146:147], v[102:103], v[138:139]
	v_lshlrev_b32_e32 v138, 16, v141
	v_and_b32_e32 v139, 0xffff0000, v141
	v_mul_f32_e32 v138, 0xbfb8aa3b, v138
	v_mul_f32_e32 v139, 0xbfb8aa3b, v139
	v_exp_f32_e32 v138, v138
	v_exp_f32_e32 v139, v139
	v_cvt_pk_bf16_f32 v140, v146, v147
	v_add_f32_e32 v138, 1.0, v138
	v_add_f32_e32 v139, 1.0, v139
	v_rcp_f32_e32 v138, v138
	v_rcp_f32_e32 v139, v139
	s_nop 0
	v_pk_mul_f32 v[148:149], v[104:105], v[138:139]
	v_cvt_pk_bf16_f32 v138, v142, v143
	v_mad_i64_i32 v[142:143], s[0:1], v196, s78, v[162:163]
	v_cvt_pk_bf16_f32 v139, v144, v145
	v_cvt_pk_bf16_f32 v141, v148, v149
	v_lshl_add_u64 v[142:143], v[142:143], 0, v[186:187]
	global_store_dwordx4 v[142:143], v[138:141], off
	s_nop 1
	v_lshlrev_b32_e32 v138, 16, v134
	v_and_b32_e32 v134, 0xffff0000, v134
	v_mul_f32_e32 v134, 0xbfb8aa3b, v134
	v_exp_f32_e32 v134, v134
	v_mul_f32_e32 v138, 0xbfb8aa3b, v138
	v_exp_f32_e32 v138, v138
	v_add_f32_e32 v134, 1.0, v134
	v_rcp_f32_e32 v139, v134
	v_lshlrev_b32_e32 v134, 16, v135
	v_and_b32_e32 v135, 0xffff0000, v135
	v_mul_f32_e32 v134, 0xbfb8aa3b, v134
	v_mul_f32_e32 v135, 0xbfb8aa3b, v135
	v_exp_f32_e32 v134, v134
	v_exp_f32_e32 v135, v135
	v_add_f32_e32 v138, 1.0, v138
	v_rcp_f32_e32 v138, v138
	v_add_f32_e32 v134, 1.0, v134
	v_add_f32_e32 v135, 1.0, v135
	v_rcp_f32_e32 v134, v134
	v_rcp_f32_e32 v135, v135
	v_pk_mul_f32 v[138:139], v[74:75], v[138:139]
	v_pk_mul_f32 v[140:141], v[76:77], v[134:135]
	v_lshlrev_b32_e32 v134, 16, v136
	v_and_b32_e32 v135, 0xffff0000, v136
	v_mul_f32_e32 v134, 0xbfb8aa3b, v134
	v_mul_f32_e32 v135, 0xbfb8aa3b, v135
	v_exp_f32_e32 v134, v134
	v_exp_f32_e32 v135, v135
	v_add_f32_e32 v134, 1.0, v134
	v_add_f32_e32 v135, 1.0, v135
	v_rcp_f32_e32 v134, v134
	v_rcp_f32_e32 v135, v135
	s_nop 0
	v_pk_mul_f32 v[144:145], v[70:71], v[134:135]
	v_lshlrev_b32_e32 v134, 16, v137
	v_and_b32_e32 v135, 0xffff0000, v137
	v_mul_f32_e32 v134, 0xbfb8aa3b, v134
	v_mul_f32_e32 v135, 0xbfb8aa3b, v135
	v_exp_f32_e32 v134, v134
	v_exp_f32_e32 v135, v135
	v_cvt_pk_bf16_f32 v136, v144, v145
	v_add_f32_e32 v134, 1.0, v134
	v_add_f32_e32 v135, 1.0, v135
	v_rcp_f32_e32 v134, v134
	v_rcp_f32_e32 v135, v135
	s_nop 0
	v_pk_mul_f32 v[146:147], v[72:73], v[134:135]
	v_cvt_pk_bf16_f32 v134, v138, v139
	v_cvt_pk_bf16_f32 v135, v140, v141
	v_cvt_pk_bf16_f32 v137, v146, v147
	global_store_dwordx4 v[142:143], v[134:137], off offset:256
	s_nop 1
	v_mad_i64_i32 v[134:135], s[0:1], v195, s78, v[28:29]
	v_add_co_u32_e32 v134, vcc, s16, v134
	s_nop 1
	v_addc_co_u32_e32 v135, vcc, 0, v135, vcc
	global_load_dwordx4 v[200:203], v[134:135], off
	global_load_dwordx4 v[158:161], v[134:135], off offset:256
	v_mad_i64_i32 v[134:135], s[0:1], v194, s78, v[28:29]
	v_add_co_u32_e32 v134, vcc, s16, v134
	s_waitcnt vmcnt(0)
	v_lshlrev_b32_e32 v199, 16, v203
	v_addc_co_u32_e32 v135, vcc, 0, v135, vcc
	global_load_dwordx4 v[154:157], v[134:135], off
	global_load_dwordx4 v[150:153], v[134:135], off offset:256
	v_mul_f32_e32 v199, 0xbfb8aa3b, v199
	v_exp_f32_e32 v199, v199
	v_lshlrev_b32_e32 v168, 16, v201
	v_and_b32_e32 v169, 0xffff0000, v201
	v_lshlrev_b32_e32 v166, 16, v200
	v_add_f32_e32 v199, 1.0, v199
	v_and_b32_e32 v167, 0xffff0000, v200
	v_mul_f32_e32 v168, 0xbfb8aa3b, v168
	v_mul_f32_e32 v169, 0xbfb8aa3b, v169
	v_rcp_f32_e32 v200, v199
	v_and_b32_e32 v199, 0xffff0000, v203
	v_exp_f32_e32 v168, v168
	v_exp_f32_e32 v169, v169
	v_mul_f32_e32 v199, 0xbfb8aa3b, v199
	v_exp_f32_e32 v199, v199
	v_add_f32_e32 v168, 1.0, v168
	v_add_f32_e32 v169, 1.0, v169
	v_rcp_f32_e32 v168, v168
	v_rcp_f32_e32 v169, v169
	v_add_f32_e32 v199, 1.0, v199
	v_rcp_f32_e32 v201, v199
	v_lshlrev_b32_e32 v188, 16, v202
	v_pk_mul_f32 v[168:169], v[68:69], v[168:169]
	v_and_b32_e32 v189, 0xffff0000, v202
	v_pk_mul_f32 v[204:205], v[64:65], v[200:201]
	v_cvt_pk_bf16_f32 v201, v168, v169
	v_lshlrev_b32_e32 v168, 16, v158
	v_and_b32_e32 v158, 0xffff0000, v158
	v_mul_f32_e32 v158, 0xbfb8aa3b, v158
	v_exp_f32_e32 v158, v158
	v_mul_f32_e32 v188, 0xbfb8aa3b, v188
	v_mul_f32_e32 v189, 0xbfb8aa3b, v189
	v_exp_f32_e32 v188, v188
	v_add_f32_e32 v158, 1.0, v158
	v_rcp_f32_e32 v169, v158
	v_lshlrev_b32_e32 v158, 16, v159
	v_and_b32_e32 v159, 0xffff0000, v159
	v_exp_f32_e32 v189, v189
	v_mul_f32_e32 v158, 0xbfb8aa3b, v158
	v_mul_f32_e32 v159, 0xbfb8aa3b, v159
	v_exp_f32_e32 v158, v158
	v_exp_f32_e32 v159, v159
	v_add_f32_e32 v188, 1.0, v188
	v_add_f32_e32 v189, 1.0, v189
	v_rcp_f32_e32 v188, v188
	v_rcp_f32_e32 v189, v189
	v_add_f32_e32 v158, 1.0, v158
	v_add_f32_e32 v159, 1.0, v159
	v_rcp_f32_e32 v158, v158
	v_rcp_f32_e32 v159, v159
	v_mul_f32_e32 v166, 0xbfb8aa3b, v166
	v_mul_f32_e32 v167, 0xbfb8aa3b, v167
	v_exp_f32_e32 v166, v166
	v_exp_f32_e32 v167, v167
	v_pk_mul_f32 v[188:189], v[62:63], v[188:189]
	v_mad_i64_i32 v[134:135], s[0:1], v165, s78, v[28:29]
	v_cvt_pk_bf16_f32 v202, v188, v189
	v_pk_mul_f32 v[188:189], v[36:37], v[158:159]
	v_lshlrev_b32_e32 v158, 16, v160
	v_and_b32_e32 v159, 0xffff0000, v160
	v_mul_f32_e32 v158, 0xbfb8aa3b, v158
	v_mul_f32_e32 v159, 0xbfb8aa3b, v159
	v_exp_f32_e32 v158, v158
	v_exp_f32_e32 v159, v159
	v_add_f32_e32 v166, 1.0, v166
	v_add_f32_e32 v167, 1.0, v167
	v_rcp_f32_e32 v166, v166
	v_rcp_f32_e32 v167, v167
	v_add_co_u32_e32 v134, vcc, s16, v134
	v_add_f32_e32 v158, 1.0, v158
	v_add_f32_e32 v159, 1.0, v159
	v_addc_co_u32_e32 v135, vcc, 0, v135, vcc
	v_rcp_f32_e32 v158, v158
	v_rcp_f32_e32 v159, v159
	global_load_dwordx4 v[146:149], v[134:135], off
	global_load_dwordx4 v[142:145], v[134:135], off offset:256
	v_mad_i64_i32 v[134:135], s[0:1], v164, s78, v[28:29]
	v_pk_mul_f32 v[166:167], v[66:67], v[166:167]
	v_add_co_u32_e32 v134, vcc, s16, v134
	v_cvt_pk_bf16_f32 v200, v166, v167
	v_mad_i64_i32 v[166:167], s[0:1], v195, s78, v[162:163]
	v_addc_co_u32_e32 v135, vcc, 0, v135, vcc
	v_cvt_pk_bf16_f32 v203, v204, v205
	v_lshl_add_u64 v[166:167], v[166:167], 0, v[186:187]
	global_load_dwordx4 v[138:141], v[134:135], off
	s_nop 0
	global_load_dwordx4 v[134:137], v[134:135], off offset:256
	v_mul_f32_e32 v168, 0xbfb8aa3b, v168
	global_store_dwordx4 v[166:167], v[200:203], off
	v_exp_f32_e32 v168, v168
	s_nop 0
	v_pk_mul_f32 v[200:201], v[30:31], v[158:159]
	v_lshlrev_b32_e32 v158, 16, v161
	v_and_b32_e32 v159, 0xffff0000, v161
	v_mul_f32_e32 v158, 0xbfb8aa3b, v158
	v_mul_f32_e32 v159, 0xbfb8aa3b, v159
	v_exp_f32_e32 v158, v158
	v_exp_f32_e32 v159, v159
	v_add_f32_e32 v168, 1.0, v168
	v_rcp_f32_e32 v168, v168
	v_add_f32_e32 v158, 1.0, v158
	v_add_f32_e32 v159, 1.0, v159
	v_rcp_f32_e32 v158, v158
	v_rcp_f32_e32 v159, v159
	v_pk_mul_f32 v[168:169], v[34:35], v[168:169]
	v_cvt_pk_bf16_f32 v160, v200, v201
	v_pk_mul_f32 v[202:203], v[32:33], v[158:159]
	v_cvt_pk_bf16_f32 v158, v168, v169
	v_cvt_pk_bf16_f32 v159, v188, v189
	v_cvt_pk_bf16_f32 v161, v202, v203
	global_store_dwordx4 v[166:167], v[158:161], off offset:256
	s_waitcnt vmcnt(0)
	s_nop 0
	v_lshlrev_b32_e32 v158, 16, v154
	v_and_b32_e32 v154, 0xffff0000, v154
	v_mul_f32_e32 v154, 0xbfb8aa3b, v154
	v_exp_f32_e32 v154, v154
	v_mul_f32_e32 v158, 0xbfb8aa3b, v158
	v_exp_f32_e32 v158, v158
	v_add_f32_e32 v154, 1.0, v154
	v_rcp_f32_e32 v159, v154
	v_lshlrev_b32_e32 v154, 16, v155
	v_and_b32_e32 v155, 0xffff0000, v155
	v_mul_f32_e32 v154, 0xbfb8aa3b, v154
	v_mul_f32_e32 v155, 0xbfb8aa3b, v155
	v_exp_f32_e32 v154, v154
	v_exp_f32_e32 v155, v155
	v_add_f32_e32 v158, 1.0, v158
	v_rcp_f32_e32 v158, v158
	v_add_f32_e32 v154, 1.0, v154
	v_add_f32_e32 v155, 1.0, v155
	v_rcp_f32_e32 v154, v154
	v_rcp_f32_e32 v155, v155
	v_pk_mul_f32 v[158:159], v[58:59], v[158:159]
	v_pk_mul_f32 v[160:161], v[60:61], v[154:155]
	v_lshlrev_b32_e32 v154, 16, v156
	v_and_b32_e32 v155, 0xffff0000, v156
	v_mul_f32_e32 v154, 0xbfb8aa3b, v154
	v_mul_f32_e32 v155, 0xbfb8aa3b, v155
	v_exp_f32_e32 v154, v154
	v_exp_f32_e32 v155, v155
	v_add_f32_e32 v154, 1.0, v154
	v_add_f32_e32 v155, 1.0, v155
	v_rcp_f32_e32 v154, v154
	v_rcp_f32_e32 v155, v155
	s_nop 0
	v_pk_mul_f32 v[166:167], v[54:55], v[154:155]
	v_lshlrev_b32_e32 v154, 16, v157
	v_and_b32_e32 v155, 0xffff0000, v157
	v_mul_f32_e32 v154, 0xbfb8aa3b, v154
	v_mul_f32_e32 v155, 0xbfb8aa3b, v155
	v_exp_f32_e32 v154, v154
	v_exp_f32_e32 v155, v155
	v_cvt_pk_bf16_f32 v156, v166, v167
	v_add_f32_e32 v154, 1.0, v154
	v_add_f32_e32 v155, 1.0, v155
	v_rcp_f32_e32 v154, v154
	v_rcp_f32_e32 v155, v155
	s_nop 0
	v_pk_mul_f32 v[168:169], v[56:57], v[154:155]
	v_cvt_pk_bf16_f32 v154, v158, v159
	v_mad_i64_i32 v[158:159], s[0:1], v194, s78, v[162:163]
	v_cvt_pk_bf16_f32 v155, v160, v161
	v_cvt_pk_bf16_f32 v157, v168, v169
	v_lshl_add_u64 v[158:159], v[158:159], 0, v[186:187]
	global_store_dwordx4 v[158:159], v[154:157], off
	s_nop 1
	v_lshlrev_b32_e32 v154, 16, v150
	v_and_b32_e32 v150, 0xffff0000, v150
	v_mul_f32_e32 v150, 0xbfb8aa3b, v150
	v_exp_f32_e32 v150, v150
	v_mul_f32_e32 v154, 0xbfb8aa3b, v154
	v_exp_f32_e32 v154, v154
	v_add_f32_e32 v150, 1.0, v150
	v_rcp_f32_e32 v155, v150
	v_lshlrev_b32_e32 v150, 16, v151
	v_and_b32_e32 v151, 0xffff0000, v151
	v_mul_f32_e32 v150, 0xbfb8aa3b, v150
	v_mul_f32_e32 v151, 0xbfb8aa3b, v151
	v_exp_f32_e32 v150, v150
	v_exp_f32_e32 v151, v151
	v_add_f32_e32 v154, 1.0, v154
	v_rcp_f32_e32 v154, v154
	v_add_f32_e32 v150, 1.0, v150
	v_add_f32_e32 v151, 1.0, v151
	v_rcp_f32_e32 v150, v150
	v_rcp_f32_e32 v151, v151
	v_pk_mul_f32 v[154:155], v[22:23], v[154:155]
	v_pk_mul_f32 v[156:157], v[24:25], v[150:151]
	v_lshlrev_b32_e32 v150, 16, v152
	v_and_b32_e32 v151, 0xffff0000, v152
	v_mul_f32_e32 v150, 0xbfb8aa3b, v150
	v_mul_f32_e32 v151, 0xbfb8aa3b, v151
	v_exp_f32_e32 v150, v150
	v_exp_f32_e32 v151, v151
	v_add_f32_e32 v150, 1.0, v150
	v_add_f32_e32 v151, 1.0, v151
	v_rcp_f32_e32 v150, v150
	v_rcp_f32_e32 v151, v151
	s_nop 0
	v_pk_mul_f32 v[160:161], v[18:19], v[150:151]
	v_lshlrev_b32_e32 v150, 16, v153
	v_and_b32_e32 v151, 0xffff0000, v153
	v_mul_f32_e32 v150, 0xbfb8aa3b, v150
	v_mul_f32_e32 v151, 0xbfb8aa3b, v151
	v_exp_f32_e32 v150, v150
	v_exp_f32_e32 v151, v151
	v_cvt_pk_bf16_f32 v152, v160, v161
	v_add_f32_e32 v150, 1.0, v150
	v_add_f32_e32 v151, 1.0, v151
	v_rcp_f32_e32 v150, v150
	v_rcp_f32_e32 v151, v151
	s_nop 0
	v_pk_mul_f32 v[166:167], v[20:21], v[150:151]
	v_cvt_pk_bf16_f32 v150, v154, v155
	v_cvt_pk_bf16_f32 v151, v156, v157
	v_cvt_pk_bf16_f32 v153, v166, v167
	global_store_dwordx4 v[158:159], v[150:153], off offset:256
	s_nop 1
	v_lshlrev_b32_e32 v150, 16, v146
	v_and_b32_e32 v146, 0xffff0000, v146
	v_mul_f32_e32 v146, 0xbfb8aa3b, v146
	v_exp_f32_e32 v146, v146
	v_mul_f32_e32 v150, 0xbfb8aa3b, v150
	v_exp_f32_e32 v150, v150
	v_add_f32_e32 v146, 1.0, v146
	v_rcp_f32_e32 v151, v146
	v_lshlrev_b32_e32 v146, 16, v147
	v_and_b32_e32 v147, 0xffff0000, v147
	v_mul_f32_e32 v146, 0xbfb8aa3b, v146
	v_mul_f32_e32 v147, 0xbfb8aa3b, v147
	v_exp_f32_e32 v146, v146
	v_exp_f32_e32 v147, v147
	v_add_f32_e32 v150, 1.0, v150
	v_rcp_f32_e32 v150, v150
	v_add_f32_e32 v146, 1.0, v146
	v_add_f32_e32 v147, 1.0, v147
	v_rcp_f32_e32 v146, v146
	v_rcp_f32_e32 v147, v147
	v_pk_mul_f32 v[150:151], v[50:51], v[150:151]
	v_pk_mul_f32 v[152:153], v[52:53], v[146:147]
	v_lshlrev_b32_e32 v146, 16, v148
	v_and_b32_e32 v147, 0xffff0000, v148
	v_mul_f32_e32 v146, 0xbfb8aa3b, v146
	v_mul_f32_e32 v147, 0xbfb8aa3b, v147
	v_exp_f32_e32 v146, v146
	v_exp_f32_e32 v147, v147
	v_add_f32_e32 v146, 1.0, v146
	v_add_f32_e32 v147, 1.0, v147
	v_rcp_f32_e32 v146, v146
	v_rcp_f32_e32 v147, v147
	s_nop 0
	v_pk_mul_f32 v[154:155], v[46:47], v[146:147]
	v_lshlrev_b32_e32 v146, 16, v149
	v_and_b32_e32 v147, 0xffff0000, v149
	v_mul_f32_e32 v146, 0xbfb8aa3b, v146
	v_mul_f32_e32 v147, 0xbfb8aa3b, v147
	v_exp_f32_e32 v146, v146
	v_exp_f32_e32 v147, v147
	v_cvt_pk_bf16_f32 v148, v154, v155
	v_add_f32_e32 v146, 1.0, v146
	v_add_f32_e32 v147, 1.0, v147
	v_rcp_f32_e32 v146, v146
	v_rcp_f32_e32 v147, v147
	s_nop 0
	v_pk_mul_f32 v[156:157], v[48:49], v[146:147]
	v_cvt_pk_bf16_f32 v146, v150, v151
	v_mad_i64_i32 v[150:151], s[0:1], v165, s78, v[162:163]
	v_cvt_pk_bf16_f32 v147, v152, v153
	v_cvt_pk_bf16_f32 v149, v156, v157
	v_lshl_add_u64 v[150:151], v[150:151], 0, v[186:187]
	global_store_dwordx4 v[150:151], v[146:149], off
	s_nop 1
	v_lshlrev_b32_e32 v146, 16, v142
	v_and_b32_e32 v142, 0xffff0000, v142
	v_mul_f32_e32 v142, 0xbfb8aa3b, v142
	v_exp_f32_e32 v142, v142
	v_mul_f32_e32 v146, 0xbfb8aa3b, v146
	v_exp_f32_e32 v146, v146
	v_add_f32_e32 v142, 1.0, v142
	v_rcp_f32_e32 v147, v142
	v_lshlrev_b32_e32 v142, 16, v143
	v_and_b32_e32 v143, 0xffff0000, v143
	v_mul_f32_e32 v142, 0xbfb8aa3b, v142
	v_mul_f32_e32 v143, 0xbfb8aa3b, v143
	v_exp_f32_e32 v142, v142
	v_exp_f32_e32 v143, v143
	v_add_f32_e32 v146, 1.0, v146
	v_rcp_f32_e32 v146, v146
	v_add_f32_e32 v142, 1.0, v142
	v_add_f32_e32 v143, 1.0, v143
	v_rcp_f32_e32 v142, v142
	v_rcp_f32_e32 v143, v143
	v_pk_mul_f32 v[146:147], v[14:15], v[146:147]
	v_pk_mul_f32 v[148:149], v[16:17], v[142:143]
	v_lshlrev_b32_e32 v142, 16, v144
	v_and_b32_e32 v143, 0xffff0000, v144
	v_mul_f32_e32 v142, 0xbfb8aa3b, v142
	v_mul_f32_e32 v143, 0xbfb8aa3b, v143
	v_exp_f32_e32 v142, v142
	v_exp_f32_e32 v143, v143
	v_add_f32_e32 v142, 1.0, v142
	v_add_f32_e32 v143, 1.0, v143
	v_rcp_f32_e32 v142, v142
	v_rcp_f32_e32 v143, v143
	s_nop 0
	v_pk_mul_f32 v[152:153], v[10:11], v[142:143]
	v_lshlrev_b32_e32 v142, 16, v145
	v_and_b32_e32 v143, 0xffff0000, v145
	v_mul_f32_e32 v142, 0xbfb8aa3b, v142
	v_mul_f32_e32 v143, 0xbfb8aa3b, v143
	v_exp_f32_e32 v142, v142
	v_exp_f32_e32 v143, v143
	v_cvt_pk_bf16_f32 v144, v152, v153
	v_add_f32_e32 v142, 1.0, v142
	v_add_f32_e32 v143, 1.0, v143
	v_rcp_f32_e32 v142, v142
	v_rcp_f32_e32 v143, v143
	s_nop 0
	v_pk_mul_f32 v[154:155], v[12:13], v[142:143]
	v_cvt_pk_bf16_f32 v142, v146, v147
	v_cvt_pk_bf16_f32 v143, v148, v149
	v_cvt_pk_bf16_f32 v145, v154, v155
	global_store_dwordx4 v[150:151], v[142:145], off offset:256
	s_nop 1
	v_lshlrev_b32_e32 v142, 16, v138
	v_and_b32_e32 v138, 0xffff0000, v138
	v_mul_f32_e32 v138, 0xbfb8aa3b, v138
	v_exp_f32_e32 v138, v138
	v_mul_f32_e32 v142, 0xbfb8aa3b, v142
	v_exp_f32_e32 v142, v142
	v_add_f32_e32 v138, 1.0, v138
	v_rcp_f32_e32 v143, v138
	v_lshlrev_b32_e32 v138, 16, v139
	v_and_b32_e32 v139, 0xffff0000, v139
	v_mul_f32_e32 v138, 0xbfb8aa3b, v138
	v_mul_f32_e32 v139, 0xbfb8aa3b, v139
	v_exp_f32_e32 v138, v138
	v_exp_f32_e32 v139, v139
	v_add_f32_e32 v142, 1.0, v142
	v_rcp_f32_e32 v142, v142
	v_add_f32_e32 v138, 1.0, v138
	v_add_f32_e32 v139, 1.0, v139
	v_rcp_f32_e32 v138, v138
	v_rcp_f32_e32 v139, v139
	v_pk_mul_f32 v[142:143], v[42:43], v[142:143]
	v_pk_mul_f32 v[144:145], v[44:45], v[138:139]
	v_lshlrev_b32_e32 v138, 16, v140
	v_and_b32_e32 v139, 0xffff0000, v140
	v_mul_f32_e32 v138, 0xbfb8aa3b, v138
	v_mul_f32_e32 v139, 0xbfb8aa3b, v139
	v_exp_f32_e32 v138, v138
	v_exp_f32_e32 v139, v139
	v_add_f32_e32 v138, 1.0, v138
	v_add_f32_e32 v139, 1.0, v139
	v_rcp_f32_e32 v138, v138
	v_rcp_f32_e32 v139, v139
	s_nop 0
	v_pk_mul_f32 v[146:147], v[38:39], v[138:139]
	v_lshlrev_b32_e32 v138, 16, v141
	v_and_b32_e32 v139, 0xffff0000, v141
	v_mul_f32_e32 v138, 0xbfb8aa3b, v138
	v_mul_f32_e32 v139, 0xbfb8aa3b, v139
	v_exp_f32_e32 v138, v138
	v_exp_f32_e32 v139, v139
	v_cvt_pk_bf16_f32 v140, v146, v147
	v_add_f32_e32 v138, 1.0, v138
	v_add_f32_e32 v139, 1.0, v139
	v_rcp_f32_e32 v138, v138
	v_rcp_f32_e32 v139, v139
	s_nop 0
	v_pk_mul_f32 v[148:149], v[40:41], v[138:139]
	v_cvt_pk_bf16_f32 v138, v142, v143
	v_mad_i64_i32 v[142:143], s[0:1], v164, s78, v[162:163]
	v_cvt_pk_bf16_f32 v139, v144, v145
	v_cvt_pk_bf16_f32 v141, v148, v149
	v_lshl_add_u64 v[142:143], v[142:143], 0, v[186:187]
	global_store_dwordx4 v[142:143], v[138:141], off
	s_nop 1
	v_lshlrev_b32_e32 v138, 16, v134
	v_and_b32_e32 v134, 0xffff0000, v134
	v_mul_f32_e32 v134, 0xbfb8aa3b, v134
	v_exp_f32_e32 v134, v134
	v_mul_f32_e32 v138, 0xbfb8aa3b, v138
	v_exp_f32_e32 v138, v138
	v_add_f32_e32 v134, 1.0, v134
	v_rcp_f32_e32 v139, v134
	v_lshlrev_b32_e32 v134, 16, v135
	v_and_b32_e32 v135, 0xffff0000, v135
	v_mul_f32_e32 v134, 0xbfb8aa3b, v134
	v_mul_f32_e32 v135, 0xbfb8aa3b, v135
	v_exp_f32_e32 v134, v134
	v_exp_f32_e32 v135, v135
	v_add_f32_e32 v138, 1.0, v138
	v_rcp_f32_e32 v138, v138
	v_add_f32_e32 v134, 1.0, v134
	v_add_f32_e32 v135, 1.0, v135
	v_rcp_f32_e32 v134, v134
	v_rcp_f32_e32 v135, v135
	v_pk_mul_f32 v[138:139], v[6:7], v[138:139]
	v_pk_mul_f32 v[140:141], v[8:9], v[134:135]
	v_lshlrev_b32_e32 v134, 16, v136
	v_and_b32_e32 v135, 0xffff0000, v136
	v_mul_f32_e32 v134, 0xbfb8aa3b, v134
	v_mul_f32_e32 v135, 0xbfb8aa3b, v135
	v_exp_f32_e32 v134, v134
	v_exp_f32_e32 v135, v135
	v_add_f32_e32 v134, 1.0, v134
	v_add_f32_e32 v135, 1.0, v135
	v_rcp_f32_e32 v134, v134
	v_rcp_f32_e32 v135, v135
	s_nop 0
	v_pk_mul_f32 v[144:145], v[2:3], v[134:135]
	v_lshlrev_b32_e32 v134, 16, v137
	v_and_b32_e32 v135, 0xffff0000, v137
	v_mul_f32_e32 v134, 0xbfb8aa3b, v134
	v_mul_f32_e32 v135, 0xbfb8aa3b, v135
	v_exp_f32_e32 v134, v134
	v_exp_f32_e32 v135, v135
	v_cvt_pk_bf16_f32 v136, v144, v145
	v_add_f32_e32 v134, 1.0, v134
	v_add_f32_e32 v135, 1.0, v135
	v_rcp_f32_e32 v134, v134
	v_rcp_f32_e32 v135, v135
	s_nop 0
	v_pk_mul_f32 v[146:147], v[4:5], v[134:135]
	v_cvt_pk_bf16_f32 v134, v138, v139
	v_cvt_pk_bf16_f32 v135, v140, v141
	v_cvt_pk_bf16_f32 v137, v146, v147
	global_store_dwordx4 v[142:143], v[134:137], off offset:256
	s_cbranch_execnz .LBB0_891

.LBB0_965:
	s_add_u32 s36, s34, 0x100
	s_addc_u32 s37, s35, 0
	s_add_i32 s0, 0, 0x10000
	s_cmp_eq_u32 s31, 12
	s_cselect_b32 s47, s25, s37
	s_cselect_b32 s46, s24, s36
	s_cselect_b32 s43, s18, s29
	s_cselect_b32 s42, s19, s23
	s_add_i32 m0, s54, 0xc000
	ds_read_b128 v[148:151], v224
	ds_read_b128 v[152:155], v224 offset:1024
	ds_read_b128 v[178:181], v224 offset:2048
	ds_read_b128 v[182:185], v224 offset:3072
	ds_read_b128 v[186:189], v224 offset:4096
	ds_read_b128 v[190:193], v224 offset:5120
	ds_read_b128 v[194:197], v224 offset:6144
	ds_read_b128 v[198:201], v224 offset:7168
	global_load_lds_dwordx4 v174, s[34:35]
	v_lshl_add_u64 v[166:167], s[34:35], 0, v[176:177]
	s_add_i32 m0, s54, 0xe000
	s_nop 0
	global_load_lds_dwordx4 v[166:167], off
	s_waitcnt vmcnt(10) lgkmcnt(8)
	s_setprio 1
	s_barrier
	s_waitcnt lgkmcnt(0)
	v_mfma_f32_16x16x32_bf16 v[136:139], v[100:103], v[148:151], v[136:139]
	v_mfma_f32_16x16x32_bf16 v[132:135], v[140:143], v[148:151], v[132:135]
	v_mfma_f32_16x16x32_bf16 v[128:131], v[100:103], v[178:181], v[128:131]
	v_mfma_f32_16x16x32_bf16 v[124:127], v[140:143], v[178:181], v[124:127]
	v_mfma_f32_16x16x32_bf16 v[120:123], v[100:103], v[186:189], v[120:123]
	v_mfma_f32_16x16x32_bf16 v[116:119], v[140:143], v[186:189], v[116:119]
	v_mfma_f32_16x16x32_bf16 v[112:115], v[100:103], v[194:197], v[112:115]
	v_mfma_f32_16x16x32_bf16 v[108:111], v[140:143], v[194:197], v[108:111]
	v_mfma_f32_16x16x32_bf16 v[136:139], v[104:107], v[152:155], v[136:139]
	v_mfma_f32_16x16x32_bf16 v[132:135], v[144:147], v[152:155], v[132:135]
	v_mfma_f32_16x16x32_bf16 v[128:131], v[104:107], v[182:185], v[128:131]
	v_mfma_f32_16x16x32_bf16 v[124:127], v[144:147], v[182:185], v[124:127]
	v_mfma_f32_16x16x32_bf16 v[120:123], v[104:107], v[190:193], v[120:123]
	v_mfma_f32_16x16x32_bf16 v[116:119], v[144:147], v[190:193], v[116:119]
	v_mfma_f32_16x16x32_bf16 v[112:115], v[104:107], v[198:201], v[112:115]
	v_mfma_f32_16x16x32_bf16 v[108:111], v[144:147], v[198:201], v[108:111]
	s_barrier
	s_setprio 0
	s_add_i32 s34, 0, 0x14000
	v_add_u32_e32 v166, s34, v222
	s_add_i32 s0, s0, s53
	ds_read_b128 v[202:205], v166
	ds_read_b128 v[206:209], v166 offset:1024
	ds_read_b128 v[210:213], v166 offset:2048
	ds_read_b128 v[214:217], v166 offset:3072
	v_lshl_add_u64 v[166:167], s[42:43], 0, v[26:27]
	s_mov_b32 m0, s0
	v_lshl_add_u64 v[168:169], s[42:43], 0, v[160:161]
	global_load_lds_dwordx4 v[166:167], off
	s_add_i32 m0, s0, 0x2000
	s_nop 0
	global_load_lds_dwordx4 v[168:169], off
	s_waitcnt vmcnt(10)
	s_setprio 1
	s_barrier
	s_waitcnt lgkmcnt(0)
	v_mfma_f32_16x16x32_bf16 v[64:67], v[202:205], v[148:151], v[64:67]
	v_mfma_f32_16x16x32_bf16 v[60:63], v[210:213], v[148:151], v[60:63]
	v_mfma_f32_16x16x32_bf16 v[56:59], v[202:205], v[178:181], v[56:59]
	v_mfma_f32_16x16x32_bf16 v[52:55], v[210:213], v[178:181], v[52:55]
	v_mfma_f32_16x16x32_bf16 v[48:51], v[202:205], v[186:189], v[48:51]
	v_mfma_f32_16x16x32_bf16 v[44:47], v[210:213], v[186:189], v[44:47]
	v_mfma_f32_16x16x32_bf16 v[40:43], v[202:205], v[194:197], v[40:43]
	v_mfma_f32_16x16x32_bf16 v[36:39], v[210:213], v[194:197], v[36:39]
	v_mfma_f32_16x16x32_bf16 v[64:67], v[206:209], v[152:155], v[64:67]
	v_mfma_f32_16x16x32_bf16 v[60:63], v[214:217], v[152:155], v[60:63]
	v_mfma_f32_16x16x32_bf16 v[56:59], v[206:209], v[182:185], v[56:59]
	v_mfma_f32_16x16x32_bf16 v[52:55], v[214:217], v[182:185], v[52:55]
	v_mfma_f32_16x16x32_bf16 v[48:51], v[206:209], v[190:193], v[48:51]
	v_mfma_f32_16x16x32_bf16 v[44:47], v[214:217], v[190:193], v[44:47]
	v_mfma_f32_16x16x32_bf16 v[40:43], v[206:209], v[198:201], v[40:43]
	v_mfma_f32_16x16x32_bf16 v[36:39], v[214:217], v[198:201], v[36:39]
	s_barrier
	s_setprio 0
	s_mov_b32 m0, s54
	v_lshl_add_u64 v[218:219], s[46:47], 0, v[156:157]
	ds_read_b128 v[148:151], v224 offset:16384
	ds_read_b128 v[152:155], v224 offset:17408
	ds_read_b128 v[178:181], v224 offset:18432
	ds_read_b128 v[182:185], v224 offset:19456
	ds_read_b128 v[186:189], v224 offset:20480
	ds_read_b128 v[190:193], v224 offset:21504
	ds_read_b128 v[194:197], v224 offset:22528
	ds_read_b128 v[198:201], v224 offset:23552
	global_load_lds_dwordx4 v[218:219], off
	v_lshl_add_u64 v[220:221], s[46:47], 0, v[158:159]
	s_mov_b32 m0, s55
	s_nop 0
	global_load_lds_dwordx4 v[220:221], off
	s_waitcnt vmcnt(10)
	s_setprio 1
	s_barrier
	s_waitcnt lgkmcnt(0)
	v_mfma_f32_16x16x32_bf16 v[96:99], v[100:103], v[148:151], v[96:99]
	v_mfma_f32_16x16x32_bf16 v[92:95], v[140:143], v[148:151], v[92:95]
	v_mfma_f32_16x16x32_bf16 v[88:91], v[100:103], v[178:181], v[88:91]
	v_mfma_f32_16x16x32_bf16 v[84:87], v[140:143], v[178:181], v[84:87]
	v_mfma_f32_16x16x32_bf16 v[80:83], v[100:103], v[186:189], v[80:83]
	v_mfma_f32_16x16x32_bf16 v[76:79], v[140:143], v[186:189], v[76:79]
	v_mfma_f32_16x16x32_bf16 v[72:75], v[100:103], v[194:197], v[72:75]
	v_mfma_f32_16x16x32_bf16 v[68:71], v[140:143], v[194:197], v[68:71]
	v_mfma_f32_16x16x32_bf16 v[96:99], v[104:107], v[152:155], v[96:99]
	v_mfma_f32_16x16x32_bf16 v[92:95], v[144:147], v[152:155], v[92:95]
	v_mfma_f32_16x16x32_bf16 v[88:91], v[104:107], v[182:185], v[88:91]
	v_mfma_f32_16x16x32_bf16 v[84:87], v[144:147], v[182:185], v[84:87]
	v_mfma_f32_16x16x32_bf16 v[80:83], v[104:107], v[190:193], v[80:83]
	v_mfma_f32_16x16x32_bf16 v[76:79], v[144:147], v[190:193], v[76:79]
	v_mfma_f32_16x16x32_bf16 v[72:75], v[104:107], v[198:201], v[72:75]
	v_mfma_f32_16x16x32_bf16 v[68:71], v[144:147], v[198:201], v[68:71]
	s_barrier
	s_setprio 0
	s_add_u32 s0, s42, 0x40000
	s_addc_u32 s1, s43, 0
	s_add_i32 s34, s34, s53
	s_mov_b32 m0, s34
	s_nop 0
	global_load_lds_dwordx4 v26, s[0:1]
	s_add_i32 m0, s34, 0x2000
	s_nop 0
	global_load_lds_dwordx4 v160, s[0:1]
	v_add_u32_e32 v144, 0x18000, v222
	ds_read_b128 v[100:103], v144
	ds_read_b128 v[104:107], v144 offset:1024
	ds_read_b128 v[140:143], v144 offset:2048
	ds_read_b128 v[144:147], v144 offset:3072
	s_waitcnt vmcnt(10)
	s_setprio 1
	s_barrier
	v_mfma_f32_16x16x32_bf16 v[32:35], v[202:205], v[148:151], v[32:35]
	v_mfma_f32_16x16x32_bf16 v[28:31], v[210:213], v[148:151], v[28:31]
	v_mfma_f32_16x16x32_bf16 v[22:25], v[202:205], v[178:181], v[22:25]
	v_mfma_f32_16x16x32_bf16 v[18:21], v[210:213], v[178:181], v[18:21]
	v_mfma_f32_16x16x32_bf16 v[14:17], v[202:205], v[186:189], v[14:17]
	v_mfma_f32_16x16x32_bf16 v[10:13], v[210:213], v[186:189], v[10:13]
	v_mfma_f32_16x16x32_bf16 v[6:9], v[202:205], v[194:197], v[6:9]
	v_mfma_f32_16x16x32_bf16 v[2:5], v[210:213], v[194:197], v[2:5]
	v_mfma_f32_16x16x32_bf16 v[32:35], v[206:209], v[152:155], v[32:35]
	v_mfma_f32_16x16x32_bf16 v[28:31], v[214:217], v[152:155], v[28:31]
	v_mfma_f32_16x16x32_bf16 v[22:25], v[206:209], v[182:185], v[22:25]
	v_mfma_f32_16x16x32_bf16 v[18:21], v[214:217], v[182:185], v[18:21]
	v_mfma_f32_16x16x32_bf16 v[14:17], v[206:209], v[190:193], v[14:17]
	v_mfma_f32_16x16x32_bf16 v[10:13], v[214:217], v[190:193], v[10:13]
	v_mfma_f32_16x16x32_bf16 v[6:9], v[206:209], v[198:201], v[6:9]
	v_mfma_f32_16x16x32_bf16 v[2:5], v[214:217], v[198:201], v[2:5]
	s_barrier
	s_setprio 0
	s_add_i32 s34, 0, 0x18000
	s_add_u32 s0, s46, 0x140000
	s_addc_u32 s1, s47, 0
	s_mov_b32 m0, s56
	ds_read_b128 v[148:151], v224 offset:32768
	ds_read_b128 v[152:155], v224 offset:33792
	ds_read_b128 v[178:181], v224 offset:34816
	ds_read_b128 v[182:185], v224 offset:35840
	ds_read_b128 v[186:189], v224 offset:36864
	ds_read_b128 v[190:193], v224 offset:37888
	ds_read_b128 v[194:197], v224 offset:38912
	ds_read_b128 v[198:201], v224 offset:39936
	global_load_lds_dwordx4 v156, s[0:1]
	s_mov_b32 m0, s57
	s_nop 0
	global_load_lds_dwordx4 v158, s[0:1]
	s_waitcnt vmcnt(10) lgkmcnt(8)
	s_setprio 1
	s_barrier
	s_waitcnt lgkmcnt(0)
	v_mfma_f32_16x16x32_bf16 v[136:139], v[100:103], v[148:151], v[136:139]
	v_mfma_f32_16x16x32_bf16 v[132:135], v[140:143], v[148:151], v[132:135]
	v_mfma_f32_16x16x32_bf16 v[128:131], v[100:103], v[178:181], v[128:131]
	v_mfma_f32_16x16x32_bf16 v[124:127], v[140:143], v[178:181], v[124:127]
	v_mfma_f32_16x16x32_bf16 v[120:123], v[100:103], v[186:189], v[120:123]
	v_mfma_f32_16x16x32_bf16 v[116:119], v[140:143], v[186:189], v[116:119]
	v_mfma_f32_16x16x32_bf16 v[112:115], v[100:103], v[194:197], v[112:115]
	v_mfma_f32_16x16x32_bf16 v[108:111], v[140:143], v[194:197], v[108:111]
	v_mfma_f32_16x16x32_bf16 v[136:139], v[104:107], v[152:155], v[136:139]
	v_mfma_f32_16x16x32_bf16 v[132:135], v[144:147], v[152:155], v[132:135]
	v_mfma_f32_16x16x32_bf16 v[128:131], v[104:107], v[182:185], v[128:131]
	v_mfma_f32_16x16x32_bf16 v[124:127], v[144:147], v[182:185], v[124:127]
	v_mfma_f32_16x16x32_bf16 v[120:123], v[104:107], v[190:193], v[120:123]
	v_mfma_f32_16x16x32_bf16 v[116:119], v[144:147], v[190:193], v[116:119]
	v_mfma_f32_16x16x32_bf16 v[112:115], v[104:107], v[198:201], v[112:115]
	v_mfma_f32_16x16x32_bf16 v[108:111], v[144:147], v[198:201], v[108:111]
	s_barrier
	s_setprio 0
	s_add_i32 s35, 0, 0x1c000
	s_add_i32 s0, s34, s53
	v_add_u32_e32 v214, s35, v222
	v_lshl_add_u64 v[166:167], v[166:167], 0, s[12:13]
	s_mov_b32 m0, s0
	ds_read_b128 v[202:205], v214
	ds_read_b128 v[206:209], v214 offset:1024
	ds_read_b128 v[210:213], v214 offset:2048
	ds_read_b128 v[214:217], v214 offset:3072
	global_load_lds_dwordx4 v[166:167], off
	v_lshl_add_u64 v[166:167], v[168:169], 0, s[12:13]
	s_add_i32 m0, s0, 0x2000
	s_nop 0
	global_load_lds_dwordx4 v[166:167], off
	s_waitcnt vmcnt(10)
	s_setprio 1
	s_barrier
	s_waitcnt lgkmcnt(0)
	v_mfma_f32_16x16x32_bf16 v[64:67], v[202:205], v[148:151], v[64:67]
	v_mfma_f32_16x16x32_bf16 v[60:63], v[210:213], v[148:151], v[60:63]
	v_mfma_f32_16x16x32_bf16 v[56:59], v[202:205], v[178:181], v[56:59]
	v_mfma_f32_16x16x32_bf16 v[52:55], v[210:213], v[178:181], v[52:55]
	v_mfma_f32_16x16x32_bf16 v[48:51], v[202:205], v[186:189], v[48:51]
	v_mfma_f32_16x16x32_bf16 v[44:47], v[210:213], v[186:189], v[44:47]
	v_mfma_f32_16x16x32_bf16 v[40:43], v[202:205], v[194:197], v[40:43]
	v_mfma_f32_16x16x32_bf16 v[36:39], v[210:213], v[194:197], v[36:39]
	v_mfma_f32_16x16x32_bf16 v[64:67], v[206:209], v[152:155], v[64:67]
	v_mfma_f32_16x16x32_bf16 v[60:63], v[214:217], v[152:155], v[60:63]
	v_mfma_f32_16x16x32_bf16 v[56:59], v[206:209], v[182:185], v[56:59]
	v_mfma_f32_16x16x32_bf16 v[52:55], v[214:217], v[182:185], v[52:55]
	v_mfma_f32_16x16x32_bf16 v[48:51], v[206:209], v[190:193], v[48:51]
	v_mfma_f32_16x16x32_bf16 v[44:47], v[214:217], v[190:193], v[44:47]
	v_mfma_f32_16x16x32_bf16 v[40:43], v[206:209], v[198:201], v[40:43]
	v_mfma_f32_16x16x32_bf16 v[36:39], v[214:217], v[198:201], v[36:39]
	s_barrier
	s_setprio 0
	s_mov_b32 m0, s81
	v_lshl_add_u64 v[166:167], v[218:219], 0, s[12:13]
	ds_read_b128 v[148:151], v224 offset:49152
	ds_read_b128 v[152:155], v224 offset:50176
	ds_read_b128 v[178:181], v224 offset:51200
	ds_read_b128 v[182:185], v224 offset:52224
	ds_read_b128 v[186:189], v224 offset:53248
	ds_read_b128 v[190:193], v224 offset:54272
	ds_read_b128 v[194:197], v224 offset:55296
	ds_read_b128 v[198:201], v224 offset:56320
	global_load_lds_dwordx4 v[166:167], off
	v_lshl_add_u64 v[166:167], v[220:221], 0, s[12:13]
	s_mov_b32 m0, s17
	s_nop 0
	global_load_lds_dwordx4 v[166:167], off
	s_waitcnt vmcnt(10)
	s_setprio 1
	s_barrier
	s_waitcnt lgkmcnt(0)
	v_mfma_f32_16x16x32_bf16 v[96:99], v[100:103], v[148:151], v[96:99]
	v_mfma_f32_16x16x32_bf16 v[92:95], v[140:143], v[148:151], v[92:95]
	v_mfma_f32_16x16x32_bf16 v[88:91], v[100:103], v[178:181], v[88:91]
	v_mfma_f32_16x16x32_bf16 v[84:87], v[140:143], v[178:181], v[84:87]
	v_mfma_f32_16x16x32_bf16 v[80:83], v[100:103], v[186:189], v[80:83]
	v_mfma_f32_16x16x32_bf16 v[76:79], v[140:143], v[186:189], v[76:79]
	v_mfma_f32_16x16x32_bf16 v[72:75], v[100:103], v[194:197], v[72:75]
	v_mfma_f32_16x16x32_bf16 v[68:71], v[140:143], v[194:197], v[68:71]
	v_mfma_f32_16x16x32_bf16 v[96:99], v[104:107], v[152:155], v[96:99]
	v_mfma_f32_16x16x32_bf16 v[92:95], v[144:147], v[152:155], v[92:95]
	v_mfma_f32_16x16x32_bf16 v[88:91], v[104:107], v[182:185], v[88:91]
	v_mfma_f32_16x16x32_bf16 v[84:87], v[144:147], v[182:185], v[84:87]
	v_mfma_f32_16x16x32_bf16 v[80:83], v[104:107], v[190:193], v[80:83]
	v_mfma_f32_16x16x32_bf16 v[76:79], v[144:147], v[190:193], v[76:79]
	v_mfma_f32_16x16x32_bf16 v[72:75], v[104:107], v[198:201], v[72:75]
	v_mfma_f32_16x16x32_bf16 v[68:71], v[144:147], v[198:201], v[68:71]
	s_barrier
	s_setprio 0
	s_add_u32 s0, s42, 0x40080
	s_addc_u32 s1, s43, 0
	s_add_i32 s34, s35, s53
	s_mov_b32 m0, s34
	s_nop 0
	global_load_lds_dwordx4 v26, s[0:1]
	s_add_i32 m0, s34, 0x2000
	s_nop 0
	global_load_lds_dwordx4 v160, s[0:1]
	v_add_u32_e32 v144, 0x10000, v222
	ds_read_b128 v[100:103], v144
	ds_read_b128 v[104:107], v144 offset:1024
	ds_read_b128 v[140:143], v144 offset:2048
	ds_read_b128 v[144:147], v144 offset:3072
	s_add_i32 s31, s31, 2
	s_add_u32 s23, s23, 0x100
	s_addc_u32 s29, s29, 0
	s_cmp_gt_u32 s31, 13
	s_mov_b64 s[34:35], s[36:37]
	s_waitcnt vmcnt(10)
	s_setprio 1
	s_barrier
	v_mfma_f32_16x16x32_bf16 v[32:35], v[202:205], v[148:151], v[32:35]
	v_mfma_f32_16x16x32_bf16 v[28:31], v[210:213], v[148:151], v[28:31]
	v_mfma_f32_16x16x32_bf16 v[22:25], v[202:205], v[178:181], v[22:25]
	v_mfma_f32_16x16x32_bf16 v[18:21], v[210:213], v[178:181], v[18:21]
	v_mfma_f32_16x16x32_bf16 v[14:17], v[202:205], v[186:189], v[14:17]
	v_mfma_f32_16x16x32_bf16 v[10:13], v[210:213], v[186:189], v[10:13]
	v_mfma_f32_16x16x32_bf16 v[6:9], v[202:205], v[194:197], v[6:9]
	v_mfma_f32_16x16x32_bf16 v[2:5], v[210:213], v[194:197], v[2:5]
	v_mfma_f32_16x16x32_bf16 v[32:35], v[206:209], v[152:155], v[32:35]
	v_mfma_f32_16x16x32_bf16 v[28:31], v[214:217], v[152:155], v[28:31]
	v_mfma_f32_16x16x32_bf16 v[22:25], v[206:209], v[182:185], v[22:25]
	v_mfma_f32_16x16x32_bf16 v[18:21], v[214:217], v[182:185], v[18:21]
	v_mfma_f32_16x16x32_bf16 v[14:17], v[206:209], v[190:193], v[14:17]
	v_mfma_f32_16x16x32_bf16 v[10:13], v[214:217], v[190:193], v[10:13]
	v_mfma_f32_16x16x32_bf16 v[6:9], v[206:209], v[198:201], v[6:9]
	v_mfma_f32_16x16x32_bf16 v[2:5], v[214:217], v[198:201], v[2:5]
	s_barrier
	s_setprio 0
	s_cbranch_scc0 .LBB0_965
	s_waitcnt lgkmcnt(0)
	s_min_i32 s0, s28, 0x100
	s_ashr_i32 s0, s0, 5
	s_ashr_i32 s1, s0, 31
	s_add_i32 s18, s28, 0xffffff00
	s_cmpk_lt_i32 s28, 0x100
	s_cselect_b32 s18, s28, s18
	s_cselect_b32 s23, 0, s59
	s_cselect_b32 s29, 0, s58
	s_ashr_i32 s19, s18, 31
	s_lshl_b64 s[18:19], s[18:19], 19
	v_lshl_or_b32 v148, s30, 8, v223
	s_add_u32 s30, s44, s29
	s_addc_u32 s31, s45, s23
	s_ashr_i32 s29, s28, 31
	v_lshl_add_u64 v[100:101], s[18:19], 0, v[162:163]
	s_lshl_b64 s[18:19], s[28:29], 19
	v_lshl_add_u64 v[152:153], v[164:165], 0, s[18:19]
	s_lshl_b64 s[28:29], s[28:29], 10
	s_mul_i32 s18, s0, 0x9000
	s_mul_hi_i32 s19, s0, 0x9000
	s_add_u32 s18, s68, s18
	s_addc_u32 s19, s69, s19
	s_lshl_b64 s[0:1], s[0:1], 12
	v_ashrrev_i32_e32 v149, 31, v148
	s_add_u32 s0, s72, s0
	v_lshlrev_b64 v[154:155], 2, v[148:149]
	s_addc_u32 s1, s73, s1
	v_lshl_add_u64 v[150:151], v[100:101], 0, v[148:149]
	v_lshl_add_u64 v[104:105], s[18:19], 0, v[154:155]
	v_lshlrev_b64 v[168:169], 1, v[148:149]
	v_lshl_add_u64 v[180:181], s[0:1], 0, v[154:155]
	v_lshl_add_u64 v[166:167], v[100:101], 1, s[30:31]
	global_load_dwordx4 v[140:143], v[104:105], off offset:16
	global_load_dwordx4 v[144:147], v[104:105], off
	global_load_dwordx4 v[100:103], v[104:105], off offset:528
	s_nop 0
	global_load_dwordx4 v[104:107], v[104:105], off offset:512
	v_lshl_add_u64 v[196:197], v[150:151], 1, s[30:31]
	v_lshl_add_u64 v[178:179], v[152:153], 0, v[168:169]
	global_load_dwordx4 v[148:151], v[180:181], off offset:16
	global_load_dwordx4 v[152:155], v[180:181], off
	global_load_dwordx4 v[190:193], v[196:197], off offset:2048
	v_add_co_u32_e32 v210, vcc, s65, v196
	s_mov_b32 s1, 0x20000
	s_nop 0
	v_addc_co_u32_e32 v211, vcc, 0, v197, vcc
	global_load_dwordx4 v[198:201], v[210:211], off offset:2048
	v_add_co_u32_e32 v184, vcc, s1, v196
	s_mov_b32 s18, 0x30000
	s_nop 0
	v_addc_co_u32_e32 v185, vcc, 0, v197, vcc
	global_load_dwordx4 v[202:205], v[184:185], off offset:2048
	v_add_co_u32_e32 v188, vcc, s18, v196
	v_lshl_add_u64 v[182:183], v[166:167], 0, v[168:169]
	s_nop 0
	v_addc_co_u32_e32 v189, vcc, 0, v197, vcc
	global_load_dwordx4 v[206:209], v[188:189], off offset:2048
	s_mov_b32 s0, 0x8000
	s_mov_b32 s19, 0x80000
	s_mov_b32 s23, 0x90000
	s_waitcnt vmcnt(0)
	v_lshlrev_b32_e32 v166, 16, v190
	v_and_b32_e32 v167, 0xffff0000, v190
	v_lshlrev_b32_e32 v168, 16, v191
	v_and_b32_e32 v169, 0xffff0000, v191
	v_lshlrev_b32_e32 v186, 16, v192
	v_and_b32_e32 v187, 0xffff0000, v192
	v_lshlrev_b32_e32 v190, 16, v193
	v_and_b32_e32 v191, 0xffff0000, v193
	v_pk_fma_f32 v[138:139], v[138:139], v[146:147], v[168:169]
	v_pk_fma_f32 v[136:137], v[136:137], v[144:145], v[166:167]
	v_pk_fma_f32 v[134:135], v[134:135], v[142:143], v[190:191]
	v_pk_fma_f32 v[132:133], v[132:133], v[140:141], v[186:187]
	v_cvt_pk_bf16_f32 v190, v136, v137
	v_cvt_pk_bf16_f32 v191, v138, v139
	v_cvt_pk_bf16_f32 v192, v132, v133
	v_cvt_pk_bf16_f32 v193, v134, v135
	v_lshlrev_b32_e32 v138, 16, v190
	v_and_b32_e32 v139, 0xffff0000, v190
	v_lshlrev_b32_e32 v136, 16, v191
	v_and_b32_e32 v137, 0xffff0000, v191
	v_lshlrev_b32_e32 v134, 16, v192
	v_and_b32_e32 v135, 0xffff0000, v192
	v_lshlrev_b32_e32 v132, 16, v193
	v_and_b32_e32 v133, 0xffff0000, v193
	v_lshlrev_b32_e32 v212, 16, v200
	v_and_b32_e32 v213, 0xffff0000, v200
	v_lshlrev_b32_e32 v200, 16, v201
	v_and_b32_e32 v201, 0xffff0000, v201
	global_store_dwordx4 v[182:183], v[190:193], off offset:2048
	v_pk_mul_f32 v[166:167], v[154:155], v[136:137]
	v_pk_mul_f32 v[168:169], v[152:153], v[138:139]
	v_pk_mul_f32 v[186:187], v[150:151], v[132:133]
	v_pk_mul_f32 v[192:193], v[148:149], v[134:135]
	v_lshlrev_b32_e32 v194, 16, v198
	v_and_b32_e32 v195, 0xffff0000, v198
	v_lshlrev_b32_e32 v198, 16, v199
	v_and_b32_e32 v199, 0xffff0000, v199
	v_cvt_pk_bf16_f32 v190, v168, v169
	v_cvt_pk_bf16_f32 v191, v166, v167
	v_cvt_pk_bf16_f32 v192, v192, v193
	v_cvt_pk_bf16_f32 v193, v186, v187
	v_pk_fma_f32 v[126:127], v[126:127], v[142:143], v[200:201]
	v_pk_fma_f32 v[124:125], v[124:125], v[140:141], v[212:213]
	global_store_dwordx4 v[178:179], v[190:193], off
	v_pk_fma_f32 v[130:131], v[130:131], v[146:147], v[198:199]
	v_pk_fma_f32 v[128:129], v[128:129], v[144:145], v[194:195]
	v_cvt_pk_bf16_f32 v192, v124, v125
	v_cvt_pk_bf16_f32 v193, v126, v127
	v_add_co_u32_e32 v186, vcc, s65, v182
	v_cvt_pk_bf16_f32 v190, v128, v129
	v_cvt_pk_bf16_f32 v191, v130, v131
	v_addc_co_u32_e32 v187, vcc, 0, v183, vcc
	v_lshlrev_b32_e32 v126, 16, v192
	v_and_b32_e32 v127, 0xffff0000, v192
	v_lshlrev_b32_e32 v124, 16, v193
	v_and_b32_e32 v125, 0xffff0000, v193
	global_store_dwordx4 v[186:187], v[190:193], off offset:2048
	v_lshlrev_b32_e32 v130, 16, v190
	v_and_b32_e32 v131, 0xffff0000, v190
	v_lshlrev_b32_e32 v128, 16, v191
	v_and_b32_e32 v129, 0xffff0000, v191
	v_pk_mul_f32 v[190:191], v[150:151], v[124:125]
	v_pk_mul_f32 v[194:195], v[148:149], v[126:127]
	v_pk_mul_f32 v[166:167], v[154:155], v[128:129]
	v_pk_mul_f32 v[168:169], v[152:153], v[130:131]
	v_cvt_pk_bf16_f32 v194, v194, v195
	v_cvt_pk_bf16_f32 v195, v190, v191
	v_add_co_u32_e32 v190, vcc, s0, v178
	v_cvt_pk_bf16_f32 v192, v168, v169
	v_cvt_pk_bf16_f32 v193, v166, v167
	v_addc_co_u32_e32 v191, vcc, 0, v179, vcc
	global_store_dwordx4 v[190:191], v[192:195], off
	v_lshlrev_b32_e32 v198, 16, v204
	v_and_b32_e32 v199, 0xffff0000, v204
	v_add_co_u32_e32 v192, vcc, s19, v196
	v_lshlrev_b32_e32 v200, 16, v205
	s_nop 0
	v_addc_co_u32_e32 v193, vcc, 0, v197, vcc
	v_add_co_u32_e32 v194, vcc, s23, v196
	v_and_b32_e32 v201, 0xffff0000, v205
	global_load_dwordx4 v[212:215], v[192:193], off offset:2048
	v_addc_co_u32_e32 v195, vcc, 0, v197, vcc
	v_lshlrev_b32_e32 v166, 16, v202
	v_and_b32_e32 v167, 0xffff0000, v202
	v_lshlrev_b32_e32 v168, 16, v203
	v_and_b32_e32 v169, 0xffff0000, v203
	v_pk_fma_f32 v[118:119], v[118:119], v[142:143], v[200:201]
	v_pk_fma_f32 v[116:117], v[116:117], v[140:141], v[198:199]
	v_pk_fma_f32 v[122:123], v[122:123], v[146:147], v[168:169]
	v_pk_fma_f32 v[120:121], v[120:121], v[144:145], v[166:167]
	v_cvt_pk_bf16_f32 v202, v116, v117
	v_cvt_pk_bf16_f32 v203, v118, v119
	v_add_co_u32_e32 v198, vcc, s1, v182
	global_load_dwordx4 v[216:219], v[194:195], off offset:2048
	v_cvt_pk_bf16_f32 v200, v120, v121
	v_cvt_pk_bf16_f32 v201, v122, v123
	v_addc_co_u32_e32 v199, vcc, 0, v183, vcc
	v_lshlrev_b32_e32 v118, 16, v202
	v_and_b32_e32 v119, 0xffff0000, v202
	v_lshlrev_b32_e32 v116, 16, v203
	v_and_b32_e32 v117, 0xffff0000, v203
	global_store_dwordx4 v[198:199], v[200:203], off offset:2048
	v_lshlrev_b32_e32 v122, 16, v200
	v_and_b32_e32 v123, 0xffff0000, v200
	v_lshlrev_b32_e32 v120, 16, v201
	v_and_b32_e32 v121, 0xffff0000, v201
	v_pk_mul_f32 v[200:201], v[150:151], v[116:117]
	v_pk_mul_f32 v[204:205], v[148:149], v[118:119]
	v_lshlrev_b32_e32 v234, 16, v208
	v_and_b32_e32 v235, 0xffff0000, v208
	v_lshlrev_b32_e32 v208, 16, v209
	v_and_b32_e32 v209, 0xffff0000, v209
	v_pk_mul_f32 v[166:167], v[154:155], v[120:121]
	v_pk_mul_f32 v[168:169], v[152:153], v[122:123]
	v_cvt_pk_bf16_f32 v204, v204, v205
	v_cvt_pk_bf16_f32 v205, v200, v201
	v_add_co_u32_e32 v200, vcc, s65, v178
	v_lshlrev_b32_e32 v220, 16, v206
	v_and_b32_e32 v221, 0xffff0000, v206
	v_lshlrev_b32_e32 v206, 16, v207
	v_and_b32_e32 v207, 0xffff0000, v207
	v_cvt_pk_bf16_f32 v202, v168, v169
	v_cvt_pk_bf16_f32 v203, v166, v167
	v_addc_co_u32_e32 v201, vcc, 0, v179, vcc
	v_pk_fma_f32 v[110:111], v[110:111], v[142:143], v[208:209]
	v_pk_fma_f32 v[108:109], v[108:109], v[140:141], v[234:235]
	global_store_dwordx4 v[200:201], v[202:205], off
	v_pk_fma_f32 v[114:115], v[114:115], v[146:147], v[206:207]
	v_pk_fma_f32 v[112:113], v[112:113], v[144:145], v[220:221]
	v_cvt_pk_bf16_f32 v206, v108, v109
	v_cvt_pk_bf16_f32 v207, v110, v111
	v_add_co_u32_e32 v202, vcc, s18, v182
	v_cvt_pk_bf16_f32 v204, v112, v113
	v_cvt_pk_bf16_f32 v205, v114, v115
	v_addc_co_u32_e32 v203, vcc, 0, v183, vcc
	v_lshlrev_b32_e32 v110, 16, v206
	v_and_b32_e32 v111, 0xffff0000, v206
	v_lshlrev_b32_e32 v108, 16, v207
	v_and_b32_e32 v109, 0xffff0000, v207
	global_store_dwordx4 v[202:203], v[204:207], off offset:2048
	v_lshlrev_b32_e32 v114, 16, v204
	v_and_b32_e32 v115, 0xffff0000, v204
	v_lshlrev_b32_e32 v112, 16, v205
	v_and_b32_e32 v113, 0xffff0000, v205
	v_pk_mul_f32 v[204:205], v[150:151], v[108:109]
	v_pk_mul_f32 v[208:209], v[148:149], v[110:111]
	s_mov_b32 s0, 0x18000
	v_pk_mul_f32 v[166:167], v[154:155], v[112:113]
	v_pk_mul_f32 v[168:169], v[152:153], v[114:115]
	v_cvt_pk_bf16_f32 v208, v208, v209
	v_cvt_pk_bf16_f32 v209, v204, v205
	v_add_co_u32_e32 v204, vcc, s0, v178
	v_cvt_pk_bf16_f32 v206, v168, v169
	v_cvt_pk_bf16_f32 v207, v166, v167
	v_addc_co_u32_e32 v205, vcc, 0, v179, vcc
	global_store_dwordx4 v[204:205], v[206:209], off
	s_mov_b32 s0, 0xb0000
	s_waitcnt vmcnt(0)
	v_lshlrev_b32_e32 v166, 16, v212
	v_add_co_u32_e32 v206, vcc, s76, v196
	v_and_b32_e32 v167, 0xffff0000, v212
	s_nop 0
	v_addc_co_u32_e32 v207, vcc, 0, v197, vcc
	global_load_dwordx4 v[238:241], v[206:207], off offset:2048
	v_add_co_u32_e32 v208, vcc, s0, v196
	v_lshlrev_b32_e32 v168, 16, v213
	s_nop 0
	v_addc_co_u32_e32 v209, vcc, 0, v197, vcc
	global_load_dwordx4 v[242:245], v[208:209], off offset:2048
	v_and_b32_e32 v169, 0xffff0000, v213
	v_lshlrev_b32_e32 v212, 16, v214
	v_and_b32_e32 v213, 0xffff0000, v214
	v_lshlrev_b32_e32 v214, 16, v215
	v_and_b32_e32 v215, 0xffff0000, v215
	v_pk_fma_f32 v[94:95], v[94:95], v[142:143], v[214:215]
	v_pk_fma_f32 v[92:93], v[92:93], v[140:141], v[212:213]
	v_lshlrev_b32_e32 v220, 16, v216
	v_and_b32_e32 v221, 0xffff0000, v216
	v_lshlrev_b32_e32 v234, 16, v217
	v_and_b32_e32 v235, 0xffff0000, v217
	v_pk_fma_f32 v[98:99], v[98:99], v[146:147], v[168:169]
	v_pk_fma_f32 v[96:97], v[96:97], v[144:145], v[166:167]
	v_cvt_pk_bf16_f32 v216, v92, v93
	v_cvt_pk_bf16_f32 v217, v94, v95
	v_add_co_u32_e32 v212, vcc, s19, v182
	v_cvt_pk_bf16_f32 v214, v96, v97
	v_cvt_pk_bf16_f32 v215, v98, v99
	v_addc_co_u32_e32 v213, vcc, 0, v183, vcc
	v_lshlrev_b32_e32 v94, 16, v216
	v_and_b32_e32 v95, 0xffff0000, v216
	v_lshlrev_b32_e32 v92, 16, v217
	v_and_b32_e32 v93, 0xffff0000, v217
	v_lshlrev_b32_e32 v246, 16, v218
	v_and_b32_e32 v247, 0xffff0000, v218
	v_lshlrev_b32_e32 v248, 16, v219
	v_and_b32_e32 v249, 0xffff0000, v219
	global_store_dwordx4 v[212:213], v[214:217], off offset:2048
	v_lshlrev_b32_e32 v98, 16, v214
	v_and_b32_e32 v99, 0xffff0000, v214
	v_lshlrev_b32_e32 v96, 16, v215
	v_and_b32_e32 v97, 0xffff0000, v215
	v_pk_mul_f32 v[214:215], v[150:151], v[92:93]
	v_pk_mul_f32 v[218:219], v[148:149], v[94:95]
	s_mov_b32 s1, 0x40000
	v_pk_mul_f32 v[166:167], v[154:155], v[96:97]
	v_pk_mul_f32 v[168:169], v[152:153], v[98:99]
	v_cvt_pk_bf16_f32 v218, v218, v219
	v_cvt_pk_bf16_f32 v219, v214, v215
	v_add_co_u32_e32 v214, vcc, s1, v178
	v_cvt_pk_bf16_f32 v216, v168, v169
	v_cvt_pk_bf16_f32 v217, v166, v167
	v_addc_co_u32_e32 v215, vcc, 0, v179, vcc
	v_pk_fma_f32 v[86:87], v[86:87], v[142:143], v[248:249]
	global_store_dwordx4 v[214:215], v[216:219], off
	v_pk_fma_f32 v[90:91], v[90:91], v[146:147], v[234:235]
	v_pk_fma_f32 v[88:89], v[88:89], v[144:145], v[220:221]
	v_pk_fma_f32 v[84:85], v[84:85], v[140:141], v[246:247]
	v_cvt_pk_bf16_f32 v221, v86, v87
	v_add_co_u32_e32 v216, vcc, s23, v182
	v_cvt_pk_bf16_f32 v218, v88, v89
	v_cvt_pk_bf16_f32 v219, v90, v91
	v_cvt_pk_bf16_f32 v220, v84, v85
	v_addc_co_u32_e32 v217, vcc, 0, v183, vcc
	v_lshlrev_b32_e32 v84, 16, v221
	v_and_b32_e32 v85, 0xffff0000, v221
	global_store_dwordx4 v[216:217], v[218:221], off offset:2048
	v_lshlrev_b32_e32 v90, 16, v218
	v_and_b32_e32 v91, 0xffff0000, v218
	v_lshlrev_b32_e32 v88, 16, v219
	v_and_b32_e32 v89, 0xffff0000, v219
	v_lshlrev_b32_e32 v86, 16, v220
	v_and_b32_e32 v87, 0xffff0000, v220
	v_pk_mul_f32 v[218:219], v[150:151], v[84:85]
	s_mov_b32 s1, 0x48000
	v_pk_mul_f32 v[166:167], v[154:155], v[88:89]
	v_pk_mul_f32 v[168:169], v[152:153], v[90:91]
	v_pk_mul_f32 v[220:221], v[148:149], v[86:87]
	v_cvt_pk_bf16_f32 v249, v218, v219
	v_add_co_u32_e32 v218, vcc, s1, v178
	v_cvt_pk_bf16_f32 v246, v168, v169
	v_cvt_pk_bf16_f32 v247, v166, v167
	v_cvt_pk_bf16_f32 v248, v220, v221
	v_addc_co_u32_e32 v219, vcc, 0, v179, vcc
	global_store_dwordx4 v[218:219], v[246:249], off
	global_load_dwordx4 v[246:249], v[196:197], off offset:2304
	s_nop 0
	global_load_dwordx4 v[250:253], v[210:211], off offset:2304
	s_waitcnt vmcnt(0)
	v_lshlrev_b32_e32 v196, 16, v240
	v_and_b32_e32 v197, 0xffff0000, v240
	v_lshlrev_b32_e32 v210, 16, v241
	v_and_b32_e32 v211, 0xffff0000, v241
	v_lshlrev_b32_e32 v166, 16, v238
	v_and_b32_e32 v167, 0xffff0000, v238
	v_lshlrev_b32_e32 v168, 16, v239
	v_and_b32_e32 v169, 0xffff0000, v239
	v_pk_fma_f32 v[78:79], v[78:79], v[142:143], v[210:211]
	v_pk_fma_f32 v[76:77], v[76:77], v[140:141], v[196:197]
	v_pk_fma_f32 v[82:83], v[82:83], v[146:147], v[168:169]
	v_pk_fma_f32 v[80:81], v[80:81], v[144:145], v[166:167]
	v_cvt_pk_bf16_f32 v240, v76, v77
	v_cvt_pk_bf16_f32 v241, v78, v79
	v_add_co_u32_e32 v196, vcc, s76, v182
	v_cvt_pk_bf16_f32 v238, v80, v81
	v_cvt_pk_bf16_f32 v239, v82, v83
	v_addc_co_u32_e32 v197, vcc, 0, v183, vcc
	v_lshlrev_b32_e32 v78, 16, v240
	v_and_b32_e32 v79, 0xffff0000, v240
	v_lshlrev_b32_e32 v76, 16, v241
	v_and_b32_e32 v77, 0xffff0000, v241
	global_store_dwordx4 v[196:197], v[238:241], off offset:2048
	v_pk_mul_f32 v[210:211], v[150:151], v[76:77]
	v_lshlrev_b32_e32 v220, 16, v242
	v_pk_mul_f32 v[240:241], v[148:149], v[78:79]
	v_and_b32_e32 v221, 0xffff0000, v242
	v_lshlrev_b32_e32 v234, 16, v243
	v_and_b32_e32 v235, 0xffff0000, v243
	v_lshlrev_b32_e32 v242, 16, v244
	v_and_b32_e32 v243, 0xffff0000, v244
	v_lshlrev_b32_e32 v244, 16, v245
	v_and_b32_e32 v245, 0xffff0000, v245
	v_cvt_pk_bf16_f32 v240, v240, v241
	v_cvt_pk_bf16_f32 v241, v210, v211
	v_add_co_u32_e32 v210, vcc, s77, v178
	v_lshlrev_b32_e32 v82, 16, v238
	v_and_b32_e32 v83, 0xffff0000, v238
	v_lshlrev_b32_e32 v80, 16, v239
	v_and_b32_e32 v81, 0xffff0000, v239
	v_addc_co_u32_e32 v211, vcc, 0, v179, vcc
	v_pk_fma_f32 v[74:75], v[74:75], v[146:147], v[234:235]
	v_pk_fma_f32 v[72:73], v[72:73], v[144:145], v[220:221]
	v_pk_fma_f32 v[142:143], v[70:71], v[142:143], v[244:245]
	v_pk_fma_f32 v[70:71], v[68:69], v[140:141], v[242:243]
	v_pk_mul_f32 v[166:167], v[154:155], v[80:81]
	v_pk_mul_f32 v[168:169], v[152:153], v[82:83]
	v_cvt_pk_bf16_f32 v68, v72, v73
	v_cvt_pk_bf16_f32 v69, v74, v75
	v_cvt_pk_bf16_f32 v70, v70, v71
	v_cvt_pk_bf16_f32 v71, v142, v143
	v_add_co_u32_e32 v220, vcc, s0, v182
	v_cvt_pk_bf16_f32 v238, v168, v169
	v_cvt_pk_bf16_f32 v239, v166, v167
	v_addc_co_u32_e32 v221, vcc, 0, v183, vcc
	v_lshlrev_b32_e32 v146, 16, v68
	v_and_b32_e32 v147, 0xffff0000, v68
	v_lshlrev_b32_e32 v144, 16, v69
	v_and_b32_e32 v145, 0xffff0000, v69
	v_lshlrev_b32_e32 v142, 16, v70
	v_and_b32_e32 v143, 0xffff0000, v70
	v_lshlrev_b32_e32 v140, 16, v71
	v_and_b32_e32 v141, 0xffff0000, v71
	s_mov_b32 s0, 0x58000
	global_store_dwordx4 v[210:211], v[238:241], off
	global_store_dwordx4 v[220:221], v[68:71], off offset:2048
	v_pk_mul_f32 v[72:73], v[150:151], v[140:141]
	v_pk_mul_f32 v[74:75], v[148:149], v[142:143]
	v_pk_mul_f32 v[70:71], v[154:155], v[144:145]
	v_pk_mul_f32 v[68:69], v[152:153], v[146:147]
	v_add_co_u32_e32 v148, vcc, s0, v178
	v_cvt_pk_bf16_f32 v68, v68, v69
	v_cvt_pk_bf16_f32 v69, v70, v71
	v_cvt_pk_bf16_f32 v70, v74, v75
	v_cvt_pk_bf16_f32 v71, v72, v73
	v_addc_co_u32_e32 v149, vcc, 0, v179, vcc
	global_store_dwordx4 v[148:149], v[68:71], off
	global_load_dwordx4 v[150:153], v[184:185], off offset:2304
	global_load_dwordx4 v[238:241], v[188:189], off offset:2304
	s_nop 0
	global_load_dwordx4 v[68:71], v[180:181], off offset:528
	global_load_dwordx4 v[72:75], v[180:181], off offset:512
	v_lshlrev_b32_e32 v154, 16, v246
	v_and_b32_e32 v155, 0xffff0000, v246
	v_lshlrev_b32_e32 v166, 16, v247
	v_and_b32_e32 v167, 0xffff0000, v247
	v_lshlrev_b32_e32 v168, 16, v248
	v_and_b32_e32 v169, 0xffff0000, v248
	v_lshlrev_b32_e32 v180, 16, v249
	v_and_b32_e32 v181, 0xffff0000, v249
	v_pk_fma_f32 v[66:67], v[66:67], v[106:107], v[166:167]
	v_pk_fma_f32 v[64:65], v[64:65], v[104:105], v[154:155]
	v_pk_fma_f32 v[62:63], v[62:63], v[102:103], v[180:181]
	v_pk_fma_f32 v[60:61], v[60:61], v[100:101], v[168:169]
	v_cvt_pk_bf16_f32 v242, v64, v65
	v_cvt_pk_bf16_f32 v243, v66, v67
	v_cvt_pk_bf16_f32 v244, v60, v61
	v_cvt_pk_bf16_f32 v245, v62, v63
	v_lshlrev_b32_e32 v66, 16, v242
	v_and_b32_e32 v67, 0xffff0000, v242
	v_lshlrev_b32_e32 v64, 16, v243
	v_and_b32_e32 v65, 0xffff0000, v243
	v_lshlrev_b32_e32 v62, 16, v244
	v_and_b32_e32 v63, 0xffff0000, v244
	v_lshlrev_b32_e32 v60, 16, v245
	v_and_b32_e32 v61, 0xffff0000, v245
	v_lshlrev_b32_e32 v184, 16, v250
	v_and_b32_e32 v185, 0xffff0000, v250
	v_lshlrev_b32_e32 v188, 16, v251
	v_and_b32_e32 v189, 0xffff0000, v251
	v_lshlrev_b32_e32 v234, 16, v252
	v_and_b32_e32 v235, 0xffff0000, v252
	v_lshlrev_b32_e32 v246, 16, v253
	v_and_b32_e32 v247, 0xffff0000, v253
	global_store_dwordx4 v[182:183], v[242:245], off offset:2304
	v_pk_fma_f32 v[58:59], v[58:59], v[106:107], v[188:189]
	v_pk_fma_f32 v[56:57], v[56:57], v[104:105], v[184:185]
	v_pk_fma_f32 v[54:55], v[54:55], v[102:103], v[246:247]
	v_pk_fma_f32 v[52:53], v[52:53], v[100:101], v[234:235]
	s_waitcnt vmcnt(0)
	v_lshlrev_b32_e32 v188, 16, v240
	v_pk_mul_f32 v[168:169], v[70:71], v[60:61]
	v_pk_mul_f32 v[154:155], v[74:75], v[64:65]
	v_pk_mul_f32 v[166:167], v[72:73], v[66:67]
	v_pk_mul_f32 v[182:183], v[68:69], v[62:63]
	v_cvt_pk_bf16_f32 v180, v166, v167
	v_cvt_pk_bf16_f32 v181, v154, v155
	v_cvt_pk_bf16_f32 v182, v182, v183
	v_cvt_pk_bf16_f32 v183, v168, v169
	global_store_dwordx4 v[178:179], v[180:183], off offset:256
	v_cvt_pk_bf16_f32 v178, v56, v57
	v_cvt_pk_bf16_f32 v179, v58, v59
	v_cvt_pk_bf16_f32 v180, v52, v53
	v_cvt_pk_bf16_f32 v181, v54, v55
	v_lshlrev_b32_e32 v58, 16, v178
	v_and_b32_e32 v59, 0xffff0000, v178
	v_lshlrev_b32_e32 v56, 16, v179
	v_and_b32_e32 v57, 0xffff0000, v179
	v_lshlrev_b32_e32 v54, 16, v180
	v_and_b32_e32 v55, 0xffff0000, v180
	v_lshlrev_b32_e32 v52, 16, v181
	v_and_b32_e32 v53, 0xffff0000, v181
	global_store_dwordx4 v[186:187], v[178:181], off offset:2304
	v_pk_mul_f32 v[154:155], v[74:75], v[56:57]
	v_pk_mul_f32 v[166:167], v[72:73], v[58:59]
	v_pk_mul_f32 v[168:169], v[70:71], v[52:53]
	v_pk_mul_f32 v[180:181], v[68:69], v[54:55]
	v_cvt_pk_bf16_f32 v178, v166, v167
	v_cvt_pk_bf16_f32 v179, v154, v155
	v_cvt_pk_bf16_f32 v180, v180, v181
	v_cvt_pk_bf16_f32 v181, v168, v169
	v_lshlrev_b32_e32 v154, 16, v150
	v_and_b32_e32 v155, 0xffff0000, v150
	v_lshlrev_b32_e32 v150, 16, v151
	v_and_b32_e32 v151, 0xffff0000, v151
	v_lshlrev_b32_e32 v166, 16, v152
	v_and_b32_e32 v167, 0xffff0000, v152
	v_lshlrev_b32_e32 v152, 16, v153
	v_and_b32_e32 v153, 0xffff0000, v153
	global_store_dwordx4 v[190:191], v[178:181], off offset:256
	v_pk_fma_f32 v[50:51], v[50:51], v[106:107], v[150:151]
	v_pk_fma_f32 v[48:49], v[48:49], v[104:105], v[154:155]
	v_pk_fma_f32 v[46:47], v[46:47], v[102:103], v[152:153]
	v_pk_fma_f32 v[44:45], v[44:45], v[100:101], v[166:167]
	global_load_dwordx4 v[178:181], v[192:193], off offset:2304
	global_load_dwordx4 v[182:185], v[194:195], off offset:2304
	v_cvt_pk_bf16_f32 v150, v48, v49
	v_cvt_pk_bf16_f32 v151, v50, v51
	v_cvt_pk_bf16_f32 v152, v44, v45
	v_cvt_pk_bf16_f32 v153, v46, v47
	v_lshlrev_b32_e32 v50, 16, v150
	v_and_b32_e32 v51, 0xffff0000, v150
	v_lshlrev_b32_e32 v48, 16, v151
	v_and_b32_e32 v49, 0xffff0000, v151
	v_lshlrev_b32_e32 v46, 16, v152
	v_and_b32_e32 v47, 0xffff0000, v152
	v_lshlrev_b32_e32 v44, 16, v153
	v_and_b32_e32 v45, 0xffff0000, v153
	v_lshlrev_b32_e32 v168, 16, v238
	v_and_b32_e32 v169, 0xffff0000, v238
	v_lshlrev_b32_e32 v186, 16, v239
	v_and_b32_e32 v187, 0xffff0000, v239
	v_and_b32_e32 v189, 0xffff0000, v240
	v_lshlrev_b32_e32 v190, 16, v241
	v_and_b32_e32 v191, 0xffff0000, v241
	global_store_dwordx4 v[198:199], v[150:153], off offset:2304
	v_pk_mul_f32 v[154:155], v[70:71], v[44:45]
	v_pk_mul_f32 v[166:167], v[68:69], v[46:47]
	v_pk_mul_f32 v[152:153], v[74:75], v[48:49]
	v_pk_mul_f32 v[150:151], v[72:73], v[50:51]
	v_pk_fma_f32 v[42:43], v[42:43], v[106:107], v[186:187]
	v_cvt_pk_bf16_f32 v150, v150, v151
	v_cvt_pk_bf16_f32 v151, v152, v153
	v_cvt_pk_bf16_f32 v152, v166, v167
	v_cvt_pk_bf16_f32 v153, v154, v155
	v_pk_fma_f32 v[40:41], v[40:41], v[104:105], v[168:169]
	v_pk_fma_f32 v[38:39], v[38:39], v[102:103], v[190:191]
	v_pk_fma_f32 v[36:37], v[36:37], v[100:101], v[188:189]
	global_store_dwordx4 v[200:201], v[150:153], off offset:256
	v_mul_f32_e32 v67, v67, v67
	v_mul_f32_e32 v65, v65, v65
	v_cvt_pk_bf16_f32 v150, v40, v41
	v_cvt_pk_bf16_f32 v151, v42, v43
	v_cvt_pk_bf16_f32 v152, v36, v37
	v_cvt_pk_bf16_f32 v153, v38, v39
	v_lshlrev_b32_e32 v42, 16, v150
	v_and_b32_e32 v43, 0xffff0000, v150
	v_lshlrev_b32_e32 v40, 16, v151
	v_and_b32_e32 v41, 0xffff0000, v151
	v_lshlrev_b32_e32 v38, 16, v152
	v_and_b32_e32 v39, 0xffff0000, v152
	v_lshlrev_b32_e32 v36, 16, v153
	v_and_b32_e32 v37, 0xffff0000, v153
	global_store_dwordx4 v[202:203], v[150:153], off offset:2304
	v_pk_mul_f32 v[154:155], v[70:71], v[36:37]
	v_pk_mul_f32 v[166:167], v[68:69], v[38:39]
	v_pk_mul_f32 v[152:153], v[74:75], v[40:41]
	v_pk_mul_f32 v[150:151], v[72:73], v[42:43]
	v_fmac_f32_e32 v67, v66, v66
	v_cvt_pk_bf16_f32 v150, v150, v151
	v_cvt_pk_bf16_f32 v151, v152, v153
	v_cvt_pk_bf16_f32 v152, v166, v167
	v_cvt_pk_bf16_f32 v153, v154, v155
	global_store_dwordx4 v[204:205], v[150:153], off offset:256
	global_load_dwordx4 v[150:153], v[206:207], off offset:2304
	s_nop 0
	global_load_dwordx4 v[186:189], v[208:209], off offset:2304
	v_fmac_f32_e32 v65, v64, v64
	v_mul_f32_e32 v63, v63, v63
	v_mul_f32_e32 v61, v61, v61
	v_add_f32_e32 v64, v67, v65
	v_fmac_f32_e32 v63, v62, v62
	v_fmac_f32_e32 v61, v60, v60
	v_add_f32_e32 v60, v63, v61
	s_waitcnt vmcnt(0)
	v_lshlrev_b32_e32 v154, 16, v178
	v_and_b32_e32 v155, 0xffff0000, v178
	v_lshlrev_b32_e32 v166, 16, v179
	v_and_b32_e32 v167, 0xffff0000, v179
	v_lshlrev_b32_e32 v168, 16, v180
	v_and_b32_e32 v169, 0xffff0000, v180
	v_lshlrev_b32_e32 v178, 16, v181
	v_and_b32_e32 v179, 0xffff0000, v181
	v_pk_fma_f32 v[34:35], v[34:35], v[106:107], v[166:167]
	v_pk_fma_f32 v[32:33], v[32:33], v[104:105], v[154:155]
	v_pk_fma_f32 v[30:31], v[30:31], v[102:103], v[178:179]
	v_pk_fma_f32 v[28:29], v[28:29], v[100:101], v[168:169]
	v_cvt_pk_bf16_f32 v178, v32, v33
	v_cvt_pk_bf16_f32 v179, v34, v35
	v_cvt_pk_bf16_f32 v180, v28, v29
	v_cvt_pk_bf16_f32 v181, v30, v31
	v_lshlrev_b32_e32 v34, 16, v178
	v_and_b32_e32 v35, 0xffff0000, v178
	v_lshlrev_b32_e32 v32, 16, v179
	v_and_b32_e32 v33, 0xffff0000, v179
	v_lshlrev_b32_e32 v30, 16, v180
	v_and_b32_e32 v31, 0xffff0000, v180
	v_lshlrev_b32_e32 v28, 16, v181
	v_and_b32_e32 v29, 0xffff0000, v181
	v_lshlrev_b32_e32 v190, 16, v182
	v_and_b32_e32 v191, 0xffff0000, v182
	v_lshlrev_b32_e32 v182, 16, v183
	v_and_b32_e32 v183, 0xffff0000, v183
	global_store_dwordx4 v[212:213], v[178:181], off offset:2304
	v_pk_mul_f32 v[154:155], v[74:75], v[32:33]
	v_pk_mul_f32 v[166:167], v[72:73], v[34:35]
	v_pk_mul_f32 v[168:169], v[70:71], v[28:29]
	v_pk_mul_f32 v[180:181], v[68:69], v[30:31]
	v_lshlrev_b32_e32 v192, 16, v184
	v_and_b32_e32 v193, 0xffff0000, v184
	v_lshlrev_b32_e32 v184, 16, v185
	v_and_b32_e32 v185, 0xffff0000, v185
	v_cvt_pk_bf16_f32 v178, v166, v167
	v_cvt_pk_bf16_f32 v179, v154, v155
	v_cvt_pk_bf16_f32 v180, v180, v181
	v_cvt_pk_bf16_f32 v181, v168, v169
	v_pk_fma_f32 v[24:25], v[24:25], v[106:107], v[182:183]
	v_pk_fma_f32 v[22:23], v[22:23], v[104:105], v[190:191]
	global_store_dwordx4 v[214:215], v[178:181], off offset:256
	v_pk_fma_f32 v[20:21], v[20:21], v[102:103], v[184:185]
	v_pk_fma_f32 v[18:19], v[18:19], v[100:101], v[192:193]
	v_cvt_pk_bf16_f32 v178, v22, v23
	v_cvt_pk_bf16_f32 v179, v24, v25
	v_cvt_pk_bf16_f32 v180, v18, v19
	v_cvt_pk_bf16_f32 v181, v20, v21
	v_lshlrev_b32_e32 v24, 16, v178
	v_and_b32_e32 v25, 0xffff0000, v178
	v_lshlrev_b32_e32 v22, 16, v179
	v_and_b32_e32 v23, 0xffff0000, v179
	v_lshlrev_b32_e32 v20, 16, v180
	v_and_b32_e32 v21, 0xffff0000, v180
	v_lshlrev_b32_e32 v18, 16, v181
	v_and_b32_e32 v19, 0xffff0000, v181
	v_pk_mul_f32 v[154:155], v[74:75], v[22:23]
	v_pk_mul_f32 v[166:167], v[72:73], v[24:25]
	global_store_dwordx4 v[216:217], v[178:181], off offset:2304
	v_pk_mul_f32 v[168:169], v[70:71], v[18:19]
	v_lshlrev_b32_e32 v182, 16, v189
	v_pk_mul_f32 v[180:181], v[68:69], v[20:21]
	v_cvt_pk_bf16_f32 v178, v166, v167
	v_cvt_pk_bf16_f32 v179, v154, v155
	v_lshlrev_b32_e32 v154, 16, v150
	v_and_b32_e32 v155, 0xffff0000, v150
	v_lshlrev_b32_e32 v150, 16, v151
	v_and_b32_e32 v151, 0xffff0000, v151
	v_lshlrev_b32_e32 v166, 16, v152
	v_and_b32_e32 v167, 0xffff0000, v152
	v_lshlrev_b32_e32 v152, 16, v153
	v_and_b32_e32 v153, 0xffff0000, v153
	v_cvt_pk_bf16_f32 v180, v180, v181
	v_cvt_pk_bf16_f32 v181, v168, v169
	v_pk_fma_f32 v[16:17], v[16:17], v[106:107], v[150:151]
	v_pk_fma_f32 v[14:15], v[14:15], v[104:105], v[154:155]
	v_pk_fma_f32 v[12:13], v[12:13], v[102:103], v[152:153]
	v_pk_fma_f32 v[10:11], v[10:11], v[100:101], v[166:167]
	global_store_dwordx4 v[218:219], v[178:181], off offset:256
	v_lshlrev_b32_e32 v168, 16, v186
	v_and_b32_e32 v169, 0xffff0000, v186
	v_lshlrev_b32_e32 v178, 16, v187
	v_and_b32_e32 v179, 0xffff0000, v187
	v_lshlrev_b32_e32 v180, 16, v188
	v_and_b32_e32 v181, 0xffff0000, v188
	v_and_b32_e32 v183, 0xffff0000, v189
	v_cvt_pk_bf16_f32 v150, v14, v15
	v_cvt_pk_bf16_f32 v151, v16, v17
	v_cvt_pk_bf16_f32 v152, v10, v11
	v_cvt_pk_bf16_f32 v153, v12, v13
	v_lshlrev_b32_e32 v16, 16, v150
	v_and_b32_e32 v17, 0xffff0000, v150
	v_lshlrev_b32_e32 v14, 16, v151
	v_and_b32_e32 v15, 0xffff0000, v151
	v_lshlrev_b32_e32 v12, 16, v152
	v_and_b32_e32 v13, 0xffff0000, v152
	v_lshlrev_b32_e32 v10, 16, v153
	v_and_b32_e32 v11, 0xffff0000, v153
	v_pk_fma_f32 v[8:9], v[8:9], v[106:107], v[178:179]
	v_pk_fma_f32 v[6:7], v[6:7], v[104:105], v[168:169]
	v_pk_fma_f32 v[4:5], v[4:5], v[102:103], v[182:183]
	v_pk_fma_f32 v[2:3], v[2:3], v[100:101], v[180:181]
	global_store_dwordx4 v[196:197], v[150:153], off offset:2304
	v_pk_mul_f32 v[154:155], v[70:71], v[10:11]
	v_pk_mul_f32 v[166:167], v[68:69], v[12:13]
	v_pk_mul_f32 v[152:153], v[74:75], v[14:15]
	v_pk_mul_f32 v[150:151], v[72:73], v[16:17]
	v_cvt_pk_bf16_f32 v100, v6, v7
	v_cvt_pk_bf16_f32 v101, v8, v9
	v_cvt_pk_bf16_f32 v102, v2, v3
	v_cvt_pk_bf16_f32 v103, v4, v5
	v_cvt_pk_bf16_f32 v150, v150, v151
	v_cvt_pk_bf16_f32 v151, v152, v153
	v_cvt_pk_bf16_f32 v152, v166, v167
	v_cvt_pk_bf16_f32 v153, v154, v155
	v_lshlrev_b32_e32 v8, 16, v100
	v_and_b32_e32 v9, 0xffff0000, v100
	v_lshlrev_b32_e32 v6, 16, v101
	v_and_b32_e32 v7, 0xffff0000, v101
	v_lshlrev_b32_e32 v4, 16, v102
	v_and_b32_e32 v5, 0xffff0000, v102
	v_lshlrev_b32_e32 v2, 16, v103
	v_and_b32_e32 v3, 0xffff0000, v103
	global_store_dwordx4 v[210:211], v[150:153], off offset:256
	global_store_dwordx4 v[220:221], v[100:103], off offset:2304
	v_pk_mul_f32 v[74:75], v[74:75], v[6:7]
	v_pk_mul_f32 v[72:73], v[72:73], v[8:9]
	v_pk_mul_f32 v[100:101], v[70:71], v[2:3]
	v_pk_mul_f32 v[70:71], v[68:69], v[4:5]
	v_cvt_pk_bf16_f32 v68, v72, v73
	v_cvt_pk_bf16_f32 v69, v74, v75
	v_cvt_pk_bf16_f32 v70, v70, v71
	v_cvt_pk_bf16_f32 v71, v100, v101
	global_store_dwordx4 v[148:149], v[68:71], off offset:256
	v_xor_b32_e32 v72, 32, v227
	v_mul_f32_e32 v73, v137, v137
	v_and_b32_e32 v71, 64, v227
	v_xor_b32_e32 v70, 16, v227
	v_add_u32_e32 v71, 64, v71
	v_cmp_lt_i32_e32 vcc, v70, v71
	v_fmac_f32_e32 v73, v136, v136
	v_mul_f32_e32 v74, v133, v133
	v_cndmask_b32_e32 v70, v227, v70, vcc
	v_cmp_lt_i32_e32 vcc, v72, v71
	v_fmac_f32_e32 v74, v132, v132
	v_lshlrev_b32_e32 v70, 2, v70
	v_cndmask_b32_e32 v71, v227, v72, vcc
	v_mul_f32_e32 v72, v139, v139
	v_fmac_f32_e32 v72, v138, v138
	v_add_f32_e32 v72, v72, v73
	v_mul_f32_e32 v73, v135, v135
	v_fmac_f32_e32 v73, v134, v134
	v_add_f32_e32 v73, v73, v74
	v_add_f32_e32 v72, v72, v73
	v_add_f32_e32 v64, v72, v64
	v_add_f32_e32 v60, v60, v64
	ds_bpermute_b32 v61, v70, v60
	v_lshlrev_b32_e32 v71, 2, v71
	v_lshl_add_u64 v[68:69], v[172:173], 0, s[28:29]
	s_waitcnt lgkmcnt(0)
	v_add_f32_e32 v60, v60, v61
	ds_bpermute_b32 v61, v71, v60
	s_and_saveexec_b64 s[18:19], s[38:39]
	s_cbranch_execz .LBB0_968
	s_waitcnt lgkmcnt(0)
	v_add_f32_e32 v60, v60, v61
	global_atomic_add_f32 v[68:69], v60, off

.LBB0_1048:
	s_add_u32 s0, s24, 0xfffc0080
	s_addc_u32 s1, s25, -1
	s_add_i32 s83, 0, 0x10000
	s_cmp_eq_u32 s82, 12
	s_cselect_b32 s29, s43, s1
	s_cselect_b32 s28, s69, s0
	s_cselect_b32 s27, s45, s81
	s_cselect_b32 s26, s72, s73
	s_add_i32 m0, s23, 0xc000
	ds_read_b128 v[158:161], v165
	ds_read_b128 v[174:177], v165 offset:1024
	ds_read_b128 v[178:181], v165 offset:2048
	ds_read_b128 v[182:185], v165 offset:3072
	ds_read_b128 v[186:189], v165 offset:4096
	ds_read_b128 v[190:193], v165 offset:5120
	ds_read_b128 v[194:197], v165 offset:6144
	ds_read_b128 v[198:201], v165 offset:7168
	global_load_lds_dwordx4 v154, s[24:25]
	v_lshl_add_u64 v[166:167], s[24:25], 0, v[156:157]
	s_add_i32 m0, s23, 0xe000
	s_nop 0
	global_load_lds_dwordx4 v[166:167], off
	s_waitcnt vmcnt(10) lgkmcnt(8)
	s_setprio 1
	s_barrier
	s_waitcnt lgkmcnt(0)
	v_mfma_f32_16x16x32_bf16 v[144:147], v[68:71], v[158:161], v[144:147]
	v_mfma_f32_16x16x32_bf16 v[140:143], v[76:79], v[158:161], v[140:143]
	v_mfma_f32_16x16x32_bf16 v[128:131], v[68:71], v[178:181], v[128:131]
	v_mfma_f32_16x16x32_bf16 v[124:127], v[76:79], v[178:181], v[124:127]
	v_mfma_f32_16x16x32_bf16 v[112:115], v[68:71], v[186:189], v[112:115]
	v_mfma_f32_16x16x32_bf16 v[108:111], v[76:79], v[186:189], v[108:111]
	v_mfma_f32_16x16x32_bf16 v[96:99], v[68:71], v[194:197], v[96:99]
	v_mfma_f32_16x16x32_bf16 v[92:95], v[76:79], v[194:197], v[92:95]
	v_mfma_f32_16x16x32_bf16 v[144:147], v[72:75], v[174:177], v[144:147]
	v_mfma_f32_16x16x32_bf16 v[140:143], v[80:83], v[174:177], v[140:143]
	v_mfma_f32_16x16x32_bf16 v[128:131], v[72:75], v[182:185], v[128:131]
	v_mfma_f32_16x16x32_bf16 v[124:127], v[80:83], v[182:185], v[124:127]
	v_mfma_f32_16x16x32_bf16 v[112:115], v[72:75], v[190:193], v[112:115]
	v_mfma_f32_16x16x32_bf16 v[108:111], v[80:83], v[190:193], v[108:111]
	v_mfma_f32_16x16x32_bf16 v[96:99], v[72:75], v[198:201], v[96:99]
	v_mfma_f32_16x16x32_bf16 v[92:95], v[80:83], v[198:201], v[92:95]
	s_barrier
	s_setprio 0
	s_add_i32 s84, 0, 0x14000
	v_add_u32_e32 v166, s84, v163
	s_add_i32 s0, s83, s54
	ds_read_b128 v[202:205], v166
	ds_read_b128 v[206:209], v166 offset:1024
	ds_read_b128 v[210:213], v166 offset:2048
	ds_read_b128 v[214:217], v166 offset:3072
	v_lshl_add_u64 v[166:167], s[26:27], 0, v[26:27]
	s_mov_b32 m0, s0
	v_lshl_add_u64 v[168:169], s[26:27], 0, v[148:149]
	global_load_lds_dwordx4 v[166:167], off
	s_add_i32 m0, s0, 0x2000
	s_nop 0
	global_load_lds_dwordx4 v[168:169], off
	s_waitcnt vmcnt(10)
	s_setprio 1
	s_barrier
	s_waitcnt lgkmcnt(0)
	v_mfma_f32_16x16x32_bf16 v[136:139], v[202:205], v[158:161], v[136:139]
	v_mfma_f32_16x16x32_bf16 v[132:135], v[210:213], v[158:161], v[132:135]
	v_mfma_f32_16x16x32_bf16 v[120:123], v[202:205], v[178:181], v[120:123]
	v_mfma_f32_16x16x32_bf16 v[116:119], v[210:213], v[178:181], v[116:119]
	v_mfma_f32_16x16x32_bf16 v[104:107], v[202:205], v[186:189], v[104:107]
	v_mfma_f32_16x16x32_bf16 v[100:103], v[210:213], v[186:189], v[100:103]
	v_mfma_f32_16x16x32_bf16 v[88:91], v[202:205], v[194:197], v[88:91]
	v_mfma_f32_16x16x32_bf16 v[84:87], v[210:213], v[194:197], v[84:87]
	v_mfma_f32_16x16x32_bf16 v[136:139], v[206:209], v[174:177], v[136:139]
	v_mfma_f32_16x16x32_bf16 v[132:135], v[214:217], v[174:177], v[132:135]
	v_mfma_f32_16x16x32_bf16 v[120:123], v[206:209], v[182:185], v[120:123]
	v_mfma_f32_16x16x32_bf16 v[116:119], v[214:217], v[182:185], v[116:119]
	v_mfma_f32_16x16x32_bf16 v[104:107], v[206:209], v[190:193], v[104:107]
	v_mfma_f32_16x16x32_bf16 v[100:103], v[214:217], v[190:193], v[100:103]
	v_mfma_f32_16x16x32_bf16 v[88:91], v[206:209], v[198:201], v[88:91]
	v_mfma_f32_16x16x32_bf16 v[84:87], v[214:217], v[198:201], v[84:87]
	s_barrier
	s_setprio 0
	s_mov_b32 m0, s23
	v_lshl_add_u64 v[218:219], s[28:29], 0, v[152:153]
	ds_read_b128 v[158:161], v165 offset:16384
	ds_read_b128 v[174:177], v165 offset:17408
	ds_read_b128 v[178:181], v165 offset:18432
	ds_read_b128 v[182:185], v165 offset:19456
	ds_read_b128 v[186:189], v165 offset:20480
	ds_read_b128 v[190:193], v165 offset:21504
	ds_read_b128 v[194:197], v165 offset:22528
	ds_read_b128 v[198:201], v165 offset:23552
	global_load_lds_dwordx4 v[218:219], off
	v_lshl_add_u64 v[220:221], s[28:29], 0, v[150:151]
	s_mov_b32 m0, s57
	s_nop 0
	global_load_lds_dwordx4 v[220:221], off
	s_waitcnt vmcnt(10)
	s_setprio 1
	s_barrier
	s_waitcnt lgkmcnt(0)
	v_mfma_f32_16x16x32_bf16 v[64:67], v[68:71], v[158:161], v[64:67]
	v_mfma_f32_16x16x32_bf16 v[60:63], v[76:79], v[158:161], v[60:63]
	v_mfma_f32_16x16x32_bf16 v[48:51], v[68:71], v[178:181], v[48:51]
	v_mfma_f32_16x16x32_bf16 v[44:47], v[76:79], v[178:181], v[44:47]
	v_mfma_f32_16x16x32_bf16 v[32:35], v[68:71], v[186:189], v[32:35]
	v_mfma_f32_16x16x32_bf16 v[28:31], v[76:79], v[186:189], v[28:31]
	v_mfma_f32_16x16x32_bf16 v[14:17], v[68:71], v[194:197], v[14:17]
	v_mfma_f32_16x16x32_bf16 v[10:13], v[76:79], v[194:197], v[10:13]
	v_mfma_f32_16x16x32_bf16 v[64:67], v[72:75], v[174:177], v[64:67]
	v_mfma_f32_16x16x32_bf16 v[60:63], v[80:83], v[174:177], v[60:63]
	v_mfma_f32_16x16x32_bf16 v[48:51], v[72:75], v[182:185], v[48:51]
	v_mfma_f32_16x16x32_bf16 v[44:47], v[80:83], v[182:185], v[44:47]
	v_mfma_f32_16x16x32_bf16 v[32:35], v[72:75], v[190:193], v[32:35]
	v_mfma_f32_16x16x32_bf16 v[28:31], v[80:83], v[190:193], v[28:31]
	v_mfma_f32_16x16x32_bf16 v[14:17], v[72:75], v[198:201], v[14:17]
	v_mfma_f32_16x16x32_bf16 v[10:13], v[80:83], v[198:201], v[10:13]
	s_barrier
	s_setprio 0
	s_add_u32 s0, s26, 0x40000
	s_addc_u32 s1, s27, 0
	s_add_i32 s83, s84, s54
	s_mov_b32 m0, s83
	s_nop 0
	global_load_lds_dwordx4 v26, s[0:1]
	s_add_i32 m0, s83, 0x2000
	s_nop 0
	global_load_lds_dwordx4 v148, s[0:1]
	v_add_u32_e32 v80, 0x18000, v163
	ds_read_b128 v[68:71], v80
	ds_read_b128 v[72:75], v80 offset:1024
	ds_read_b128 v[76:79], v80 offset:2048
	ds_read_b128 v[80:83], v80 offset:3072
	s_waitcnt vmcnt(10)
	s_setprio 1
	s_barrier
	v_mfma_f32_16x16x32_bf16 v[56:59], v[202:205], v[158:161], v[56:59]
	v_mfma_f32_16x16x32_bf16 v[52:55], v[210:213], v[158:161], v[52:55]
	v_mfma_f32_16x16x32_bf16 v[40:43], v[202:205], v[178:181], v[40:43]
	v_mfma_f32_16x16x32_bf16 v[36:39], v[210:213], v[178:181], v[36:39]
	v_mfma_f32_16x16x32_bf16 v[22:25], v[202:205], v[186:189], v[22:25]
	v_mfma_f32_16x16x32_bf16 v[18:21], v[210:213], v[186:189], v[18:21]
	v_mfma_f32_16x16x32_bf16 v[6:9], v[202:205], v[194:197], v[6:9]
	v_mfma_f32_16x16x32_bf16 v[2:5], v[210:213], v[194:197], v[2:5]
	v_mfma_f32_16x16x32_bf16 v[56:59], v[206:209], v[174:177], v[56:59]
	v_mfma_f32_16x16x32_bf16 v[52:55], v[214:217], v[174:177], v[52:55]
	v_mfma_f32_16x16x32_bf16 v[40:43], v[206:209], v[182:185], v[40:43]
	v_mfma_f32_16x16x32_bf16 v[36:39], v[214:217], v[182:185], v[36:39]
	v_mfma_f32_16x16x32_bf16 v[22:25], v[206:209], v[190:193], v[22:25]
	v_mfma_f32_16x16x32_bf16 v[18:21], v[214:217], v[190:193], v[18:21]
	v_mfma_f32_16x16x32_bf16 v[6:9], v[206:209], v[198:201], v[6:9]
	v_mfma_f32_16x16x32_bf16 v[2:5], v[214:217], v[198:201], v[2:5]
	s_barrier
	s_setprio 0
	s_add_i32 s83, 0, 0x18000
	s_add_u32 s0, s28, 0x40000
	s_addc_u32 s1, s29, 0
	s_mov_b32 m0, s58
	ds_read_b128 v[158:161], v165 offset:32768
	ds_read_b128 v[174:177], v165 offset:33792
	ds_read_b128 v[178:181], v165 offset:34816
	ds_read_b128 v[182:185], v165 offset:35840
	ds_read_b128 v[186:189], v165 offset:36864
	ds_read_b128 v[190:193], v165 offset:37888
	ds_read_b128 v[194:197], v165 offset:38912
	ds_read_b128 v[198:201], v165 offset:39936
	global_load_lds_dwordx4 v152, s[0:1]
	s_mov_b32 m0, s59
	s_nop 0
	global_load_lds_dwordx4 v150, s[0:1]
	s_waitcnt vmcnt(10) lgkmcnt(8)
	s_setprio 1
	s_barrier
	s_waitcnt lgkmcnt(0)
	v_mfma_f32_16x16x32_bf16 v[144:147], v[68:71], v[158:161], v[144:147]
	v_mfma_f32_16x16x32_bf16 v[140:143], v[76:79], v[158:161], v[140:143]
	v_mfma_f32_16x16x32_bf16 v[128:131], v[68:71], v[178:181], v[128:131]
	v_mfma_f32_16x16x32_bf16 v[124:127], v[76:79], v[178:181], v[124:127]
	v_mfma_f32_16x16x32_bf16 v[112:115], v[68:71], v[186:189], v[112:115]
	v_mfma_f32_16x16x32_bf16 v[108:111], v[76:79], v[186:189], v[108:111]
	v_mfma_f32_16x16x32_bf16 v[96:99], v[68:71], v[194:197], v[96:99]
	v_mfma_f32_16x16x32_bf16 v[92:95], v[76:79], v[194:197], v[92:95]
	v_mfma_f32_16x16x32_bf16 v[144:147], v[72:75], v[174:177], v[144:147]
	v_mfma_f32_16x16x32_bf16 v[140:143], v[80:83], v[174:177], v[140:143]
	v_mfma_f32_16x16x32_bf16 v[128:131], v[72:75], v[182:185], v[128:131]
	v_mfma_f32_16x16x32_bf16 v[124:127], v[80:83], v[182:185], v[124:127]
	v_mfma_f32_16x16x32_bf16 v[112:115], v[72:75], v[190:193], v[112:115]
	v_mfma_f32_16x16x32_bf16 v[108:111], v[80:83], v[190:193], v[108:111]
	v_mfma_f32_16x16x32_bf16 v[96:99], v[72:75], v[198:201], v[96:99]
	v_mfma_f32_16x16x32_bf16 v[92:95], v[80:83], v[198:201], v[92:95]
	s_barrier
	s_setprio 0
	s_add_i32 s28, 0, 0x1c000
	s_add_i32 s0, s83, s54
	v_add_u32_e32 v173, s28, v163
	v_lshl_add_u64 v[166:167], v[166:167], 0, s[12:13]
	s_mov_b32 m0, s0
	ds_read_b128 v[202:205], v173
	ds_read_b128 v[206:209], v173 offset:1024
	ds_read_b128 v[210:213], v173 offset:2048
	ds_read_b128 v[214:217], v173 offset:3072
	global_load_lds_dwordx4 v[166:167], off
	v_lshl_add_u64 v[166:167], v[168:169], 0, s[12:13]
	s_add_i32 m0, s0, 0x2000
	s_nop 0
	global_load_lds_dwordx4 v[166:167], off
	s_waitcnt vmcnt(10)
	s_setprio 1
	s_barrier
	s_waitcnt lgkmcnt(0)
	v_mfma_f32_16x16x32_bf16 v[136:139], v[202:205], v[158:161], v[136:139]
	v_mfma_f32_16x16x32_bf16 v[132:135], v[210:213], v[158:161], v[132:135]
	v_mfma_f32_16x16x32_bf16 v[120:123], v[202:205], v[178:181], v[120:123]
	v_mfma_f32_16x16x32_bf16 v[116:119], v[210:213], v[178:181], v[116:119]
	v_mfma_f32_16x16x32_bf16 v[104:107], v[202:205], v[186:189], v[104:107]
	v_mfma_f32_16x16x32_bf16 v[100:103], v[210:213], v[186:189], v[100:103]
	v_mfma_f32_16x16x32_bf16 v[88:91], v[202:205], v[194:197], v[88:91]
	v_mfma_f32_16x16x32_bf16 v[84:87], v[210:213], v[194:197], v[84:87]
	v_mfma_f32_16x16x32_bf16 v[136:139], v[206:209], v[174:177], v[136:139]
	v_mfma_f32_16x16x32_bf16 v[132:135], v[214:217], v[174:177], v[132:135]
	v_mfma_f32_16x16x32_bf16 v[120:123], v[206:209], v[182:185], v[120:123]
	v_mfma_f32_16x16x32_bf16 v[116:119], v[214:217], v[182:185], v[116:119]
	v_mfma_f32_16x16x32_bf16 v[104:107], v[206:209], v[190:193], v[104:107]
	v_mfma_f32_16x16x32_bf16 v[100:103], v[214:217], v[190:193], v[100:103]
	v_mfma_f32_16x16x32_bf16 v[88:91], v[206:209], v[198:201], v[88:91]
	v_mfma_f32_16x16x32_bf16 v[84:87], v[214:217], v[198:201], v[84:87]
	s_barrier
	s_setprio 0
	s_mov_b32 m0, s34
	v_lshl_add_u64 v[166:167], v[218:219], 0, s[12:13]
	ds_read_b128 v[158:161], v165 offset:49152
	ds_read_b128 v[174:177], v165 offset:50176
	ds_read_b128 v[178:181], v165 offset:51200
	ds_read_b128 v[182:185], v165 offset:52224
	ds_read_b128 v[186:189], v165 offset:53248
	ds_read_b128 v[190:193], v165 offset:54272
	ds_read_b128 v[194:197], v165 offset:55296
	ds_read_b128 v[198:201], v165 offset:56320
	global_load_lds_dwordx4 v[166:167], off
	v_lshl_add_u64 v[166:167], v[220:221], 0, s[12:13]
	s_mov_b32 m0, s35
	s_nop 0
	global_load_lds_dwordx4 v[166:167], off
	s_waitcnt vmcnt(10)
	s_setprio 1
	s_barrier
	s_waitcnt lgkmcnt(0)
	v_mfma_f32_16x16x32_bf16 v[64:67], v[68:71], v[158:161], v[64:67]
	v_mfma_f32_16x16x32_bf16 v[60:63], v[76:79], v[158:161], v[60:63]
	v_mfma_f32_16x16x32_bf16 v[48:51], v[68:71], v[178:181], v[48:51]
	v_mfma_f32_16x16x32_bf16 v[44:47], v[76:79], v[178:181], v[44:47]
	v_mfma_f32_16x16x32_bf16 v[32:35], v[68:71], v[186:189], v[32:35]
	v_mfma_f32_16x16x32_bf16 v[28:31], v[76:79], v[186:189], v[28:31]
	v_mfma_f32_16x16x32_bf16 v[14:17], v[68:71], v[194:197], v[14:17]
	v_mfma_f32_16x16x32_bf16 v[10:13], v[76:79], v[194:197], v[10:13]
	v_mfma_f32_16x16x32_bf16 v[64:67], v[72:75], v[174:177], v[64:67]
	v_mfma_f32_16x16x32_bf16 v[60:63], v[80:83], v[174:177], v[60:63]
	v_mfma_f32_16x16x32_bf16 v[48:51], v[72:75], v[182:185], v[48:51]
	v_mfma_f32_16x16x32_bf16 v[44:47], v[80:83], v[182:185], v[44:47]
	v_mfma_f32_16x16x32_bf16 v[32:35], v[72:75], v[190:193], v[32:35]
	v_mfma_f32_16x16x32_bf16 v[28:31], v[80:83], v[190:193], v[28:31]
	v_mfma_f32_16x16x32_bf16 v[14:17], v[72:75], v[198:201], v[14:17]
	v_mfma_f32_16x16x32_bf16 v[10:13], v[80:83], v[198:201], v[10:13]
	s_barrier
	s_setprio 0
	s_add_u32 s0, s26, 0x40080
	s_addc_u32 s1, s27, 0
	s_add_i32 s26, s28, s54
	s_mov_b32 m0, s26
	s_nop 0
	global_load_lds_dwordx4 v26, s[0:1]
	s_add_i32 m0, s26, 0x2000
	s_nop 0
	global_load_lds_dwordx4 v148, s[0:1]
	v_add_u32_e32 v80, 0x10000, v163
	ds_read_b128 v[68:71], v80
	ds_read_b128 v[72:75], v80 offset:1024
	ds_read_b128 v[76:79], v80 offset:2048
	ds_read_b128 v[80:83], v80 offset:3072
	s_add_i32 s82, s82, 2
	s_add_u32 s24, s24, 0x100
	s_addc_u32 s25, s25, 0
	s_add_u32 s73, s73, 0x100
	s_addc_u32 s81, s81, 0
	s_cmp_gt_u32 s82, 13
	s_waitcnt vmcnt(10)
	s_setprio 1
	s_barrier
	v_mfma_f32_16x16x32_bf16 v[56:59], v[202:205], v[158:161], v[56:59]
	v_mfma_f32_16x16x32_bf16 v[52:55], v[210:213], v[158:161], v[52:55]
	v_mfma_f32_16x16x32_bf16 v[40:43], v[202:205], v[178:181], v[40:43]
	v_mfma_f32_16x16x32_bf16 v[36:39], v[210:213], v[178:181], v[36:39]
	v_mfma_f32_16x16x32_bf16 v[22:25], v[202:205], v[186:189], v[22:25]
	v_mfma_f32_16x16x32_bf16 v[18:21], v[210:213], v[186:189], v[18:21]
	v_mfma_f32_16x16x32_bf16 v[6:9], v[202:205], v[194:197], v[6:9]
	v_mfma_f32_16x16x32_bf16 v[2:5], v[210:213], v[194:197], v[2:5]
	v_mfma_f32_16x16x32_bf16 v[56:59], v[206:209], v[174:177], v[56:59]
	v_mfma_f32_16x16x32_bf16 v[52:55], v[214:217], v[174:177], v[52:55]
	v_mfma_f32_16x16x32_bf16 v[40:43], v[206:209], v[182:185], v[40:43]
	v_mfma_f32_16x16x32_bf16 v[36:39], v[214:217], v[182:185], v[36:39]
	v_mfma_f32_16x16x32_bf16 v[22:25], v[206:209], v[190:193], v[22:25]
	v_mfma_f32_16x16x32_bf16 v[18:21], v[214:217], v[190:193], v[18:21]
	v_mfma_f32_16x16x32_bf16 v[6:9], v[206:209], v[198:201], v[6:9]
	v_mfma_f32_16x16x32_bf16 v[2:5], v[214:217], v[198:201], v[2:5]
	s_barrier
	s_setprio 0
	s_cbranch_scc0 .LBB0_1048
	s_waitcnt lgkmcnt(0)
	v_readlane_b32 s82, v255, 51
	s_cmpk_gt_i32 s22, 0xff
	s_mov_b64 s[24:25], 0xb000
	v_readlane_b32 s83, v255, 52
	s_cbranch_scc1 .LBB0_1044
	s_ashr_i32 s0, s22, 5
	s_mul_hi_i32 s25, s0, 0x1600
	s_mul_i32 s24, s0, 0x1600
	s_branch .LBB0_1044

.LBB0_1122:
	s_add_u32 s26, s24, 0x100
	s_addc_u32 s27, s25, 0
	s_add_i32 s0, 0, 0x10000
	s_cmp_eq_u32 s72, 40
	s_cselect_b32 s31, s43, s27
	s_cselect_b32 s30, s42, s26
	s_cselect_b32 s29, s45, s69
	s_cselect_b32 s28, s44, s68
	s_add_i32 m0, s36, 0xc000
	ds_read_b128 v[162:165], v188
	ds_read_b128 v[172:175], v188 offset:1024
	ds_read_b128 v[176:179], v188 offset:2048
	ds_read_b128 v[180:183], v188 offset:3072
	ds_read_b128 v[190:193], v188 offset:4096
	ds_read_b128 v[194:197], v188 offset:5120
	ds_read_b128 v[198:201], v188 offset:6144
	ds_read_b128 v[202:205], v188 offset:7168
	global_load_lds_dwordx4 v150, s[24:25]
	v_lshl_add_u64 v[166:167], s[24:25], 0, v[152:153]
	s_add_i32 m0, s36, 0xe000
	s_nop 0
	global_load_lds_dwordx4 v[166:167], off
	s_waitcnt vmcnt(10) lgkmcnt(8)
	s_setprio 1
	s_barrier
	s_waitcnt lgkmcnt(0)
	v_mfma_f32_16x16x32_bf16 v[128:131], v[132:135], v[162:165], v[128:131]
	v_mfma_f32_16x16x32_bf16 v[124:127], v[154:157], v[162:165], v[124:127]
	v_mfma_f32_16x16x32_bf16 v[120:123], v[132:135], v[176:179], v[120:123]
	v_mfma_f32_16x16x32_bf16 v[116:119], v[154:157], v[176:179], v[116:119]
	v_mfma_f32_16x16x32_bf16 v[112:115], v[132:135], v[190:193], v[112:115]
	v_mfma_f32_16x16x32_bf16 v[108:111], v[154:157], v[190:193], v[108:111]
	v_mfma_f32_16x16x32_bf16 v[104:107], v[132:135], v[198:201], v[104:107]
	v_mfma_f32_16x16x32_bf16 v[100:103], v[154:157], v[198:201], v[100:103]
	v_mfma_f32_16x16x32_bf16 v[128:131], v[136:139], v[172:175], v[128:131]
	v_mfma_f32_16x16x32_bf16 v[124:127], v[158:161], v[172:175], v[124:127]
	v_mfma_f32_16x16x32_bf16 v[120:123], v[136:139], v[180:183], v[120:123]
	v_mfma_f32_16x16x32_bf16 v[116:119], v[158:161], v[180:183], v[116:119]
	v_mfma_f32_16x16x32_bf16 v[112:115], v[136:139], v[194:197], v[112:115]
	v_mfma_f32_16x16x32_bf16 v[108:111], v[158:161], v[194:197], v[108:111]
	v_mfma_f32_16x16x32_bf16 v[104:107], v[136:139], v[202:205], v[104:107]
	v_mfma_f32_16x16x32_bf16 v[100:103], v[158:161], v[202:205], v[100:103]
	s_barrier
	s_setprio 0
	s_add_i32 s24, 0, 0x14000
	v_add_u32_e32 v166, s24, v186
	s_add_i32 s0, s0, s17
	ds_read_b128 v[206:209], v166
	ds_read_b128 v[210:213], v166 offset:1024
	ds_read_b128 v[214:217], v166 offset:2048
	ds_read_b128 v[218:221], v166 offset:3072
	v_lshl_add_u64 v[166:167], s[28:29], 0, v[26:27]
	s_mov_b32 m0, s0
	v_lshl_add_u64 v[168:169], s[28:29], 0, v[144:145]
	global_load_lds_dwordx4 v[166:167], off
	s_add_i32 m0, s0, 0x2000
	s_nop 0
	global_load_lds_dwordx4 v[168:169], off
	s_waitcnt vmcnt(10)
	s_setprio 1
	s_barrier
	s_waitcnt lgkmcnt(0)
	v_mfma_f32_16x16x32_bf16 v[68:71], v[206:209], v[162:165], v[68:71]
	v_mfma_f32_16x16x32_bf16 v[60:63], v[214:217], v[162:165], v[60:63]
	v_mfma_f32_16x16x32_bf16 v[56:59], v[206:209], v[176:179], v[56:59]
	v_mfma_f32_16x16x32_bf16 v[52:55], v[214:217], v[176:179], v[52:55]
	v_mfma_f32_16x16x32_bf16 v[48:51], v[206:209], v[190:193], v[48:51]
	v_mfma_f32_16x16x32_bf16 v[44:47], v[214:217], v[190:193], v[44:47]
	v_mfma_f32_16x16x32_bf16 v[40:43], v[206:209], v[198:201], v[40:43]
	v_mfma_f32_16x16x32_bf16 v[36:39], v[214:217], v[198:201], v[36:39]
	v_mfma_f32_16x16x32_bf16 v[68:71], v[210:213], v[172:175], v[68:71]
	v_mfma_f32_16x16x32_bf16 v[60:63], v[218:221], v[172:175], v[60:63]
	v_mfma_f32_16x16x32_bf16 v[56:59], v[210:213], v[180:183], v[56:59]
	v_mfma_f32_16x16x32_bf16 v[52:55], v[218:221], v[180:183], v[52:55]
	v_mfma_f32_16x16x32_bf16 v[48:51], v[210:213], v[194:197], v[48:51]
	v_mfma_f32_16x16x32_bf16 v[44:47], v[218:221], v[194:197], v[44:47]
	v_mfma_f32_16x16x32_bf16 v[40:43], v[210:213], v[202:205], v[40:43]
	v_mfma_f32_16x16x32_bf16 v[36:39], v[218:221], v[202:205], v[36:39]
	s_barrier
	s_setprio 0
	s_mov_b32 m0, s36
	v_lshl_add_u64 v[184:185], s[30:31], 0, v[140:141]
	ds_read_b128 v[162:165], v188 offset:16384
	ds_read_b128 v[172:175], v188 offset:17408
	ds_read_b128 v[176:179], v188 offset:18432
	ds_read_b128 v[180:183], v188 offset:19456
	ds_read_b128 v[190:193], v188 offset:20480
	ds_read_b128 v[194:197], v188 offset:21504
	ds_read_b128 v[198:201], v188 offset:22528
	ds_read_b128 v[202:205], v188 offset:23552
	global_load_lds_dwordx4 v[184:185], off
	v_lshl_add_u64 v[222:223], s[30:31], 0, v[142:143]
	s_mov_b32 m0, s37
	s_nop 0
	global_load_lds_dwordx4 v[222:223], off
	s_waitcnt vmcnt(10)
	s_setprio 1
	s_barrier
	s_waitcnt lgkmcnt(0)
	v_mfma_f32_16x16x32_bf16 v[96:99], v[132:135], v[162:165], v[96:99]
	v_mfma_f32_16x16x32_bf16 v[92:95], v[154:157], v[162:165], v[92:95]
	v_mfma_f32_16x16x32_bf16 v[88:91], v[132:135], v[176:179], v[88:91]
	v_mfma_f32_16x16x32_bf16 v[84:87], v[154:157], v[176:179], v[84:87]
	v_mfma_f32_16x16x32_bf16 v[80:83], v[132:135], v[190:193], v[80:83]
	v_mfma_f32_16x16x32_bf16 v[76:79], v[154:157], v[190:193], v[76:79]
	v_mfma_f32_16x16x32_bf16 v[72:75], v[132:135], v[198:201], v[72:75]
	v_mfma_f32_16x16x32_bf16 v[64:67], v[154:157], v[198:201], v[64:67]
	v_mfma_f32_16x16x32_bf16 v[96:99], v[136:139], v[172:175], v[96:99]
	v_mfma_f32_16x16x32_bf16 v[92:95], v[158:161], v[172:175], v[92:95]
	v_mfma_f32_16x16x32_bf16 v[88:91], v[136:139], v[180:183], v[88:91]
	v_mfma_f32_16x16x32_bf16 v[84:87], v[158:161], v[180:183], v[84:87]
	v_mfma_f32_16x16x32_bf16 v[80:83], v[136:139], v[194:197], v[80:83]
	v_mfma_f32_16x16x32_bf16 v[76:79], v[158:161], v[194:197], v[76:79]
	v_mfma_f32_16x16x32_bf16 v[72:75], v[136:139], v[202:205], v[72:75]
	v_mfma_f32_16x16x32_bf16 v[64:67], v[158:161], v[202:205], v[64:67]
	s_barrier
	s_setprio 0
	s_add_u32 s0, s28, 0xb0000
	s_addc_u32 s1, s29, 0
	s_add_i32 s24, s24, s17
	s_mov_b32 m0, s24
	s_nop 0
	global_load_lds_dwordx4 v26, s[0:1]
	s_add_i32 m0, s24, 0x2000
	s_nop 0
	global_load_lds_dwordx4 v144, s[0:1]
	v_add_u32_e32 v158, 0x18000, v186
	ds_read_b128 v[132:135], v158
	ds_read_b128 v[136:139], v158 offset:1024
	ds_read_b128 v[154:157], v158 offset:2048
	ds_read_b128 v[158:161], v158 offset:3072
	s_waitcnt vmcnt(10)
	s_setprio 1
	s_barrier
	v_mfma_f32_16x16x32_bf16 v[32:35], v[206:209], v[162:165], v[32:35]
	v_mfma_f32_16x16x32_bf16 v[28:31], v[214:217], v[162:165], v[28:31]
	v_mfma_f32_16x16x32_bf16 v[22:25], v[206:209], v[176:179], v[22:25]
	v_mfma_f32_16x16x32_bf16 v[18:21], v[214:217], v[176:179], v[18:21]
	v_mfma_f32_16x16x32_bf16 v[14:17], v[206:209], v[190:193], v[14:17]
	v_mfma_f32_16x16x32_bf16 v[10:13], v[214:217], v[190:193], v[10:13]
	v_mfma_f32_16x16x32_bf16 v[6:9], v[206:209], v[198:201], v[6:9]
	v_mfma_f32_16x16x32_bf16 v[2:5], v[214:217], v[198:201], v[2:5]
	v_mfma_f32_16x16x32_bf16 v[32:35], v[210:213], v[172:175], v[32:35]
	v_mfma_f32_16x16x32_bf16 v[28:31], v[218:221], v[172:175], v[28:31]
	v_mfma_f32_16x16x32_bf16 v[22:25], v[210:213], v[180:183], v[22:25]
	v_mfma_f32_16x16x32_bf16 v[18:21], v[218:221], v[180:183], v[18:21]
	v_mfma_f32_16x16x32_bf16 v[14:17], v[210:213], v[194:197], v[14:17]
	v_mfma_f32_16x16x32_bf16 v[10:13], v[218:221], v[194:197], v[10:13]
	v_mfma_f32_16x16x32_bf16 v[6:9], v[210:213], v[202:205], v[6:9]
	v_mfma_f32_16x16x32_bf16 v[2:5], v[218:221], v[202:205], v[2:5]
	s_barrier
	s_setprio 0
	s_add_i32 s24, 0, 0x18000
	s_add_u32 s0, s30, 0xb0000
	s_addc_u32 s1, s31, 0
	s_mov_b32 m0, s52
	ds_read_b128 v[162:165], v188 offset:32768
	ds_read_b128 v[172:175], v188 offset:33792
	ds_read_b128 v[176:179], v188 offset:34816
	ds_read_b128 v[180:183], v188 offset:35840
	ds_read_b128 v[190:193], v188 offset:36864
	ds_read_b128 v[194:197], v188 offset:37888
	ds_read_b128 v[198:201], v188 offset:38912
	ds_read_b128 v[202:205], v188 offset:39936
	global_load_lds_dwordx4 v140, s[0:1]
	s_mov_b32 m0, s54
	s_nop 0
	global_load_lds_dwordx4 v142, s[0:1]
	s_waitcnt vmcnt(10) lgkmcnt(8)
	s_setprio 1
	s_barrier
	s_waitcnt lgkmcnt(0)
	v_mfma_f32_16x16x32_bf16 v[128:131], v[132:135], v[162:165], v[128:131]
	v_mfma_f32_16x16x32_bf16 v[124:127], v[154:157], v[162:165], v[124:127]
	v_mfma_f32_16x16x32_bf16 v[120:123], v[132:135], v[176:179], v[120:123]
	v_mfma_f32_16x16x32_bf16 v[116:119], v[154:157], v[176:179], v[116:119]
	v_mfma_f32_16x16x32_bf16 v[112:115], v[132:135], v[190:193], v[112:115]
	v_mfma_f32_16x16x32_bf16 v[108:111], v[154:157], v[190:193], v[108:111]
	v_mfma_f32_16x16x32_bf16 v[104:107], v[132:135], v[198:201], v[104:107]
	v_mfma_f32_16x16x32_bf16 v[100:103], v[154:157], v[198:201], v[100:103]
	v_mfma_f32_16x16x32_bf16 v[128:131], v[136:139], v[172:175], v[128:131]
	v_mfma_f32_16x16x32_bf16 v[124:127], v[158:161], v[172:175], v[124:127]
	v_mfma_f32_16x16x32_bf16 v[120:123], v[136:139], v[180:183], v[120:123]
	v_mfma_f32_16x16x32_bf16 v[116:119], v[158:161], v[180:183], v[116:119]
	v_mfma_f32_16x16x32_bf16 v[112:115], v[136:139], v[194:197], v[112:115]
	v_mfma_f32_16x16x32_bf16 v[108:111], v[158:161], v[194:197], v[108:111]
	v_mfma_f32_16x16x32_bf16 v[104:107], v[136:139], v[202:205], v[104:107]
	v_mfma_f32_16x16x32_bf16 v[100:103], v[158:161], v[202:205], v[100:103]
	s_barrier
	s_setprio 0
	s_add_i32 s25, 0, 0x1c000
	s_add_i32 s0, s24, s17
	v_add_u32_e32 v189, s25, v186
	v_lshl_add_u64 v[166:167], v[166:167], 0, s[12:13]
	s_mov_b32 m0, s0
	ds_read_b128 v[206:209], v189
	ds_read_b128 v[210:213], v189 offset:1024
	ds_read_b128 v[214:217], v189 offset:2048
	ds_read_b128 v[218:221], v189 offset:3072
	global_load_lds_dwordx4 v[166:167], off
	v_lshl_add_u64 v[166:167], v[168:169], 0, s[12:13]
	s_add_i32 m0, s0, 0x2000
	s_nop 0
	global_load_lds_dwordx4 v[166:167], off
	s_waitcnt vmcnt(10)
	s_setprio 1
	s_barrier
	s_waitcnt lgkmcnt(0)
	v_mfma_f32_16x16x32_bf16 v[68:71], v[206:209], v[162:165], v[68:71]
	v_mfma_f32_16x16x32_bf16 v[60:63], v[214:217], v[162:165], v[60:63]
	v_mfma_f32_16x16x32_bf16 v[56:59], v[206:209], v[176:179], v[56:59]
	v_mfma_f32_16x16x32_bf16 v[52:55], v[214:217], v[176:179], v[52:55]
	v_mfma_f32_16x16x32_bf16 v[48:51], v[206:209], v[190:193], v[48:51]
	v_mfma_f32_16x16x32_bf16 v[44:47], v[214:217], v[190:193], v[44:47]
	v_mfma_f32_16x16x32_bf16 v[40:43], v[206:209], v[198:201], v[40:43]
	v_mfma_f32_16x16x32_bf16 v[36:39], v[214:217], v[198:201], v[36:39]
	v_mfma_f32_16x16x32_bf16 v[68:71], v[210:213], v[172:175], v[68:71]
	v_mfma_f32_16x16x32_bf16 v[60:63], v[218:221], v[172:175], v[60:63]
	v_mfma_f32_16x16x32_bf16 v[56:59], v[210:213], v[180:183], v[56:59]
	v_mfma_f32_16x16x32_bf16 v[52:55], v[218:221], v[180:183], v[52:55]
	v_mfma_f32_16x16x32_bf16 v[48:51], v[210:213], v[194:197], v[48:51]
	v_mfma_f32_16x16x32_bf16 v[44:47], v[218:221], v[194:197], v[44:47]
	v_mfma_f32_16x16x32_bf16 v[40:43], v[210:213], v[202:205], v[40:43]
	v_mfma_f32_16x16x32_bf16 v[36:39], v[218:221], v[202:205], v[36:39]
	s_barrier
	s_setprio 0
	s_mov_b32 m0, s55
	v_lshl_add_u64 v[166:167], v[184:185], 0, s[12:13]
	ds_read_b128 v[162:165], v188 offset:49152
	ds_read_b128 v[172:175], v188 offset:50176
	ds_read_b128 v[176:179], v188 offset:51200
	ds_read_b128 v[180:183], v188 offset:52224
	ds_read_b128 v[190:193], v188 offset:53248
	ds_read_b128 v[194:197], v188 offset:54272
	ds_read_b128 v[198:201], v188 offset:55296
	ds_read_b128 v[202:205], v188 offset:56320
	global_load_lds_dwordx4 v[166:167], off
	v_lshl_add_u64 v[166:167], v[222:223], 0, s[12:13]
	s_mov_b32 m0, s56
	s_nop 0
	global_load_lds_dwordx4 v[166:167], off
	s_waitcnt vmcnt(10)
	s_setprio 1
	s_barrier
	s_waitcnt lgkmcnt(0)
	v_mfma_f32_16x16x32_bf16 v[96:99], v[132:135], v[162:165], v[96:99]
	v_mfma_f32_16x16x32_bf16 v[92:95], v[154:157], v[162:165], v[92:95]
	v_mfma_f32_16x16x32_bf16 v[88:91], v[132:135], v[176:179], v[88:91]
	v_mfma_f32_16x16x32_bf16 v[84:87], v[154:157], v[176:179], v[84:87]
	v_mfma_f32_16x16x32_bf16 v[80:83], v[132:135], v[190:193], v[80:83]
	v_mfma_f32_16x16x32_bf16 v[76:79], v[154:157], v[190:193], v[76:79]
	v_mfma_f32_16x16x32_bf16 v[72:75], v[132:135], v[198:201], v[72:75]
	v_mfma_f32_16x16x32_bf16 v[64:67], v[154:157], v[198:201], v[64:67]
	v_mfma_f32_16x16x32_bf16 v[96:99], v[136:139], v[172:175], v[96:99]
	v_mfma_f32_16x16x32_bf16 v[92:95], v[158:161], v[172:175], v[92:95]
	v_mfma_f32_16x16x32_bf16 v[88:91], v[136:139], v[180:183], v[88:91]
	v_mfma_f32_16x16x32_bf16 v[84:87], v[158:161], v[180:183], v[84:87]
	v_mfma_f32_16x16x32_bf16 v[80:83], v[136:139], v[194:197], v[80:83]
	v_mfma_f32_16x16x32_bf16 v[76:79], v[158:161], v[194:197], v[76:79]
	v_mfma_f32_16x16x32_bf16 v[72:75], v[136:139], v[202:205], v[72:75]
	v_mfma_f32_16x16x32_bf16 v[64:67], v[158:161], v[202:205], v[64:67]
	s_barrier
	s_setprio 0
	s_add_u32 s0, s28, 0xb0080
	s_addc_u32 s1, s29, 0
	s_add_i32 s24, s25, s17
	s_mov_b32 m0, s24
	s_nop 0
	global_load_lds_dwordx4 v26, s[0:1]
	s_add_i32 m0, s24, 0x2000
	s_nop 0
	global_load_lds_dwordx4 v144, s[0:1]
	v_add_u32_e32 v158, 0x10000, v186
	ds_read_b128 v[132:135], v158
	ds_read_b128 v[136:139], v158 offset:1024
	ds_read_b128 v[154:157], v158 offset:2048
	ds_read_b128 v[158:161], v158 offset:3072
	s_add_i32 s72, s72, 2
	s_add_u32 s68, s68, 0x100
	s_addc_u32 s69, s69, 0
	s_cmp_gt_u32 s72, 41
	s_mov_b64 s[24:25], s[26:27]
	s_waitcnt vmcnt(10)
	s_setprio 1
	s_barrier
	v_mfma_f32_16x16x32_bf16 v[32:35], v[206:209], v[162:165], v[32:35]
	v_mfma_f32_16x16x32_bf16 v[28:31], v[214:217], v[162:165], v[28:31]
	v_mfma_f32_16x16x32_bf16 v[22:25], v[206:209], v[176:179], v[22:25]
	v_mfma_f32_16x16x32_bf16 v[18:21], v[214:217], v[176:179], v[18:21]
	v_mfma_f32_16x16x32_bf16 v[14:17], v[206:209], v[190:193], v[14:17]
	v_mfma_f32_16x16x32_bf16 v[10:13], v[214:217], v[190:193], v[10:13]
	v_mfma_f32_16x16x32_bf16 v[6:9], v[206:209], v[198:201], v[6:9]
	v_mfma_f32_16x16x32_bf16 v[2:5], v[214:217], v[198:201], v[2:5]
	v_mfma_f32_16x16x32_bf16 v[32:35], v[210:213], v[172:175], v[32:35]
	v_mfma_f32_16x16x32_bf16 v[28:31], v[218:221], v[172:175], v[28:31]
	v_mfma_f32_16x16x32_bf16 v[22:25], v[210:213], v[180:183], v[22:25]
	v_mfma_f32_16x16x32_bf16 v[18:21], v[218:221], v[180:183], v[18:21]
	v_mfma_f32_16x16x32_bf16 v[14:17], v[210:213], v[194:197], v[14:17]
	v_mfma_f32_16x16x32_bf16 v[10:13], v[218:221], v[194:197], v[10:13]
	v_mfma_f32_16x16x32_bf16 v[6:9], v[210:213], v[202:205], v[6:9]
	v_mfma_f32_16x16x32_bf16 v[2:5], v[218:221], v[202:205], v[2:5]
	s_barrier
	s_setprio 0
	s_cbranch_scc0 .LBB0_1122
	s_waitcnt lgkmcnt(0)
	s_min_i32 s0, s22, 0x100
	s_ashr_i32 s26, s0, 5
	s_add_i32 s0, s22, 0xffffff00
	s_cmpk_lt_i32 s22, 0x100
	s_cselect_b32 s0, s22, s0
	s_cselect_b32 s25, 0, s51
	s_cselect_b32 s24, 0, s50
	s_ashr_i32 s1, s0, 31
	s_lshl_b64 s[0:1], s[0:1], 19
	s_add_u32 s24, s20, s24
	v_lshl_or_b32 v166, s23, 8, v187
	s_addc_u32 s25, s21, s25
	s_ashr_i32 s23, s22, 31
	v_lshl_add_u64 v[132:133], s[0:1], 0, v[146:147]
	s_lshl_b64 s[22:23], s[22:23], 10
	s_mul_hi_i32 s1, s26, 0x9000
	s_mul_i32 s26, s26, 0x9000
	s_add_u32 s0, s34, s26
	v_ashrrev_i32_e32 v167, 31, v166
	s_addc_u32 s1, s35, s1
	v_lshl_add_u64 v[154:155], v[166:167], 2, s[0:1]
	v_lshl_add_u64 v[168:169], v[132:133], 0, v[166:167]
	v_lshl_add_u64 v[176:177], v[132:133], 1, s[24:25]
	global_load_dwordx4 v[132:135], v[154:155], off offset:16
	global_load_dwordx4 v[136:139], v[154:155], off
	v_lshl_add_u64 v[182:183], v[168:169], 1, s[24:25]
	v_add_co_u32_e32 v184, vcc, s65, v182
	s_mov_b32 s0, 0x20000
	s_nop 0
	v_addc_co_u32_e32 v185, vcc, 0, v183, vcc
	v_add_co_u32_e32 v178, vcc, s0, v182
	s_mov_b32 s1, 0x30000
	s_nop 0
	v_addc_co_u32_e32 v179, vcc, 0, v183, vcc
	v_add_co_u32_e32 v180, vcc, s1, v182
	v_lshl_add_u64 v[176:177], v[166:167], 1, v[176:177]
	s_nop 0
	v_addc_co_u32_e32 v181, vcc, 0, v183, vcc
	s_mov_b32 s24, 0x80000
	s_mov_b32 s25, 0x90000
	s_waitcnt vmcnt(0)
	v_pk_mul_f32 v[164:165], v[134:135], 0.5 op_sel_hi:[1,0]
	v_pk_mul_f32 v[174:175], v[138:139], 0.5 op_sel_hi:[1,0]
	v_pk_mul_f32 v[172:173], v[136:137], 0.5 op_sel_hi:[1,0]
	v_pk_mul_f32 v[162:163], v[132:133], 0.5 op_sel_hi:[1,0]
	global_load_dwordx4 v[132:135], v[154:155], off offset:528
	global_load_dwordx4 v[136:139], v[154:155], off offset:512
	global_load_dwordx4 v[190:193], v[182:183], off offset:2048
	global_load_dwordx4 v[194:197], v[184:185], off offset:2048
	s_waitcnt vmcnt(0)
	v_pk_mul_f32 v[156:157], v[134:135], 0.5 op_sel_hi:[1,0]
	v_pk_mul_f32 v[160:161], v[138:139], 0.5 op_sel_hi:[1,0]
	v_pk_mul_f32 v[158:159], v[136:137], 0.5 op_sel_hi:[1,0]
	global_load_dwordx4 v[136:139], v[178:179], off offset:2048
	v_pk_mul_f32 v[154:155], v[132:133], 0.5 op_sel_hi:[1,0]
	global_load_dwordx4 v[132:135], v[180:181], off offset:2048
	v_lshlrev_b32_e32 v166, 16, v190
	v_and_b32_e32 v167, 0xffff0000, v190
	v_lshlrev_b32_e32 v168, 16, v191
	v_and_b32_e32 v169, 0xffff0000, v191
	v_lshlrev_b32_e32 v190, 16, v192
	v_and_b32_e32 v191, 0xffff0000, v192
	v_lshlrev_b32_e32 v192, 16, v193
	v_and_b32_e32 v193, 0xffff0000, v193
	v_pk_fma_f32 v[130:131], v[130:131], v[174:175], v[168:169]
	v_pk_fma_f32 v[128:129], v[128:129], v[172:173], v[166:167]
	v_pk_fma_f32 v[166:167], v[126:127], v[164:165], v[192:193]
	v_pk_fma_f32 v[126:127], v[124:125], v[162:163], v[190:191]
	v_lshlrev_b32_e32 v202, 16, v196
	v_and_b32_e32 v203, 0xffff0000, v196
	v_lshlrev_b32_e32 v204, 16, v197
	v_and_b32_e32 v205, 0xffff0000, v197
	v_cvt_pk_bf16_f32 v124, v128, v129
	v_cvt_pk_bf16_f32 v125, v130, v131
	v_cvt_pk_bf16_f32 v126, v126, v127
	v_cvt_pk_bf16_f32 v127, v166, v167
	v_lshlrev_b32_e32 v200, 16, v195
	v_and_b32_e32 v201, 0xffff0000, v195
	global_store_dwordx4 v[176:177], v[124:127], off offset:2048
	v_lshlrev_b32_e32 v193, 16, v124
	v_and_b32_e32 v196, 0xffff0000, v124
	v_lshlrev_b32_e32 v191, 16, v125
	v_and_b32_e32 v195, 0xffff0000, v125
	v_pk_fma_f32 v[124:125], v[118:119], v[164:165], v[204:205]
	v_pk_fma_f32 v[118:119], v[116:117], v[162:163], v[202:203]
	v_lshlrev_b32_e32 v198, 16, v194
	v_cvt_pk_bf16_f32 v118, v118, v119
	v_cvt_pk_bf16_f32 v119, v124, v125
	v_add_co_u32_e32 v124, vcc, s65, v176
	v_and_b32_e32 v199, 0xffff0000, v194
	s_nop 0
	v_addc_co_u32_e32 v125, vcc, 0, v177, vcc
	v_lshlrev_b32_e32 v190, 16, v126
	v_and_b32_e32 v194, 0xffff0000, v126
	v_add_co_u32_e32 v126, vcc, s24, v182
	v_lshlrev_b32_e32 v189, 16, v127
	v_and_b32_e32 v192, 0xffff0000, v127
	v_addc_co_u32_e32 v127, vcc, 0, v183, vcc
	v_add_co_u32_e32 v128, vcc, s25, v182
	v_pk_fma_f32 v[122:123], v[122:123], v[174:175], v[200:201]
	v_pk_fma_f32 v[120:121], v[120:121], v[172:173], v[198:199]
	v_addc_co_u32_e32 v129, vcc, 0, v183, vcc
	v_cvt_pk_bf16_f32 v116, v120, v121
	v_cvt_pk_bf16_f32 v117, v122, v123
	global_store_dwordx4 v[124:125], v[116:119], off offset:2048
	global_load_dwordx4 v[120:123], v[126:127], off offset:2048
	global_load_dwordx4 v[198:201], v[128:129], off offset:2048
	s_waitcnt vmcnt(0)
	v_lshlrev_b32_e32 v130, 16, v136
	v_and_b32_e32 v131, 0xffff0000, v136
	v_lshlrev_b32_e32 v166, 16, v138
	v_and_b32_e32 v167, 0xffff0000, v138
	v_lshlrev_b32_e32 v138, 16, v139
	v_and_b32_e32 v139, 0xffff0000, v139
	v_pk_fma_f32 v[112:113], v[112:113], v[172:173], v[130:131]
	v_pk_fma_f32 v[130:131], v[110:111], v[164:165], v[138:139]
	v_pk_fma_f32 v[110:111], v[108:109], v[162:163], v[166:167]
	v_lshlrev_b32_e32 v168, 16, v132
	v_cvt_pk_bf16_f32 v110, v110, v111
	v_cvt_pk_bf16_f32 v111, v130, v131
	v_add_co_u32_e32 v130, vcc, s0, v176
	v_and_b32_e32 v169, 0xffff0000, v132
	v_lshlrev_b32_e32 v132, 16, v133
	v_and_b32_e32 v133, 0xffff0000, v133
	v_addc_co_u32_e32 v131, vcc, 0, v177, vcc
	v_lshlrev_b32_e32 v136, 16, v137
	v_and_b32_e32 v137, 0xffff0000, v137
	v_lshlrev_b32_e32 v202, 16, v134
	v_and_b32_e32 v203, 0xffff0000, v134
	v_lshlrev_b32_e32 v134, 16, v135
	v_and_b32_e32 v135, 0xffff0000, v135
	v_pk_fma_f32 v[106:107], v[106:107], v[174:175], v[132:133]
	v_add_co_u32_e32 v132, vcc, s1, v176
	v_pk_fma_f32 v[114:115], v[114:115], v[174:175], v[136:137]
	v_cvt_pk_bf16_f32 v108, v112, v113
	v_pk_fma_f32 v[104:105], v[104:105], v[172:173], v[168:169]
	v_pk_fma_f32 v[112:113], v[102:103], v[164:165], v[134:135]
	v_pk_fma_f32 v[102:103], v[100:101], v[162:163], v[202:203]
	v_addc_co_u32_e32 v133, vcc, 0, v177, vcc
	v_cvt_pk_bf16_f32 v109, v114, v115
	v_cvt_pk_bf16_f32 v100, v104, v105
	v_cvt_pk_bf16_f32 v101, v106, v107
	v_cvt_pk_bf16_f32 v102, v102, v103
	v_cvt_pk_bf16_f32 v103, v112, v113
	v_add_co_u32_e32 v134, vcc, s76, v182
	global_store_dwordx4 v[130:131], v[108:111], off offset:2048
	global_store_dwordx4 v[132:133], v[100:103], off offset:2048
	v_addc_co_u32_e32 v135, vcc, 0, v183, vcc
	s_mov_b32 s0, 0xb0000
	global_load_dwordx4 v[112:115], v[134:135], off offset:2048
	v_add_co_u32_e32 v136, vcc, s0, v182
	v_lshlrev_b32_e32 v138, 16, v120
	s_nop 0
	v_addc_co_u32_e32 v137, vcc, 0, v183, vcc
	global_load_dwordx4 v[104:107], v[136:137], off offset:2048
	v_and_b32_e32 v139, 0xffff0000, v120
	v_lshlrev_b32_e32 v120, 16, v121
	v_and_b32_e32 v121, 0xffff0000, v121
	v_lshlrev_b32_e32 v166, 16, v122
	v_and_b32_e32 v167, 0xffff0000, v122
	v_lshlrev_b32_e32 v122, 16, v123
	v_and_b32_e32 v123, 0xffff0000, v123
	v_pk_fma_f32 v[96:97], v[96:97], v[172:173], v[138:139]
	v_lshlrev_b32_e32 v168, 16, v198
	v_and_b32_e32 v169, 0xffff0000, v198
	v_lshlrev_b32_e32 v198, 16, v199
	v_and_b32_e32 v199, 0xffff0000, v199
	v_pk_fma_f32 v[98:99], v[98:99], v[174:175], v[120:121]
	v_pk_fma_f32 v[120:121], v[94:95], v[164:165], v[122:123]
	v_pk_fma_f32 v[94:95], v[92:93], v[162:163], v[166:167]
	v_cvt_pk_bf16_f32 v92, v96, v97
	v_add_co_u32_e32 v96, vcc, s24, v176
	v_lshlrev_b32_e32 v202, 16, v200
	v_and_b32_e32 v203, 0xffff0000, v200
	v_lshlrev_b32_e32 v200, 16, v201
	v_and_b32_e32 v201, 0xffff0000, v201
	v_addc_co_u32_e32 v97, vcc, 0, v177, vcc
	v_pk_fma_f32 v[90:91], v[90:91], v[174:175], v[198:199]
	v_pk_fma_f32 v[88:89], v[88:89], v[172:173], v[168:169]
	v_cvt_pk_bf16_f32 v93, v98, v99
	v_pk_fma_f32 v[98:99], v[86:87], v[164:165], v[200:201]
	v_pk_fma_f32 v[86:87], v[84:85], v[162:163], v[202:203]
	v_cvt_pk_bf16_f32 v84, v88, v89
	v_cvt_pk_bf16_f32 v85, v90, v91
	v_add_co_u32_e32 v88, vcc, s25, v176
	v_cvt_pk_bf16_f32 v86, v86, v87
	v_cvt_pk_bf16_f32 v87, v98, v99
	v_addc_co_u32_e32 v89, vcc, 0, v177, vcc
	v_cvt_pk_bf16_f32 v94, v94, v95
	v_cvt_pk_bf16_f32 v95, v120, v121
	global_store_dwordx4 v[96:97], v[92:95], off offset:2048
	global_store_dwordx4 v[88:89], v[84:87], off offset:2048
	global_load_dwordx4 v[120:123], v[182:183], off offset:2304
	s_nop 0
	global_load_dwordx4 v[182:185], v[184:185], off offset:2304
	s_waitcnt vmcnt(0)
	v_lshlrev_b32_e32 v90, 16, v112
	v_and_b32_e32 v91, 0xffff0000, v112
	v_lshlrev_b32_e32 v98, 16, v113
	v_and_b32_e32 v99, 0xffff0000, v113
	v_lshlrev_b32_e32 v112, 16, v114
	v_and_b32_e32 v113, 0xffff0000, v114
	v_lshlrev_b32_e32 v114, 16, v115
	v_and_b32_e32 v115, 0xffff0000, v115
	v_pk_fma_f32 v[80:81], v[80:81], v[172:173], v[90:91]
	v_pk_fma_f32 v[90:91], v[78:79], v[164:165], v[114:115]
	v_pk_fma_f32 v[78:79], v[76:77], v[162:163], v[112:113]
	v_cvt_pk_bf16_f32 v76, v80, v81
	v_add_co_u32_e32 v80, vcc, s76, v176
	v_lshlrev_b32_e32 v138, 16, v104
	v_and_b32_e32 v139, 0xffff0000, v104
	v_lshlrev_b32_e32 v104, 16, v105
	v_and_b32_e32 v105, 0xffff0000, v105
	v_lshlrev_b32_e32 v166, 16, v106
	v_and_b32_e32 v167, 0xffff0000, v106
	v_lshlrev_b32_e32 v106, 16, v107
	v_and_b32_e32 v107, 0xffff0000, v107
	v_pk_fma_f32 v[82:83], v[82:83], v[174:175], v[98:99]
	v_addc_co_u32_e32 v81, vcc, 0, v177, vcc
	v_pk_fma_f32 v[72:73], v[72:73], v[172:173], v[138:139]
	v_cvt_pk_bf16_f32 v77, v82, v83
	v_pk_fma_f32 v[74:75], v[74:75], v[174:175], v[104:105]
	v_pk_fma_f32 v[82:83], v[66:67], v[164:165], v[106:107]
	v_pk_fma_f32 v[66:67], v[64:65], v[162:163], v[166:167]
	v_cvt_pk_bf16_f32 v64, v72, v73
	v_add_co_u32_e32 v72, vcc, s0, v176
	v_cvt_pk_bf16_f32 v78, v78, v79
	v_cvt_pk_bf16_f32 v79, v90, v91
	v_cvt_pk_bf16_f32 v65, v74, v75
	v_cvt_pk_bf16_f32 v66, v66, v67
	v_cvt_pk_bf16_f32 v67, v82, v83
	v_addc_co_u32_e32 v73, vcc, 0, v177, vcc
	global_store_dwordx4 v[80:81], v[76:79], off offset:2048
	global_store_dwordx4 v[72:73], v[64:67], off offset:2048
	global_load_dwordx4 v[104:107], v[178:179], off offset:2304
	global_load_dwordx4 v[112:115], v[180:181], off offset:2304
	v_lshlrev_b32_e32 v74, 16, v120
	v_and_b32_e32 v75, 0xffff0000, v120
	v_lshlrev_b32_e32 v82, 16, v121
	v_and_b32_e32 v83, 0xffff0000, v121
	v_lshlrev_b32_e32 v90, 16, v122
	v_and_b32_e32 v91, 0xffff0000, v122
	v_lshlrev_b32_e32 v98, 16, v123
	v_and_b32_e32 v99, 0xffff0000, v123
	v_pk_fma_f32 v[70:71], v[70:71], v[160:161], v[82:83]
	v_pk_fma_f32 v[68:69], v[68:69], v[158:159], v[74:75]
	v_pk_fma_f32 v[74:75], v[62:63], v[156:157], v[98:99]
	v_pk_fma_f32 v[62:63], v[60:61], v[154:155], v[90:91]
	v_lshlrev_b32_e32 v120, 16, v182
	v_and_b32_e32 v121, 0xffff0000, v182
	v_lshlrev_b32_e32 v122, 16, v183
	v_and_b32_e32 v123, 0xffff0000, v183
	v_lshlrev_b32_e32 v138, 16, v184
	v_and_b32_e32 v139, 0xffff0000, v184
	v_lshlrev_b32_e32 v162, 16, v185
	v_and_b32_e32 v163, 0xffff0000, v185
	v_cvt_pk_bf16_f32 v60, v68, v69
	v_cvt_pk_bf16_f32 v61, v70, v71
	v_cvt_pk_bf16_f32 v62, v62, v63
	v_cvt_pk_bf16_f32 v63, v74, v75
	global_store_dwordx4 v[176:177], v[60:63], off offset:2304
	v_lshlrev_b32_e32 v164, 16, v60
	v_and_b32_e32 v165, 0xffff0000, v60
	v_lshlrev_b32_e32 v166, 16, v61
	v_and_b32_e32 v167, 0xffff0000, v61
	v_pk_fma_f32 v[58:59], v[58:59], v[160:161], v[122:123]
	v_pk_fma_f32 v[56:57], v[56:57], v[158:159], v[120:121]
	v_pk_fma_f32 v[60:61], v[54:55], v[156:157], v[162:163]
	v_pk_fma_f32 v[54:55], v[52:53], v[154:155], v[138:139]
	v_cvt_pk_bf16_f32 v52, v56, v57
	v_cvt_pk_bf16_f32 v53, v58, v59
	v_cvt_pk_bf16_f32 v54, v54, v55
	v_cvt_pk_bf16_f32 v55, v60, v61
	global_store_dwordx4 v[124:125], v[52:55], off offset:2304
	v_lshlrev_b32_e32 v168, 16, v62
	v_and_b32_e32 v169, 0xffff0000, v62
	v_lshlrev_b32_e32 v172, 16, v63
	v_and_b32_e32 v173, 0xffff0000, v63
	global_load_dwordx4 v[56:59], v[126:127], off offset:2304
	global_load_dwordx4 v[60:63], v[128:129], off offset:2304
	s_waitcnt vmcnt(0)
	v_lshlrev_b32_e32 v68, 16, v104
	v_and_b32_e32 v69, 0xffff0000, v104
	v_lshlrev_b32_e32 v70, 16, v105
	v_and_b32_e32 v71, 0xffff0000, v105
	v_lshlrev_b32_e32 v74, 16, v106
	v_and_b32_e32 v75, 0xffff0000, v106
	v_lshlrev_b32_e32 v82, 16, v107
	v_and_b32_e32 v83, 0xffff0000, v107
	v_lshlrev_b32_e32 v90, 16, v112
	v_and_b32_e32 v91, 0xffff0000, v112
	v_lshlrev_b32_e32 v98, 16, v113
	v_and_b32_e32 v99, 0xffff0000, v113
	v_lshlrev_b32_e32 v104, 16, v114
	v_and_b32_e32 v105, 0xffff0000, v114
	v_lshlrev_b32_e32 v106, 16, v115
	v_and_b32_e32 v107, 0xffff0000, v115
	v_pk_fma_f32 v[48:49], v[48:49], v[158:159], v[68:69]
	v_pk_fma_f32 v[50:51], v[50:51], v[160:161], v[70:71]
	v_pk_fma_f32 v[68:69], v[46:47], v[156:157], v[82:83]
	v_pk_fma_f32 v[46:47], v[44:45], v[154:155], v[74:75]
	v_cvt_pk_bf16_f32 v44, v48, v49
	v_pk_fma_f32 v[42:43], v[42:43], v[160:161], v[98:99]
	v_pk_fma_f32 v[40:41], v[40:41], v[158:159], v[90:91]
	v_pk_fma_f32 v[48:49], v[38:39], v[156:157], v[106:107]
	v_pk_fma_f32 v[38:39], v[36:37], v[154:155], v[104:105]
	v_cvt_pk_bf16_f32 v45, v50, v51
	v_cvt_pk_bf16_f32 v46, v46, v47
	v_cvt_pk_bf16_f32 v47, v68, v69
	v_cvt_pk_bf16_f32 v36, v40, v41
	v_cvt_pk_bf16_f32 v37, v42, v43
	v_cvt_pk_bf16_f32 v38, v38, v39
	v_cvt_pk_bf16_f32 v39, v48, v49
	global_store_dwordx4 v[130:131], v[44:47], off offset:2304
	global_store_dwordx4 v[132:133], v[36:39], off offset:2304
	global_load_dwordx4 v[40:43], v[134:135], off offset:2304
	global_load_dwordx4 v[48:51], v[136:137], off offset:2304
	v_lshlrev_b32_e32 v68, 16, v56
	v_and_b32_e32 v69, 0xffff0000, v56
	v_lshlrev_b32_e32 v56, 16, v57
	v_and_b32_e32 v57, 0xffff0000, v57
	v_lshlrev_b32_e32 v70, 16, v58
	v_and_b32_e32 v71, 0xffff0000, v58
	v_lshlrev_b32_e32 v58, 16, v59
	v_and_b32_e32 v59, 0xffff0000, v59
	v_lshlrev_b32_e32 v74, 16, v60
	v_and_b32_e32 v75, 0xffff0000, v60
	v_lshlrev_b32_e32 v82, 16, v62
	v_and_b32_e32 v83, 0xffff0000, v62
	v_lshlrev_b32_e32 v62, 16, v63
	v_and_b32_e32 v63, 0xffff0000, v63
	v_pk_fma_f32 v[32:33], v[32:33], v[158:159], v[68:69]
	v_lshlrev_b32_e32 v60, 16, v61
	v_and_b32_e32 v61, 0xffff0000, v61
	v_pk_fma_f32 v[34:35], v[34:35], v[160:161], v[56:57]
	v_pk_fma_f32 v[56:57], v[30:31], v[156:157], v[58:59]
	v_pk_fma_f32 v[30:31], v[28:29], v[154:155], v[70:71]
	v_cvt_pk_bf16_f32 v28, v32, v33
	v_pk_fma_f32 v[22:23], v[22:23], v[158:159], v[74:75]
	v_pk_fma_f32 v[32:33], v[20:21], v[156:157], v[62:63]
	v_pk_fma_f32 v[20:21], v[18:19], v[154:155], v[82:83]
	v_cvt_pk_bf16_f32 v29, v34, v35
	v_pk_fma_f32 v[24:25], v[24:25], v[160:161], v[60:61]
	v_cvt_pk_bf16_f32 v18, v22, v23
	v_cvt_pk_bf16_f32 v20, v20, v21
	v_cvt_pk_bf16_f32 v21, v32, v33
	v_cvt_pk_bf16_f32 v19, v24, v25
	v_cvt_pk_bf16_f32 v30, v30, v31
	v_cvt_pk_bf16_f32 v31, v56, v57
	global_store_dwordx4 v[96:97], v[28:31], off offset:2304
	global_store_dwordx4 v[88:89], v[18:21], off offset:2304
	s_waitcnt vmcnt(0)
	v_lshlrev_b32_e32 v22, 16, v40
	v_and_b32_e32 v23, 0xffff0000, v40
	v_lshlrev_b32_e32 v32, 16, v42
	v_and_b32_e32 v33, 0xffff0000, v42
	v_lshlrev_b32_e32 v34, 16, v43
	v_and_b32_e32 v35, 0xffff0000, v43
	v_lshlrev_b32_e32 v42, 16, v49
	v_and_b32_e32 v43, 0xffff0000, v49
	v_lshlrev_b32_e32 v24, 16, v41
	v_and_b32_e32 v25, 0xffff0000, v41
	v_lshlrev_b32_e32 v40, 16, v48
	v_and_b32_e32 v41, 0xffff0000, v48
	v_lshlrev_b32_e32 v48, 16, v50
	v_and_b32_e32 v49, 0xffff0000, v50
	v_lshlrev_b32_e32 v50, 16, v51
	v_and_b32_e32 v51, 0xffff0000, v51
	v_pk_fma_f32 v[14:15], v[14:15], v[158:159], v[22:23]
	v_pk_fma_f32 v[8:9], v[8:9], v[160:161], v[42:43]
	v_pk_fma_f32 v[22:23], v[12:13], v[156:157], v[34:35]
	v_pk_fma_f32 v[12:13], v[10:11], v[154:155], v[32:33]
	v_cvt_pk_bf16_f32 v10, v14, v15
	v_pk_fma_f32 v[14:15], v[4:5], v[156:157], v[50:51]
	v_pk_fma_f32 v[4:5], v[2:3], v[154:155], v[48:49]
	v_cvt_pk_bf16_f32 v3, v8, v9
	v_and_b32_e32 v9, 64, v227
	v_xor_b32_e32 v8, 16, v227
	v_add_u32_e32 v9, 64, v9
	v_cvt_pk_bf16_f32 v4, v4, v5
	v_cvt_pk_bf16_f32 v5, v14, v15
	v_cmp_lt_i32_e32 vcc, v8, v9
	v_xor_b32_e32 v14, 32, v227
	v_mul_f32_e32 v15, v195, v195
	v_cndmask_b32_e32 v8, v227, v8, vcc
	v_cmp_lt_i32_e32 vcc, v14, v9
	v_pk_fma_f32 v[16:17], v[16:17], v[160:161], v[24:25]
	v_fmac_f32_e32 v15, v191, v191
	v_cndmask_b32_e32 v9, v227, v14, vcc
	v_mul_f32_e32 v14, v196, v196
	v_fmac_f32_e32 v14, v193, v193
	v_cvt_pk_bf16_f32 v11, v16, v17
	v_add_f32_e32 v14, v14, v15
	v_mul_f32_e32 v15, v194, v194
	v_mul_f32_e32 v16, v192, v192
	v_fmac_f32_e32 v15, v190, v190
	v_fmac_f32_e32 v16, v189, v189
	v_add_f32_e32 v15, v15, v16
	v_add_f32_e32 v14, v14, v15
	v_mul_f32_e32 v15, v165, v165
	v_mul_f32_e32 v16, v167, v167
	v_fmac_f32_e32 v15, v164, v164
	v_fmac_f32_e32 v16, v166, v166
	v_add_f32_e32 v15, v15, v16
	v_add_f32_e32 v14, v14, v15
	v_mul_f32_e32 v15, v169, v169
	v_mul_f32_e32 v16, v173, v173
	v_fmac_f32_e32 v15, v168, v168
	v_fmac_f32_e32 v16, v172, v172
	v_add_f32_e32 v15, v15, v16
	v_lshlrev_b32_e32 v8, 2, v8
	v_add_f32_e32 v14, v15, v14
	ds_bpermute_b32 v15, v8, v14
	v_lshlrev_b32_e32 v9, 2, v9
	v_pk_fma_f32 v[6:7], v[6:7], v[158:159], v[40:41]
	v_cvt_pk_bf16_f32 v12, v12, v13
	v_cvt_pk_bf16_f32 v13, v22, v23
	s_waitcnt lgkmcnt(0)
	v_add_f32_e32 v14, v14, v15
	ds_bpermute_b32 v15, v9, v14
	v_cvt_pk_bf16_f32 v2, v6, v7
	v_lshl_add_u64 v[6:7], v[148:149], 0, s[22:23]
	global_store_dwordx4 v[80:81], v[10:13], off offset:2304
	global_store_dwordx4 v[72:73], v[2:5], off offset:2304
	s_and_saveexec_b64 s[22:23], s[38:39]
	s_cbranch_execz .LBB0_1125
	s_waitcnt lgkmcnt(0)
	v_add_f32_e32 v14, v14, v15
	global_atomic_add_f32 v[6:7], v14, off

.LBB0_1156:
	s_add_u32 s28, s26, 0x100
	s_addc_u32 s29, s27, 0
	s_add_i32 s0, 0, 0x10000
	s_cmp_eq_u32 s81, 40
	s_cselect_b32 s35, s43, s29
	s_cselect_b32 s34, s42, s28
	s_cselect_b32 s31, s23, s45
	s_cselect_b32 s30, s22, s44
	s_add_i32 m0, s52, 0xc000
	ds_read_b128 v[172:175], v224
	ds_read_b128 v[176:179], v224 offset:1024
	ds_read_b128 v[180:183], v224 offset:2048
	ds_read_b128 v[184:187], v224 offset:3072
	ds_read_b128 v[188:191], v224 offset:4096
	ds_read_b128 v[192:195], v224 offset:5120
	ds_read_b128 v[196:199], v224 offset:6144
	ds_read_b128 v[200:203], v224 offset:7168
	global_load_lds_dwordx4 v152, s[26:27]
	v_lshl_add_u64 v[164:165], s[26:27], 0, v[154:155]
	s_add_i32 m0, s52, 0xe000
	s_nop 0
	global_load_lds_dwordx4 v[164:165], off
	s_waitcnt vmcnt(10) lgkmcnt(8)
	s_setprio 1
	s_barrier
	s_waitcnt lgkmcnt(0)
	v_mfma_f32_16x16x32_bf16 v[128:131], v[132:135], v[172:175], v[128:131]
	v_mfma_f32_16x16x32_bf16 v[124:127], v[156:159], v[172:175], v[124:127]
	v_mfma_f32_16x16x32_bf16 v[120:123], v[132:135], v[180:183], v[120:123]
	v_mfma_f32_16x16x32_bf16 v[116:119], v[156:159], v[180:183], v[116:119]
	v_mfma_f32_16x16x32_bf16 v[112:115], v[132:135], v[188:191], v[112:115]
	v_mfma_f32_16x16x32_bf16 v[108:111], v[156:159], v[188:191], v[108:111]
	v_mfma_f32_16x16x32_bf16 v[104:107], v[132:135], v[196:199], v[104:107]
	v_mfma_f32_16x16x32_bf16 v[100:103], v[156:159], v[196:199], v[100:103]
	v_mfma_f32_16x16x32_bf16 v[128:131], v[136:139], v[176:179], v[128:131]
	v_mfma_f32_16x16x32_bf16 v[124:127], v[160:163], v[176:179], v[124:127]
	v_mfma_f32_16x16x32_bf16 v[120:123], v[136:139], v[184:187], v[120:123]
	v_mfma_f32_16x16x32_bf16 v[116:119], v[160:163], v[184:187], v[116:119]
	v_mfma_f32_16x16x32_bf16 v[112:115], v[136:139], v[192:195], v[112:115]
	v_mfma_f32_16x16x32_bf16 v[108:111], v[160:163], v[192:195], v[108:111]
	v_mfma_f32_16x16x32_bf16 v[104:107], v[136:139], v[200:203], v[104:107]
	v_mfma_f32_16x16x32_bf16 v[100:103], v[160:163], v[200:203], v[100:103]
	s_barrier
	s_setprio 0
	s_add_i32 s26, 0, 0x14000
	v_add_u32_e32 v164, s26, v222
	s_add_i32 s0, s0, s17
	ds_read_b128 v[204:207], v164
	ds_read_b128 v[208:211], v164 offset:1024
	ds_read_b128 v[212:215], v164 offset:2048
	ds_read_b128 v[216:219], v164 offset:3072
	v_lshl_add_u64 v[164:165], s[30:31], 0, v[26:27]
	s_mov_b32 m0, s0
	v_lshl_add_u64 v[166:167], s[30:31], 0, v[144:145]
	global_load_lds_dwordx4 v[164:165], off
	s_add_i32 m0, s0, 0x2000
	s_nop 0
	global_load_lds_dwordx4 v[166:167], off
	s_waitcnt vmcnt(10)
	s_setprio 1
	s_barrier
	s_waitcnt lgkmcnt(0)
	v_mfma_f32_16x16x32_bf16 v[64:67], v[204:207], v[172:175], v[64:67]
	v_mfma_f32_16x16x32_bf16 v[60:63], v[212:215], v[172:175], v[60:63]
	v_mfma_f32_16x16x32_bf16 v[56:59], v[204:207], v[180:183], v[56:59]
	v_mfma_f32_16x16x32_bf16 v[52:55], v[212:215], v[180:183], v[52:55]
	v_mfma_f32_16x16x32_bf16 v[48:51], v[204:207], v[188:191], v[48:51]
	v_mfma_f32_16x16x32_bf16 v[44:47], v[212:215], v[188:191], v[44:47]
	v_mfma_f32_16x16x32_bf16 v[40:43], v[204:207], v[196:199], v[40:43]
	v_mfma_f32_16x16x32_bf16 v[36:39], v[212:215], v[196:199], v[36:39]
	v_mfma_f32_16x16x32_bf16 v[64:67], v[208:211], v[176:179], v[64:67]
	v_mfma_f32_16x16x32_bf16 v[60:63], v[216:219], v[176:179], v[60:63]
	v_mfma_f32_16x16x32_bf16 v[56:59], v[208:211], v[184:187], v[56:59]
	v_mfma_f32_16x16x32_bf16 v[52:55], v[216:219], v[184:187], v[52:55]
	v_mfma_f32_16x16x32_bf16 v[48:51], v[208:211], v[192:195], v[48:51]
	v_mfma_f32_16x16x32_bf16 v[44:47], v[216:219], v[192:195], v[44:47]
	v_mfma_f32_16x16x32_bf16 v[40:43], v[208:211], v[200:203], v[40:43]
	v_mfma_f32_16x16x32_bf16 v[36:39], v[216:219], v[200:203], v[36:39]
	s_barrier
	s_setprio 0
	s_mov_b32 m0, s52
	v_lshl_add_u64 v[168:169], s[34:35], 0, v[140:141]
	ds_read_b128 v[172:175], v224 offset:16384
	ds_read_b128 v[176:179], v224 offset:17408
	ds_read_b128 v[180:183], v224 offset:18432
	ds_read_b128 v[184:187], v224 offset:19456
	ds_read_b128 v[188:191], v224 offset:20480
	ds_read_b128 v[192:195], v224 offset:21504
	ds_read_b128 v[196:199], v224 offset:22528
	ds_read_b128 v[200:203], v224 offset:23552
	global_load_lds_dwordx4 v[168:169], off
	v_lshl_add_u64 v[220:221], s[34:35], 0, v[142:143]
	s_mov_b32 m0, s54
	s_nop 0
	global_load_lds_dwordx4 v[220:221], off
	s_waitcnt vmcnt(10)
	s_setprio 1
	s_barrier
	s_waitcnt lgkmcnt(0)
	v_mfma_f32_16x16x32_bf16 v[96:99], v[132:135], v[172:175], v[96:99]
	v_mfma_f32_16x16x32_bf16 v[92:95], v[156:159], v[172:175], v[92:95]
	v_mfma_f32_16x16x32_bf16 v[88:91], v[132:135], v[180:183], v[88:91]
	v_mfma_f32_16x16x32_bf16 v[84:87], v[156:159], v[180:183], v[84:87]
	v_mfma_f32_16x16x32_bf16 v[80:83], v[132:135], v[188:191], v[80:83]
	v_mfma_f32_16x16x32_bf16 v[76:79], v[156:159], v[188:191], v[76:79]
	v_mfma_f32_16x16x32_bf16 v[72:75], v[132:135], v[196:199], v[72:75]
	v_mfma_f32_16x16x32_bf16 v[68:71], v[156:159], v[196:199], v[68:71]
	v_mfma_f32_16x16x32_bf16 v[96:99], v[136:139], v[176:179], v[96:99]
	v_mfma_f32_16x16x32_bf16 v[92:95], v[160:163], v[176:179], v[92:95]
	v_mfma_f32_16x16x32_bf16 v[88:91], v[136:139], v[184:187], v[88:91]
	v_mfma_f32_16x16x32_bf16 v[84:87], v[160:163], v[184:187], v[84:87]
	v_mfma_f32_16x16x32_bf16 v[80:83], v[136:139], v[192:195], v[80:83]
	v_mfma_f32_16x16x32_bf16 v[76:79], v[160:163], v[192:195], v[76:79]
	v_mfma_f32_16x16x32_bf16 v[72:75], v[136:139], v[200:203], v[72:75]
	v_mfma_f32_16x16x32_bf16 v[68:71], v[160:163], v[200:203], v[68:71]
	s_barrier
	s_setprio 0
	s_add_u32 s0, s30, 0xb0000
	s_addc_u32 s1, s31, 0
	s_add_i32 s26, s26, s17
	s_mov_b32 m0, s26
	s_nop 0
	global_load_lds_dwordx4 v26, s[0:1]
	s_add_i32 m0, s26, 0x2000
	s_nop 0
	global_load_lds_dwordx4 v144, s[0:1]
	v_add_u32_e32 v160, 0x18000, v222
	ds_read_b128 v[132:135], v160
	ds_read_b128 v[136:139], v160 offset:1024
	ds_read_b128 v[156:159], v160 offset:2048
	ds_read_b128 v[160:163], v160 offset:3072
	s_waitcnt vmcnt(10)
	s_setprio 1
	s_barrier
	v_mfma_f32_16x16x32_bf16 v[32:35], v[204:207], v[172:175], v[32:35]
	v_mfma_f32_16x16x32_bf16 v[28:31], v[212:215], v[172:175], v[28:31]
	v_mfma_f32_16x16x32_bf16 v[22:25], v[204:207], v[180:183], v[22:25]
	v_mfma_f32_16x16x32_bf16 v[18:21], v[212:215], v[180:183], v[18:21]
	v_mfma_f32_16x16x32_bf16 v[14:17], v[204:207], v[188:191], v[14:17]
	v_mfma_f32_16x16x32_bf16 v[10:13], v[212:215], v[188:191], v[10:13]
	v_mfma_f32_16x16x32_bf16 v[6:9], v[204:207], v[196:199], v[6:9]
	v_mfma_f32_16x16x32_bf16 v[2:5], v[212:215], v[196:199], v[2:5]
	v_mfma_f32_16x16x32_bf16 v[32:35], v[208:211], v[176:179], v[32:35]
	v_mfma_f32_16x16x32_bf16 v[28:31], v[216:219], v[176:179], v[28:31]
	v_mfma_f32_16x16x32_bf16 v[22:25], v[208:211], v[184:187], v[22:25]
	v_mfma_f32_16x16x32_bf16 v[18:21], v[216:219], v[184:187], v[18:21]
	v_mfma_f32_16x16x32_bf16 v[14:17], v[208:211], v[192:195], v[14:17]
	v_mfma_f32_16x16x32_bf16 v[10:13], v[216:219], v[192:195], v[10:13]
	v_mfma_f32_16x16x32_bf16 v[6:9], v[208:211], v[200:203], v[6:9]
	v_mfma_f32_16x16x32_bf16 v[2:5], v[216:219], v[200:203], v[2:5]
	s_barrier
	s_setprio 0
	s_add_i32 s26, 0, 0x18000
	s_add_u32 s0, s34, 0xb0000
	s_addc_u32 s1, s35, 0
	s_mov_b32 m0, s55
	ds_read_b128 v[172:175], v224 offset:32768
	ds_read_b128 v[176:179], v224 offset:33792
	ds_read_b128 v[180:183], v224 offset:34816
	ds_read_b128 v[184:187], v224 offset:35840
	ds_read_b128 v[188:191], v224 offset:36864
	ds_read_b128 v[192:195], v224 offset:37888
	ds_read_b128 v[196:199], v224 offset:38912
	ds_read_b128 v[200:203], v224 offset:39936
	global_load_lds_dwordx4 v140, s[0:1]
	s_mov_b32 m0, s56
	s_nop 0
	global_load_lds_dwordx4 v142, s[0:1]
	s_waitcnt vmcnt(10) lgkmcnt(8)
	s_setprio 1
	s_barrier
	s_waitcnt lgkmcnt(0)
	v_mfma_f32_16x16x32_bf16 v[128:131], v[132:135], v[172:175], v[128:131]
	v_mfma_f32_16x16x32_bf16 v[124:127], v[156:159], v[172:175], v[124:127]
	v_mfma_f32_16x16x32_bf16 v[120:123], v[132:135], v[180:183], v[120:123]
	v_mfma_f32_16x16x32_bf16 v[116:119], v[156:159], v[180:183], v[116:119]
	v_mfma_f32_16x16x32_bf16 v[112:115], v[132:135], v[188:191], v[112:115]
	v_mfma_f32_16x16x32_bf16 v[108:111], v[156:159], v[188:191], v[108:111]
	v_mfma_f32_16x16x32_bf16 v[104:107], v[132:135], v[196:199], v[104:107]
	v_mfma_f32_16x16x32_bf16 v[100:103], v[156:159], v[196:199], v[100:103]
	v_mfma_f32_16x16x32_bf16 v[128:131], v[136:139], v[176:179], v[128:131]
	v_mfma_f32_16x16x32_bf16 v[124:127], v[160:163], v[176:179], v[124:127]
	v_mfma_f32_16x16x32_bf16 v[120:123], v[136:139], v[184:187], v[120:123]
	v_mfma_f32_16x16x32_bf16 v[116:119], v[160:163], v[184:187], v[116:119]
	v_mfma_f32_16x16x32_bf16 v[112:115], v[136:139], v[192:195], v[112:115]
	v_mfma_f32_16x16x32_bf16 v[108:111], v[160:163], v[192:195], v[108:111]
	v_mfma_f32_16x16x32_bf16 v[104:107], v[136:139], v[200:203], v[104:107]
	v_mfma_f32_16x16x32_bf16 v[100:103], v[160:163], v[200:203], v[100:103]
	s_barrier
	s_setprio 0
	s_add_i32 s27, 0, 0x1c000
	s_add_i32 s0, s26, s17
	v_add_u32_e32 v216, s27, v222
	v_lshl_add_u64 v[164:165], v[164:165], 0, s[12:13]
	s_mov_b32 m0, s0
	ds_read_b128 v[204:207], v216
	ds_read_b128 v[208:211], v216 offset:1024
	ds_read_b128 v[212:215], v216 offset:2048
	ds_read_b128 v[216:219], v216 offset:3072
	global_load_lds_dwordx4 v[164:165], off
	v_lshl_add_u64 v[164:165], v[166:167], 0, s[12:13]
	s_add_i32 m0, s0, 0x2000
	s_nop 0
	global_load_lds_dwordx4 v[164:165], off
	s_waitcnt vmcnt(10)
	s_setprio 1
	s_barrier
	s_waitcnt lgkmcnt(0)
	v_mfma_f32_16x16x32_bf16 v[64:67], v[204:207], v[172:175], v[64:67]
	v_mfma_f32_16x16x32_bf16 v[60:63], v[212:215], v[172:175], v[60:63]
	v_mfma_f32_16x16x32_bf16 v[56:59], v[204:207], v[180:183], v[56:59]
	v_mfma_f32_16x16x32_bf16 v[52:55], v[212:215], v[180:183], v[52:55]
	v_mfma_f32_16x16x32_bf16 v[48:51], v[204:207], v[188:191], v[48:51]
	v_mfma_f32_16x16x32_bf16 v[44:47], v[212:215], v[188:191], v[44:47]
	v_mfma_f32_16x16x32_bf16 v[40:43], v[204:207], v[196:199], v[40:43]
	v_mfma_f32_16x16x32_bf16 v[36:39], v[212:215], v[196:199], v[36:39]
	v_mfma_f32_16x16x32_bf16 v[64:67], v[208:211], v[176:179], v[64:67]
	v_mfma_f32_16x16x32_bf16 v[60:63], v[216:219], v[176:179], v[60:63]
	v_mfma_f32_16x16x32_bf16 v[56:59], v[208:211], v[184:187], v[56:59]
	v_mfma_f32_16x16x32_bf16 v[52:55], v[216:219], v[184:187], v[52:55]
	v_mfma_f32_16x16x32_bf16 v[48:51], v[208:211], v[192:195], v[48:51]
	v_mfma_f32_16x16x32_bf16 v[44:47], v[216:219], v[192:195], v[44:47]
	v_mfma_f32_16x16x32_bf16 v[40:43], v[208:211], v[200:203], v[40:43]
	v_mfma_f32_16x16x32_bf16 v[36:39], v[216:219], v[200:203], v[36:39]
	s_barrier
	s_setprio 0
	s_mov_b32 m0, s59
	v_lshl_add_u64 v[164:165], v[168:169], 0, s[12:13]
	ds_read_b128 v[172:175], v224 offset:49152
	ds_read_b128 v[176:179], v224 offset:50176
	ds_read_b128 v[180:183], v224 offset:51200
	ds_read_b128 v[184:187], v224 offset:52224
	ds_read_b128 v[188:191], v224 offset:53248
	ds_read_b128 v[192:195], v224 offset:54272
	ds_read_b128 v[196:199], v224 offset:55296
	ds_read_b128 v[200:203], v224 offset:56320
	global_load_lds_dwordx4 v[164:165], off
	v_lshl_add_u64 v[164:165], v[220:221], 0, s[12:13]
	s_mov_b32 m0, s68
	s_nop 0
	global_load_lds_dwordx4 v[164:165], off
	s_waitcnt vmcnt(10)
	s_setprio 1
	s_barrier
	s_waitcnt lgkmcnt(0)
	v_mfma_f32_16x16x32_bf16 v[96:99], v[132:135], v[172:175], v[96:99]
	v_mfma_f32_16x16x32_bf16 v[92:95], v[156:159], v[172:175], v[92:95]
	v_mfma_f32_16x16x32_bf16 v[88:91], v[132:135], v[180:183], v[88:91]
	v_mfma_f32_16x16x32_bf16 v[84:87], v[156:159], v[180:183], v[84:87]
	v_mfma_f32_16x16x32_bf16 v[80:83], v[132:135], v[188:191], v[80:83]
	v_mfma_f32_16x16x32_bf16 v[76:79], v[156:159], v[188:191], v[76:79]
	v_mfma_f32_16x16x32_bf16 v[72:75], v[132:135], v[196:199], v[72:75]
	v_mfma_f32_16x16x32_bf16 v[68:71], v[156:159], v[196:199], v[68:71]
	v_mfma_f32_16x16x32_bf16 v[96:99], v[136:139], v[176:179], v[96:99]
	v_mfma_f32_16x16x32_bf16 v[92:95], v[160:163], v[176:179], v[92:95]
	v_mfma_f32_16x16x32_bf16 v[88:91], v[136:139], v[184:187], v[88:91]
	v_mfma_f32_16x16x32_bf16 v[84:87], v[160:163], v[184:187], v[84:87]
	v_mfma_f32_16x16x32_bf16 v[80:83], v[136:139], v[192:195], v[80:83]
	v_mfma_f32_16x16x32_bf16 v[76:79], v[160:163], v[192:195], v[76:79]
	v_mfma_f32_16x16x32_bf16 v[72:75], v[136:139], v[200:203], v[72:75]
	v_mfma_f32_16x16x32_bf16 v[68:71], v[160:163], v[200:203], v[68:71]
	s_barrier
	s_setprio 0
	s_add_u32 s0, s30, 0xb0080
	s_addc_u32 s1, s31, 0
	s_add_i32 s26, s27, s17
	s_mov_b32 m0, s26
	s_nop 0
	global_load_lds_dwordx4 v26, s[0:1]
	s_add_i32 m0, s26, 0x2000
	s_nop 0
	global_load_lds_dwordx4 v144, s[0:1]
	v_add_u32_e32 v160, 0x10000, v222
	ds_read_b128 v[132:135], v160
	ds_read_b128 v[136:139], v160 offset:1024
	ds_read_b128 v[156:159], v160 offset:2048
	ds_read_b128 v[160:163], v160 offset:3072
	s_add_i32 s81, s81, 2
	s_add_u32 s44, s44, 0x100
	s_addc_u32 s45, s45, 0
	s_cmp_gt_u32 s81, 41
	s_mov_b64 s[26:27], s[28:29]
	s_waitcnt vmcnt(10)
	s_setprio 1
	s_barrier
	v_mfma_f32_16x16x32_bf16 v[32:35], v[204:207], v[172:175], v[32:35]
	v_mfma_f32_16x16x32_bf16 v[28:31], v[212:215], v[172:175], v[28:31]
	v_mfma_f32_16x16x32_bf16 v[22:25], v[204:207], v[180:183], v[22:25]
	v_mfma_f32_16x16x32_bf16 v[18:21], v[212:215], v[180:183], v[18:21]
	v_mfma_f32_16x16x32_bf16 v[14:17], v[204:207], v[188:191], v[14:17]
	v_mfma_f32_16x16x32_bf16 v[10:13], v[212:215], v[188:191], v[10:13]
	v_mfma_f32_16x16x32_bf16 v[6:9], v[204:207], v[196:199], v[6:9]
	v_mfma_f32_16x16x32_bf16 v[2:5], v[212:215], v[196:199], v[2:5]
	v_mfma_f32_16x16x32_bf16 v[32:35], v[208:211], v[176:179], v[32:35]
	v_mfma_f32_16x16x32_bf16 v[28:31], v[216:219], v[176:179], v[28:31]
	v_mfma_f32_16x16x32_bf16 v[22:25], v[208:211], v[184:187], v[22:25]
	v_mfma_f32_16x16x32_bf16 v[18:21], v[216:219], v[184:187], v[18:21]
	v_mfma_f32_16x16x32_bf16 v[14:17], v[208:211], v[192:195], v[14:17]
	v_mfma_f32_16x16x32_bf16 v[10:13], v[216:219], v[192:195], v[10:13]
	v_mfma_f32_16x16x32_bf16 v[6:9], v[208:211], v[200:203], v[6:9]
	v_mfma_f32_16x16x32_bf16 v[2:5], v[216:219], v[200:203], v[2:5]
	s_barrier
	s_setprio 0
	s_cbranch_scc0 .LBB0_1156
	s_waitcnt lgkmcnt(0)
	s_min_i32 s0, s24, 0x100
	s_ashr_i32 s0, s0, 5
	s_ashr_i32 s1, s0, 31
	s_add_i32 s26, s24, 0xffffff00
	s_cmpk_lt_i32 s24, 0x100
	s_cselect_b32 s26, s24, s26
	s_cselect_b32 s28, 0, s51
	s_cselect_b32 s29, 0, s50
	s_ashr_i32 s27, s26, 31
	s_lshl_b64 s[26:27], s[26:27], 19
	v_lshl_add_u64 v[132:133], s[26:27], 0, v[146:147]
	s_add_u32 s26, s20, s29
	v_lshl_or_b32 v166, s25, 8, v223
	s_addc_u32 s27, s21, s28
	s_ashr_i32 s25, s24, 31
	s_lshl_b64 s[28:29], s[24:25], 19
	v_lshl_add_u64 v[178:179], v[148:149], 0, s[28:29]
	s_lshl_b64 s[24:25], s[24:25], 10
	s_mul_i32 s28, s0, 0x9000
	v_ashrrev_i32_e32 v167, 31, v166
	s_mul_hi_i32 s29, s0, 0x9000
	s_add_u32 s28, s36, s28
	s_addc_u32 s29, s37, s29
	v_lshlrev_b64 v[180:181], 2, v[166:167]
	v_lshl_add_u64 v[156:157], s[28:29], 0, v[180:181]
	v_lshl_add_u64 v[168:169], v[132:133], 0, v[166:167]
	v_lshl_add_u64 v[182:183], v[132:133], 1, s[26:27]
	global_load_dwordx4 v[132:135], v[156:157], off offset:16
	global_load_dwordx4 v[136:139], v[156:157], off
	s_lshl_b64 s[0:1], s[0:1], 12
	s_add_u32 s28, s57, s0
	s_addc_u32 s29, s58, s1
	v_lshl_add_u64 v[180:181], s[28:29], 0, v[180:181]
	v_lshl_add_u64 v[196:197], v[168:169], 1, s[26:27]
	v_add_co_u32_e32 v210, vcc, s65, v196
	s_mov_b32 s1, 0x20000
	s_nop 0
	v_addc_co_u32_e32 v211, vcc, 0, v197, vcc
	v_add_co_u32_e32 v184, vcc, s1, v196
	s_mov_b32 s26, 0x30000
	s_nop 0
	v_addc_co_u32_e32 v185, vcc, 0, v197, vcc
	v_add_co_u32_e32 v188, vcc, s26, v196
	v_lshlrev_b64 v[166:167], 1, v[166:167]
	s_nop 0
	v_addc_co_u32_e32 v189, vcc, 0, v197, vcc
	v_lshl_add_u64 v[178:179], v[178:179], 0, v[166:167]
	v_lshl_add_u64 v[182:183], v[182:183], 0, v[166:167]
	s_mov_b32 s0, 0x8000
	s_mov_b32 s27, 0x80000
	s_mov_b32 s28, 0x90000
	s_waitcnt vmcnt(0)
	v_pk_mul_f32 v[172:173], v[134:135], 0.5 op_sel_hi:[1,0]
	v_pk_mul_f32 v[176:177], v[138:139], 0.5 op_sel_hi:[1,0]
	v_pk_mul_f32 v[174:175], v[136:137], 0.5 op_sel_hi:[1,0]
	v_pk_mul_f32 v[164:165], v[132:133], 0.5 op_sel_hi:[1,0]
	global_load_dwordx4 v[132:135], v[156:157], off offset:528
	global_load_dwordx4 v[136:139], v[156:157], off offset:512
	s_waitcnt vmcnt(0)
	v_pk_mul_f32 v[158:159], v[134:135], 0.5 op_sel_hi:[1,0]
	v_pk_mul_f32 v[162:163], v[138:139], 0.5 op_sel_hi:[1,0]
	v_pk_mul_f32 v[160:161], v[136:137], 0.5 op_sel_hi:[1,0]
	v_pk_mul_f32 v[156:157], v[132:133], 0.5 op_sel_hi:[1,0]
	global_load_dwordx4 v[132:135], v[180:181], off offset:16
	global_load_dwordx4 v[136:139], v[180:181], off
	global_load_dwordx4 v[190:193], v[196:197], off offset:2048
	global_load_dwordx4 v[198:201], v[210:211], off offset:2048
	global_load_dwordx4 v[202:205], v[184:185], off offset:2048
	global_load_dwordx4 v[206:209], v[188:189], off offset:2048
	s_waitcnt vmcnt(0)
	v_lshlrev_b32_e32 v166, 16, v190
	v_and_b32_e32 v167, 0xffff0000, v190
	v_lshlrev_b32_e32 v168, 16, v191
	v_and_b32_e32 v169, 0xffff0000, v191
	v_lshlrev_b32_e32 v186, 16, v192
	v_and_b32_e32 v187, 0xffff0000, v192
	v_lshlrev_b32_e32 v190, 16, v193
	v_and_b32_e32 v191, 0xffff0000, v193
	v_pk_fma_f32 v[130:131], v[130:131], v[176:177], v[168:169]
	v_pk_fma_f32 v[128:129], v[128:129], v[174:175], v[166:167]
	v_pk_fma_f32 v[126:127], v[126:127], v[172:173], v[190:191]
	v_pk_fma_f32 v[124:125], v[124:125], v[164:165], v[186:187]
	v_cvt_pk_bf16_f32 v190, v128, v129
	v_cvt_pk_bf16_f32 v191, v130, v131
	v_cvt_pk_bf16_f32 v192, v124, v125
	v_cvt_pk_bf16_f32 v193, v126, v127
	v_lshlrev_b32_e32 v130, 16, v190
	v_and_b32_e32 v131, 0xffff0000, v190
	v_lshlrev_b32_e32 v128, 16, v191
	v_and_b32_e32 v129, 0xffff0000, v191
	v_lshlrev_b32_e32 v126, 16, v192
	v_and_b32_e32 v127, 0xffff0000, v192
	v_lshlrev_b32_e32 v124, 16, v193
	v_and_b32_e32 v125, 0xffff0000, v193
	v_lshlrev_b32_e32 v212, 16, v200
	v_and_b32_e32 v213, 0xffff0000, v200
	v_lshlrev_b32_e32 v200, 16, v201
	v_and_b32_e32 v201, 0xffff0000, v201
	global_store_dwordx4 v[182:183], v[190:193], off offset:2048
	v_pk_mul_f32 v[166:167], v[138:139], v[128:129]
	v_pk_mul_f32 v[168:169], v[136:137], v[130:131]
	v_pk_mul_f32 v[186:187], v[134:135], v[124:125]
	v_pk_mul_f32 v[192:193], v[132:133], v[126:127]
	v_lshlrev_b32_e32 v194, 16, v198
	v_and_b32_e32 v195, 0xffff0000, v198
	v_lshlrev_b32_e32 v198, 16, v199
	v_and_b32_e32 v199, 0xffff0000, v199
	v_cvt_pk_bf16_f32 v190, v168, v169
	v_cvt_pk_bf16_f32 v191, v166, v167
	v_cvt_pk_bf16_f32 v192, v192, v193
	v_cvt_pk_bf16_f32 v193, v186, v187
	v_pk_fma_f32 v[118:119], v[118:119], v[172:173], v[200:201]
	v_pk_fma_f32 v[116:117], v[116:117], v[164:165], v[212:213]
	global_store_dwordx4 v[178:179], v[190:193], off
	v_pk_fma_f32 v[122:123], v[122:123], v[176:177], v[198:199]
	v_pk_fma_f32 v[120:121], v[120:121], v[174:175], v[194:195]
	v_cvt_pk_bf16_f32 v192, v116, v117
	v_cvt_pk_bf16_f32 v193, v118, v119
	v_add_co_u32_e32 v186, vcc, s65, v182
	v_cvt_pk_bf16_f32 v190, v120, v121
	v_cvt_pk_bf16_f32 v191, v122, v123
	v_addc_co_u32_e32 v187, vcc, 0, v183, vcc
	v_lshlrev_b32_e32 v118, 16, v192
	v_and_b32_e32 v119, 0xffff0000, v192
	v_lshlrev_b32_e32 v116, 16, v193
	v_and_b32_e32 v117, 0xffff0000, v193
	global_store_dwordx4 v[186:187], v[190:193], off offset:2048
	v_lshlrev_b32_e32 v122, 16, v190
	v_and_b32_e32 v123, 0xffff0000, v190
	v_lshlrev_b32_e32 v120, 16, v191
	v_and_b32_e32 v121, 0xffff0000, v191
	v_pk_mul_f32 v[190:191], v[134:135], v[116:117]
	v_pk_mul_f32 v[194:195], v[132:133], v[118:119]
	v_pk_mul_f32 v[166:167], v[138:139], v[120:121]
	v_pk_mul_f32 v[168:169], v[136:137], v[122:123]
	v_cvt_pk_bf16_f32 v194, v194, v195
	v_cvt_pk_bf16_f32 v195, v190, v191
	v_add_co_u32_e32 v190, vcc, s0, v178
	v_cvt_pk_bf16_f32 v192, v168, v169
	v_cvt_pk_bf16_f32 v193, v166, v167
	v_addc_co_u32_e32 v191, vcc, 0, v179, vcc
	global_store_dwordx4 v[190:191], v[192:195], off
	v_lshlrev_b32_e32 v198, 16, v204
	v_and_b32_e32 v199, 0xffff0000, v204
	v_add_co_u32_e32 v192, vcc, s27, v196
	v_lshlrev_b32_e32 v200, 16, v205
	s_nop 0
	v_addc_co_u32_e32 v193, vcc, 0, v197, vcc
	v_add_co_u32_e32 v194, vcc, s28, v196
	v_and_b32_e32 v201, 0xffff0000, v205
	global_load_dwordx4 v[212:215], v[192:193], off offset:2048
	v_addc_co_u32_e32 v195, vcc, 0, v197, vcc
	v_lshlrev_b32_e32 v166, 16, v202
	v_and_b32_e32 v167, 0xffff0000, v202
	v_lshlrev_b32_e32 v168, 16, v203
	v_and_b32_e32 v169, 0xffff0000, v203
	v_pk_fma_f32 v[110:111], v[110:111], v[172:173], v[200:201]
	v_pk_fma_f32 v[108:109], v[108:109], v[164:165], v[198:199]
	v_pk_fma_f32 v[114:115], v[114:115], v[176:177], v[168:169]
	v_pk_fma_f32 v[112:113], v[112:113], v[174:175], v[166:167]
	v_cvt_pk_bf16_f32 v202, v108, v109
	v_cvt_pk_bf16_f32 v203, v110, v111
	v_add_co_u32_e32 v198, vcc, s1, v182
	global_load_dwordx4 v[216:219], v[194:195], off offset:2048
	v_cvt_pk_bf16_f32 v200, v112, v113
	v_cvt_pk_bf16_f32 v201, v114, v115
	v_addc_co_u32_e32 v199, vcc, 0, v183, vcc
	v_lshlrev_b32_e32 v110, 16, v202
	v_and_b32_e32 v111, 0xffff0000, v202
	v_lshlrev_b32_e32 v108, 16, v203
	v_and_b32_e32 v109, 0xffff0000, v203
	global_store_dwordx4 v[198:199], v[200:203], off offset:2048
	v_lshlrev_b32_e32 v114, 16, v200
	v_and_b32_e32 v115, 0xffff0000, v200
	v_lshlrev_b32_e32 v112, 16, v201
	v_and_b32_e32 v113, 0xffff0000, v201
	v_pk_mul_f32 v[200:201], v[134:135], v[108:109]
	v_pk_mul_f32 v[204:205], v[132:133], v[110:111]
	v_lshlrev_b32_e32 v234, 16, v208
	v_and_b32_e32 v235, 0xffff0000, v208
	v_lshlrev_b32_e32 v208, 16, v209
	v_and_b32_e32 v209, 0xffff0000, v209
	v_pk_mul_f32 v[166:167], v[138:139], v[112:113]
	v_pk_mul_f32 v[168:169], v[136:137], v[114:115]
	v_cvt_pk_bf16_f32 v204, v204, v205
	v_cvt_pk_bf16_f32 v205, v200, v201
	v_add_co_u32_e32 v200, vcc, s65, v178
	v_lshlrev_b32_e32 v220, 16, v206
	v_and_b32_e32 v221, 0xffff0000, v206
	v_lshlrev_b32_e32 v206, 16, v207
	v_and_b32_e32 v207, 0xffff0000, v207
	v_cvt_pk_bf16_f32 v202, v168, v169
	v_cvt_pk_bf16_f32 v203, v166, v167
	v_addc_co_u32_e32 v201, vcc, 0, v179, vcc
	v_pk_fma_f32 v[102:103], v[102:103], v[172:173], v[208:209]
	v_pk_fma_f32 v[100:101], v[100:101], v[164:165], v[234:235]
	global_store_dwordx4 v[200:201], v[202:205], off
	v_pk_fma_f32 v[106:107], v[106:107], v[176:177], v[206:207]
	v_pk_fma_f32 v[104:105], v[104:105], v[174:175], v[220:221]
	v_cvt_pk_bf16_f32 v206, v100, v101
	v_cvt_pk_bf16_f32 v207, v102, v103
	v_add_co_u32_e32 v202, vcc, s26, v182
	v_cvt_pk_bf16_f32 v204, v104, v105
	v_cvt_pk_bf16_f32 v205, v106, v107
	v_addc_co_u32_e32 v203, vcc, 0, v183, vcc
	v_lshlrev_b32_e32 v102, 16, v206
	v_and_b32_e32 v103, 0xffff0000, v206
	v_lshlrev_b32_e32 v100, 16, v207
	v_and_b32_e32 v101, 0xffff0000, v207
	global_store_dwordx4 v[202:203], v[204:207], off offset:2048
	v_lshlrev_b32_e32 v106, 16, v204
	v_and_b32_e32 v107, 0xffff0000, v204
	v_lshlrev_b32_e32 v104, 16, v205
	v_and_b32_e32 v105, 0xffff0000, v205
	v_pk_mul_f32 v[204:205], v[134:135], v[100:101]
	v_pk_mul_f32 v[208:209], v[132:133], v[102:103]
	s_mov_b32 s0, 0x18000
	v_pk_mul_f32 v[166:167], v[138:139], v[104:105]
	v_pk_mul_f32 v[168:169], v[136:137], v[106:107]
	v_cvt_pk_bf16_f32 v208, v208, v209
	v_cvt_pk_bf16_f32 v209, v204, v205
	v_add_co_u32_e32 v204, vcc, s0, v178
	v_cvt_pk_bf16_f32 v206, v168, v169
	v_cvt_pk_bf16_f32 v207, v166, v167
	v_addc_co_u32_e32 v205, vcc, 0, v179, vcc
	global_store_dwordx4 v[204:205], v[206:209], off
	s_mov_b32 s0, 0xb0000
	s_waitcnt vmcnt(0)
	v_lshlrev_b32_e32 v166, 16, v212
	v_add_co_u32_e32 v206, vcc, s76, v196
	v_and_b32_e32 v167, 0xffff0000, v212
	s_nop 0
	v_addc_co_u32_e32 v207, vcc, 0, v197, vcc
	global_load_dwordx4 v[238:241], v[206:207], off offset:2048
	v_add_co_u32_e32 v208, vcc, s0, v196
	v_lshlrev_b32_e32 v168, 16, v213
	s_nop 0
	v_addc_co_u32_e32 v209, vcc, 0, v197, vcc
	global_load_dwordx4 v[242:245], v[208:209], off offset:2048
	v_and_b32_e32 v169, 0xffff0000, v213
	v_lshlrev_b32_e32 v212, 16, v214
	v_and_b32_e32 v213, 0xffff0000, v214
	v_lshlrev_b32_e32 v214, 16, v215
	v_and_b32_e32 v215, 0xffff0000, v215
	v_pk_fma_f32 v[94:95], v[94:95], v[172:173], v[214:215]
	v_pk_fma_f32 v[92:93], v[92:93], v[164:165], v[212:213]
	v_lshlrev_b32_e32 v220, 16, v216
	v_and_b32_e32 v221, 0xffff0000, v216
	v_lshlrev_b32_e32 v234, 16, v217
	v_and_b32_e32 v235, 0xffff0000, v217
	v_pk_fma_f32 v[98:99], v[98:99], v[176:177], v[168:169]
	v_pk_fma_f32 v[96:97], v[96:97], v[174:175], v[166:167]
	v_cvt_pk_bf16_f32 v216, v92, v93
	v_cvt_pk_bf16_f32 v217, v94, v95
	v_add_co_u32_e32 v212, vcc, s27, v182
	v_cvt_pk_bf16_f32 v214, v96, v97
	v_cvt_pk_bf16_f32 v215, v98, v99
	v_addc_co_u32_e32 v213, vcc, 0, v183, vcc
	v_lshlrev_b32_e32 v94, 16, v216
	v_and_b32_e32 v95, 0xffff0000, v216
	v_lshlrev_b32_e32 v92, 16, v217
	v_and_b32_e32 v93, 0xffff0000, v217
	v_lshlrev_b32_e32 v246, 16, v218
	v_and_b32_e32 v247, 0xffff0000, v218
	v_lshlrev_b32_e32 v248, 16, v219
	v_and_b32_e32 v249, 0xffff0000, v219
	global_store_dwordx4 v[212:213], v[214:217], off offset:2048
	v_lshlrev_b32_e32 v98, 16, v214
	v_and_b32_e32 v99, 0xffff0000, v214
	v_lshlrev_b32_e32 v96, 16, v215
	v_and_b32_e32 v97, 0xffff0000, v215
	v_pk_mul_f32 v[214:215], v[134:135], v[92:93]
	v_pk_mul_f32 v[218:219], v[132:133], v[94:95]
	s_mov_b32 s1, 0x40000
	v_pk_mul_f32 v[166:167], v[138:139], v[96:97]
	v_pk_mul_f32 v[168:169], v[136:137], v[98:99]
	v_cvt_pk_bf16_f32 v218, v218, v219
	v_cvt_pk_bf16_f32 v219, v214, v215
	v_add_co_u32_e32 v214, vcc, s1, v178
	v_cvt_pk_bf16_f32 v216, v168, v169
	v_cvt_pk_bf16_f32 v217, v166, v167
	v_addc_co_u32_e32 v215, vcc, 0, v179, vcc
	v_pk_fma_f32 v[86:87], v[86:87], v[172:173], v[248:249]
	global_store_dwordx4 v[214:215], v[216:219], off
	v_pk_fma_f32 v[90:91], v[90:91], v[176:177], v[234:235]
	v_pk_fma_f32 v[88:89], v[88:89], v[174:175], v[220:221]
	v_pk_fma_f32 v[84:85], v[84:85], v[164:165], v[246:247]
	v_cvt_pk_bf16_f32 v221, v86, v87
	v_add_co_u32_e32 v216, vcc, s28, v182
	v_cvt_pk_bf16_f32 v218, v88, v89
	v_cvt_pk_bf16_f32 v219, v90, v91
	v_cvt_pk_bf16_f32 v220, v84, v85
	v_addc_co_u32_e32 v217, vcc, 0, v183, vcc
	v_lshlrev_b32_e32 v84, 16, v221
	v_and_b32_e32 v85, 0xffff0000, v221
	global_store_dwordx4 v[216:217], v[218:221], off offset:2048
	v_lshlrev_b32_e32 v90, 16, v218
	v_and_b32_e32 v91, 0xffff0000, v218
	v_lshlrev_b32_e32 v88, 16, v219
	v_and_b32_e32 v89, 0xffff0000, v219
	v_lshlrev_b32_e32 v86, 16, v220
	v_and_b32_e32 v87, 0xffff0000, v220
	v_pk_mul_f32 v[218:219], v[134:135], v[84:85]
	s_mov_b32 s1, 0x48000
	v_pk_mul_f32 v[166:167], v[138:139], v[88:89]
	v_pk_mul_f32 v[168:169], v[136:137], v[90:91]
	v_pk_mul_f32 v[220:221], v[132:133], v[86:87]
	v_cvt_pk_bf16_f32 v249, v218, v219
	v_add_co_u32_e32 v218, vcc, s1, v178
	v_cvt_pk_bf16_f32 v246, v168, v169
	v_cvt_pk_bf16_f32 v247, v166, v167
	v_cvt_pk_bf16_f32 v248, v220, v221
	v_addc_co_u32_e32 v219, vcc, 0, v179, vcc
	global_store_dwordx4 v[218:219], v[246:249], off
	global_load_dwordx4 v[246:249], v[196:197], off offset:2304
	s_nop 0
	global_load_dwordx4 v[250:253], v[210:211], off offset:2304
	s_waitcnt vmcnt(0)
	v_lshlrev_b32_e32 v196, 16, v240
	v_and_b32_e32 v197, 0xffff0000, v240
	v_lshlrev_b32_e32 v210, 16, v241
	v_and_b32_e32 v211, 0xffff0000, v241
	v_lshlrev_b32_e32 v166, 16, v238
	v_and_b32_e32 v167, 0xffff0000, v238
	v_lshlrev_b32_e32 v168, 16, v239
	v_and_b32_e32 v169, 0xffff0000, v239
	v_pk_fma_f32 v[78:79], v[78:79], v[172:173], v[210:211]
	v_pk_fma_f32 v[76:77], v[76:77], v[164:165], v[196:197]
	v_pk_fma_f32 v[82:83], v[82:83], v[176:177], v[168:169]
	v_pk_fma_f32 v[80:81], v[80:81], v[174:175], v[166:167]
	v_cvt_pk_bf16_f32 v240, v76, v77
	v_cvt_pk_bf16_f32 v241, v78, v79
	v_add_co_u32_e32 v196, vcc, s76, v182
	v_cvt_pk_bf16_f32 v238, v80, v81
	v_cvt_pk_bf16_f32 v239, v82, v83
	v_addc_co_u32_e32 v197, vcc, 0, v183, vcc
	v_lshlrev_b32_e32 v78, 16, v240
	v_and_b32_e32 v79, 0xffff0000, v240
	v_lshlrev_b32_e32 v76, 16, v241
	v_and_b32_e32 v77, 0xffff0000, v241
	global_store_dwordx4 v[196:197], v[238:241], off offset:2048
	v_lshlrev_b32_e32 v80, 16, v239
	v_and_b32_e32 v81, 0xffff0000, v239
	v_pk_mul_f32 v[210:211], v[134:135], v[76:77]
	v_pk_mul_f32 v[240:241], v[132:133], v[78:79]
	v_lshlrev_b32_e32 v220, 16, v242
	v_and_b32_e32 v221, 0xffff0000, v242
	v_lshlrev_b32_e32 v234, 16, v243
	v_and_b32_e32 v235, 0xffff0000, v243
	v_lshlrev_b32_e32 v242, 16, v244
	v_and_b32_e32 v243, 0xffff0000, v244
	v_lshlrev_b32_e32 v244, 16, v245
	v_and_b32_e32 v245, 0xffff0000, v245
	v_pk_mul_f32 v[166:167], v[138:139], v[80:81]
	v_cvt_pk_bf16_f32 v240, v240, v241
	v_cvt_pk_bf16_f32 v241, v210, v211
	v_add_co_u32_e32 v210, vcc, s77, v178
	v_lshlrev_b32_e32 v82, 16, v238
	v_and_b32_e32 v83, 0xffff0000, v238
	v_cvt_pk_bf16_f32 v239, v166, v167
	v_addc_co_u32_e32 v211, vcc, 0, v179, vcc
	v_pk_fma_f32 v[74:75], v[74:75], v[176:177], v[234:235]
	v_pk_fma_f32 v[72:73], v[72:73], v[174:175], v[220:221]
	v_pk_fma_f32 v[166:167], v[70:71], v[172:173], v[244:245]
	v_pk_fma_f32 v[70:71], v[68:69], v[164:165], v[242:243]
	v_pk_mul_f32 v[168:169], v[136:137], v[82:83]
	v_cvt_pk_bf16_f32 v68, v72, v73
	v_cvt_pk_bf16_f32 v69, v74, v75
	v_cvt_pk_bf16_f32 v70, v70, v71
	v_cvt_pk_bf16_f32 v71, v166, v167
	v_add_co_u32_e32 v220, vcc, s0, v182
	v_cvt_pk_bf16_f32 v238, v168, v169
	s_nop 0
	v_addc_co_u32_e32 v221, vcc, 0, v183, vcc
	v_lshlrev_b32_e32 v176, 16, v68
	v_and_b32_e32 v177, 0xffff0000, v68
	v_lshlrev_b32_e32 v174, 16, v69
	v_and_b32_e32 v175, 0xffff0000, v69
	v_lshlrev_b32_e32 v172, 16, v70
	v_and_b32_e32 v173, 0xffff0000, v70
	v_lshlrev_b32_e32 v164, 16, v71
	v_and_b32_e32 v165, 0xffff0000, v71
	s_mov_b32 s0, 0x58000
	global_store_dwordx4 v[210:211], v[238:241], off
	global_store_dwordx4 v[220:221], v[68:71], off offset:2048
	v_pk_mul_f32 v[72:73], v[134:135], v[164:165]
	v_pk_mul_f32 v[74:75], v[132:133], v[172:173]
	v_pk_mul_f32 v[70:71], v[138:139], v[174:175]
	v_pk_mul_f32 v[68:69], v[136:137], v[176:177]
	v_add_co_u32_e32 v132, vcc, s0, v178
	v_cvt_pk_bf16_f32 v68, v68, v69
	v_cvt_pk_bf16_f32 v69, v70, v71
	v_cvt_pk_bf16_f32 v70, v74, v75
	v_cvt_pk_bf16_f32 v71, v72, v73
	v_addc_co_u32_e32 v133, vcc, 0, v179, vcc
	global_store_dwordx4 v[132:133], v[68:71], off
	global_load_dwordx4 v[134:137], v[184:185], off offset:2304
	global_load_dwordx4 v[238:241], v[188:189], off offset:2304
	s_nop 0
	global_load_dwordx4 v[68:71], v[180:181], off offset:528
	global_load_dwordx4 v[72:75], v[180:181], off offset:512
	v_lshlrev_b32_e32 v138, 16, v246
	v_and_b32_e32 v139, 0xffff0000, v246
	v_lshlrev_b32_e32 v166, 16, v247
	v_and_b32_e32 v167, 0xffff0000, v247
	v_lshlrev_b32_e32 v168, 16, v248
	v_and_b32_e32 v169, 0xffff0000, v248
	v_lshlrev_b32_e32 v180, 16, v249
	v_and_b32_e32 v181, 0xffff0000, v249
	v_pk_fma_f32 v[66:67], v[66:67], v[162:163], v[166:167]
	v_pk_fma_f32 v[64:65], v[64:65], v[160:161], v[138:139]
	v_pk_fma_f32 v[62:63], v[62:63], v[158:159], v[180:181]
	v_pk_fma_f32 v[60:61], v[60:61], v[156:157], v[168:169]
	v_cvt_pk_bf16_f32 v242, v64, v65
	v_cvt_pk_bf16_f32 v243, v66, v67
	v_cvt_pk_bf16_f32 v244, v60, v61
	v_cvt_pk_bf16_f32 v245, v62, v63
	v_lshlrev_b32_e32 v66, 16, v242
	v_and_b32_e32 v67, 0xffff0000, v242
	v_lshlrev_b32_e32 v64, 16, v243
	v_and_b32_e32 v65, 0xffff0000, v243
	v_lshlrev_b32_e32 v62, 16, v244
	v_and_b32_e32 v63, 0xffff0000, v244
	v_lshlrev_b32_e32 v60, 16, v245
	v_and_b32_e32 v61, 0xffff0000, v245
	v_lshlrev_b32_e32 v184, 16, v250
	v_and_b32_e32 v185, 0xffff0000, v250
	v_lshlrev_b32_e32 v188, 16, v251
	v_and_b32_e32 v189, 0xffff0000, v251
	v_lshlrev_b32_e32 v234, 16, v252
	v_and_b32_e32 v235, 0xffff0000, v252
	v_lshlrev_b32_e32 v246, 16, v253
	v_and_b32_e32 v247, 0xffff0000, v253
	global_store_dwordx4 v[182:183], v[242:245], off offset:2304
	v_pk_fma_f32 v[58:59], v[58:59], v[162:163], v[188:189]
	v_pk_fma_f32 v[56:57], v[56:57], v[160:161], v[184:185]
	v_pk_fma_f32 v[54:55], v[54:55], v[158:159], v[246:247]
	v_pk_fma_f32 v[52:53], v[52:53], v[156:157], v[234:235]
	s_waitcnt vmcnt(0)
	v_lshlrev_b32_e32 v188, 16, v240
	v_pk_mul_f32 v[168:169], v[70:71], v[60:61]
	v_pk_mul_f32 v[138:139], v[74:75], v[64:65]
	v_pk_mul_f32 v[166:167], v[72:73], v[66:67]
	v_pk_mul_f32 v[182:183], v[68:69], v[62:63]
	v_cvt_pk_bf16_f32 v180, v166, v167
	v_cvt_pk_bf16_f32 v181, v138, v139
	v_cvt_pk_bf16_f32 v182, v182, v183
	v_cvt_pk_bf16_f32 v183, v168, v169
	global_store_dwordx4 v[178:179], v[180:183], off offset:256
	v_cvt_pk_bf16_f32 v178, v56, v57
	v_cvt_pk_bf16_f32 v179, v58, v59
	v_cvt_pk_bf16_f32 v180, v52, v53
	v_cvt_pk_bf16_f32 v181, v54, v55
	v_lshlrev_b32_e32 v58, 16, v178
	v_and_b32_e32 v59, 0xffff0000, v178
	v_lshlrev_b32_e32 v56, 16, v179
	v_and_b32_e32 v57, 0xffff0000, v179
	v_lshlrev_b32_e32 v54, 16, v180
	v_and_b32_e32 v55, 0xffff0000, v180
	v_lshlrev_b32_e32 v52, 16, v181
	v_and_b32_e32 v53, 0xffff0000, v181
	global_store_dwordx4 v[186:187], v[178:181], off offset:2304
	v_pk_mul_f32 v[138:139], v[74:75], v[56:57]
	v_pk_mul_f32 v[166:167], v[72:73], v[58:59]
	v_pk_mul_f32 v[168:169], v[70:71], v[52:53]
	v_pk_mul_f32 v[180:181], v[68:69], v[54:55]
	v_cvt_pk_bf16_f32 v178, v166, v167
	v_cvt_pk_bf16_f32 v179, v138, v139
	v_cvt_pk_bf16_f32 v180, v180, v181
	v_cvt_pk_bf16_f32 v181, v168, v169
	v_lshlrev_b32_e32 v138, 16, v134
	v_and_b32_e32 v139, 0xffff0000, v134
	v_lshlrev_b32_e32 v134, 16, v135
	v_and_b32_e32 v135, 0xffff0000, v135
	v_lshlrev_b32_e32 v166, 16, v136
	v_and_b32_e32 v167, 0xffff0000, v136
	v_lshlrev_b32_e32 v136, 16, v137
	v_and_b32_e32 v137, 0xffff0000, v137
	global_store_dwordx4 v[190:191], v[178:181], off offset:256
	v_pk_fma_f32 v[50:51], v[50:51], v[162:163], v[134:135]
	v_pk_fma_f32 v[48:49], v[48:49], v[160:161], v[138:139]
	v_pk_fma_f32 v[46:47], v[46:47], v[158:159], v[136:137]
	v_pk_fma_f32 v[44:45], v[44:45], v[156:157], v[166:167]
	global_load_dwordx4 v[178:181], v[192:193], off offset:2304
	global_load_dwordx4 v[182:185], v[194:195], off offset:2304
	v_cvt_pk_bf16_f32 v134, v48, v49
	v_cvt_pk_bf16_f32 v135, v50, v51
	v_cvt_pk_bf16_f32 v136, v44, v45
	v_cvt_pk_bf16_f32 v137, v46, v47
	v_lshlrev_b32_e32 v50, 16, v134
	v_and_b32_e32 v51, 0xffff0000, v134
	v_lshlrev_b32_e32 v48, 16, v135
	v_and_b32_e32 v49, 0xffff0000, v135
	v_lshlrev_b32_e32 v46, 16, v136
	v_and_b32_e32 v47, 0xffff0000, v136
	v_lshlrev_b32_e32 v44, 16, v137
	v_and_b32_e32 v45, 0xffff0000, v137
	v_lshlrev_b32_e32 v168, 16, v238
	v_and_b32_e32 v169, 0xffff0000, v238
	v_lshlrev_b32_e32 v186, 16, v239
	v_and_b32_e32 v187, 0xffff0000, v239
	v_and_b32_e32 v189, 0xffff0000, v240
	v_lshlrev_b32_e32 v190, 16, v241
	v_and_b32_e32 v191, 0xffff0000, v241
	global_store_dwordx4 v[198:199], v[134:137], off offset:2304
	v_pk_mul_f32 v[138:139], v[70:71], v[44:45]
	v_pk_mul_f32 v[166:167], v[68:69], v[46:47]
	v_pk_mul_f32 v[136:137], v[74:75], v[48:49]
	v_pk_mul_f32 v[134:135], v[72:73], v[50:51]
	v_pk_fma_f32 v[42:43], v[42:43], v[162:163], v[186:187]
	v_cvt_pk_bf16_f32 v134, v134, v135
	v_cvt_pk_bf16_f32 v135, v136, v137
	v_cvt_pk_bf16_f32 v136, v166, v167
	v_cvt_pk_bf16_f32 v137, v138, v139
	v_pk_fma_f32 v[40:41], v[40:41], v[160:161], v[168:169]
	v_pk_fma_f32 v[38:39], v[38:39], v[158:159], v[190:191]
	v_pk_fma_f32 v[36:37], v[36:37], v[156:157], v[188:189]
	global_store_dwordx4 v[200:201], v[134:137], off offset:256
	v_mul_f32_e32 v67, v67, v67
	v_mul_f32_e32 v65, v65, v65
	v_cvt_pk_bf16_f32 v134, v40, v41
	v_cvt_pk_bf16_f32 v135, v42, v43
	v_cvt_pk_bf16_f32 v136, v36, v37
	v_cvt_pk_bf16_f32 v137, v38, v39
	v_lshlrev_b32_e32 v42, 16, v134
	v_and_b32_e32 v43, 0xffff0000, v134
	v_lshlrev_b32_e32 v40, 16, v135
	v_and_b32_e32 v41, 0xffff0000, v135
	v_lshlrev_b32_e32 v38, 16, v136
	v_and_b32_e32 v39, 0xffff0000, v136
	v_lshlrev_b32_e32 v36, 16, v137
	v_and_b32_e32 v37, 0xffff0000, v137
	global_store_dwordx4 v[202:203], v[134:137], off offset:2304
	v_pk_mul_f32 v[138:139], v[70:71], v[36:37]
	v_pk_mul_f32 v[166:167], v[68:69], v[38:39]
	v_pk_mul_f32 v[136:137], v[74:75], v[40:41]
	v_pk_mul_f32 v[134:135], v[72:73], v[42:43]
	v_fmac_f32_e32 v67, v66, v66
	v_cvt_pk_bf16_f32 v134, v134, v135
	v_cvt_pk_bf16_f32 v135, v136, v137
	v_cvt_pk_bf16_f32 v136, v166, v167
	v_cvt_pk_bf16_f32 v137, v138, v139
	global_store_dwordx4 v[204:205], v[134:137], off offset:256
	global_load_dwordx4 v[134:137], v[206:207], off offset:2304
	s_nop 0
	global_load_dwordx4 v[186:189], v[208:209], off offset:2304
	v_fmac_f32_e32 v65, v64, v64
	v_mul_f32_e32 v63, v63, v63
	v_mul_f32_e32 v61, v61, v61
	v_add_f32_e32 v64, v67, v65
	v_fmac_f32_e32 v63, v62, v62
	v_fmac_f32_e32 v61, v60, v60
	v_add_f32_e32 v60, v63, v61
	s_waitcnt vmcnt(0)
	v_lshlrev_b32_e32 v138, 16, v178
	v_and_b32_e32 v139, 0xffff0000, v178
	v_lshlrev_b32_e32 v166, 16, v179
	v_and_b32_e32 v167, 0xffff0000, v179
	v_lshlrev_b32_e32 v168, 16, v180
	v_and_b32_e32 v169, 0xffff0000, v180
	v_lshlrev_b32_e32 v178, 16, v181
	v_and_b32_e32 v179, 0xffff0000, v181
	v_pk_fma_f32 v[34:35], v[34:35], v[162:163], v[166:167]
	v_pk_fma_f32 v[32:33], v[32:33], v[160:161], v[138:139]
	v_pk_fma_f32 v[30:31], v[30:31], v[158:159], v[178:179]
	v_pk_fma_f32 v[28:29], v[28:29], v[156:157], v[168:169]
	v_cvt_pk_bf16_f32 v178, v32, v33
	v_cvt_pk_bf16_f32 v179, v34, v35
	v_cvt_pk_bf16_f32 v180, v28, v29
	v_cvt_pk_bf16_f32 v181, v30, v31
	v_lshlrev_b32_e32 v34, 16, v178
	v_and_b32_e32 v35, 0xffff0000, v178
	v_lshlrev_b32_e32 v32, 16, v179
	v_and_b32_e32 v33, 0xffff0000, v179
	v_lshlrev_b32_e32 v30, 16, v180
	v_and_b32_e32 v31, 0xffff0000, v180
	v_lshlrev_b32_e32 v28, 16, v181
	v_and_b32_e32 v29, 0xffff0000, v181
	v_lshlrev_b32_e32 v190, 16, v182
	v_and_b32_e32 v191, 0xffff0000, v182
	v_lshlrev_b32_e32 v182, 16, v183
	v_and_b32_e32 v183, 0xffff0000, v183
	global_store_dwordx4 v[212:213], v[178:181], off offset:2304
	v_pk_mul_f32 v[138:139], v[74:75], v[32:33]
	v_pk_mul_f32 v[166:167], v[72:73], v[34:35]
	v_pk_mul_f32 v[168:169], v[70:71], v[28:29]
	v_pk_mul_f32 v[180:181], v[68:69], v[30:31]
	v_cvt_pk_bf16_f32 v178, v166, v167
	v_cvt_pk_bf16_f32 v179, v138, v139
	v_cvt_pk_bf16_f32 v180, v180, v181
	v_cvt_pk_bf16_f32 v181, v168, v169
	v_pk_fma_f32 v[24:25], v[24:25], v[162:163], v[182:183]
	v_pk_fma_f32 v[22:23], v[22:23], v[160:161], v[190:191]
	v_lshlrev_b32_e32 v192, 16, v184
	v_and_b32_e32 v193, 0xffff0000, v184
	v_lshlrev_b32_e32 v184, 16, v185
	v_and_b32_e32 v185, 0xffff0000, v185
	global_store_dwordx4 v[214:215], v[178:181], off offset:256
	v_pk_fma_f32 v[20:21], v[20:21], v[158:159], v[184:185]
	v_pk_fma_f32 v[18:19], v[18:19], v[156:157], v[192:193]
	v_cvt_pk_bf16_f32 v178, v22, v23
	v_cvt_pk_bf16_f32 v179, v24, v25
	v_lshlrev_b32_e32 v24, 16, v178
	v_and_b32_e32 v25, 0xffff0000, v178
	v_lshlrev_b32_e32 v22, 16, v179
	v_and_b32_e32 v23, 0xffff0000, v179
	v_cvt_pk_bf16_f32 v180, v18, v19
	v_cvt_pk_bf16_f32 v181, v20, v21
	v_pk_mul_f32 v[138:139], v[74:75], v[22:23]
	v_pk_mul_f32 v[166:167], v[72:73], v[24:25]
	global_store_dwordx4 v[216:217], v[178:181], off offset:2304
	v_lshlrev_b32_e32 v20, 16, v180
	v_and_b32_e32 v21, 0xffff0000, v180
	v_cvt_pk_bf16_f32 v178, v166, v167
	v_cvt_pk_bf16_f32 v179, v138, v139
	v_lshlrev_b32_e32 v138, 16, v134
	v_and_b32_e32 v139, 0xffff0000, v134
	v_lshlrev_b32_e32 v134, 16, v135
	v_and_b32_e32 v135, 0xffff0000, v135
	v_lshlrev_b32_e32 v166, 16, v136
	v_and_b32_e32 v167, 0xffff0000, v136
	v_lshlrev_b32_e32 v136, 16, v137
	v_and_b32_e32 v137, 0xffff0000, v137
	v_lshlrev_b32_e32 v18, 16, v181
	v_and_b32_e32 v19, 0xffff0000, v181
	v_pk_fma_f32 v[16:17], v[16:17], v[162:163], v[134:135]
	v_pk_fma_f32 v[14:15], v[14:15], v[160:161], v[138:139]
	v_pk_fma_f32 v[12:13], v[12:13], v[158:159], v[136:137]
	v_pk_fma_f32 v[10:11], v[10:11], v[156:157], v[166:167]
	v_pk_mul_f32 v[168:169], v[70:71], v[18:19]
	v_pk_mul_f32 v[180:181], v[68:69], v[20:21]
	v_cvt_pk_bf16_f32 v134, v14, v15
	v_cvt_pk_bf16_f32 v135, v16, v17
	v_cvt_pk_bf16_f32 v136, v10, v11
	v_cvt_pk_bf16_f32 v137, v12, v13
	v_cvt_pk_bf16_f32 v180, v180, v181
	v_cvt_pk_bf16_f32 v181, v168, v169
	v_lshlrev_b32_e32 v16, 16, v134
	v_and_b32_e32 v17, 0xffff0000, v134
	v_lshlrev_b32_e32 v14, 16, v135
	v_and_b32_e32 v15, 0xffff0000, v135
	v_lshlrev_b32_e32 v12, 16, v136
	v_and_b32_e32 v13, 0xffff0000, v136
	v_lshlrev_b32_e32 v10, 16, v137
	v_and_b32_e32 v11, 0xffff0000, v137
	global_store_dwordx4 v[218:219], v[178:181], off offset:256
	v_lshlrev_b32_e32 v168, 16, v186
	v_and_b32_e32 v169, 0xffff0000, v186
	v_lshlrev_b32_e32 v178, 16, v187
	v_and_b32_e32 v179, 0xffff0000, v187
	v_lshlrev_b32_e32 v180, 16, v188
	v_and_b32_e32 v181, 0xffff0000, v188
	v_lshlrev_b32_e32 v182, 16, v189
	v_and_b32_e32 v183, 0xffff0000, v189
	global_store_dwordx4 v[196:197], v[134:137], off offset:2304
	v_pk_mul_f32 v[138:139], v[70:71], v[10:11]
	v_pk_mul_f32 v[166:167], v[68:69], v[12:13]
	v_pk_mul_f32 v[136:137], v[74:75], v[14:15]
	v_pk_mul_f32 v[134:135], v[72:73], v[16:17]
	v_pk_fma_f32 v[8:9], v[8:9], v[162:163], v[178:179]
	v_cvt_pk_bf16_f32 v134, v134, v135
	v_cvt_pk_bf16_f32 v135, v136, v137
	v_cvt_pk_bf16_f32 v136, v166, v167
	v_cvt_pk_bf16_f32 v137, v138, v139
	v_pk_fma_f32 v[6:7], v[6:7], v[160:161], v[168:169]
	v_pk_fma_f32 v[4:5], v[4:5], v[158:159], v[182:183]
	v_pk_fma_f32 v[2:3], v[2:3], v[156:157], v[180:181]
	global_store_dwordx4 v[210:211], v[134:137], off offset:256
	s_nop 1
	v_cvt_pk_bf16_f32 v134, v6, v7
	v_cvt_pk_bf16_f32 v135, v8, v9
	v_cvt_pk_bf16_f32 v136, v2, v3
	v_cvt_pk_bf16_f32 v137, v4, v5
	v_lshlrev_b32_e32 v8, 16, v134
	v_and_b32_e32 v9, 0xffff0000, v134
	v_lshlrev_b32_e32 v6, 16, v135
	v_and_b32_e32 v7, 0xffff0000, v135
	v_lshlrev_b32_e32 v4, 16, v136
	v_and_b32_e32 v5, 0xffff0000, v136
	v_lshlrev_b32_e32 v2, 16, v137
	v_and_b32_e32 v3, 0xffff0000, v137
	global_store_dwordx4 v[220:221], v[134:137], off offset:2304
	v_pk_mul_f32 v[74:75], v[74:75], v[6:7]
	v_pk_mul_f32 v[72:73], v[72:73], v[8:9]
	v_pk_mul_f32 v[134:135], v[70:71], v[2:3]
	v_pk_mul_f32 v[70:71], v[68:69], v[4:5]
	v_cvt_pk_bf16_f32 v68, v72, v73
	v_cvt_pk_bf16_f32 v69, v74, v75
	v_cvt_pk_bf16_f32 v70, v70, v71
	v_cvt_pk_bf16_f32 v71, v134, v135
	global_store_dwordx4 v[132:133], v[68:71], off offset:256
	v_xor_b32_e32 v72, 32, v227
	v_mul_f32_e32 v73, v129, v129
	v_and_b32_e32 v71, 64, v227
	v_xor_b32_e32 v70, 16, v227
	v_add_u32_e32 v71, 64, v71
	v_cmp_lt_i32_e32 vcc, v70, v71
	v_fmac_f32_e32 v73, v128, v128
	v_mul_f32_e32 v74, v125, v125
	v_cndmask_b32_e32 v70, v227, v70, vcc
	v_cmp_lt_i32_e32 vcc, v72, v71
	v_fmac_f32_e32 v74, v124, v124
	v_lshlrev_b32_e32 v70, 2, v70
	v_cndmask_b32_e32 v71, v227, v72, vcc
	v_mul_f32_e32 v72, v131, v131
	v_fmac_f32_e32 v72, v130, v130
	v_add_f32_e32 v72, v72, v73
	v_mul_f32_e32 v73, v127, v127
	v_fmac_f32_e32 v73, v126, v126
	v_add_f32_e32 v73, v73, v74
	v_add_f32_e32 v72, v72, v73
	v_add_f32_e32 v64, v72, v64
	v_add_f32_e32 v60, v60, v64
	ds_bpermute_b32 v61, v70, v60
	v_lshlrev_b32_e32 v71, 2, v71
	v_lshl_add_u64 v[68:69], v[150:151], 0, s[24:25]
	s_waitcnt lgkmcnt(0)
	v_add_f32_e32 v60, v60, v61
	ds_bpermute_b32 v61, v71, v60
	s_and_saveexec_b64 s[24:25], s[38:39]
	s_cbranch_execz .LBB0_1159
	s_waitcnt lgkmcnt(0)
	v_add_f32_e32 v60, v60, v61
	global_atomic_add_f32 v[68:69], v60, off
